# pointer-table reads through ds_read_b64 + lgkmcnt instead of flat_load + vmcnt(0): epilogues no longer drain the next unit's in-flight LDS-DMA prefetch (on top of v13)
# speedup vs baseline: 1.0098x; 1.0053x over previous
; #define GAS __attribute__((address_space(1)))
; __device__ __forceinline__ const float* ptr(int i) { const unsigned long long v = *(const volatile unsigned long long*)(g_lds + PTAB_OFF + 8 * i);
;     const unsigned lo = __builtin_amdgcn_readfirstlane((unsigned)v), hi = __builtin_amdgcn_readfirstlane((unsigned)(v >> 32)); return (const float*)(GAS const float*)(((unsigned long long)hi << 32) | lo); }
; __device__ __forceinline__ void phase0(const Ctx&, const In& in, float* h, unsigned char* ws) { const Ctx c = mk_ctx();
;     float* rss = (float*)(ws + WS_R + R_RSP + RB_ATTN * RSP_BYTES);
;     float* tab = (float*)(ws + WS_ROPE); const int* pos = (const int*)in[2];
;     for (int i = c.gw * 64 + c.lane; i < T * 16; i += c.NGW * 64) { const int row = i >> 4, k = i & 15;
;         const float inv = exp2f(-(float)k * (13.287712379549449f / 16.0f)); const float ang = (float)pos[row] * inv;
;         const float kq = rintf(ang * 0.15915494309189535f); float r = fmaf(-kq, 6.28125f, ang); r = fmaf(-kq, 0.0019353071795864769f, r);
;         tab[row * 32 + k] = cosf(r); tab[row * 32 + 16 + k] = sinf(r); }
.LBB0_17:
	s_or_b64 exec, exec, s[4:5]
	s_mov_b64 s[2:3], src_shared_base
	s_add_i32 s2, 0, 0x20108
	s_cmp_lg_u32 s2, -1
	v_writelane_b32 v254, s2, 3
	s_cselect_b32 s2, s2, 0
	s_cselect_b32 s4, s3, 0
	v_mov_b32_e32 v2, s2
	s_add_i32 s2, 0, 0x20110
	s_cmp_lg_u32 s2, -1
	v_mov_b32_e32 v3, s4
	v_writelane_b32 v254, s2, 4
	s_cselect_b32 s2, s2, 0
	s_cselect_b32 s4, s3, 0
	s_waitcnt lgkmcnt(0)
	s_barrier
	ds_read_b64 v[4:5], v2
	s_waitcnt lgkmcnt(0)
	v_mov_b32_e32 v2, s2
	v_mov_b32_e32 v3, s4
	ds_read_b64 v[8:9], v2
	s_waitcnt lgkmcnt(0)
	v_mov_b32_e32 v2, v147
	v_readlane_b32 s2, v254, 0
	v_readfirstlane_b32 s4, v2
	s_ashr_i32 s23, s4, 6
	s_lshl_b32 s24, s2, 3
	s_add_i32 s2, s23, s24
	s_add_u32 s4, s0, 0x118
	s_load_dword s0, s[0:1], 0x118
	s_addc_u32 s5, s1, 0
	v_writelane_b32 v254, s4, 5
	v_and_b32_e32 v1, 63, v2
	s_waitcnt lgkmcnt(0)
	v_readfirstlane_b32 s11, v5
	v_writelane_b32 v254, s5, 6
	v_writelane_b32 v254, s0, 7
	s_add_i32 s0, 0, 0x20010
	s_cmp_lg_u32 s0, -1
	s_cselect_b32 s0, s0, 0
	s_cselect_b32 s1, s3, 0
	v_mov_b32_e32 v6, s0
	v_mov_b32_e32 v7, s1
	ds_read_b64 v[10:11], v6
	s_waitcnt lgkmcnt(0)
	s_mov_b32 s0, 0x40000
	v_lshl_or_b32 v6, s2, 6, v1
	v_readfirstlane_b32 s10, v4
	v_readfirstlane_b32 s3, v9
	v_readfirstlane_b32 s22, v8
	v_cmp_gt_i32_e32 vcc, s0, v6
	s_waitcnt lgkmcnt(0)
	v_readfirstlane_b32 s13, v11
	v_readfirstlane_b32 s12, v10
	s_and_saveexec_b64 s[14:15], vcc
	s_cbranch_execz .LBB0_28
	v_and_b32_e32 v7, 15, v2
	v_cvt_f32_ubyte0_e32 v2, v7
	v_mul_f32_e32 v3, 0xbf549a78, v2
	s_mov_b32 s0, 0xc2fc0000
	v_mov_b32_e32 v4, 0x42800000
	v_cmp_gt_f32_e32 vcc, s0, v3
	v_not_b32_e32 v8, 63
	s_add_u32 s16, s22, 0x200000
	v_cndmask_b32_e32 v3, 0, v4, vcc
	v_fmac_f32_e32 v3, 0xbf549a78, v2
	v_exp_f32_e32 v2, v3
	v_readlane_b32 s0, v254, 7
	v_cndmask_b32_e32 v3, 0, v8, vcc
	s_addc_u32 s17, s3, 0
	s_lshl_b32 s25, s0, 9
	v_ldexp_f32 v9, v2, v3
	s_mov_b64 s[18:19], 0
	s_brev_b32 s26, 18
	s_mov_b32 s27, 0xfe5163ab
	v_mov_b32_e32 v3, 0
	s_mov_b32 s28, 0x3c439041
	s_mov_b32 s29, 0xdb629599
	s_mov_b32 s30, 0xf534ddc0
	s_mov_b32 s31, 0xfc2757d1
	s_mov_b32 s33, 0x4e441529
	s_mov_b32 s34, 0xa2f9836e
	s_mov_b32 s35, 0x3fc90fda
	s_mov_b32 s36, 0x3f22f983
	s_mov_b32 s37, 0xbfc90fda
	v_mov_b32_e32 v10, 0x3c0881c4
	v_mov_b32_e32 v11, 0xbab64f3b
	s_brev_b32 s38, 1
	s_movk_i32 s39, 0x1f8
	s_mov_b32 s40, 0x3ffff
	v_not_b32_e32 v12, 31
	v_mov_b32_e32 v13, 0x7fc00000
	s_branch .LBB0_20

; __device__ __forceinline__ v2u pk4(f32x4 v) { v2u o; o.x = pk2(v[0], v[1]); o.y = pk2(v[2], v[3]); return o; }
; __device__ __forceinline__ void phase0(const Ctx&, const In& in, float* h, unsigned char* ws) { const Ctx c = mk_ctx();
;     ...
;     const float* x = in[0]; const float* g0 = in[3]; bf16* hA = (bf16*)(ws + WS_R + R_HA2);
;     for (int row = c.gw; row < T; row += c.NGW) { float s = 0.f;
; #pragma unroll
;         for (int j = 0; j < 4; ++j) { const int col = 4 * c.lane + 256 * j; const f32x4 v = *(const f32x4*)(x + (size_t)row * 1024 + col); *(f32x4*)(h + (size_t)row * 1024 + col) = v;
;             s += (v[0] * v[0] + v[1] * v[1]) + (v[2] * v[2] + v[3] * v[3]); *(v2u*)(hA + (size_t)row * 1024 + col) = pk4(v * *(const f32x4*)(g0 + col)); }
;         s = wave_sum(s); if (c.lane < 16) rss[(size_t)row * 32 + c.lane] = c.lane == 0 ? s : 0.f; }
.LBB0_28:
	s_or_b64 exec, exec, s[14:15]
	s_mov_b64 s[0:1], src_shared_base
	v_readlane_b32 s0, v254, 7
	s_lshl_b32 s30, s0, 3
	s_add_i32 s0, 0, 0x20000
	s_cmp_lg_u32 s0, -1
	s_cselect_b32 s0, s0, 0
	s_cselect_b32 s4, s1, 0
	v_mov_b32_e32 v2, s0
	s_add_i32 s0, 0, 0x20018
	s_cmp_lg_u32 s0, -1
	v_writelane_b32 v254, s0, 8
	s_cselect_b32 s0, s0, 0
	s_cselect_b32 s1, s1, 0
	v_mov_b32_e32 v3, s4
	v_mov_b32_e32 v4, s0
	v_mov_b32_e32 v5, s1
	ds_read_b64 v[2:3], v2
	s_waitcnt lgkmcnt(0)
	s_cmpk_gt_i32 s2, 0x3fff
	ds_read_b64 v[4:5], v4
	s_waitcnt lgkmcnt(0)
	v_mbcnt_lo_u32_b32 v33, -1, 0
	s_waitcnt lgkmcnt(0)
	v_readfirstlane_b32 s7, v3
	v_readfirstlane_b32 s6, v2
	v_readfirstlane_b32 s5, v5
	v_readfirstlane_b32 s4, v4
	s_cbranch_scc1 .LBB0_33
	v_mov_b32_e32 v9, 0
	v_lshlrev_b32_e32 v6, 4, v1
	v_mov_b32_e32 v7, v9
	v_lshl_add_u64 v[2:3], s[4:5], 0, v[6:7]
	s_ashr_i32 s5, s23, 31
	s_ashr_i32 s8, s24, 31
	s_add_u32 s4, s23, s24
	s_addc_u32 s5, s5, s8
	s_lshl_b64 s[8:9], s[4:5], 7
	s_add_u32 s8, s22, s8
	v_lshlrev_b32_e32 v8, 2, v1
	s_addc_u32 s9, s3, s9
	v_lshl_add_u64 v[4:5], s[8:9], 0, v[8:9]
	s_mov_b64 s[8:9], 0x15600000
	s_ashr_i32 s31, s30, 31
	s_lshl_b64 s[12:13], s[4:5], 12
	v_lshl_add_u64 v[4:5], v[4:5], 0, s[8:9]
	s_lshl_b64 s[8:9], s[30:31], 7
	v_or_b32_e32 v6, s12, v6
	v_mov_b32_e32 v7, s13
	s_lshl_b64 s[12:13], s[30:31], 12
	s_lshl_b64 s[4:5], s[4:5], 11
	s_add_u32 s4, s22, s4
	v_cmp_gt_u32_e32 vcc, 16, v1
	v_cmp_eq_u32_e64 s[0:1], 0, v1
	v_lshlrev_b32_e32 v8, 3, v1
	s_addc_u32 s5, s3, s5
	v_mbcnt_hi_u32_b32 v1, -1, v33
	v_lshl_add_u64 v[8:9], s[4:5], 0, v[8:9]
	s_mov_b64 s[4:5], 0x11c00400
	v_and_b32_e32 v10, 64, v1
	v_lshl_add_u64 v[8:9], v[8:9], 0, s[4:5]
	s_lshl_b64 s[14:15], s[30:31], 11
	v_add_u32_e32 v10, 64, v10
	v_xor_b32_e32 v11, 1, v1
	v_xor_b32_e32 v12, 2, v1
	v_xor_b32_e32 v13, 4, v1
	v_xor_b32_e32 v14, 8, v1
	v_xor_b32_e32 v15, 16, v1
	v_xor_b32_e32 v16, 32, v1
	s_branch .LBB0_31

; __device__ __forceinline__ void transpose_mat(const Ctx& c, const float* W, int K, int N, bf16* WT) {
;     float* scr = (float*)(c.lds + c.wid * 16384); const int items = (K / 64) * (N / 32), nblk = N / 32, lane = c.lane;
;     float tv[32];
;     int it = c.gw;
;     if (it < items) { const int k0 = 64 * (it / nblk), n0 = 32 * (it % nblk);
; #pragma unroll
;         for (int i = 0; i < 32; ++i) tv[i] = W[(size_t)(k0 + 2 * i + (lane >> 5)) * N + n0 + (lane & 31)]; }
; __device__ __forceinline__ void conv_mixer(const Ctx&, const In& in, unsigned char* ws, int layer) { const Ctx c = mk_ctx();
;     const int j = layer >> 1; unsigned char* W = ws + WS_W;
;     if ((layer & 1) == 0) {
;         transpose_mat(c, in[13] + (size_t)j * 1024 * 3360, 1024, 3360, (bf16*)(W + W_HYBIN));
.LBB0_33:
	s_mov_b64 s[0:1], src_shared_base
	v_readlane_b32 s0, v254, 4
	s_cmp_lg_u32 s0, -1
	s_cselect_b32 s0, s0, 0
	s_cselect_b32 s2, s1, 0
	v_mov_b32_e32 v2, s0
	v_mov_b32_e32 v3, s2
	v_mov_b32_e32 v40, v147
	v_readlane_b32 s0, v254, 0
	ds_read_b64 v[2:3], v2
	s_waitcnt lgkmcnt(0)
	s_lshl_b32 s0, s0, 3
	v_readfirstlane_b32 s2, v40
	s_ashr_i32 s2, s2, 6
	s_add_i32 s4, s2, s0
	s_add_i32 s0, 0, 0x20068
	s_cmp_lg_u32 s0, -1
	v_writelane_b32 v254, s0, 9
	s_cselect_b32 s0, s0, 0
	s_cselect_b32 s1, s1, 0
	v_mov_b32_e32 v4, s0
	v_mov_b32_e32 v5, s1
	ds_read_b64 v[4:5], v4
	s_waitcnt lgkmcnt(0)
	v_and_b32_e32 v38, 63, v40
	s_cmpk_gt_i32 s4, 0x68f
	s_waitcnt lgkmcnt(0)
	v_readfirstlane_b32 s1, v3
	v_readfirstlane_b32 s0, v2
	v_readfirstlane_b32 s7, v5
	v_readfirstlane_b32 s6, v4
	s_cbranch_scc1 .LBB0_38
	s_lshl_b32 s3, s2, 14
	s_add_i32 s5, s3, 0
	s_mul_hi_i32 s3, s4, 0x9c09c09d
	s_add_i32 s3, s3, s4
	s_lshr_b32 s8, s3, 31
	s_ashr_i32 s3, s3, 6
	s_add_i32 s3, s3, s8
	s_mul_i32 s8, s3, 0x69
	s_sub_i32 s8, s4, s8
	s_lshl_b32 s8, s8, 5
	s_ashr_i32 s9, s8, 31
	s_lshl_b64 s[8:9], s[8:9], 2
	v_lshrrev_b32_e32 v39, 5, v38
	s_add_u32 s8, s6, s8
	v_lshlrev_b32_e32 v2, 2, v40
	v_lshl_or_b32 v1, s3, 6, v39
	s_addc_u32 s9, s7, s9
	v_and_b32_e32 v2, 0x7c, v2
	v_mov_b32_e32 v3, 0
	v_lshl_add_u64 v[4:5], s[8:9], 0, v[2:3]
	s_movk_i32 s3, 0x3480
	v_or_b32_e32 v6, 2, v1
	v_mad_i64_i32 v[20:21], s[8:9], v6, s3, v[4:5]
	v_or_b32_e32 v6, 4, v1
	v_mad_i64_i32 v[22:23], s[8:9], v6, s3, v[4:5]
	v_or_b32_e32 v6, 6, v1
	v_mad_i64_i32 v[24:25], s[8:9], v6, s3, v[4:5]
	v_or_b32_e32 v6, 8, v1
	v_mad_i64_i32 v[26:27], s[8:9], v6, s3, v[4:5]
	v_or_b32_e32 v6, 10, v1
	v_mad_i64_i32 v[28:29], s[8:9], v6, s3, v[4:5]
	v_or_b32_e32 v6, 12, v1
	v_mad_i64_i32 v[30:31], s[8:9], v6, s3, v[4:5]
	v_or_b32_e32 v6, 14, v1
	v_mad_i64_i32 v[44:45], s[8:9], v6, s3, v[4:5]
	v_or_b32_e32 v6, 16, v1
	v_mad_i64_i32 v[46:47], s[8:9], v6, s3, v[4:5]
	v_or_b32_e32 v6, 18, v1
	v_mad_i64_i32 v[48:49], s[8:9], v6, s3, v[4:5]
	v_or_b32_e32 v6, 20, v1
	v_mad_i64_i32 v[50:51], s[8:9], v6, s3, v[4:5]
	v_or_b32_e32 v6, 22, v1
	v_mad_i64_i32 v[52:53], s[8:9], v6, s3, v[4:5]
	v_or_b32_e32 v6, 24, v1
	v_mad_i64_i32 v[54:55], s[8:9], v6, s3, v[4:5]
	v_or_b32_e32 v6, 26, v1
	v_mad_i64_i32 v[56:57], s[8:9], v6, s3, v[4:5]
	v_or_b32_e32 v6, 28, v1
	v_mad_i64_i32 v[58:59], s[8:9], v6, s3, v[4:5]
	v_or_b32_e32 v6, 30, v1
	v_mad_i64_i32 v[60:61], s[8:9], v6, s3, v[4:5]
	v_or_b32_e32 v6, 32, v1
	v_mad_i64_i32 v[62:63], s[8:9], v6, s3, v[4:5]
	v_or_b32_e32 v6, 34, v1
	v_mad_i64_i32 v[64:65], s[8:9], v6, s3, v[4:5]
	v_or_b32_e32 v6, 36, v1
	v_mad_i64_i32 v[66:67], s[8:9], v6, s3, v[4:5]
	v_or_b32_e32 v6, 38, v1
	v_mad_i64_i32 v[68:69], s[8:9], v6, s3, v[4:5]
	v_or_b32_e32 v6, 40, v1
	v_mad_i64_i32 v[18:19], s[8:9], v1, s3, v[4:5]
	v_mad_i64_i32 v[70:71], s[8:9], v6, s3, v[4:5]
	v_or_b32_e32 v6, 42, v1
	v_or_b32_e32 v7, 44, v1
	v_or_b32_e32 v8, 46, v1
	v_or_b32_e32 v9, 48, v1
	v_or_b32_e32 v10, 50, v1
	v_or_b32_e32 v11, 52, v1
	v_or_b32_e32 v12, 54, v1
	v_or_b32_e32 v13, 56, v1
	v_or_b32_e32 v14, 58, v1
	v_or_b32_e32 v15, 60, v1
	v_or_b32_e32 v1, 62, v1
	v_mad_i64_i32 v[92:93], s[8:9], v1, s3, v[4:5]
	v_lshlrev_b32_e32 v1, 3, v38
	v_and_b32_e32 v1, 56, v1
	v_lshrrev_b32_e32 v41, 3, v38
	v_mad_i64_i32 v[72:73], s[8:9], v6, s3, v[4:5]
	v_mad_i64_i32 v[74:75], s[8:9], v7, s3, v[4:5]
	v_mad_i64_i32 v[76:77], s[8:9], v8, s3, v[4:5]
	v_mad_i64_i32 v[78:79], s[8:9], v9, s3, v[4:5]
	v_mad_i64_i32 v[80:81], s[8:9], v10, s3, v[4:5]
	v_mad_i64_i32 v[82:83], s[8:9], v11, s3, v[4:5]
	v_mad_i64_i32 v[84:85], s[8:9], v12, s3, v[4:5]
	v_mad_i64_i32 v[86:87], s[8:9], v13, s3, v[4:5]
	v_mad_i64_i32 v[88:89], s[8:9], v14, s3, v[4:5]
	v_mad_i64_i32 v[90:91], s[8:9], v15, s3, v[4:5]
	v_mul_u32_u24_e32 v4, 0x84, v1
	v_lshlrev_b32_e32 v5, 2, v41
	v_add3_u32 v42, s5, v4, v5
	v_lshlrev_b32_e32 v4, 1, v1
	v_mov_b32_e32 v5, v3
	v_mul_u32_u24_e32 v1, 0x84, v39
	v_add3_u32 v43, s5, v1, v2
	v_lshl_add_u64 v[34:35], s[6:7], 0, v[2:3]
	v_lshl_add_u64 v[2:3], s[0:1], 0, v[4:5]
	s_mov_b64 s[6:7], 0x2400000
	v_lshl_add_u64 v[36:37], v[2:3], 0, s[6:7]
	global_load_dword v2, v[18:19], off
	global_load_dword v1, v[20:21], off
	global_load_dword v4, v[22:23], off
	global_load_dword v3, v[24:25], off
	global_load_dword v6, v[26:27], off
	global_load_dword v5, v[28:29], off
	global_load_dword v8, v[30:31], off
	global_load_dword v7, v[44:45], off
	global_load_dword v10, v[46:47], off
	global_load_dword v9, v[48:49], off
	global_load_dword v12, v[50:51], off
	global_load_dword v11, v[52:53], off
	global_load_dword v14, v[54:55], off
	global_load_dword v13, v[56:57], off
	global_load_dword v16, v[58:59], off
	global_load_dword v15, v[60:61], off
	global_load_dword v18, v[62:63], off
	global_load_dword v17, v[64:65], off
	global_load_dword v20, v[66:67], off
	global_load_dword v19, v[68:69], off
	global_load_dword v22, v[70:71], off
	global_load_dword v21, v[72:73], off
	global_load_dword v24, v[74:75], off
	global_load_dword v23, v[76:77], off
	global_load_dword v26, v[78:79], off
	global_load_dword v25, v[80:81], off
	global_load_dword v28, v[82:83], off
	global_load_dword v27, v[84:85], off
	global_load_dword v30, v[86:87], off
	global_load_dword v29, v[88:89], off
	global_load_dword v32, v[90:91], off
	global_load_dword v31, v[92:93], off
	s_lshl_b32 s8, s30, 5
	s_lshl_b32 s5, s4, 5
	s_mov_b32 s9, s8
	s_mov_b32 s11, s4
	s_branch .LBB0_36

; __device__ __forceinline__ void transpose_mat(const Ctx& c, const float* W, int K, int N, bf16* WT) {
;     float* scr = (float*)(c.lds + c.wid * 16384); const int items = (K / 64) * (N / 32), nblk = N / 32, lane = c.lane;
;     float tv[32];
;     int it = c.gw;
;     if (it < items) { const int k0 = 64 * (it / nblk), n0 = 32 * (it % nblk);
; #pragma unroll
;         for (int i = 0; i < 32; ++i) tv[i] = W[(size_t)(k0 + 2 * i + (lane >> 5)) * N + n0 + (lane & 31)]; }
; __device__ __forceinline__ void conv_mixer(const Ctx&, const In& in, unsigned char* ws, int layer) { const Ctx c = mk_ctx();
;     ...
;         transpose_mat(c, in[14] + (size_t)j * 1024 * 1024, 1024, 1024, (bf16*)(W + W_HYBOUT));
.LBB0_42:
	s_add_i32 s3, 0, 0x20070
	s_mov_b64 s[6:7], src_shared_base
	s_cmp_lg_u32 s3, -1
	v_writelane_b32 v254, s3, 10
	s_cselect_b32 s3, s3, 0
	s_cselect_b32 s6, s7, 0
	v_mov_b32_e32 v2, s3
	v_mov_b32_e32 v3, s6
	ds_read_b64 v[2:3], v2
	s_waitcnt lgkmcnt(0)
	s_cmpk_gt_i32 s4, 0x1ff
	s_waitcnt lgkmcnt(0)
	v_readfirstlane_b32 s7, v3
	v_readfirstlane_b32 s6, v2
	s_cbranch_scc1 .LBB0_47
	s_lshr_b32 s3, s5, 27
	s_add_i32 s3, s4, s3
	s_lshl_b32 s5, s3, 1
	s_and_b32 s3, s3, 0x7ffffe0
	s_sub_i32 s3, s4, s3
	s_lshl_b32 s8, s3, 5
	s_lshl_b32 s2, s2, 14
	s_ashr_i32 s9, s8, 31
	s_add_i32 s2, s2, 0
	s_andn2_b32 s5, s5, 63
	v_lshrrev_b32_e32 v39, 5, v38
	s_lshl_b64 s[8:9], s[8:9], 2
	v_or_b32_e32 v4, s5, v39
	s_add_u32 s8, s6, s8
	v_lshlrev_b32_e32 v1, 2, v40
	s_addc_u32 s9, s7, s9
	v_and_b32_e32 v2, 0x7c, v1
	v_mov_b32_e32 v3, 0
	v_ashrrev_i32_e32 v5, 31, v4
	v_lshl_add_u64 v[6:7], s[8:9], 0, v[2:3]
	v_lshlrev_b64 v[8:9], 12, v[4:5]
	v_lshl_add_u64 v[18:19], v[6:7], 0, v[8:9]
	v_or_b32_e32 v8, 2, v4
	v_ashrrev_i32_e32 v9, 31, v8
	v_lshlrev_b64 v[8:9], 12, v[8:9]
	v_lshl_add_u64 v[20:21], v[6:7], 0, v[8:9]
	v_or_b32_e32 v8, 4, v4
	v_ashrrev_i32_e32 v9, 31, v8
	v_lshlrev_b64 v[8:9], 12, v[8:9]
	v_lshl_add_u64 v[22:23], v[6:7], 0, v[8:9]
	v_or_b32_e32 v8, 6, v4
	v_ashrrev_i32_e32 v9, 31, v8
	v_lshlrev_b64 v[8:9], 12, v[8:9]
	v_lshl_add_u64 v[24:25], v[6:7], 0, v[8:9]
	v_or_b32_e32 v8, 8, v4
	v_ashrrev_i32_e32 v9, 31, v8
	v_lshlrev_b64 v[8:9], 12, v[8:9]
	v_lshl_add_u64 v[26:27], v[6:7], 0, v[8:9]
	v_or_b32_e32 v8, 10, v4
	v_ashrrev_i32_e32 v9, 31, v8
	v_lshlrev_b64 v[8:9], 12, v[8:9]
	v_lshl_add_u64 v[28:29], v[6:7], 0, v[8:9]
	v_or_b32_e32 v8, 12, v4
	v_ashrrev_i32_e32 v9, 31, v8
	v_lshlrev_b64 v[8:9], 12, v[8:9]
	v_lshl_add_u64 v[30:31], v[6:7], 0, v[8:9]
	v_or_b32_e32 v8, 14, v4
	v_ashrrev_i32_e32 v9, 31, v8
	v_lshlrev_b64 v[8:9], 12, v[8:9]
	v_lshl_add_u64 v[44:45], v[6:7], 0, v[8:9]
	v_or_b32_e32 v8, 16, v4
	v_ashrrev_i32_e32 v9, 31, v8
	v_lshlrev_b64 v[8:9], 12, v[8:9]
	v_lshl_add_u64 v[46:47], v[6:7], 0, v[8:9]
	v_or_b32_e32 v8, 18, v4
	v_ashrrev_i32_e32 v9, 31, v8
	v_lshlrev_b64 v[8:9], 12, v[8:9]
	v_lshl_add_u64 v[48:49], v[6:7], 0, v[8:9]
	v_or_b32_e32 v8, 20, v4
	v_ashrrev_i32_e32 v9, 31, v8
	v_lshlrev_b64 v[8:9], 12, v[8:9]
	v_lshl_add_u64 v[50:51], v[6:7], 0, v[8:9]
	v_or_b32_e32 v8, 22, v4
	v_ashrrev_i32_e32 v9, 31, v8
	v_lshlrev_b64 v[8:9], 12, v[8:9]
	v_lshl_add_u64 v[52:53], v[6:7], 0, v[8:9]
	v_or_b32_e32 v8, 24, v4
	v_ashrrev_i32_e32 v9, 31, v8
	v_lshlrev_b64 v[8:9], 12, v[8:9]
	v_lshl_add_u64 v[54:55], v[6:7], 0, v[8:9]
	v_or_b32_e32 v8, 26, v4
	v_ashrrev_i32_e32 v9, 31, v8
	v_lshlrev_b64 v[8:9], 12, v[8:9]
	v_lshl_add_u64 v[56:57], v[6:7], 0, v[8:9]
	v_or_b32_e32 v8, 28, v4
	v_ashrrev_i32_e32 v9, 31, v8
	v_lshlrev_b64 v[8:9], 12, v[8:9]
	v_lshl_add_u64 v[58:59], v[6:7], 0, v[8:9]
	v_or_b32_e32 v8, 30, v4
	v_ashrrev_i32_e32 v9, 31, v8
	v_lshlrev_b64 v[8:9], 12, v[8:9]
	v_lshl_add_u64 v[60:61], v[6:7], 0, v[8:9]
	v_or_b32_e32 v8, 32, v4
	v_ashrrev_i32_e32 v9, 31, v8
	v_lshlrev_b64 v[8:9], 12, v[8:9]
	v_lshl_add_u64 v[62:63], v[6:7], 0, v[8:9]
	v_or_b32_e32 v8, 34, v4
	v_ashrrev_i32_e32 v9, 31, v8
	v_lshlrev_b64 v[8:9], 12, v[8:9]
	v_lshl_add_u64 v[64:65], v[6:7], 0, v[8:9]
	v_or_b32_e32 v8, 36, v4
	v_ashrrev_i32_e32 v9, 31, v8
	v_lshlrev_b64 v[8:9], 12, v[8:9]
	v_lshl_add_u64 v[66:67], v[6:7], 0, v[8:9]
	v_or_b32_e32 v8, 38, v4
	v_ashrrev_i32_e32 v9, 31, v8
	v_lshlrev_b64 v[8:9], 12, v[8:9]
	v_lshl_add_u64 v[68:69], v[6:7], 0, v[8:9]
	v_or_b32_e32 v8, 40, v4
	v_ashrrev_i32_e32 v9, 31, v8
	v_lshlrev_b64 v[8:9], 12, v[8:9]
	v_lshl_add_u64 v[70:71], v[6:7], 0, v[8:9]
	v_or_b32_e32 v8, 42, v4
	v_ashrrev_i32_e32 v9, 31, v8
	v_lshlrev_b64 v[8:9], 12, v[8:9]
	v_lshl_add_u64 v[72:73], v[6:7], 0, v[8:9]
	v_or_b32_e32 v8, 44, v4
	v_ashrrev_i32_e32 v9, 31, v8
	v_lshlrev_b64 v[8:9], 12, v[8:9]
	v_lshl_add_u64 v[74:75], v[6:7], 0, v[8:9]
	v_or_b32_e32 v8, 46, v4
	v_ashrrev_i32_e32 v9, 31, v8
	v_lshlrev_b64 v[8:9], 12, v[8:9]
	v_lshl_add_u64 v[76:77], v[6:7], 0, v[8:9]
	v_or_b32_e32 v8, 48, v4
	v_ashrrev_i32_e32 v9, 31, v8
	v_lshlrev_b64 v[8:9], 12, v[8:9]
	v_lshl_add_u64 v[78:79], v[6:7], 0, v[8:9]
	v_or_b32_e32 v8, 50, v4
	v_ashrrev_i32_e32 v9, 31, v8
	v_lshlrev_b64 v[8:9], 12, v[8:9]
	v_lshl_add_u64 v[80:81], v[6:7], 0, v[8:9]
	v_or_b32_e32 v8, 52, v4
	v_ashrrev_i32_e32 v9, 31, v8
	v_lshlrev_b64 v[8:9], 12, v[8:9]
	v_lshl_add_u64 v[82:83], v[6:7], 0, v[8:9]
	v_or_b32_e32 v8, 54, v4
	v_ashrrev_i32_e32 v9, 31, v8
	v_lshlrev_b64 v[8:9], 12, v[8:9]
	v_lshl_add_u64 v[84:85], v[6:7], 0, v[8:9]
	v_or_b32_e32 v8, 56, v4
	v_ashrrev_i32_e32 v9, 31, v8
	v_lshlrev_b64 v[8:9], 12, v[8:9]
	v_lshl_add_u64 v[86:87], v[6:7], 0, v[8:9]
	v_or_b32_e32 v8, 58, v4
	v_ashrrev_i32_e32 v9, 31, v8
	v_lshlrev_b64 v[8:9], 12, v[8:9]
	v_lshl_add_u64 v[88:89], v[6:7], 0, v[8:9]
	v_or_b32_e32 v8, 60, v4
	v_or_b32_e32 v4, 62, v4
	v_ashrrev_i32_e32 v9, 31, v8
	v_ashrrev_i32_e32 v5, 31, v4
	v_lshlrev_b32_e32 v1, 3, v38
	v_lshlrev_b64 v[8:9], 12, v[8:9]
	v_lshlrev_b64 v[4:5], 12, v[4:5]
	v_lshrrev_b32_e32 v40, 3, v38
	v_and_b32_e32 v1, 56, v1
	v_lshl_add_u64 v[90:91], v[6:7], 0, v[8:9]
	v_lshl_add_u64 v[92:93], v[6:7], 0, v[4:5]
	v_mul_u32_u24_e32 v6, 0x84, v1
	v_lshlrev_b32_e32 v4, 1, v1
	v_mov_b32_e32 v5, v3
	v_lshlrev_b32_e32 v1, 2, v40
	v_lshl_add_u64 v[34:35], s[6:7], 0, v[2:3]
	v_lshl_add_u64 v[4:5], s[0:1], 0, v[4:5]
	s_mov_b64 s[6:7], 0x2c80000
	v_add3_u32 v41, s2, v6, v1
	v_mul_u32_u24_e32 v1, 0x84, v39
	v_lshl_add_u64 v[36:37], v[4:5], 0, s[6:7]
	v_add3_u32 v42, s2, v1, v2
	global_load_dword v2, v[18:19], off
	global_load_dword v1, v[20:21], off
	global_load_dword v4, v[22:23], off
	global_load_dword v3, v[24:25], off
	global_load_dword v6, v[26:27], off
	global_load_dword v5, v[28:29], off
	global_load_dword v8, v[30:31], off
	global_load_dword v7, v[44:45], off
	global_load_dword v10, v[46:47], off
	global_load_dword v9, v[48:49], off
	global_load_dword v12, v[50:51], off
	global_load_dword v11, v[52:53], off
	global_load_dword v14, v[54:55], off
	global_load_dword v13, v[56:57], off
	global_load_dword v16, v[58:59], off
	global_load_dword v15, v[60:61], off
	global_load_dword v18, v[62:63], off
	global_load_dword v17, v[64:65], off
	global_load_dword v20, v[66:67], off
	global_load_dword v19, v[68:69], off
	global_load_dword v22, v[70:71], off
	global_load_dword v21, v[72:73], off
	global_load_dword v24, v[74:75], off
	global_load_dword v23, v[76:77], off
	global_load_dword v26, v[78:79], off
	global_load_dword v25, v[80:81], off
	global_load_dword v28, v[82:83], off
	global_load_dword v27, v[84:85], off
	global_load_dword v30, v[86:87], off
	global_load_dword v29, v[88:89], off
	global_load_dword v32, v[90:91], off
	global_load_dword v31, v[92:93], off
	s_lshl_b32 s3, s30, 5
	s_lshl_b32 s2, s4, 5
	s_mov_b32 s5, s3
	s_mov_b32 s9, s4
	s_branch .LBB0_45

; __device__ __forceinline__ unsigned f2bf(float f) { unsigned u = __builtin_bit_cast(unsigned, f); return (u + 0x7fffu + ((u >> 16) & 1u)) >> 16; }
; __device__ __forceinline__ void conv_mixer(const Ctx&, const In& in, unsigned char* ws, int layer) { const Ctx c = mk_ctx();
;     ...
;         bf16* L = (bf16*)(W + W_LORA); const float* w2 = in[17] + (size_t)j * 64 * 512; const float* a2 = in[19] + (size_t)j * 64 * 512; const float* g2 = in[20] + (size_t)j * 160 * 512;
;         for (int i = c.gw * 64 + c.lane; i < 1536 * 384; i += c.NGW * 64) { const int n = i / 384, k = i % 384; float v = 0.f;
;             if (n < 512) { if (k < 64) v = w2[k * 512 + n]; } else if (n < 1024) { if (k >= 64 && k < 128) v = a2[(k - 64) * 512 + n - 512]; } else { if (k >= 128 && k < 288) v = g2[(k - 128) * 512 + n - 1024]; }
;             L[i] = (bf16)f2bf(v); }
.LBB0_47:
	s_mov_b64 s[2:3], src_shared_base
	s_add_i32 s2, 0, 0x20088
	s_cmp_lg_u32 s2, -1
	v_writelane_b32 v254, s2, 11
	s_cselect_b32 s2, s2, 0
	s_cselect_b32 s5, s3, 0
	s_waitcnt vmcnt(35)
	v_mov_b32_e32 v2, s2
	s_add_i32 s2, 0, 0x20098
	s_cmp_lg_u32 s2, -1
	s_waitcnt vmcnt(32)
	v_mov_b32_e32 v3, s5
	v_writelane_b32 v254, s2, 12
	s_cselect_b32 s2, s2, 0
	s_waitcnt vmcnt(30)
	ds_read_b64 v[4:5], v2
	s_waitcnt lgkmcnt(0)
	s_cselect_b32 s5, s3, 0
	v_mov_b32_e32 v2, s2
	s_add_i32 s2, 0, 0x200a0
	s_cmp_lg_u32 s2, -1
	v_mov_b32_e32 v3, s5
	v_writelane_b32 v254, s2, 13
	s_cselect_b32 s2, s2, 0
	s_cselect_b32 s3, s3, 0
	ds_read_b64 v[6:7], v2
	s_waitcnt lgkmcnt(0)
	v_mov_b32_e32 v2, s2
	v_mov_b32_e32 v3, s3
	ds_read_b64 v[8:9], v2
	s_waitcnt lgkmcnt(0)
	v_lshl_or_b32 v2, s4, 6, v38
	s_mov_b32 s2, 0x90000
	v_cmp_gt_i32_e32 vcc, s2, v2
	s_waitcnt lgkmcnt(0)
	v_readfirstlane_b32 s5, v5
	v_readfirstlane_b32 s4, v4
	v_readfirstlane_b32 s7, v7
	v_readfirstlane_b32 s6, v6
	v_readfirstlane_b32 s9, v9
	v_readfirstlane_b32 s8, v8
	s_and_saveexec_b64 s[10:11], vcc
	s_cbranch_execz .LBB0_64
	s_add_u32 s0, s0, 0x2b00000
	v_readlane_b32 s3, v254, 7
	s_addc_u32 s1, s1, 0
	s_lshl_b32 s2, s3, 9
	v_lshlrev_b32_e32 v1, 9, v2
	s_lshl_b32 s3, s3, 18
	s_mov_b64 s[12:13], 0
	s_mov_b32 s20, 0x2aaaaaab
	s_mov_b32 s21, 0x2ffff
	s_mov_b32 s22, 0x5ffff
	s_movk_i32 s23, 0xa0
	s_mov_b32 s24, 0xffff0000
	s_movk_i32 s25, 0x8000
	v_mov_b32_e32 v5, 0
	s_movk_i32 s26, 0x7fff
	s_mov_b32 s27, 0x8ffff
	s_branch .LBB0_51

; __device__ __forceinline__ void transpose_mat(const Ctx& c, const float* W, int K, int N, bf16* WT) {
;     float* scr = (float*)(c.lds + c.wid * 16384); const int items = (K / 64) * (N / 32), nblk = N / 32, lane = c.lane;
;     float tv[32];
;     int it = c.gw;
;     if (it < items) { const int k0 = 64 * (it / nblk), n0 = 32 * (it % nblk);
; #pragma unroll
;         for (int i = 0; i < 32; ++i) tv[i] = W[(size_t)(k0 + 2 * i + (lane >> 5)) * N + n0 + (lane & 31)]; }
; __device__ __forceinline__ void conv_ffn(const Ctx&, const In& in, unsigned char* ws, int layer) { const Ctx c = mk_ctx();
;     unsigned char* W = ws + WS_W;
;     transpose_mat(c, in[5] + (size_t)layer * 1024 * 5632, 1024, 5632, (bf16*)(W + W_FFNIN));
.LBB0_64:
	s_or_b64 exec, exec, s[10:11]
	s_mov_b64 s[0:1], src_shared_base
	v_readlane_b32 s0, v254, 4
	s_cmp_lg_u32 s0, -1
	s_cselect_b32 s0, s0, 0
	s_cselect_b32 s2, s1, 0
	v_mov_b32_e32 v2, s0
	v_mov_b32_e32 v3, s2
	v_mov_b32_e32 v39, v147
	v_readlane_b32 s0, v254, 0
	ds_read_b64 v[2:3], v2
	s_waitcnt lgkmcnt(0)
	s_lshl_b32 s0, s0, 3
	v_readfirstlane_b32 s2, v39
	s_ashr_i32 s3, s2, 6
	s_add_i32 s2, s3, s0
	s_add_i32 s0, 0, 0x20028
	s_cmp_lg_u32 s0, -1
	v_writelane_b32 v254, s0, 14
	s_cselect_b32 s0, s0, 0
	s_cselect_b32 s1, s1, 0
	v_mov_b32_e32 v4, s0
	v_mov_b32_e32 v5, s1
	ds_read_b64 v[4:5], v4
	s_waitcnt lgkmcnt(0)
	v_and_b32_e32 v38, 63, v39
	s_cmpk_gt_i32 s2, 0xaff
	s_waitcnt lgkmcnt(0)
	v_readfirstlane_b32 s1, v3
	v_readfirstlane_b32 s0, v2
	v_readfirstlane_b32 s5, v5
	v_readfirstlane_b32 s4, v4
	s_cbranch_scc1 .LBB0_69
	s_lshl_b32 s6, s3, 14
	s_add_i32 s10, s6, 0
	s_mul_hi_i32 s6, s2, 0x2e8ba2e9
	s_lshr_b32 s7, s6, 31
	s_ashr_i32 s6, s6, 5
	s_add_i32 s7, s6, s7
	s_mul_i32 s6, s7, 0xb0
	s_sub_i32 s6, s2, s6
	s_lshl_b32 s6, s6, 5
	v_lshrrev_b32_e32 v40, 5, v38
	v_lshl_or_b32 v1, s7, 6, v40
	s_ashr_i32 s7, s6, 31
	s_lshl_b64 s[6:7], s[6:7], 2
	s_add_u32 s6, s4, s6
	v_lshlrev_b32_e32 v2, 2, v39
	s_addc_u32 s7, s5, s7
	v_and_b32_e32 v2, 0x7c, v2
	v_mov_b32_e32 v3, 0
	v_lshl_add_u64 v[4:5], s[6:7], 0, v[2:3]
	s_movk_i32 s6, 0x5800
	v_or_b32_e32 v6, 2, v1
	v_mad_i64_i32 v[20:21], s[8:9], v6, s6, v[4:5]
	v_or_b32_e32 v6, 4, v1
	v_mad_i64_i32 v[22:23], s[8:9], v6, s6, v[4:5]
	v_or_b32_e32 v6, 6, v1
	v_mad_i64_i32 v[24:25], s[8:9], v6, s6, v[4:5]
	v_or_b32_e32 v6, 8, v1
	v_mad_i64_i32 v[26:27], s[8:9], v6, s6, v[4:5]
	v_or_b32_e32 v6, 10, v1
	v_mad_i64_i32 v[28:29], s[8:9], v6, s6, v[4:5]
	v_or_b32_e32 v6, 12, v1
	v_mad_i64_i32 v[30:31], s[8:9], v6, s6, v[4:5]
	v_or_b32_e32 v6, 14, v1
	v_mad_i64_i32 v[44:45], s[8:9], v6, s6, v[4:5]
	v_or_b32_e32 v6, 16, v1
	v_mad_i64_i32 v[46:47], s[8:9], v6, s6, v[4:5]
	v_or_b32_e32 v6, 18, v1
	v_mad_i64_i32 v[48:49], s[8:9], v6, s6, v[4:5]
	v_or_b32_e32 v6, 20, v1
	v_mad_i64_i32 v[50:51], s[8:9], v6, s6, v[4:5]
	v_or_b32_e32 v6, 22, v1
	v_mad_i64_i32 v[52:53], s[8:9], v6, s6, v[4:5]
	v_or_b32_e32 v6, 24, v1
	v_mad_i64_i32 v[54:55], s[8:9], v6, s6, v[4:5]
	v_or_b32_e32 v6, 26, v1
	v_mad_i64_i32 v[56:57], s[8:9], v6, s6, v[4:5]
	v_or_b32_e32 v6, 28, v1
	v_mad_i64_i32 v[58:59], s[8:9], v6, s6, v[4:5]
	v_or_b32_e32 v6, 30, v1
	v_mad_i64_i32 v[60:61], s[8:9], v6, s6, v[4:5]
	v_or_b32_e32 v6, 32, v1
	v_mad_i64_i32 v[62:63], s[8:9], v6, s6, v[4:5]
	v_or_b32_e32 v6, 34, v1
	v_mad_i64_i32 v[64:65], s[8:9], v6, s6, v[4:5]
	v_or_b32_e32 v6, 36, v1
	v_mad_i64_i32 v[66:67], s[8:9], v6, s6, v[4:5]
	v_or_b32_e32 v6, 38, v1
	v_mad_i64_i32 v[68:69], s[8:9], v6, s6, v[4:5]
	v_or_b32_e32 v6, 40, v1
	v_mad_i64_i32 v[70:71], s[8:9], v6, s6, v[4:5]
	v_or_b32_e32 v6, 42, v1
	v_mad_i64_i32 v[72:73], s[8:9], v6, s6, v[4:5]
	v_or_b32_e32 v6, 44, v1
	v_mad_i64_i32 v[74:75], s[8:9], v6, s6, v[4:5]
	v_or_b32_e32 v6, 46, v1
	v_mad_i64_i32 v[76:77], s[8:9], v6, s6, v[4:5]
	v_or_b32_e32 v6, 48, v1
	v_mad_i64_i32 v[78:79], s[8:9], v6, s6, v[4:5]
	v_or_b32_e32 v6, 50, v1
	v_mad_i64_i32 v[80:81], s[8:9], v6, s6, v[4:5]
	v_or_b32_e32 v6, 52, v1
	v_mad_i64_i32 v[82:83], s[8:9], v6, s6, v[4:5]
	v_or_b32_e32 v6, 54, v1
	v_mad_i64_i32 v[84:85], s[8:9], v6, s6, v[4:5]
	v_or_b32_e32 v6, 56, v1
	v_mad_i64_i32 v[86:87], s[8:9], v6, s6, v[4:5]
	v_or_b32_e32 v6, 58, v1
	v_mad_i64_i32 v[18:19], s[8:9], v1, s6, v[4:5]
	v_mad_i64_i32 v[88:89], s[8:9], v6, s6, v[4:5]
	v_or_b32_e32 v6, 60, v1
	v_or_b32_e32 v1, 62, v1
	v_mad_i64_i32 v[92:93], s[8:9], v1, s6, v[4:5]
	v_lshlrev_b32_e32 v1, 3, v38
	v_lshrrev_b32_e32 v41, 3, v38
	v_and_b32_e32 v1, 56, v1
	v_mad_i64_i32 v[90:91], s[8:9], v6, s6, v[4:5]
	v_mul_u32_u24_e32 v6, 0x84, v1
	v_lshlrev_b32_e32 v4, 1, v1
	v_mov_b32_e32 v5, v3
	v_lshlrev_b32_e32 v1, 2, v41
	v_lshl_add_u64 v[34:35], s[4:5], 0, v[2:3]
	v_lshl_add_u64 v[4:5], s[0:1], 0, v[4:5]
	s_mov_b64 s[4:5], 0x3000000
	v_add3_u32 v42, s10, v6, v1
	v_mul_u32_u24_e32 v1, 0x84, v40
	v_lshl_add_u64 v[36:37], v[4:5], 0, s[4:5]
	v_add3_u32 v43, s10, v1, v2
	global_load_dword v2, v[18:19], off
	global_load_dword v1, v[20:21], off
	global_load_dword v4, v[22:23], off
	global_load_dword v3, v[24:25], off
	global_load_dword v6, v[26:27], off
	global_load_dword v5, v[28:29], off
	global_load_dword v8, v[30:31], off
	global_load_dword v7, v[44:45], off
	global_load_dword v10, v[46:47], off
	global_load_dword v9, v[48:49], off
	global_load_dword v12, v[50:51], off
	global_load_dword v11, v[52:53], off
	global_load_dword v14, v[54:55], off
	global_load_dword v13, v[56:57], off
	global_load_dword v16, v[58:59], off
	global_load_dword v15, v[60:61], off
	global_load_dword v18, v[62:63], off
	global_load_dword v17, v[64:65], off
	global_load_dword v20, v[66:67], off
	global_load_dword v19, v[68:69], off
	global_load_dword v22, v[70:71], off
	global_load_dword v21, v[72:73], off
	global_load_dword v24, v[74:75], off
	global_load_dword v23, v[76:77], off
	global_load_dword v26, v[78:79], off
	global_load_dword v25, v[80:81], off
	global_load_dword v28, v[82:83], off
	global_load_dword v27, v[84:85], off
	global_load_dword v30, v[86:87], off
	global_load_dword v29, v[88:89], off
	global_load_dword v32, v[90:91], off
	global_load_dword v31, v[92:93], off
	s_lshl_b32 s8, s30, 5
	s_lshl_b32 s7, s2, 5
	s_mov_b32 s9, s8
	s_mov_b32 s11, s2
	s_branch .LBB0_67

; #define GAS __attribute__((address_space(1)))
; __device__ __forceinline__ const float* ptr(int i) { const unsigned long long v = *(const volatile unsigned long long*)(g_lds + PTAB_OFF + 8 * i);
;     const unsigned lo = __builtin_amdgcn_readfirstlane((unsigned)v), hi = __builtin_amdgcn_readfirstlane((unsigned)(v >> 32)); return (const float*)(GAS const float*)(((unsigned long long)hi << 32) | lo); }
; __device__ __forceinline__ void conv_ffn(const Ctx&, const In& in, unsigned char* ws, int layer) { const Ctx c = mk_ctx();
;     unsigned char* W = ws + WS_W;
;     transpose_mat(c, in[5] + (size_t)layer * 1024 * 5632, 1024, 5632, (bf16*)(W + W_FFNIN));
;     transpose_mat(c, in[8] + (size_t)layer * 2816 * 1024, 2816, 1024, (bf16*)(W + W_FFNOUT));
.LBB0_69:
	s_mov_b64 s[4:5], src_shared_base
	s_add_i32 s4, 0, 0x20040
	s_cmp_lg_u32 s4, -1
	v_writelane_b32 v254, s4, 15
	s_cselect_b32 s4, s4, 0
	s_cselect_b32 s5, s5, 0
	s_waitcnt vmcnt(35)
	v_mov_b32_e32 v2, s4
	s_waitcnt vmcnt(32)
	v_mov_b32_e32 v3, s5
	ds_read_b64 v[2:3], v2
	s_waitcnt lgkmcnt(0)
	s_mul_i32 s6, s30, 0x16000
	s_cmpk_gt_i32 s2, 0x57f
	v_writelane_b32 v254, s6, 16
	s_waitcnt lgkmcnt(0)
	v_readfirstlane_b32 s5, v3
	v_readfirstlane_b32 s4, v2
	s_cbranch_scc1 .LBB0_74
; __device__ __forceinline__ void transpose_mat(const Ctx& c, const float* W, int K, int N, bf16* WT) {
;     float* scr = (float*)(c.lds + c.wid * 16384); const int items = (K / 64) * (N / 32), nblk = N / 32, lane = c.lane;
;     float tv[32];
;     int it = c.gw;
;     if (it < items) { const int k0 = 64 * (it / nblk), n0 = 32 * (it % nblk);
; #pragma unroll
;         for (int i = 0; i < 32; ++i) tv[i] = W[(size_t)(k0 + 2 * i + (lane >> 5)) * N + n0 + (lane & 31)]; }
	s_ashr_i32 s7, s2, 31
	s_lshr_b32 s7, s7, 27
	s_add_i32 s7, s2, s7
	s_lshl_b32 s8, s7, 1
	s_and_b32 s7, s7, 0x7ffffe0
	s_sub_i32 s7, s2, s7
	s_and_b32 s9, s8, 0xffffffc0
	s_lshl_b32 s8, s7, 5
	v_lshrrev_b32_e32 v40, 5, v38
	s_lshl_b32 s6, s3, 14
	v_or_b32_e32 v4, s9, v40
	s_ashr_i32 s9, s8, 31
	s_add_i32 s6, s6, 0
	s_lshl_b64 s[8:9], s[8:9], 2
	s_add_u32 s8, s4, s8
	v_lshlrev_b32_e32 v1, 2, v39
	s_addc_u32 s9, s5, s9
	v_and_b32_e32 v2, 0x7c, v1
	v_mov_b32_e32 v3, 0
	v_ashrrev_i32_e32 v5, 31, v4
	v_lshl_add_u64 v[6:7], s[8:9], 0, v[2:3]
	v_lshlrev_b64 v[8:9], 12, v[4:5]
	v_lshl_add_u64 v[18:19], v[6:7], 0, v[8:9]
	v_or_b32_e32 v8, 2, v4
	v_ashrrev_i32_e32 v9, 31, v8
	v_lshlrev_b64 v[8:9], 12, v[8:9]
	v_lshl_add_u64 v[20:21], v[6:7], 0, v[8:9]
	v_or_b32_e32 v8, 4, v4
	v_ashrrev_i32_e32 v9, 31, v8
	v_lshlrev_b64 v[8:9], 12, v[8:9]
	v_lshl_add_u64 v[22:23], v[6:7], 0, v[8:9]
	v_or_b32_e32 v8, 6, v4
	v_ashrrev_i32_e32 v9, 31, v8
	v_lshlrev_b64 v[8:9], 12, v[8:9]
	v_lshl_add_u64 v[24:25], v[6:7], 0, v[8:9]
	v_or_b32_e32 v8, 8, v4
	v_ashrrev_i32_e32 v9, 31, v8
	v_lshlrev_b64 v[8:9], 12, v[8:9]
	v_lshl_add_u64 v[26:27], v[6:7], 0, v[8:9]
	v_or_b32_e32 v8, 10, v4
	v_ashrrev_i32_e32 v9, 31, v8
	v_lshlrev_b64 v[8:9], 12, v[8:9]
	v_lshl_add_u64 v[28:29], v[6:7], 0, v[8:9]
	v_or_b32_e32 v8, 12, v4
	v_ashrrev_i32_e32 v9, 31, v8
	v_lshlrev_b64 v[8:9], 12, v[8:9]
	v_lshl_add_u64 v[30:31], v[6:7], 0, v[8:9]
	v_or_b32_e32 v8, 14, v4
	v_ashrrev_i32_e32 v9, 31, v8
	v_lshlrev_b64 v[8:9], 12, v[8:9]
	v_lshl_add_u64 v[44:45], v[6:7], 0, v[8:9]
	v_or_b32_e32 v8, 16, v4
	v_ashrrev_i32_e32 v9, 31, v8
	v_lshlrev_b64 v[8:9], 12, v[8:9]
	v_lshl_add_u64 v[46:47], v[6:7], 0, v[8:9]
	v_or_b32_e32 v8, 18, v4
	v_ashrrev_i32_e32 v9, 31, v8
	v_lshlrev_b64 v[8:9], 12, v[8:9]
	v_lshl_add_u64 v[48:49], v[6:7], 0, v[8:9]
	v_or_b32_e32 v8, 20, v4
	v_ashrrev_i32_e32 v9, 31, v8
	v_lshlrev_b64 v[8:9], 12, v[8:9]
	v_lshl_add_u64 v[50:51], v[6:7], 0, v[8:9]
	v_or_b32_e32 v8, 22, v4
	v_ashrrev_i32_e32 v9, 31, v8
	v_lshlrev_b64 v[8:9], 12, v[8:9]
	v_lshl_add_u64 v[52:53], v[6:7], 0, v[8:9]
	v_or_b32_e32 v8, 24, v4
	v_ashrrev_i32_e32 v9, 31, v8
	v_lshlrev_b64 v[8:9], 12, v[8:9]
	v_lshl_add_u64 v[54:55], v[6:7], 0, v[8:9]
	v_or_b32_e32 v8, 26, v4
	v_ashrrev_i32_e32 v9, 31, v8
	v_lshlrev_b64 v[8:9], 12, v[8:9]
	v_lshl_add_u64 v[56:57], v[6:7], 0, v[8:9]
	v_or_b32_e32 v8, 28, v4
	v_ashrrev_i32_e32 v9, 31, v8
	v_lshlrev_b64 v[8:9], 12, v[8:9]
	v_lshl_add_u64 v[58:59], v[6:7], 0, v[8:9]
	v_or_b32_e32 v8, 30, v4
	v_ashrrev_i32_e32 v9, 31, v8
	v_lshlrev_b64 v[8:9], 12, v[8:9]
	v_lshl_add_u64 v[60:61], v[6:7], 0, v[8:9]
	v_or_b32_e32 v8, 32, v4
	v_ashrrev_i32_e32 v9, 31, v8
	v_lshlrev_b64 v[8:9], 12, v[8:9]
	v_lshl_add_u64 v[62:63], v[6:7], 0, v[8:9]
	v_or_b32_e32 v8, 34, v4
	v_ashrrev_i32_e32 v9, 31, v8
	v_lshlrev_b64 v[8:9], 12, v[8:9]
	v_lshl_add_u64 v[64:65], v[6:7], 0, v[8:9]
	v_or_b32_e32 v8, 36, v4
	v_ashrrev_i32_e32 v9, 31, v8
	v_lshlrev_b64 v[8:9], 12, v[8:9]
	v_lshl_add_u64 v[66:67], v[6:7], 0, v[8:9]
	v_or_b32_e32 v8, 38, v4
	v_ashrrev_i32_e32 v9, 31, v8
	v_lshlrev_b64 v[8:9], 12, v[8:9]
	v_lshl_add_u64 v[68:69], v[6:7], 0, v[8:9]
	v_or_b32_e32 v8, 40, v4
	v_ashrrev_i32_e32 v9, 31, v8
	v_lshlrev_b64 v[8:9], 12, v[8:9]
	v_lshl_add_u64 v[70:71], v[6:7], 0, v[8:9]
	v_or_b32_e32 v8, 42, v4
	v_ashrrev_i32_e32 v9, 31, v8
	v_lshlrev_b64 v[8:9], 12, v[8:9]
	v_lshl_add_u64 v[72:73], v[6:7], 0, v[8:9]
	v_or_b32_e32 v8, 44, v4
	v_ashrrev_i32_e32 v9, 31, v8
	v_lshlrev_b64 v[8:9], 12, v[8:9]
	v_lshl_add_u64 v[74:75], v[6:7], 0, v[8:9]
	v_or_b32_e32 v8, 46, v4
	v_ashrrev_i32_e32 v9, 31, v8
	v_lshlrev_b64 v[8:9], 12, v[8:9]
	v_lshl_add_u64 v[76:77], v[6:7], 0, v[8:9]
	v_or_b32_e32 v8, 48, v4
	v_ashrrev_i32_e32 v9, 31, v8
	v_lshlrev_b64 v[8:9], 12, v[8:9]
	v_lshl_add_u64 v[78:79], v[6:7], 0, v[8:9]
	v_or_b32_e32 v8, 50, v4
	v_ashrrev_i32_e32 v9, 31, v8
	v_lshlrev_b64 v[8:9], 12, v[8:9]
	v_lshl_add_u64 v[80:81], v[6:7], 0, v[8:9]
	v_or_b32_e32 v8, 52, v4
	v_ashrrev_i32_e32 v9, 31, v8
	v_lshlrev_b64 v[8:9], 12, v[8:9]
	v_lshl_add_u64 v[82:83], v[6:7], 0, v[8:9]
	v_or_b32_e32 v8, 54, v4
	v_ashrrev_i32_e32 v9, 31, v8
	v_lshlrev_b64 v[8:9], 12, v[8:9]
	v_lshl_add_u64 v[84:85], v[6:7], 0, v[8:9]
	v_or_b32_e32 v8, 56, v4
	v_ashrrev_i32_e32 v9, 31, v8
	v_lshlrev_b64 v[8:9], 12, v[8:9]
	v_lshl_add_u64 v[86:87], v[6:7], 0, v[8:9]
	v_or_b32_e32 v8, 58, v4
	v_ashrrev_i32_e32 v9, 31, v8
	v_lshlrev_b64 v[8:9], 12, v[8:9]
	v_lshl_add_u64 v[88:89], v[6:7], 0, v[8:9]
	v_or_b32_e32 v8, 60, v4
	v_or_b32_e32 v4, 62, v4
	v_ashrrev_i32_e32 v5, 31, v4
	v_lshlrev_b64 v[4:5], 12, v[4:5]
	v_ashrrev_i32_e32 v9, 31, v8
	v_lshl_add_u64 v[92:93], v[6:7], 0, v[4:5]
	v_lshlrev_b32_e32 v4, 3, v38
	v_lshlrev_b64 v[8:9], 12, v[8:9]
	v_and_b32_e32 v4, 56, v4
	v_lshl_add_u64 v[90:91], v[6:7], 0, v[8:9]
	v_lshrrev_b32_e32 v1, 3, v38
	v_mul_u32_u24_e32 v6, 0x84, v4
	v_lshlrev_b32_e32 v4, 1, v4
	v_mov_b32_e32 v5, v3
	v_lshl_add_u64 v[34:35], s[4:5], 0, v[2:3]
	v_lshl_add_u64 v[4:5], s[0:1], 0, v[4:5]
	s_mov_b64 s[4:5], 0x3b00000
	v_lshlrev_b32_e32 v3, 2, v1
	v_lshl_add_u64 v[36:37], v[4:5], 0, s[4:5]
	v_add3_u32 v41, s6, v6, v3
	v_mul_u32_u24_e32 v3, 0x84, v40
	s_mul_i32 s4, s2, 0x16000
	v_add3_u32 v42, s6, v3, v2
	s_movk_i32 s5, 0xb00
	v_mov_b32_e32 v2, s4
	v_mad_u32_u24 v43, v1, s5, v2
	global_load_dword v2, v[18:19], off
	global_load_dword v1, v[20:21], off
	global_load_dword v4, v[22:23], off
	global_load_dword v3, v[24:25], off
	global_load_dword v6, v[26:27], off
	global_load_dword v5, v[28:29], off
	global_load_dword v8, v[30:31], off
	global_load_dword v7, v[44:45], off
	global_load_dword v10, v[46:47], off
	global_load_dword v9, v[48:49], off
	global_load_dword v12, v[50:51], off
	global_load_dword v11, v[52:53], off
	global_load_dword v14, v[54:55], off
	global_load_dword v13, v[56:57], off
	global_load_dword v16, v[58:59], off
	global_load_dword v15, v[60:61], off
	global_load_dword v18, v[62:63], off
	global_load_dword v17, v[64:65], off
	global_load_dword v20, v[66:67], off
	global_load_dword v19, v[68:69], off
	global_load_dword v22, v[70:71], off
	global_load_dword v21, v[72:73], off
	global_load_dword v24, v[74:75], off
	global_load_dword v23, v[76:77], off
	global_load_dword v26, v[78:79], off
	global_load_dword v25, v[80:81], off
	global_load_dword v28, v[82:83], off
	global_load_dword v27, v[84:85], off
	global_load_dword v30, v[86:87], off
	global_load_dword v29, v[88:89], off
	global_load_dword v32, v[90:91], off
	global_load_dword v31, v[92:93], off
	s_add_i32 s4, s30, s2
	s_lshl_b32 s6, s4, 5
	s_lshl_b32 s7, s30, 5
	s_mov_b32 s9, s2
	s_branch .LBB0_72

; __device__ __forceinline__ void transpose_mat(const Ctx& c, const float* W, int K, int N, bf16* WT) {
;     float* scr = (float*)(c.lds + c.wid * 16384); const int items = (K / 64) * (N / 32), nblk = N / 32, lane = c.lane;
;     float tv[32];
;     int it = c.gw;
;     if (it < items) { const int k0 = 64 * (it / nblk), n0 = 32 * (it % nblk);
; #pragma unroll
;         for (int i = 0; i < 32; ++i) tv[i] = W[(size_t)(k0 + 2 * i + (lane >> 5)) * N + n0 + (lane & 31)]; }
; __device__ __forceinline__ void conv_ffn(const Ctx&, const In& in, unsigned char* ws, int layer) { const Ctx c = mk_ctx();
;     ...
;     transpose_mat(c, in[9] + (size_t)layer * 256 * 1024, 256, 1024, (bf16*)(W + W_PLEP));
.LBB0_74:
	s_mov_b64 s[4:5], src_shared_base
	s_add_i32 s4, 0, 0x20048
	s_cmp_lg_u32 s4, -1
	v_writelane_b32 v254, s4, 17
	s_cselect_b32 s4, s4, 0
	s_cselect_b32 s5, s5, 0
	s_waitcnt vmcnt(35)
	v_mov_b32_e32 v2, s4
	s_waitcnt vmcnt(32)
	v_mov_b32_e32 v3, s5
	ds_read_b64 v[2:3], v2
	s_waitcnt lgkmcnt(0)
	s_cmpk_gt_i32 s2, 0x7f
	s_waitcnt lgkmcnt(0)
	v_readfirstlane_b32 s5, v3
	v_readfirstlane_b32 s4, v2
	s_cbranch_scc1 .LBB0_79
	s_ashr_i32 s7, s2, 31
	s_lshr_b32 s7, s7, 27
	s_add_i32 s7, s2, s7
	s_lshl_b32 s8, s7, 1
	s_and_b32 s7, s7, 0x7ffffe0
	s_sub_i32 s7, s2, s7
	s_and_b32 s9, s8, 0xffffffc0
	s_lshl_b32 s8, s7, 5
	v_lshrrev_b32_e32 v40, 5, v38
	s_lshl_b32 s6, s3, 14
	v_or_b32_e32 v4, s9, v40
	s_ashr_i32 s9, s8, 31
	s_add_i32 s6, s6, 0
	s_lshl_b64 s[8:9], s[8:9], 2
	s_add_u32 s8, s4, s8
	v_lshlrev_b32_e32 v1, 2, v39
	s_addc_u32 s9, s5, s9
	v_and_b32_e32 v2, 0x7c, v1
	v_mov_b32_e32 v3, 0
	v_ashrrev_i32_e32 v5, 31, v4
	v_lshl_add_u64 v[6:7], s[8:9], 0, v[2:3]
	v_lshlrev_b64 v[8:9], 12, v[4:5]
	v_lshl_add_u64 v[18:19], v[6:7], 0, v[8:9]
	v_or_b32_e32 v8, 2, v4
	v_ashrrev_i32_e32 v9, 31, v8
	v_lshlrev_b64 v[8:9], 12, v[8:9]
	v_lshl_add_u64 v[20:21], v[6:7], 0, v[8:9]
	v_or_b32_e32 v8, 4, v4
	v_ashrrev_i32_e32 v9, 31, v8
	v_lshlrev_b64 v[8:9], 12, v[8:9]
	v_lshl_add_u64 v[22:23], v[6:7], 0, v[8:9]
	v_or_b32_e32 v8, 6, v4
	v_ashrrev_i32_e32 v9, 31, v8
	v_lshlrev_b64 v[8:9], 12, v[8:9]
	v_lshl_add_u64 v[24:25], v[6:7], 0, v[8:9]
	v_or_b32_e32 v8, 8, v4
	v_ashrrev_i32_e32 v9, 31, v8
	v_lshlrev_b64 v[8:9], 12, v[8:9]
	v_lshl_add_u64 v[26:27], v[6:7], 0, v[8:9]
	v_or_b32_e32 v8, 10, v4
	v_ashrrev_i32_e32 v9, 31, v8
	v_lshlrev_b64 v[8:9], 12, v[8:9]
	v_lshl_add_u64 v[28:29], v[6:7], 0, v[8:9]
	v_or_b32_e32 v8, 12, v4
	v_ashrrev_i32_e32 v9, 31, v8
	v_lshlrev_b64 v[8:9], 12, v[8:9]
	v_lshl_add_u64 v[30:31], v[6:7], 0, v[8:9]
	v_or_b32_e32 v8, 14, v4
	v_ashrrev_i32_e32 v9, 31, v8
	v_lshlrev_b64 v[8:9], 12, v[8:9]
	v_lshl_add_u64 v[44:45], v[6:7], 0, v[8:9]
	v_or_b32_e32 v8, 16, v4
	v_ashrrev_i32_e32 v9, 31, v8
	v_lshlrev_b64 v[8:9], 12, v[8:9]
	v_lshl_add_u64 v[46:47], v[6:7], 0, v[8:9]
	v_or_b32_e32 v8, 18, v4
	v_ashrrev_i32_e32 v9, 31, v8
	v_lshlrev_b64 v[8:9], 12, v[8:9]
	v_lshl_add_u64 v[48:49], v[6:7], 0, v[8:9]
	v_or_b32_e32 v8, 20, v4
	v_ashrrev_i32_e32 v9, 31, v8
	v_lshlrev_b64 v[8:9], 12, v[8:9]
	v_lshl_add_u64 v[50:51], v[6:7], 0, v[8:9]
	v_or_b32_e32 v8, 22, v4
	v_ashrrev_i32_e32 v9, 31, v8
	v_lshlrev_b64 v[8:9], 12, v[8:9]
	v_lshl_add_u64 v[52:53], v[6:7], 0, v[8:9]
	v_or_b32_e32 v8, 24, v4
	v_ashrrev_i32_e32 v9, 31, v8
	v_lshlrev_b64 v[8:9], 12, v[8:9]
	v_lshl_add_u64 v[54:55], v[6:7], 0, v[8:9]
	v_or_b32_e32 v8, 26, v4
	v_ashrrev_i32_e32 v9, 31, v8
	v_lshlrev_b64 v[8:9], 12, v[8:9]
	v_lshl_add_u64 v[56:57], v[6:7], 0, v[8:9]
	v_or_b32_e32 v8, 28, v4
	v_ashrrev_i32_e32 v9, 31, v8
	v_lshlrev_b64 v[8:9], 12, v[8:9]
	v_lshl_add_u64 v[58:59], v[6:7], 0, v[8:9]
	v_or_b32_e32 v8, 30, v4
	v_ashrrev_i32_e32 v9, 31, v8
	v_lshlrev_b64 v[8:9], 12, v[8:9]
	v_lshl_add_u64 v[60:61], v[6:7], 0, v[8:9]
	v_or_b32_e32 v8, 32, v4
	v_ashrrev_i32_e32 v9, 31, v8
	v_lshlrev_b64 v[8:9], 12, v[8:9]
	v_lshl_add_u64 v[62:63], v[6:7], 0, v[8:9]
	v_or_b32_e32 v8, 34, v4
	v_ashrrev_i32_e32 v9, 31, v8
	v_lshlrev_b64 v[8:9], 12, v[8:9]
	v_lshl_add_u64 v[64:65], v[6:7], 0, v[8:9]
	v_or_b32_e32 v8, 36, v4
	v_ashrrev_i32_e32 v9, 31, v8
	v_lshlrev_b64 v[8:9], 12, v[8:9]
	v_lshl_add_u64 v[66:67], v[6:7], 0, v[8:9]
	v_or_b32_e32 v8, 38, v4
	v_ashrrev_i32_e32 v9, 31, v8
	v_lshlrev_b64 v[8:9], 12, v[8:9]
	v_lshl_add_u64 v[68:69], v[6:7], 0, v[8:9]
	v_or_b32_e32 v8, 40, v4
	v_ashrrev_i32_e32 v9, 31, v8
	v_lshlrev_b64 v[8:9], 12, v[8:9]
	v_lshl_add_u64 v[70:71], v[6:7], 0, v[8:9]
	v_or_b32_e32 v8, 42, v4
	v_ashrrev_i32_e32 v9, 31, v8
	v_lshlrev_b64 v[8:9], 12, v[8:9]
	v_lshl_add_u64 v[72:73], v[6:7], 0, v[8:9]
	v_or_b32_e32 v8, 44, v4
	v_ashrrev_i32_e32 v9, 31, v8
	v_lshlrev_b64 v[8:9], 12, v[8:9]
	v_lshl_add_u64 v[74:75], v[6:7], 0, v[8:9]
	v_or_b32_e32 v8, 46, v4
	v_ashrrev_i32_e32 v9, 31, v8
	v_lshlrev_b64 v[8:9], 12, v[8:9]
	v_lshl_add_u64 v[76:77], v[6:7], 0, v[8:9]
	v_or_b32_e32 v8, 48, v4
	v_ashrrev_i32_e32 v9, 31, v8
	v_lshlrev_b64 v[8:9], 12, v[8:9]
	v_lshl_add_u64 v[78:79], v[6:7], 0, v[8:9]
	v_or_b32_e32 v8, 50, v4
	v_ashrrev_i32_e32 v9, 31, v8
	v_lshlrev_b64 v[8:9], 12, v[8:9]
	v_lshl_add_u64 v[80:81], v[6:7], 0, v[8:9]
	v_or_b32_e32 v8, 52, v4
	v_ashrrev_i32_e32 v9, 31, v8
	v_lshlrev_b64 v[8:9], 12, v[8:9]
	v_lshl_add_u64 v[82:83], v[6:7], 0, v[8:9]
	v_or_b32_e32 v8, 54, v4
	v_ashrrev_i32_e32 v9, 31, v8
	v_lshlrev_b64 v[8:9], 12, v[8:9]
	v_lshl_add_u64 v[84:85], v[6:7], 0, v[8:9]
	v_or_b32_e32 v8, 56, v4
	v_ashrrev_i32_e32 v9, 31, v8
	v_lshlrev_b64 v[8:9], 12, v[8:9]
	v_lshl_add_u64 v[86:87], v[6:7], 0, v[8:9]
	v_or_b32_e32 v8, 58, v4
	v_ashrrev_i32_e32 v9, 31, v8
	v_lshlrev_b64 v[8:9], 12, v[8:9]
	v_lshl_add_u64 v[88:89], v[6:7], 0, v[8:9]
	v_or_b32_e32 v8, 60, v4
	v_or_b32_e32 v4, 62, v4
	v_ashrrev_i32_e32 v9, 31, v8
	v_ashrrev_i32_e32 v5, 31, v4
	v_lshlrev_b32_e32 v1, 3, v38
	v_lshlrev_b64 v[8:9], 12, v[8:9]
	v_lshlrev_b64 v[4:5], 12, v[4:5]
	v_lshrrev_b32_e32 v41, 3, v38
	v_and_b32_e32 v1, 56, v1
	v_lshl_add_u64 v[90:91], v[6:7], 0, v[8:9]
	v_lshl_add_u64 v[92:93], v[6:7], 0, v[4:5]
	v_mul_u32_u24_e32 v6, 0x84, v1
	v_lshlrev_b32_e32 v4, 1, v1
	v_mov_b32_e32 v5, v3
	v_lshlrev_b32_e32 v1, 2, v41
	v_lshl_add_u64 v[34:35], s[4:5], 0, v[2:3]
	v_lshl_add_u64 v[4:5], s[0:1], 0, v[4:5]
	s_mov_b64 s[4:5], 0x4080000
	v_add3_u32 v42, s6, v6, v1
	v_mul_u32_u24_e32 v1, 0x84, v40
	v_lshl_add_u64 v[36:37], v[4:5], 0, s[4:5]
	v_add3_u32 v43, s6, v1, v2
	global_load_dword v2, v[18:19], off
	global_load_dword v1, v[20:21], off
	global_load_dword v4, v[22:23], off
	global_load_dword v3, v[24:25], off
	global_load_dword v6, v[26:27], off
	global_load_dword v5, v[28:29], off
	global_load_dword v8, v[30:31], off
	global_load_dword v7, v[44:45], off
	global_load_dword v10, v[46:47], off
	global_load_dword v9, v[48:49], off
	global_load_dword v12, v[50:51], off
	global_load_dword v11, v[52:53], off
	global_load_dword v14, v[54:55], off
	global_load_dword v13, v[56:57], off
	global_load_dword v16, v[58:59], off
	global_load_dword v15, v[60:61], off
	global_load_dword v18, v[62:63], off
	global_load_dword v17, v[64:65], off
	global_load_dword v20, v[66:67], off
	global_load_dword v19, v[68:69], off
	global_load_dword v22, v[70:71], off
	global_load_dword v21, v[72:73], off
	global_load_dword v24, v[74:75], off
	global_load_dword v23, v[76:77], off
	global_load_dword v26, v[78:79], off
	global_load_dword v25, v[80:81], off
	global_load_dword v28, v[82:83], off
	global_load_dword v27, v[84:85], off
	global_load_dword v30, v[86:87], off
	global_load_dword v29, v[88:89], off
	global_load_dword v32, v[90:91], off
	global_load_dword v31, v[92:93], off
	s_lshl_b32 s7, s30, 5
	s_lshl_b32 s6, s2, 5
	s_mov_b32 s8, s7
	s_mov_b32 s10, s2
	s_branch .LBB0_77

; __device__ __forceinline__ void transpose_mat(const Ctx& c, const float* W, int K, int N, bf16* WT) {
;     float* scr = (float*)(c.lds + c.wid * 16384); const int items = (K / 64) * (N / 32), nblk = N / 32, lane = c.lane;
;     float tv[32];
;     int it = c.gw;
;     if (it < items) { const int k0 = 64 * (it / nblk), n0 = 32 * (it % nblk);
; #pragma unroll
;         for (int i = 0; i < 32; ++i) tv[i] = W[(size_t)(k0 + 2 * i + (lane >> 5)) * N + n0 + (lane & 31)]; }
; __device__ __forceinline__ void conv_ffn(const Ctx&, const In& in, unsigned char* ws, int layer) { const Ctx c = mk_ctx();
;     ...
;     transpose_mat(c, in[12] + (size_t)layer * 1024 * 1024, 1024, 1024, (bf16*)(W + W_PLEG));
.LBB0_79:
	s_mov_b64 s[4:5], src_shared_base
	s_add_i32 s4, 0, 0x20060
	s_cmp_lg_u32 s4, -1
	v_writelane_b32 v254, s4, 18
	s_cselect_b32 s4, s4, 0
	s_cselect_b32 s5, s5, 0
	s_waitcnt vmcnt(35)
	v_mov_b32_e32 v2, s4
	s_waitcnt vmcnt(32)
	v_mov_b32_e32 v3, s5
	ds_read_b64 v[2:3], v2
	s_waitcnt lgkmcnt(0)
	s_cmpk_gt_i32 s2, 0x1ff
	s_waitcnt lgkmcnt(0)
	v_readfirstlane_b32 s5, v3
	v_readfirstlane_b32 s4, v2
	s_cbranch_scc1 .LBB0_84
	s_ashr_i32 s6, s2, 31
	s_lshr_b32 s6, s6, 27
	s_add_i32 s6, s2, s6
	s_lshl_b32 s7, s6, 1
	s_and_b32 s6, s6, 0x7ffffe0
	s_sub_i32 s6, s2, s6
	s_andn2_b32 s7, s7, 63
	s_lshl_b32 s6, s6, 5
	v_lshrrev_b32_e32 v40, 5, v38
	s_lshl_b32 s3, s3, 14
	v_or_b32_e32 v4, s7, v40
	s_ashr_i32 s7, s6, 31
	s_add_i32 s3, s3, 0
	s_lshl_b64 s[6:7], s[6:7], 2
	s_add_u32 s6, s4, s6
	v_lshlrev_b32_e32 v1, 2, v39
	s_addc_u32 s7, s5, s7
	v_and_b32_e32 v2, 0x7c, v1
	v_mov_b32_e32 v3, 0
	v_ashrrev_i32_e32 v5, 31, v4
	v_lshl_add_u64 v[6:7], s[6:7], 0, v[2:3]
	v_lshlrev_b64 v[8:9], 12, v[4:5]
	v_lshl_add_u64 v[18:19], v[6:7], 0, v[8:9]
	v_or_b32_e32 v8, 2, v4
	v_ashrrev_i32_e32 v9, 31, v8
	v_lshlrev_b64 v[8:9], 12, v[8:9]
	v_lshl_add_u64 v[20:21], v[6:7], 0, v[8:9]
	v_or_b32_e32 v8, 4, v4
	v_ashrrev_i32_e32 v9, 31, v8
	v_lshlrev_b64 v[8:9], 12, v[8:9]
	v_lshl_add_u64 v[22:23], v[6:7], 0, v[8:9]
	v_or_b32_e32 v8, 6, v4
	v_ashrrev_i32_e32 v9, 31, v8
	v_lshlrev_b64 v[8:9], 12, v[8:9]
	v_lshl_add_u64 v[24:25], v[6:7], 0, v[8:9]
	v_or_b32_e32 v8, 8, v4
	v_ashrrev_i32_e32 v9, 31, v8
	v_lshlrev_b64 v[8:9], 12, v[8:9]
	v_lshl_add_u64 v[26:27], v[6:7], 0, v[8:9]
	v_or_b32_e32 v8, 10, v4
	v_ashrrev_i32_e32 v9, 31, v8
	v_lshlrev_b64 v[8:9], 12, v[8:9]
	v_lshl_add_u64 v[28:29], v[6:7], 0, v[8:9]
	v_or_b32_e32 v8, 12, v4
	v_ashrrev_i32_e32 v9, 31, v8
	v_lshlrev_b64 v[8:9], 12, v[8:9]
	v_lshl_add_u64 v[30:31], v[6:7], 0, v[8:9]
	v_or_b32_e32 v8, 14, v4
	v_ashrrev_i32_e32 v9, 31, v8
	v_lshlrev_b64 v[8:9], 12, v[8:9]
	v_lshl_add_u64 v[42:43], v[6:7], 0, v[8:9]
	v_or_b32_e32 v8, 16, v4
	v_ashrrev_i32_e32 v9, 31, v8
	v_lshlrev_b64 v[8:9], 12, v[8:9]
	v_lshl_add_u64 v[44:45], v[6:7], 0, v[8:9]
	v_or_b32_e32 v8, 18, v4
	v_ashrrev_i32_e32 v9, 31, v8
	v_lshlrev_b64 v[8:9], 12, v[8:9]
	v_lshl_add_u64 v[46:47], v[6:7], 0, v[8:9]
	v_or_b32_e32 v8, 20, v4
	v_ashrrev_i32_e32 v9, 31, v8
	v_lshlrev_b64 v[8:9], 12, v[8:9]
	v_lshl_add_u64 v[48:49], v[6:7], 0, v[8:9]
	v_or_b32_e32 v8, 22, v4
	v_ashrrev_i32_e32 v9, 31, v8
	v_lshlrev_b64 v[8:9], 12, v[8:9]
	v_lshl_add_u64 v[50:51], v[6:7], 0, v[8:9]
	v_or_b32_e32 v8, 24, v4
	v_ashrrev_i32_e32 v9, 31, v8
	v_lshlrev_b64 v[8:9], 12, v[8:9]
	v_lshl_add_u64 v[52:53], v[6:7], 0, v[8:9]
	v_or_b32_e32 v8, 26, v4
	v_ashrrev_i32_e32 v9, 31, v8
	v_lshlrev_b64 v[8:9], 12, v[8:9]
	v_lshl_add_u64 v[54:55], v[6:7], 0, v[8:9]
	v_or_b32_e32 v8, 28, v4
	v_ashrrev_i32_e32 v9, 31, v8
	v_lshlrev_b64 v[8:9], 12, v[8:9]
	v_lshl_add_u64 v[56:57], v[6:7], 0, v[8:9]
	v_or_b32_e32 v8, 30, v4
	v_ashrrev_i32_e32 v9, 31, v8
	v_lshlrev_b64 v[8:9], 12, v[8:9]
	v_lshl_add_u64 v[58:59], v[6:7], 0, v[8:9]
	v_or_b32_e32 v8, 32, v4
	v_ashrrev_i32_e32 v9, 31, v8
	v_lshlrev_b64 v[8:9], 12, v[8:9]
	v_lshl_add_u64 v[60:61], v[6:7], 0, v[8:9]
	v_or_b32_e32 v8, 34, v4
	v_ashrrev_i32_e32 v9, 31, v8
	v_lshlrev_b64 v[8:9], 12, v[8:9]
	v_lshl_add_u64 v[62:63], v[6:7], 0, v[8:9]
	v_or_b32_e32 v8, 36, v4
	v_ashrrev_i32_e32 v9, 31, v8
	v_lshlrev_b64 v[8:9], 12, v[8:9]
	v_lshl_add_u64 v[64:65], v[6:7], 0, v[8:9]
	v_or_b32_e32 v8, 38, v4
	v_ashrrev_i32_e32 v9, 31, v8
	v_lshlrev_b64 v[8:9], 12, v[8:9]
	v_lshl_add_u64 v[66:67], v[6:7], 0, v[8:9]
	v_or_b32_e32 v8, 40, v4
	v_ashrrev_i32_e32 v9, 31, v8
	v_lshlrev_b64 v[8:9], 12, v[8:9]
	v_lshl_add_u64 v[68:69], v[6:7], 0, v[8:9]
	v_or_b32_e32 v8, 42, v4
	v_ashrrev_i32_e32 v9, 31, v8
	v_lshlrev_b64 v[8:9], 12, v[8:9]
	v_lshl_add_u64 v[70:71], v[6:7], 0, v[8:9]
	v_or_b32_e32 v8, 44, v4
	v_ashrrev_i32_e32 v9, 31, v8
	v_lshlrev_b64 v[8:9], 12, v[8:9]
	v_lshl_add_u64 v[72:73], v[6:7], 0, v[8:9]
	v_or_b32_e32 v8, 46, v4
	v_ashrrev_i32_e32 v9, 31, v8
	v_lshlrev_b64 v[8:9], 12, v[8:9]
	v_lshl_add_u64 v[74:75], v[6:7], 0, v[8:9]
	v_or_b32_e32 v8, 48, v4
	v_ashrrev_i32_e32 v9, 31, v8
	v_lshlrev_b64 v[8:9], 12, v[8:9]
	v_lshl_add_u64 v[76:77], v[6:7], 0, v[8:9]
	v_or_b32_e32 v8, 50, v4
	v_ashrrev_i32_e32 v9, 31, v8
	v_lshlrev_b64 v[8:9], 12, v[8:9]
	v_lshl_add_u64 v[78:79], v[6:7], 0, v[8:9]
	v_or_b32_e32 v8, 52, v4
	v_ashrrev_i32_e32 v9, 31, v8
	v_lshlrev_b64 v[8:9], 12, v[8:9]
	v_lshl_add_u64 v[80:81], v[6:7], 0, v[8:9]
	v_or_b32_e32 v8, 54, v4
	v_ashrrev_i32_e32 v9, 31, v8
	v_lshlrev_b64 v[8:9], 12, v[8:9]
	v_lshl_add_u64 v[82:83], v[6:7], 0, v[8:9]
	v_or_b32_e32 v8, 56, v4
	v_ashrrev_i32_e32 v9, 31, v8
	v_lshlrev_b64 v[8:9], 12, v[8:9]
	v_lshl_add_u64 v[84:85], v[6:7], 0, v[8:9]
	v_or_b32_e32 v8, 58, v4
	v_ashrrev_i32_e32 v9, 31, v8
	v_lshlrev_b64 v[8:9], 12, v[8:9]
	v_lshl_add_u64 v[86:87], v[6:7], 0, v[8:9]
	v_or_b32_e32 v8, 60, v4
	v_or_b32_e32 v4, 62, v4
	v_ashrrev_i32_e32 v9, 31, v8
	v_ashrrev_i32_e32 v5, 31, v4
	v_lshlrev_b32_e32 v1, 3, v38
	v_lshlrev_b64 v[8:9], 12, v[8:9]
	v_lshlrev_b64 v[4:5], 12, v[4:5]
	v_lshrrev_b32_e32 v39, 3, v38
	v_and_b32_e32 v1, 56, v1
	v_lshl_add_u64 v[88:89], v[6:7], 0, v[8:9]
	v_lshl_add_u64 v[90:91], v[6:7], 0, v[4:5]
	v_mul_u32_u24_e32 v6, 0x84, v1
	v_lshlrev_b32_e32 v4, 1, v1
	v_mov_b32_e32 v5, v3
	v_lshlrev_b32_e32 v1, 2, v39
	v_lshl_add_u64 v[4:5], s[0:1], 0, v[4:5]
	s_mov_b64 s[0:1], 0x4100000
	v_add3_u32 v38, s3, v6, v1
	v_mul_u32_u24_e32 v1, 0x84, v40
	v_lshl_add_u64 v[34:35], s[4:5], 0, v[2:3]
	v_lshl_add_u64 v[36:37], v[4:5], 0, s[0:1]
	v_add3_u32 v41, s3, v1, v2
	global_load_dword v2, v[18:19], off
	global_load_dword v1, v[20:21], off
	global_load_dword v4, v[22:23], off
	global_load_dword v3, v[24:25], off
	global_load_dword v6, v[26:27], off
	global_load_dword v5, v[28:29], off
	global_load_dword v8, v[30:31], off
	global_load_dword v7, v[42:43], off
	global_load_dword v10, v[44:45], off
	global_load_dword v9, v[46:47], off
	global_load_dword v12, v[48:49], off
	global_load_dword v11, v[50:51], off
	global_load_dword v14, v[52:53], off
	global_load_dword v13, v[54:55], off
	global_load_dword v16, v[56:57], off
	global_load_dword v15, v[58:59], off
	global_load_dword v18, v[60:61], off
	global_load_dword v17, v[62:63], off
	global_load_dword v20, v[64:65], off
	global_load_dword v19, v[66:67], off
	global_load_dword v22, v[68:69], off
	global_load_dword v21, v[70:71], off
	global_load_dword v24, v[72:73], off
	global_load_dword v23, v[74:75], off
	global_load_dword v26, v[76:77], off
	global_load_dword v25, v[78:79], off
	global_load_dword v28, v[80:81], off
	global_load_dword v27, v[82:83], off
	global_load_dword v30, v[84:85], off
	global_load_dword v29, v[86:87], off
	global_load_dword v32, v[88:89], off
	global_load_dword v31, v[90:91], off
	s_lshl_b32 s4, s30, 5
	s_lshl_b32 s3, s2, 5
	s_mov_b32 s5, s4
	s_branch .LBB0_82

; __device__ __forceinline__ v2u pk4(f32x4 v) { v2u o; o.x = pk2(v[0], v[1]); o.y = pk2(v[2], v[3]); return o; }
; __device__ __forceinline__ void conv_p(const Ctx&, const In& in, unsigned char* ws, int layer) { const Ctx c = mk_ctx();
;     const f32x4* src = (const f32x4*)(in[1] + (size_t)layer * T * 256); v2u* dst = (v2u*)(ws + WS_PB);
;     for (int i = c.gw * 64 + c.lane; i < T * 256 / 4; i += c.NGW * 64) dst[i] = pk4(src[i]);
.LBB0_84:
	s_mov_b64 s[0:1], src_shared_base
	v_readlane_b32 s0, v254, 4
	s_cmp_lg_u32 s0, -1
	s_cselect_b32 s0, s0, 0
	s_cselect_b32 s2, s1, 0
	s_waitcnt vmcnt(35)
	v_mov_b32_e32 v2, s0
	s_waitcnt vmcnt(32)
	v_mov_b32_e32 v3, s2
	v_mov_b32_e32 v1, v147
	s_waitcnt vmcnt(30)
	ds_read_b64 v[4:5], v2
	s_waitcnt lgkmcnt(0)
	v_readlane_b32 s3, v254, 7
	v_readfirstlane_b32 s2, v1
	s_andn2_b32 s2, s2, 63
	s_lshl_b32 s24, s3, 9
	s_add_i32 s3, 0, 0x20008
	s_cmp_lg_u32 s3, -1
	v_readlane_b32 s0, v254, 0
	v_writelane_b32 v254, s3, 19
	s_cselect_b32 s3, s3, 0
	s_cselect_b32 s1, s1, 0
	v_mov_b32_e32 v2, s3
	v_mov_b32_e32 v3, s1
	ds_read_b64 v[6:7], v2
	s_waitcnt lgkmcnt(0)
	s_lshl_b32 s0, s0, 9
	s_add_i32 s2, s2, s0
	s_mov_b32 s1, 0x100000
	v_and_or_b32 v2, v1, 63, s2
	v_cmp_gt_i32_e32 vcc, s1, v2
	s_waitcnt lgkmcnt(0)
	v_readfirstlane_b32 s5, v5
	v_readfirstlane_b32 s4, v4
	v_readfirstlane_b32 s7, v7
	v_readfirstlane_b32 s6, v6
	s_and_saveexec_b64 s[0:1], vcc
	s_cbranch_execz .LBB0_87
	v_ashrrev_i32_e32 v3, 31, v2
	v_lshl_add_u64 v[4:5], v[2:3], 3, s[4:5]
	s_mov_b64 s[2:3], 0x4400000
	s_ashr_i32 s25, s24, 31
	v_lshl_add_u64 v[4:5], v[4:5], 0, s[2:3]
	s_lshl_b64 s[4:5], s[24:25], 3
	v_lshl_add_u64 v[6:7], v[2:3], 4, s[6:7]
	s_lshl_b64 s[6:7], s[24:25], 4
	s_mov_b64 s[8:9], 0
	s_mov_b32 s2, 0xfffff

; __device__ __forceinline__ void xcd_barrier(const XcdBarrier& b) {
;     asm volatile("s_waitcnt vmcnt(0)" ::: "memory");
;     __syncthreads();
;     if (threadIdx.x == 0) {
;         unsigned* bar = b.bar;
;         __builtin_amdgcn_s_waitcnt(0);
;         unsigned nloc = b.st[0], nx = b.st[1];
;         if (nloc == 0u) { xcd_barrier_complete(bar, b.x, nloc, nx); b.st[0] = nloc; b.st[1] = nx; }
.LBB0_87:
	s_or_b64 exec, exec, s[0:1]
	s_mov_b64 s[0:1], src_shared_base
	v_readlane_b32 s0, v254, 4
	s_cmp_lg_u32 s0, -1
	s_cselect_b32 s0, s0, 0
	s_cselect_b32 s1, s1, 0
	s_waitcnt vmcnt(0) lgkmcnt(0)
	v_mov_b32_e32 v2, s0
	v_mov_b32_e32 v3, s1
	ds_read_b64 v[2:3], v2
	s_waitcnt lgkmcnt(0)
	s_getreg_b32 s2, hwreg(HW_REG_XCC_ID, 0, 4)
	s_waitcnt vmcnt(0)
	s_waitcnt lgkmcnt(0)
	s_barrier
	v_readfirstlane_b32 s5, v3
	v_readfirstlane_b32 s4, v2
	s_mov_b64 s[0:1], exec
	v_readlane_b32 s6, v254, 1
	v_readlane_b32 s7, v254, 2
	s_and_b64 s[6:7], s[0:1], s[6:7]
	s_mov_b64 exec, s[6:7]
	s_cbranch_execz .LBB0_139
	s_add_i32 s3, 0, 0x20180
	v_mov_b32_e32 v1, s3
	s_waitcnt vmcnt(0) expcnt(0) lgkmcnt(0)
	ds_read_b32 v3, v1
	s_add_i32 s3, 0, 0x20184
	v_mov_b32_e32 v1, s3
	ds_read_b32 v1, v1
	s_and_b32 s2, s2, 15
	s_waitcnt lgkmcnt(1)
	v_cmp_ne_u32_e32 vcc, 0, v3
	s_cbranch_vccnz .LBB0_103
	v_readlane_b32 s6, v254, 5
	v_readlane_b32 s7, v254, 6
	s_load_dwordx2 s[10:11], s[6:7], 0x4
	s_add_u32 s6, s4, 0x1000
	s_addc_u32 s7, s5, 0
	s_add_u32 s8, s4, 0x1100
	s_addc_u32 s9, s5, 0
	v_readlane_b32 s3, v254, 7
	s_waitcnt lgkmcnt(0)
	s_mul_i32 s3, s10, s3
	s_add_u32 s10, s4, 0x1200
	s_mul_i32 s3, s3, s11
	s_addc_u32 s11, s5, 0
	s_add_u32 s12, s4, 0x1300
	s_addc_u32 s13, s5, 0
	s_mov_b32 s20, 1
	v_mov_b32_e32 v17, 0
	s_branch .LBB0_91

;     __host__ __device__ bool next(int i, Unit& u) const {
;         const long L = (long)i * G + c; if (L >= nwg) return false;
;         int wgid = (int)L; { const int q = nwg / NXCD, r = nwg % NXCD, xcd = wgid % NXCD, off = wgid / NXCD; wgid = (xcd < r ? xcd * (q + 1) : r * (q + 1) + (xcd - r) * q) + off; }
;         const int nig = WGM * nN, gid = wgid / nig, fm = gid * WGM, gsz = (nM - fm) < WGM ? (nM - fm) : WGM;
;         u.pm = fm + ((wgid % nig) % gsz); u.pn = (wgid % nig) / gsz; return true;
; __global__ void __launch_bounds__(512, 2) mega_fwd(Args a) {
;     ...
;             if (PH(0)) { EpiMlaDown e{layer};
;               run_gemm<3>(ldsl, hA2, (const bf16*)(W + W_DOWN), T, 768, 1024, e); }
.LBB0_142:
	s_lshr_b32 s90, s88, 1
	s_bitcmp1_b32 s88, 0
	s_cselect_b64 s[0:1], -1, 0
	v_writelane_b32 v255, s0, 0
	s_and_b64 vcc, exec, s[0:1]
	s_nop 0
	v_writelane_b32 v255, s1, 1
	s_mov_b64 s[0:1], -1
	s_cbranch_vccz .LBB0_953
	v_readlane_b32 s0, v254, 4
	s_cmp_lg_u32 s0, -1
	s_mov_b64 s[4:5], src_shared_base
	s_cselect_b32 s0, s0, 0
	s_cselect_b32 s1, s5, 0
	v_mov_b64_e32 v[2:3], s[0:1]
	ds_read_b64 v[4:5], v2
	s_waitcnt lgkmcnt(0)
	s_movk_i32 s0, 0x400
	ds_read_b64 v[2:3], v2
	s_waitcnt lgkmcnt(0)
	s_movk_i32 s4, 0x300
	s_ashr_i32 s5, s4, 31
	s_lshr_b32 s5, s5, 24
	s_add_i32 s4, s4, s5
	s_ashr_i32 s26, s4, 8
	s_lshl_b32 s4, s26, 6
	v_readlane_b32 s11, v254, 0
	s_cmp_lt_i32 s11, s4
	v_readfirstlane_b32 s5, v147
	s_cselect_b64 s[6:7], -1, 0
	s_cmp_ge_i32 s11, s4
	s_waitcnt lgkmcnt(0)
	v_readfirstlane_b32 s1, v5
	v_readfirstlane_b32 s8, v4
	v_readfirstlane_b32 s9, v3
	v_readfirstlane_b32 s10, v2
	s_cbranch_scc1 .LBB0_145
	s_lshl_b32 s11, s26, 3
	s_abs_i32 s12, s11
	v_cvt_f32_u32_e32 v1, s12
	v_readlane_b32 s13, v254, 24
	s_or_b32 s13, s11, s13
	v_readlane_b32 s14, v254, 37
	v_rcp_iflag_f32_e32 v1, v1
	s_mul_i32 s13, s13, s14
	s_sub_i32 s14, 0, s12
	v_readlane_b32 s15, v254, 23
	v_mul_f32_e32 v1, 0x4f7ffffe, v1
	v_cvt_u32_f32_e32 v1, v1
	s_add_i32 s13, s13, s15
	s_abs_i32 s16, s13
	s_xor_b32 s15, s13, s11
	v_readfirstlane_b32 s17, v1
	s_mul_i32 s14, s14, s17
	s_mul_hi_u32 s14, s17, s14
	s_add_i32 s17, s17, s14
	s_mul_hi_u32 s14, s16, s17
	s_mul_i32 s17, s14, s12
	s_sub_i32 s16, s16, s17
	s_ashr_i32 s15, s15, 31
	s_add_i32 s18, s14, 1
	s_sub_i32 s17, s16, s12
	s_cmp_ge_u32 s16, s12
	s_cselect_b32 s14, s18, s14
	s_cselect_b32 s16, s17, s16
	s_add_i32 s17, s14, 1
	s_cmp_ge_u32 s16, s12
	s_cselect_b32 s12, s17, s14
	s_xor_b32 s12, s12, s15
	s_sub_i32 s12, s12, s15
	s_lshl_b32 s14, s12, 3
	s_sub_i32 s15, 64, s14
	s_min_i32 s15, s15, 8
	s_abs_i32 s16, s15
	v_cvt_f32_u32_e32 v1, s16
	s_sub_i32 s17, 0, s16
	s_mul_i32 s12, s12, s11
	s_sub_i32 s11, s13, s12
	v_rcp_iflag_f32_e32 v1, v1
	s_abs_i32 s12, s11
	s_xor_b32 s13, s11, s15
	s_ashr_i32 s13, s13, 31
	v_mul_f32_e32 v1, 0x4f7ffffe, v1
	v_cvt_u32_f32_e32 v1, v1
	s_nop 0
	v_readfirstlane_b32 s18, v1
	s_mul_i32 s17, s17, s18
	s_mul_hi_u32 s17, s18, s17
	s_add_i32 s18, s18, s17
	s_mul_hi_u32 s17, s12, s18
	s_mul_i32 s18, s17, s16
	s_sub_i32 s12, s12, s18
	s_add_i32 s19, s17, 1
	s_sub_i32 s18, s12, s16
	s_cmp_ge_u32 s12, s16
	s_cselect_b32 s17, s19, s17
	s_cselect_b32 s12, s18, s12
	s_add_i32 s18, s17, 1
	s_cmp_ge_u32 s12, s16
	s_cselect_b32 s12, s18, s17
	s_xor_b32 s12, s12, s13
	s_sub_i32 s61, s12, s13
	s_mul_i32 s12, s61, s15
	s_sub_i32 s11, s11, s12
	s_add_i32 s33, s11, s14

;     for (int i = 0; i < nslot4; ++i) { const f32x4 v = p[i]; s += (v[0] + v[1]) + (v[2] + v[3]); } return rsqrtf(s * invn + EPS); }
.LBB0_162:
	s_lshl_b32 s78, s61, 8
	v_readlane_b32 s6, v254, 4
	s_cmp_lg_u32 s6, -1
	s_cselect_b32 s8, s6, 0
	s_mov_b64 s[6:7], src_shared_base
	s_cselect_b32 s6, s7, 0
	v_mov_b32_e32 v140, s8
	v_mov_b32_e32 v141, s6
	ds_read_b64 v[140:141], v140
	s_waitcnt lgkmcnt(0)
	s_mul_i32 s9, s90, 0x600
	v_lshl_add_u32 v142, s33, 8, v1
	v_ashrrev_i32_e32 v143, 31, v142
	v_lshlrev_b64 v[160:161], 7, v[142:143]
	s_waitcnt lgkmcnt(0)
	v_readfirstlane_b32 s44, v140
	v_readfirstlane_b32 s45, v141
	s_add_u32 s36, s44, 0x4c00000
	s_addc_u32 s37, s45, 0
	s_add_u32 s46, s44, 0x15600000
	s_addc_u32 s47, s45, 0
	s_add_i32 s6, 0, 0x200d8
	s_cmp_lg_u32 s6, -1
	s_cselect_b32 s6, s6, 0
	s_cselect_b32 s8, s7, 0
	v_mov_b32_e32 v140, s6
	v_mov_b32_e32 v141, s8
	ds_read_b64 v[140:141], v140
	s_waitcnt lgkmcnt(0)
	v_lshl_add_u64 v[144:145], s[46:47], 0, v[160:161]
	s_waitcnt lgkmcnt(0)
	v_readfirstlane_b32 s8, v140
	v_readfirstlane_b32 s6, v141
	s_add_u32 s30, s8, s9
	s_mul_hi_u32 s8, s90, 0x600
	s_addc_u32 s31, s6, s8
	s_add_i32 s6, 0, 0x200e0
	s_cmp_lg_u32 s6, -1
	s_cselect_b32 s6, s6, 0
	s_cselect_b32 s7, s7, 0
	v_mov_b32_e32 v140, s6
	v_mov_b32_e32 v141, s7
	ds_read_b64 v[140:141], v140
	s_waitcnt lgkmcnt(0)
	global_load_dwordx4 v[154:157], v[144:145], off offset:48
	global_load_dwordx4 v[162:165], v[144:145], off offset:32
	global_load_dwordx4 v[166:169], v[144:145], off offset:16
	global_load_dwordx4 v[174:177], v[144:145], off
	s_waitcnt vmcnt(0)
	v_add_f32_e32 v162, v162, v163
	v_mov_b32_e32 v158, v167
	v_mov_b32_e32 v144, v175
	v_mov_b32_e32 v145, v176
	v_mov_b32_e32 v175, v177
	v_mov_b32_e32 v159, v168
	v_mov_b32_e32 v167, v169
	v_pk_add_f32 v[144:145], v[144:145], v[174:175]
	v_pk_add_f32 v[158:159], v[158:159], v[166:167]
	s_waitcnt lgkmcnt(0)
	v_readfirstlane_b32 s6, v141
	v_add_f32_e32 v141, v144, v145
	v_pk_add_f32 v[158:159], v[158:159], v[158:159] op_sel:[0,1] op_sel_hi:[1,0]
	v_add_f32_e32 v144, 0, v141
	v_add_f32_e32 v164, v164, v165
	v_mov_b32_e32 v145, v154
	v_mov_b32_e32 v159, v155
	v_mov_b32_e32 v163, v156
	v_mov_b32_e32 v165, v157
	v_pk_add_f32 v[144:145], v[144:145], v[158:159]
	v_pk_add_f32 v[154:155], v[162:163], v[164:165]
	v_readfirstlane_b32 s7, v140
	v_pk_add_f32 v[144:145], v[144:145], v[154:155]
	s_add_u32 s34, s7, s24
	v_add_f32_e32 v141, v144, v145
	v_fmamk_f32 v141, v141, 0x3a800000, v152
	v_cmp_gt_f32_e32 vcc, s93, v141
	v_mul_f32_e32 v144, 0x4b800000, v141
	s_addc_u32 s35, s6, s25
	v_cndmask_b32_e32 v141, v141, v144, vcc
	v_rsq_f32_e32 v141, v141
	s_add_u32 s6, s44, s75
	s_addc_u32 s7, s45, 0
	s_add_u32 s38, s6, 0x15e00000
	v_lshlrev_b64 v[154:155], 9, v[142:143]
	s_addc_u32 s39, s7, 0
	v_mul_f32_e32 v144, 0x45800000, v141
	v_lshl_add_u64 v[158:159], s[44:45], 0, v[154:155]
	v_mov_b64_e32 v[154:155], s[36:37]
	s_movk_i32 s6, 0x300
	v_cndmask_b32_e32 v144, v141, v144, vcc
	v_mad_i64_i32 v[156:157], s[6:7], v142, s6, v[154:155]
	s_cmp_lt_i32 s61, 3
	v_or_b32_e32 v140, s78, v171
	v_mov_b32_e32 v145, v144
	v_lshl_add_u64 v[154:155], s[38:39], 0, v[160:161]
	s_cselect_b64 s[6:7], -1, 0
	s_cmp_gt_i32 s61, 2
	s_cbranch_scc1 .LBB0_174
	s_cmp_lg_u32 s61, 2
	v_mov_b32_e32 v162, v144
	v_mov_b32_e32 v163, v144
	v_ashrrev_i32_e32 v141, 31, v140
	s_cselect_b64 s[8:9], -1, 0
	s_cmp_eq_u32 s61, 2
	v_pk_mul_f32 v[128:129], v[128:129], v[162:163]
	v_pk_mul_f32 v[126:127], v[126:127], v[144:145]
	s_mov_b64 s[48:49], -1
	v_lshl_add_u64 v[164:165], v[140:141], 1, v[156:157]
	v_lshl_add_u64 v[166:167], v[140:141], 2, s[30:31]
	s_cbranch_scc1 .LBB0_165
	global_load_dwordx4 v[174:177], v[166:167], off
	s_mov_b64 s[48:49], 0
	s_waitcnt vmcnt(0)
	v_pk_mul_f32 v[168:169], v[126:127], v[174:175]
	v_pk_mul_f32 v[162:163], v[128:129], v[176:177]
	v_cvt_pk_bf16_f32 v168, v168, v169
	s_nop 0
	v_cvt_pk_bf16_f32 v169, v162, v163
	global_store_dwordx2 v[164:165], v[168:169], off

; __device__ __forceinline__ void transpose_mat(const Ctx& c, const float* W, int K, int N, bf16* WT) {
;     float* scr = (float*)(c.lds + c.wid * 16384); const int items = (K / 64) * (N / 32), nblk = N / 32, lane = c.lane;
;     float tv[32];
;     int it = c.gw;
;     if (it < items) { const int k0 = 64 * (it / nblk), n0 = 32 * (it % nblk);
; #pragma unroll
;         for (int i = 0; i < 32; ++i) tv[i] = W[(size_t)(k0 + 2 * i + (lane >> 5)) * N + n0 + (lane & 31)]; }
; __device__ __forceinline__ void conv_ffn(const Ctx&, const In& in, unsigned char* ws, int layer) { const Ctx c = mk_ctx();
;     ...
;     transpose_mat(c, in[5] + (size_t)layer * 1024 * 5632, 1024, 5632, (bf16*)(W + W_FFNIN));
.LBB0_390:
	s_mov_b64 s[0:1], src_shared_base
	v_readlane_b32 s0, v254, 4
	s_cmp_lg_u32 s0, -1
	s_cselect_b32 s0, s0, 0
	s_cselect_b32 s4, s1, 0
	v_mov_b32_e32 v2, s0
	s_waitcnt lgkmcnt(0)
	v_mov_b32_e32 v3, s4
	v_mov_b32_e32 v42, v147
	v_readlane_b32 s0, v254, 0
	ds_read_b64 v[2:3], v2
	s_waitcnt lgkmcnt(0)
	s_lshl_b32 s0, s0, 3
	v_readfirstlane_b32 s4, v42
	s_ashr_i32 s7, s4, 6
	s_add_i32 s6, s7, s0
	v_readlane_b32 s0, v254, 14
	s_cmp_lg_u32 s0, -1
	s_cselect_b32 s0, s0, 0
	s_cselect_b32 s1, s1, 0
	v_mov_b32_e32 v4, s0
	v_mov_b32_e32 v5, s1
	ds_read_b64 v[4:5], v4
	s_waitcnt lgkmcnt(0)
	v_and_b32_e32 v33, 63, v42
	s_cmpk_gt_i32 s6, 0xaff
	s_mov_b32 s89, s97
	s_waitcnt lgkmcnt(0)
	v_readfirstlane_b32 s1, v3
	v_readfirstlane_b32 s0, v2
	v_readfirstlane_b32 s5, v5
	v_readfirstlane_b32 s4, v4
	s_cbranch_scc1 .LBB0_395
	s_mul_i32 s9, s88, 0x1600000
	s_mul_hi_u32 s8, s88, 0x1600000
	s_add_u32 s4, s4, s9
	s_mul_hi_i32 s9, s6, 0x2e8ba2e9
	s_addc_u32 s5, s5, s8
	s_lshr_b32 s10, s9, 31
	s_ashr_i32 s9, s9, 5
	s_add_i32 s9, s9, s10
	s_mul_i32 s10, s9, 0xb0
	s_sub_i32 s10, s6, s10
	s_lshl_b32 s10, s10, 5
	s_lshl_b32 s8, s7, 14
	s_ashr_i32 s11, s10, 31
	s_add_i32 s8, s8, 0
	s_lshl_b64 s[10:11], s[10:11], 2
	v_lshrrev_b32_e32 v40, 5, v33
	s_add_u32 s10, s4, s10
	v_lshlrev_b32_e32 v1, 2, v42
	v_lshl_or_b32 v38, s9, 6, v40
	s_addc_u32 s11, s5, s11
	v_and_b32_e32 v150, 0x7c, v1
	v_lshl_add_u64 v[34:35], s[10:11], 0, v[150:151]
	s_movk_i32 s9, 0x5800
	v_or_b32_e32 v1, 2, v38
	v_mad_i64_i32 v[2:3], s[10:11], v38, s9, v[34:35]
	v_mad_i64_i32 v[4:5], s[10:11], v1, s9, v[34:35]
	global_load_dword v2, v[2:3], off
	v_lshrrev_b32_e32 v41, 3, v33
	global_load_dword v1, v[4:5], off
	v_or_b32_e32 v3, 4, v38
	v_mad_i64_i32 v[4:5], s[10:11], v3, s9, v[34:35]
	v_or_b32_e32 v3, 6, v38
	v_mad_i64_i32 v[6:7], s[10:11], v3, s9, v[34:35]
	global_load_dword v4, v[4:5], off
	v_lshlrev_b32_e32 v39, 2, v41
	global_load_dword v3, v[6:7], off
	v_or_b32_e32 v5, 8, v38
	v_mad_i64_i32 v[6:7], s[10:11], v5, s9, v[34:35]
	v_or_b32_e32 v5, 10, v38
	v_mad_i64_i32 v[8:9], s[10:11], v5, s9, v[34:35]
	global_load_dword v6, v[6:7], off
	s_mov_b32 s12, s6
	global_load_dword v5, v[8:9], off
	v_or_b32_e32 v7, 12, v38
	v_mad_i64_i32 v[8:9], s[10:11], v7, s9, v[34:35]
	v_or_b32_e32 v7, 14, v38
	v_mad_i64_i32 v[10:11], s[10:11], v7, s9, v[34:35]
	global_load_dword v8, v[8:9], off
	s_nop 0
	global_load_dword v7, v[10:11], off
	v_or_b32_e32 v9, 16, v38
	v_mad_i64_i32 v[10:11], s[10:11], v9, s9, v[34:35]
	v_or_b32_e32 v9, 18, v38
	v_mad_i64_i32 v[12:13], s[10:11], v9, s9, v[34:35]
	global_load_dword v10, v[10:11], off
	s_nop 0
	global_load_dword v9, v[12:13], off
	v_or_b32_e32 v11, 20, v38
	v_mad_i64_i32 v[12:13], s[10:11], v11, s9, v[34:35]
	v_or_b32_e32 v11, 22, v38
	v_mad_i64_i32 v[14:15], s[10:11], v11, s9, v[34:35]
	global_load_dword v12, v[12:13], off
	s_nop 0
	global_load_dword v11, v[14:15], off
	v_or_b32_e32 v13, 24, v38
	v_mad_i64_i32 v[14:15], s[10:11], v13, s9, v[34:35]
	v_or_b32_e32 v13, 26, v38
	v_mad_i64_i32 v[16:17], s[10:11], v13, s9, v[34:35]
	global_load_dword v14, v[14:15], off
	s_nop 0
	global_load_dword v13, v[16:17], off
	v_or_b32_e32 v15, 28, v38
	v_mad_i64_i32 v[16:17], s[10:11], v15, s9, v[34:35]
	v_or_b32_e32 v15, 30, v38
	v_mad_i64_i32 v[18:19], s[10:11], v15, s9, v[34:35]
	global_load_dword v16, v[16:17], off
	s_nop 0
	global_load_dword v15, v[18:19], off
	v_or_b32_e32 v17, 32, v38
	v_mad_i64_i32 v[18:19], s[10:11], v17, s9, v[34:35]
	v_or_b32_e32 v17, 34, v38
	v_mad_i64_i32 v[20:21], s[10:11], v17, s9, v[34:35]
	global_load_dword v18, v[18:19], off
	s_nop 0
	global_load_dword v17, v[20:21], off
	v_or_b32_e32 v19, 36, v38
	v_mad_i64_i32 v[20:21], s[10:11], v19, s9, v[34:35]
	v_or_b32_e32 v19, 38, v38
	v_mad_i64_i32 v[22:23], s[10:11], v19, s9, v[34:35]
	global_load_dword v20, v[20:21], off
	s_nop 0
	global_load_dword v19, v[22:23], off
	v_or_b32_e32 v21, 40, v38
	v_mad_i64_i32 v[22:23], s[10:11], v21, s9, v[34:35]
	v_or_b32_e32 v21, 42, v38
	v_mad_i64_i32 v[24:25], s[10:11], v21, s9, v[34:35]
	global_load_dword v22, v[22:23], off
	s_nop 0
	global_load_dword v21, v[24:25], off
	v_or_b32_e32 v23, 44, v38
	v_mad_i64_i32 v[24:25], s[10:11], v23, s9, v[34:35]
	v_or_b32_e32 v23, 46, v38
	v_mad_i64_i32 v[26:27], s[10:11], v23, s9, v[34:35]
	global_load_dword v24, v[24:25], off
	s_nop 0
	global_load_dword v23, v[26:27], off
	v_or_b32_e32 v25, 48, v38
	v_mad_i64_i32 v[26:27], s[10:11], v25, s9, v[34:35]
	v_or_b32_e32 v25, 50, v38
	v_mad_i64_i32 v[28:29], s[10:11], v25, s9, v[34:35]
	global_load_dword v26, v[26:27], off
	s_nop 0
	global_load_dword v25, v[28:29], off
	v_or_b32_e32 v27, 52, v38
	v_mad_i64_i32 v[28:29], s[10:11], v27, s9, v[34:35]
	v_or_b32_e32 v27, 54, v38
	v_mad_i64_i32 v[30:31], s[10:11], v27, s9, v[34:35]
	global_load_dword v28, v[28:29], off
	s_nop 0
	global_load_dword v27, v[30:31], off
	v_or_b32_e32 v29, 56, v38
	v_mad_i64_i32 v[30:31], s[10:11], v29, s9, v[34:35]
	v_or_b32_e32 v29, 58, v38
	v_mad_i64_i32 v[36:37], s[10:11], v29, s9, v[34:35]
	global_load_dword v30, v[30:31], off
	s_nop 0
	global_load_dword v29, v[36:37], off
	v_or_b32_e32 v31, 60, v38
	v_mad_i64_i32 v[36:37], s[10:11], v31, s9, v[34:35]
	v_or_b32_e32 v31, 62, v38
	v_mad_i64_i32 v[34:35], s[10:11], v31, s9, v[34:35]
	global_load_dword v32, v[36:37], off
	global_load_dword v31, v[34:35], off
	v_lshlrev_b32_e32 v36, 3, v33
	v_and_b32_e32 v36, 56, v36
	v_mul_u32_u24_e32 v38, 0x84, v36
	v_lshlrev_b32_e32 v36, 1, v36
	v_mov_b32_e32 v37, v151
	v_lshl_add_u64 v[34:35], s[4:5], 0, v[150:151]
	v_lshl_add_u64 v[36:37], s[0:1], 0, v[36:37]
	s_mov_b64 s[4:5], 0x3000000
	v_lshl_add_u64 v[36:37], v[36:37], 0, s[4:5]
	v_readlane_b32 s4, v254, 48
	v_add3_u32 v43, s8, v38, v39
	v_mul_u32_u24_e32 v38, 0x84, v40
	s_lshl_b32 s9, s4, 5
	v_add3_u32 v44, s8, v38, v150
	s_lshl_b32 s8, s6, 5
	s_mov_b32 s10, s9
	v_readlane_b32 s5, v254, 49
	s_branch .LBB0_393

; __device__ __forceinline__ void transpose_mat(const Ctx& c, const float* W, int K, int N, bf16* WT) {
;     float* scr = (float*)(c.lds + c.wid * 16384); const int items = (K / 64) * (N / 32), nblk = N / 32, lane = c.lane;
;     float tv[32];
;     int it = c.gw;
;     if (it < items) { const int k0 = 64 * (it / nblk), n0 = 32 * (it % nblk);
; #pragma unroll
;         for (int i = 0; i < 32; ++i) tv[i] = W[(size_t)(k0 + 2 * i + (lane >> 5)) * N + n0 + (lane & 31)]; }
; __device__ __forceinline__ void conv_ffn(const Ctx&, const In& in, unsigned char* ws, int layer) { const Ctx c = mk_ctx();
;     ...
;     transpose_mat(c, in[8] + (size_t)layer * 2816 * 1024, 2816, 1024, (bf16*)(W + W_FFNOUT));
.LBB0_395:
	s_mov_b64 s[4:5], src_shared_base
	v_readlane_b32 s4, v254, 15
	s_cmp_lg_u32 s4, -1
	s_cselect_b32 s4, s4, 0
	s_cselect_b32 s5, s5, 0
	s_waitcnt vmcnt(35)
	v_mov_b32_e32 v2, s4
	s_waitcnt vmcnt(32)
	v_mov_b32_e32 v3, s5
	ds_read_b64 v[2:3], v2
	s_waitcnt lgkmcnt(0)
	s_cmpk_gt_i32 s6, 0x57f
	s_waitcnt lgkmcnt(0)
	v_readfirstlane_b32 s5, v3
	v_readfirstlane_b32 s4, v2
	s_cbranch_scc1 .LBB0_400
	s_mul_i32 s9, s88, 0xb00000
	s_mul_hi_u32 s8, s88, 0xb00000
	s_add_u32 s4, s4, s9
	s_addc_u32 s5, s5, s8
	s_ashr_i32 s9, s6, 31
	s_lshr_b32 s9, s9, 27
	s_add_i32 s9, s6, s9
	s_lshl_b32 s10, s9, 1
	s_and_b32 s9, s9, 0x7ffffe0
	s_sub_i32 s9, s6, s9
	s_and_b32 s11, s10, 0xffffffc0
	s_lshl_b32 s10, s9, 5
	v_lshrrev_b32_e32 v43, 5, v33
	s_lshl_b32 s8, s7, 14
	v_or_b32_e32 v34, s11, v43
	s_ashr_i32 s11, s10, 31
	s_add_i32 s8, s8, 0
	s_lshl_b64 s[10:11], s[10:11], 2
	s_add_u32 s10, s4, s10
	v_lshlrev_b32_e32 v1, 2, v42
	v_or_b32_e32 v4, 2, v34
	s_addc_u32 s11, s5, s11
	v_and_b32_e32 v150, 0x7c, v1
	v_ashrrev_i32_e32 v35, 31, v34
	v_ashrrev_i32_e32 v5, 31, v4
	v_lshl_add_u64 v[36:37], s[10:11], 0, v[150:151]
	v_lshlrev_b64 v[2:3], 12, v[34:35]
	v_lshlrev_b64 v[4:5], 12, v[4:5]
	v_lshl_add_u64 v[2:3], v[36:37], 0, v[2:3]
	v_lshl_add_u64 v[4:5], v[36:37], 0, v[4:5]
	global_load_dword v2, v[2:3], off
	v_or_b32_e32 v6, 6, v34
	global_load_dword v1, v[4:5], off
	v_or_b32_e32 v4, 4, v34
	v_ashrrev_i32_e32 v5, 31, v4
	v_ashrrev_i32_e32 v7, 31, v6
	v_lshlrev_b64 v[4:5], 12, v[4:5]
	v_lshlrev_b64 v[6:7], 12, v[6:7]
	v_lshl_add_u64 v[4:5], v[36:37], 0, v[4:5]
	v_lshl_add_u64 v[6:7], v[36:37], 0, v[6:7]
	global_load_dword v4, v[4:5], off
	v_or_b32_e32 v8, 10, v34
	global_load_dword v3, v[6:7], off
	v_or_b32_e32 v6, 8, v34
	v_ashrrev_i32_e32 v7, 31, v6
	v_ashrrev_i32_e32 v9, 31, v8
	v_lshlrev_b64 v[6:7], 12, v[6:7]
	v_lshlrev_b64 v[8:9], 12, v[8:9]
	v_lshl_add_u64 v[6:7], v[36:37], 0, v[6:7]
	v_lshl_add_u64 v[8:9], v[36:37], 0, v[8:9]
	global_load_dword v6, v[6:7], off
	v_or_b32_e32 v10, 14, v34
	global_load_dword v5, v[8:9], off
	v_or_b32_e32 v8, 12, v34
	v_ashrrev_i32_e32 v9, 31, v8
	v_ashrrev_i32_e32 v11, 31, v10
	v_lshlrev_b64 v[8:9], 12, v[8:9]
	v_lshlrev_b64 v[10:11], 12, v[10:11]
	v_lshl_add_u64 v[8:9], v[36:37], 0, v[8:9]
	v_lshl_add_u64 v[10:11], v[36:37], 0, v[10:11]
	global_load_dword v8, v[8:9], off
	v_or_b32_e32 v12, 18, v34
	global_load_dword v7, v[10:11], off
	v_or_b32_e32 v10, 16, v34
	v_ashrrev_i32_e32 v11, 31, v10
	v_ashrrev_i32_e32 v13, 31, v12
	v_lshlrev_b64 v[10:11], 12, v[10:11]
	v_lshlrev_b64 v[12:13], 12, v[12:13]
	v_lshl_add_u64 v[10:11], v[36:37], 0, v[10:11]
	v_lshl_add_u64 v[12:13], v[36:37], 0, v[12:13]
	global_load_dword v10, v[10:11], off
	v_or_b32_e32 v14, 22, v34
	global_load_dword v9, v[12:13], off
	v_or_b32_e32 v12, 20, v34
	v_ashrrev_i32_e32 v13, 31, v12
	v_ashrrev_i32_e32 v15, 31, v14
	v_lshlrev_b64 v[12:13], 12, v[12:13]
	v_lshlrev_b64 v[14:15], 12, v[14:15]
	v_lshl_add_u64 v[12:13], v[36:37], 0, v[12:13]
	v_lshl_add_u64 v[14:15], v[36:37], 0, v[14:15]
	global_load_dword v12, v[12:13], off
	v_or_b32_e32 v16, 26, v34
	global_load_dword v11, v[14:15], off
	v_or_b32_e32 v14, 24, v34
	v_ashrrev_i32_e32 v15, 31, v14
	v_ashrrev_i32_e32 v17, 31, v16
	v_lshlrev_b64 v[14:15], 12, v[14:15]
	v_lshlrev_b64 v[16:17], 12, v[16:17]
	v_lshl_add_u64 v[14:15], v[36:37], 0, v[14:15]
	v_lshl_add_u64 v[16:17], v[36:37], 0, v[16:17]
	global_load_dword v14, v[14:15], off
	v_or_b32_e32 v18, 30, v34
	global_load_dword v13, v[16:17], off
	v_or_b32_e32 v16, 28, v34
	v_ashrrev_i32_e32 v17, 31, v16
	v_ashrrev_i32_e32 v19, 31, v18
	v_lshlrev_b64 v[16:17], 12, v[16:17]
	v_lshlrev_b64 v[18:19], 12, v[18:19]
	v_lshl_add_u64 v[16:17], v[36:37], 0, v[16:17]
	v_lshl_add_u64 v[18:19], v[36:37], 0, v[18:19]
; __device__ __forceinline__ void transpose_mat(const Ctx& c, const float* W, int K, int N, bf16* WT) {
;     float* scr = (float*)(c.lds + c.wid * 16384); const int items = (K / 64) * (N / 32), nblk = N / 32, lane = c.lane;
;     float tv[32];
;     int it = c.gw;
;     if (it < items) { const int k0 = 64 * (it / nblk), n0 = 32 * (it % nblk);
; #pragma unroll
;         for (int i = 0; i < 32; ++i) tv[i] = W[(size_t)(k0 + 2 * i + (lane >> 5)) * N + n0 + (lane & 31)]; }
	global_load_dword v16, v[16:17], off
	v_or_b32_e32 v20, 34, v34
	global_load_dword v15, v[18:19], off
	v_or_b32_e32 v18, 32, v34
	v_ashrrev_i32_e32 v19, 31, v18
	v_ashrrev_i32_e32 v21, 31, v20
	v_lshlrev_b64 v[18:19], 12, v[18:19]
	v_lshlrev_b64 v[20:21], 12, v[20:21]
	v_lshl_add_u64 v[18:19], v[36:37], 0, v[18:19]
	v_lshl_add_u64 v[20:21], v[36:37], 0, v[20:21]
	global_load_dword v18, v[18:19], off
	v_or_b32_e32 v22, 38, v34
	global_load_dword v17, v[20:21], off
	v_or_b32_e32 v20, 36, v34
	v_ashrrev_i32_e32 v21, 31, v20
	v_ashrrev_i32_e32 v23, 31, v22
	v_lshlrev_b64 v[20:21], 12, v[20:21]
	v_lshlrev_b64 v[22:23], 12, v[22:23]
	v_lshl_add_u64 v[20:21], v[36:37], 0, v[20:21]
	v_lshl_add_u64 v[22:23], v[36:37], 0, v[22:23]
	global_load_dword v20, v[20:21], off
	v_or_b32_e32 v24, 42, v34
	global_load_dword v19, v[22:23], off
	v_or_b32_e32 v22, 40, v34
	v_ashrrev_i32_e32 v23, 31, v22
	v_ashrrev_i32_e32 v25, 31, v24
	v_lshlrev_b64 v[22:23], 12, v[22:23]
	v_lshlrev_b64 v[24:25], 12, v[24:25]
	v_lshl_add_u64 v[22:23], v[36:37], 0, v[22:23]
	v_lshl_add_u64 v[24:25], v[36:37], 0, v[24:25]
	global_load_dword v22, v[22:23], off
	v_or_b32_e32 v26, 46, v34
	global_load_dword v21, v[24:25], off
	v_or_b32_e32 v24, 44, v34
	v_ashrrev_i32_e32 v25, 31, v24
	v_ashrrev_i32_e32 v27, 31, v26
	v_lshlrev_b64 v[24:25], 12, v[24:25]
	v_lshlrev_b64 v[26:27], 12, v[26:27]
	v_lshl_add_u64 v[24:25], v[36:37], 0, v[24:25]
	v_lshl_add_u64 v[26:27], v[36:37], 0, v[26:27]
	global_load_dword v24, v[24:25], off
	v_or_b32_e32 v28, 50, v34
	global_load_dword v23, v[26:27], off
	v_or_b32_e32 v26, 48, v34
	v_ashrrev_i32_e32 v27, 31, v26
	v_ashrrev_i32_e32 v29, 31, v28
	v_lshlrev_b64 v[26:27], 12, v[26:27]
	v_lshlrev_b64 v[28:29], 12, v[28:29]
	v_lshl_add_u64 v[26:27], v[36:37], 0, v[26:27]
	v_lshl_add_u64 v[28:29], v[36:37], 0, v[28:29]
	global_load_dword v26, v[26:27], off
	v_or_b32_e32 v30, 54, v34
	global_load_dword v25, v[28:29], off
	v_or_b32_e32 v28, 52, v34
	v_ashrrev_i32_e32 v29, 31, v28
	v_ashrrev_i32_e32 v31, 31, v30
	v_lshlrev_b64 v[28:29], 12, v[28:29]
	v_lshlrev_b64 v[30:31], 12, v[30:31]
	v_lshl_add_u64 v[28:29], v[36:37], 0, v[28:29]
	v_lshl_add_u64 v[30:31], v[36:37], 0, v[30:31]
	global_load_dword v28, v[28:29], off
	v_or_b32_e32 v38, 58, v34
	global_load_dword v27, v[30:31], off
	v_or_b32_e32 v30, 56, v34
	v_ashrrev_i32_e32 v31, 31, v30
	v_ashrrev_i32_e32 v39, 31, v38
	v_lshlrev_b64 v[30:31], 12, v[30:31]
	v_lshlrev_b64 v[38:39], 12, v[38:39]
	v_lshl_add_u64 v[30:31], v[36:37], 0, v[30:31]
	v_lshl_add_u64 v[38:39], v[36:37], 0, v[38:39]
	global_load_dword v30, v[30:31], off
	v_readlane_b32 s10, v254, 48
	global_load_dword v29, v[38:39], off
	v_or_b32_e32 v38, 60, v34
	v_or_b32_e32 v34, 62, v34
	v_ashrrev_i32_e32 v39, 31, v38
	v_ashrrev_i32_e32 v35, 31, v34
	v_lshlrev_b64 v[38:39], 12, v[38:39]
	v_lshlrev_b64 v[34:35], 12, v[34:35]
	v_lshl_add_u64 v[38:39], v[36:37], 0, v[38:39]
	v_lshl_add_u64 v[34:35], v[36:37], 0, v[34:35]
	global_load_dword v32, v[38:39], off
	global_load_dword v31, v[34:35], off
	v_lshlrev_b32_e32 v36, 3, v33
	v_and_b32_e32 v36, 56, v36
	v_lshrrev_b32_e32 v38, 3, v33
	v_mul_u32_u24_e32 v39, 0x84, v36
	v_lshlrev_b32_e32 v36, 1, v36
	v_mov_b32_e32 v37, v151
	v_lshl_add_u64 v[34:35], s[4:5], 0, v[150:151]
	v_lshl_add_u64 v[36:37], s[0:1], 0, v[36:37]
	s_mov_b64 s[4:5], 0x3b00000
	v_lshlrev_b32_e32 v40, 2, v38
	v_lshl_add_u64 v[36:37], v[36:37], 0, s[4:5]
	v_add3_u32 v44, s8, v39, v40
	v_mul_u32_u24_e32 v39, 0x84, v43
	s_mul_i32 s4, s6, 0x16000
	v_add3_u32 v45, s8, v39, v150
	v_mov_b32_e32 v39, s4
	s_movk_i32 s4, 0xb00
	v_mad_u32_u24 v46, v38, s4, v39
	v_readlane_b32 s11, v254, 49
	s_add_i32 s4, s10, s6
	s_lshl_b32 s8, s4, 5
	s_lshl_b32 s9, s10, 5
	s_mov_b32 s11, s6
	s_branch .LBB0_398

; __device__ __forceinline__ void transpose_mat(const Ctx& c, const float* W, int K, int N, bf16* WT) {
;     float* scr = (float*)(c.lds + c.wid * 16384); const int items = (K / 64) * (N / 32), nblk = N / 32, lane = c.lane;
;     float tv[32];
;     int it = c.gw;
;     if (it < items) { const int k0 = 64 * (it / nblk), n0 = 32 * (it % nblk);
; #pragma unroll
;         for (int i = 0; i < 32; ++i) tv[i] = W[(size_t)(k0 + 2 * i + (lane >> 5)) * N + n0 + (lane & 31)]; }
; __device__ __forceinline__ void conv_ffn(const Ctx&, const In& in, unsigned char* ws, int layer) { const Ctx c = mk_ctx();
;     ...
;     transpose_mat(c, in[9] + (size_t)layer * 256 * 1024, 256, 1024, (bf16*)(W + W_PLEP));
.LBB0_400:
	s_mov_b64 s[4:5], src_shared_base
	v_readlane_b32 s4, v254, 17
	s_cmp_lg_u32 s4, -1
	s_cselect_b32 s4, s4, 0
	s_cselect_b32 s5, s5, 0
	s_waitcnt vmcnt(35)
	v_mov_b32_e32 v2, s4
	s_waitcnt vmcnt(32)
	v_mov_b32_e32 v3, s5
	ds_read_b64 v[2:3], v2
	s_waitcnt lgkmcnt(0)
	s_cmpk_gt_i32 s6, 0x7f
	s_waitcnt lgkmcnt(0)
	v_readfirstlane_b32 s5, v3
	v_readfirstlane_b32 s4, v2
	s_cbranch_scc1 .LBB0_405
; __device__ __forceinline__ void transpose_mat(const Ctx& c, const float* W, int K, int N, bf16* WT) {
;     float* scr = (float*)(c.lds + c.wid * 16384); const int items = (K / 64) * (N / 32), nblk = N / 32, lane = c.lane;
;     float tv[32];
;     int it = c.gw;
;     if (it < items) { const int k0 = 64 * (it / nblk), n0 = 32 * (it % nblk);
; #pragma unroll
;         for (int i = 0; i < 32; ++i) tv[i] = W[(size_t)(k0 + 2 * i + (lane >> 5)) * N + n0 + (lane & 31)]; }
	s_lshl_b64 s[8:9], s[88:89], 20
	s_add_u32 s4, s4, s8
	s_addc_u32 s5, s5, s9
	s_ashr_i32 s9, s6, 31
	s_lshr_b32 s9, s9, 27
	s_add_i32 s9, s6, s9
	s_lshl_b32 s10, s9, 1
	s_and_b32 s9, s9, 0x7ffffe0
	s_sub_i32 s9, s6, s9
	s_and_b32 s11, s10, 0xffffffc0
	s_lshl_b32 s10, s9, 5
	v_lshrrev_b32_e32 v43, 5, v33
	s_lshl_b32 s8, s7, 14
	v_or_b32_e32 v34, s11, v43
	s_ashr_i32 s11, s10, 31
	s_add_i32 s8, s8, 0
	s_lshl_b64 s[10:11], s[10:11], 2
	s_add_u32 s10, s4, s10
	v_lshlrev_b32_e32 v1, 2, v42
	v_or_b32_e32 v4, 2, v34
	s_addc_u32 s11, s5, s11
	v_and_b32_e32 v150, 0x7c, v1
	v_ashrrev_i32_e32 v35, 31, v34
	v_ashrrev_i32_e32 v5, 31, v4
	v_lshl_add_u64 v[36:37], s[10:11], 0, v[150:151]
	v_lshlrev_b64 v[2:3], 12, v[34:35]
	v_lshlrev_b64 v[4:5], 12, v[4:5]
	v_lshl_add_u64 v[2:3], v[36:37], 0, v[2:3]
	v_lshl_add_u64 v[4:5], v[36:37], 0, v[4:5]
	global_load_dword v2, v[2:3], off
	v_or_b32_e32 v6, 6, v34
	global_load_dword v1, v[4:5], off
	v_or_b32_e32 v4, 4, v34
	v_ashrrev_i32_e32 v5, 31, v4
	v_ashrrev_i32_e32 v7, 31, v6
	v_lshlrev_b64 v[4:5], 12, v[4:5]
	v_lshlrev_b64 v[6:7], 12, v[6:7]
	v_lshl_add_u64 v[4:5], v[36:37], 0, v[4:5]
	v_lshl_add_u64 v[6:7], v[36:37], 0, v[6:7]
	global_load_dword v4, v[4:5], off
	v_or_b32_e32 v8, 10, v34
	global_load_dword v3, v[6:7], off
	v_or_b32_e32 v6, 8, v34
	v_ashrrev_i32_e32 v7, 31, v6
	v_ashrrev_i32_e32 v9, 31, v8
	v_lshlrev_b64 v[6:7], 12, v[6:7]
	v_lshlrev_b64 v[8:9], 12, v[8:9]
	v_lshl_add_u64 v[6:7], v[36:37], 0, v[6:7]
	v_lshl_add_u64 v[8:9], v[36:37], 0, v[8:9]
	global_load_dword v6, v[6:7], off
	v_or_b32_e32 v10, 14, v34
	global_load_dword v5, v[8:9], off
	v_or_b32_e32 v8, 12, v34
	v_ashrrev_i32_e32 v9, 31, v8
	v_ashrrev_i32_e32 v11, 31, v10
	v_lshlrev_b64 v[8:9], 12, v[8:9]
	v_lshlrev_b64 v[10:11], 12, v[10:11]
	v_lshl_add_u64 v[8:9], v[36:37], 0, v[8:9]
	v_lshl_add_u64 v[10:11], v[36:37], 0, v[10:11]
	global_load_dword v8, v[8:9], off
	v_or_b32_e32 v12, 18, v34
	global_load_dword v7, v[10:11], off
	v_or_b32_e32 v10, 16, v34
	v_ashrrev_i32_e32 v11, 31, v10
	v_ashrrev_i32_e32 v13, 31, v12
	v_lshlrev_b64 v[10:11], 12, v[10:11]
	v_lshlrev_b64 v[12:13], 12, v[12:13]
	v_lshl_add_u64 v[10:11], v[36:37], 0, v[10:11]
	v_lshl_add_u64 v[12:13], v[36:37], 0, v[12:13]
	global_load_dword v10, v[10:11], off
	v_or_b32_e32 v14, 22, v34
	global_load_dword v9, v[12:13], off
	v_or_b32_e32 v12, 20, v34
	v_ashrrev_i32_e32 v13, 31, v12
	v_ashrrev_i32_e32 v15, 31, v14
	v_lshlrev_b64 v[12:13], 12, v[12:13]
	v_lshlrev_b64 v[14:15], 12, v[14:15]
	v_lshl_add_u64 v[12:13], v[36:37], 0, v[12:13]
	v_lshl_add_u64 v[14:15], v[36:37], 0, v[14:15]
	global_load_dword v12, v[12:13], off
	v_or_b32_e32 v16, 26, v34
	global_load_dword v11, v[14:15], off
	v_or_b32_e32 v14, 24, v34
	v_ashrrev_i32_e32 v15, 31, v14
	v_ashrrev_i32_e32 v17, 31, v16
	v_lshlrev_b64 v[14:15], 12, v[14:15]
	v_lshlrev_b64 v[16:17], 12, v[16:17]
	v_lshl_add_u64 v[14:15], v[36:37], 0, v[14:15]
	v_lshl_add_u64 v[16:17], v[36:37], 0, v[16:17]
	global_load_dword v14, v[14:15], off
	v_or_b32_e32 v18, 30, v34
	global_load_dword v13, v[16:17], off
	v_or_b32_e32 v16, 28, v34
	v_ashrrev_i32_e32 v17, 31, v16
	v_ashrrev_i32_e32 v19, 31, v18
	v_lshlrev_b64 v[16:17], 12, v[16:17]
	v_lshlrev_b64 v[18:19], 12, v[18:19]
	v_lshl_add_u64 v[16:17], v[36:37], 0, v[16:17]
	v_lshl_add_u64 v[18:19], v[36:37], 0, v[18:19]
	global_load_dword v16, v[16:17], off
	v_or_b32_e32 v20, 34, v34
	global_load_dword v15, v[18:19], off
	v_or_b32_e32 v18, 32, v34
	v_ashrrev_i32_e32 v19, 31, v18
	v_ashrrev_i32_e32 v21, 31, v20
	v_lshlrev_b64 v[18:19], 12, v[18:19]
	v_lshlrev_b64 v[20:21], 12, v[20:21]
	v_lshl_add_u64 v[18:19], v[36:37], 0, v[18:19]
	v_lshl_add_u64 v[20:21], v[36:37], 0, v[20:21]
	global_load_dword v18, v[18:19], off
	v_or_b32_e32 v22, 38, v34
	global_load_dword v17, v[20:21], off
	v_or_b32_e32 v20, 36, v34
	v_ashrrev_i32_e32 v21, 31, v20
	v_ashrrev_i32_e32 v23, 31, v22
	v_lshlrev_b64 v[20:21], 12, v[20:21]
	v_lshlrev_b64 v[22:23], 12, v[22:23]
	v_lshl_add_u64 v[20:21], v[36:37], 0, v[20:21]
	v_lshl_add_u64 v[22:23], v[36:37], 0, v[22:23]
	global_load_dword v20, v[20:21], off
	v_or_b32_e32 v24, 42, v34
	global_load_dword v19, v[22:23], off
	v_or_b32_e32 v22, 40, v34
	v_ashrrev_i32_e32 v23, 31, v22
	v_ashrrev_i32_e32 v25, 31, v24
	v_lshlrev_b64 v[22:23], 12, v[22:23]
	v_lshlrev_b64 v[24:25], 12, v[24:25]
	v_lshl_add_u64 v[22:23], v[36:37], 0, v[22:23]
	v_lshl_add_u64 v[24:25], v[36:37], 0, v[24:25]
	global_load_dword v22, v[22:23], off
	v_or_b32_e32 v26, 46, v34
	global_load_dword v21, v[24:25], off
	v_or_b32_e32 v24, 44, v34
	v_ashrrev_i32_e32 v25, 31, v24
	v_ashrrev_i32_e32 v27, 31, v26
	v_lshlrev_b64 v[24:25], 12, v[24:25]
	v_lshlrev_b64 v[26:27], 12, v[26:27]
	v_lshl_add_u64 v[24:25], v[36:37], 0, v[24:25]
	v_lshl_add_u64 v[26:27], v[36:37], 0, v[26:27]
	global_load_dword v24, v[24:25], off
	v_or_b32_e32 v28, 50, v34
	global_load_dword v23, v[26:27], off
	v_or_b32_e32 v26, 48, v34
	v_ashrrev_i32_e32 v27, 31, v26
	v_ashrrev_i32_e32 v29, 31, v28
	v_lshlrev_b64 v[26:27], 12, v[26:27]
	v_lshlrev_b64 v[28:29], 12, v[28:29]
	v_lshl_add_u64 v[26:27], v[36:37], 0, v[26:27]
	v_lshl_add_u64 v[28:29], v[36:37], 0, v[28:29]
	global_load_dword v26, v[26:27], off
	v_or_b32_e32 v30, 54, v34
	global_load_dword v25, v[28:29], off
	v_or_b32_e32 v28, 52, v34
	v_ashrrev_i32_e32 v29, 31, v28
	v_ashrrev_i32_e32 v31, 31, v30
	v_lshlrev_b64 v[28:29], 12, v[28:29]
	v_lshlrev_b64 v[30:31], 12, v[30:31]
	v_lshl_add_u64 v[28:29], v[36:37], 0, v[28:29]
	v_lshl_add_u64 v[30:31], v[36:37], 0, v[30:31]
	global_load_dword v28, v[28:29], off
	v_or_b32_e32 v38, 58, v34
	global_load_dword v27, v[30:31], off
	v_or_b32_e32 v30, 56, v34
	v_ashrrev_i32_e32 v31, 31, v30
	v_ashrrev_i32_e32 v39, 31, v38
	v_lshlrev_b64 v[30:31], 12, v[30:31]
	v_lshlrev_b64 v[38:39], 12, v[38:39]
	v_lshl_add_u64 v[30:31], v[36:37], 0, v[30:31]
	v_lshl_add_u64 v[38:39], v[36:37], 0, v[38:39]
	global_load_dword v30, v[30:31], off
	v_lshrrev_b32_e32 v44, 3, v33
	global_load_dword v29, v[38:39], off
	v_or_b32_e32 v38, 60, v34
	v_or_b32_e32 v34, 62, v34
	v_ashrrev_i32_e32 v39, 31, v38
	v_ashrrev_i32_e32 v35, 31, v34
	v_lshlrev_b64 v[38:39], 12, v[38:39]
	v_lshlrev_b64 v[34:35], 12, v[34:35]
	v_lshl_add_u64 v[38:39], v[36:37], 0, v[38:39]
	v_lshl_add_u64 v[34:35], v[36:37], 0, v[34:35]
	global_load_dword v32, v[38:39], off
	global_load_dword v31, v[34:35], off
	v_lshlrev_b32_e32 v36, 3, v33
	v_and_b32_e32 v36, 56, v36
	v_mul_u32_u24_e32 v38, 0x84, v36
	v_lshlrev_b32_e32 v36, 1, v36
	v_mov_b32_e32 v37, v151
	v_lshl_add_u64 v[34:35], s[4:5], 0, v[150:151]
	v_lshl_add_u64 v[36:37], s[0:1], 0, v[36:37]
	s_mov_b64 s[4:5], 0x4080000
	v_lshl_add_u64 v[36:37], v[36:37], 0, s[4:5]
	v_lshlrev_b32_e32 v39, 2, v44
	v_readlane_b32 s4, v254, 48
	v_add3_u32 v45, s8, v38, v39
	v_mul_u32_u24_e32 v38, 0x84, v43
	s_lshl_b32 s9, s4, 5
	v_add3_u32 v46, s8, v38, v150
	s_lshl_b32 s8, s6, 5
	s_mov_b32 s10, s9
	s_mov_b32 s12, s6
	v_readlane_b32 s5, v254, 49
	s_branch .LBB0_403

; __device__ __forceinline__ void transpose_mat(const Ctx& c, const float* W, int K, int N, bf16* WT) {
;     float* scr = (float*)(c.lds + c.wid * 16384); const int items = (K / 64) * (N / 32), nblk = N / 32, lane = c.lane;
;     float tv[32];
;     int it = c.gw;
;     if (it < items) { const int k0 = 64 * (it / nblk), n0 = 32 * (it % nblk);
; #pragma unroll
;         for (int i = 0; i < 32; ++i) tv[i] = W[(size_t)(k0 + 2 * i + (lane >> 5)) * N + n0 + (lane & 31)]; }
; __device__ __forceinline__ void conv_ffn(const Ctx&, const In& in, unsigned char* ws, int layer) { const Ctx c = mk_ctx();
;     ...
;     transpose_mat(c, in[12] + (size_t)layer * 1024 * 1024, 1024, 1024, (bf16*)(W + W_PLEG));
.LBB0_405:
	s_mov_b64 s[4:5], src_shared_base
	v_readlane_b32 s4, v254, 18
	s_cmp_lg_u32 s4, -1
	s_cselect_b32 s4, s4, 0
	s_cselect_b32 s5, s5, 0
	s_waitcnt vmcnt(35)
	v_mov_b32_e32 v2, s4
	s_waitcnt vmcnt(32)
	v_mov_b32_e32 v3, s5
	ds_read_b64 v[2:3], v2
	s_waitcnt lgkmcnt(0)
	s_cmpk_gt_i32 s6, 0x1ff
	s_waitcnt lgkmcnt(0)
	v_readfirstlane_b32 s5, v3
	v_readfirstlane_b32 s4, v2
	s_cbranch_scc1 .LBB0_410
; __device__ __forceinline__ void transpose_mat(const Ctx& c, const float* W, int K, int N, bf16* WT) {
;     float* scr = (float*)(c.lds + c.wid * 16384); const int items = (K / 64) * (N / 32), nblk = N / 32, lane = c.lane;
;     float tv[32];
;     int it = c.gw;
;     if (it < items) { const int k0 = 64 * (it / nblk), n0 = 32 * (it % nblk);
; #pragma unroll
;         for (int i = 0; i < 32; ++i) tv[i] = W[(size_t)(k0 + 2 * i + (lane >> 5)) * N + n0 + (lane & 31)]; }
	s_lshl_b64 s[8:9], s[88:89], 22
	s_add_u32 s4, s4, s8
	s_addc_u32 s5, s5, s9
	s_ashr_i32 s8, s6, 31
	s_lshr_b32 s8, s8, 27
	s_add_i32 s8, s6, s8
	s_lshl_b32 s9, s8, 1
	s_and_b32 s8, s8, 0x7ffffe0
	s_sub_i32 s8, s6, s8
	s_andn2_b32 s9, s9, 63
	s_lshl_b32 s8, s8, 5
	v_lshrrev_b32_e32 v43, 5, v33
	s_lshl_b32 s7, s7, 14
	v_or_b32_e32 v34, s9, v43
	s_ashr_i32 s9, s8, 31
	s_add_i32 s7, s7, 0
	s_lshl_b64 s[8:9], s[8:9], 2
	s_add_u32 s8, s4, s8
	v_lshlrev_b32_e32 v1, 2, v42
	v_or_b32_e32 v4, 2, v34
	s_addc_u32 s9, s5, s9
	v_and_b32_e32 v150, 0x7c, v1
	v_ashrrev_i32_e32 v35, 31, v34
	v_ashrrev_i32_e32 v5, 31, v4
	v_lshl_add_u64 v[36:37], s[8:9], 0, v[150:151]
	v_lshlrev_b64 v[2:3], 12, v[34:35]
	v_lshlrev_b64 v[4:5], 12, v[4:5]
	v_lshl_add_u64 v[2:3], v[36:37], 0, v[2:3]
	v_lshl_add_u64 v[4:5], v[36:37], 0, v[4:5]
	global_load_dword v2, v[2:3], off
	v_or_b32_e32 v6, 6, v34
	global_load_dword v1, v[4:5], off
	v_or_b32_e32 v4, 4, v34
	v_ashrrev_i32_e32 v5, 31, v4
	v_ashrrev_i32_e32 v7, 31, v6
	v_lshlrev_b64 v[4:5], 12, v[4:5]
	v_lshlrev_b64 v[6:7], 12, v[6:7]
	v_lshl_add_u64 v[4:5], v[36:37], 0, v[4:5]
	v_lshl_add_u64 v[6:7], v[36:37], 0, v[6:7]
	global_load_dword v4, v[4:5], off
	v_or_b32_e32 v8, 10, v34
	global_load_dword v3, v[6:7], off
	v_or_b32_e32 v6, 8, v34
	v_ashrrev_i32_e32 v7, 31, v6
	v_ashrrev_i32_e32 v9, 31, v8
	v_lshlrev_b64 v[6:7], 12, v[6:7]
	v_lshlrev_b64 v[8:9], 12, v[8:9]
	v_lshl_add_u64 v[6:7], v[36:37], 0, v[6:7]
	v_lshl_add_u64 v[8:9], v[36:37], 0, v[8:9]
	global_load_dword v6, v[6:7], off
	v_or_b32_e32 v10, 14, v34
	global_load_dword v5, v[8:9], off
	v_or_b32_e32 v8, 12, v34
	v_ashrrev_i32_e32 v9, 31, v8
	v_ashrrev_i32_e32 v11, 31, v10
	v_lshlrev_b64 v[8:9], 12, v[8:9]
	v_lshlrev_b64 v[10:11], 12, v[10:11]
	v_lshl_add_u64 v[8:9], v[36:37], 0, v[8:9]
	v_lshl_add_u64 v[10:11], v[36:37], 0, v[10:11]
	global_load_dword v8, v[8:9], off
	v_or_b32_e32 v12, 18, v34
	global_load_dword v7, v[10:11], off
	v_or_b32_e32 v10, 16, v34
	v_ashrrev_i32_e32 v11, 31, v10
	v_ashrrev_i32_e32 v13, 31, v12
	v_lshlrev_b64 v[10:11], 12, v[10:11]
	v_lshlrev_b64 v[12:13], 12, v[12:13]
	v_lshl_add_u64 v[10:11], v[36:37], 0, v[10:11]
	v_lshl_add_u64 v[12:13], v[36:37], 0, v[12:13]
	global_load_dword v10, v[10:11], off
	v_or_b32_e32 v14, 22, v34
	global_load_dword v9, v[12:13], off
	v_or_b32_e32 v12, 20, v34
	v_ashrrev_i32_e32 v13, 31, v12
	v_ashrrev_i32_e32 v15, 31, v14
	v_lshlrev_b64 v[12:13], 12, v[12:13]
	v_lshlrev_b64 v[14:15], 12, v[14:15]
	v_lshl_add_u64 v[12:13], v[36:37], 0, v[12:13]
	v_lshl_add_u64 v[14:15], v[36:37], 0, v[14:15]
	global_load_dword v12, v[12:13], off
	v_or_b32_e32 v16, 26, v34
	global_load_dword v11, v[14:15], off
	v_or_b32_e32 v14, 24, v34
	v_ashrrev_i32_e32 v15, 31, v14
	v_ashrrev_i32_e32 v17, 31, v16
	v_lshlrev_b64 v[14:15], 12, v[14:15]
	v_lshlrev_b64 v[16:17], 12, v[16:17]
	v_lshl_add_u64 v[14:15], v[36:37], 0, v[14:15]
	v_lshl_add_u64 v[16:17], v[36:37], 0, v[16:17]
	global_load_dword v14, v[14:15], off
	v_or_b32_e32 v18, 30, v34
	global_load_dword v13, v[16:17], off
	v_or_b32_e32 v16, 28, v34
	v_ashrrev_i32_e32 v17, 31, v16
	v_ashrrev_i32_e32 v19, 31, v18
	v_lshlrev_b64 v[16:17], 12, v[16:17]
	v_lshlrev_b64 v[18:19], 12, v[18:19]
	v_lshl_add_u64 v[16:17], v[36:37], 0, v[16:17]
	v_lshl_add_u64 v[18:19], v[36:37], 0, v[18:19]
	global_load_dword v16, v[16:17], off
	v_or_b32_e32 v20, 34, v34
	global_load_dword v15, v[18:19], off
	v_or_b32_e32 v18, 32, v34
	v_ashrrev_i32_e32 v19, 31, v18
	v_ashrrev_i32_e32 v21, 31, v20
	v_lshlrev_b64 v[18:19], 12, v[18:19]
	v_lshlrev_b64 v[20:21], 12, v[20:21]
	v_lshl_add_u64 v[18:19], v[36:37], 0, v[18:19]
	v_lshl_add_u64 v[20:21], v[36:37], 0, v[20:21]
	global_load_dword v18, v[18:19], off
	v_or_b32_e32 v22, 38, v34
	global_load_dword v17, v[20:21], off
	v_or_b32_e32 v20, 36, v34
	v_ashrrev_i32_e32 v21, 31, v20
	v_ashrrev_i32_e32 v23, 31, v22
	v_lshlrev_b64 v[20:21], 12, v[20:21]
	v_lshlrev_b64 v[22:23], 12, v[22:23]
	v_lshl_add_u64 v[20:21], v[36:37], 0, v[20:21]
	v_lshl_add_u64 v[22:23], v[36:37], 0, v[22:23]
	global_load_dword v20, v[20:21], off
	v_or_b32_e32 v24, 42, v34
	global_load_dword v19, v[22:23], off
	v_or_b32_e32 v22, 40, v34
	v_ashrrev_i32_e32 v23, 31, v22
	v_ashrrev_i32_e32 v25, 31, v24
	v_lshlrev_b64 v[22:23], 12, v[22:23]
	v_lshlrev_b64 v[24:25], 12, v[24:25]
	v_lshl_add_u64 v[22:23], v[36:37], 0, v[22:23]
	v_lshl_add_u64 v[24:25], v[36:37], 0, v[24:25]
	global_load_dword v22, v[22:23], off
	v_or_b32_e32 v26, 46, v34
	global_load_dword v21, v[24:25], off
	v_or_b32_e32 v24, 44, v34
	v_ashrrev_i32_e32 v25, 31, v24
	v_ashrrev_i32_e32 v27, 31, v26
	v_lshlrev_b64 v[24:25], 12, v[24:25]
	v_lshlrev_b64 v[26:27], 12, v[26:27]
	v_lshl_add_u64 v[24:25], v[36:37], 0, v[24:25]
	v_lshl_add_u64 v[26:27], v[36:37], 0, v[26:27]
	global_load_dword v24, v[24:25], off
	v_or_b32_e32 v28, 50, v34
	global_load_dword v23, v[26:27], off
	v_or_b32_e32 v26, 48, v34
	v_ashrrev_i32_e32 v27, 31, v26
	v_ashrrev_i32_e32 v29, 31, v28
	v_lshlrev_b64 v[26:27], 12, v[26:27]
	v_lshlrev_b64 v[28:29], 12, v[28:29]
	v_lshl_add_u64 v[26:27], v[36:37], 0, v[26:27]
	v_lshl_add_u64 v[28:29], v[36:37], 0, v[28:29]
	global_load_dword v26, v[26:27], off
	v_or_b32_e32 v30, 54, v34
	global_load_dword v25, v[28:29], off
	v_or_b32_e32 v28, 52, v34
	v_ashrrev_i32_e32 v29, 31, v28
	v_ashrrev_i32_e32 v31, 31, v30
	v_lshlrev_b64 v[28:29], 12, v[28:29]
	v_lshlrev_b64 v[30:31], 12, v[30:31]
	v_lshl_add_u64 v[28:29], v[36:37], 0, v[28:29]
	v_lshl_add_u64 v[30:31], v[36:37], 0, v[30:31]
	global_load_dword v28, v[28:29], off
	v_or_b32_e32 v38, 58, v34
	global_load_dword v27, v[30:31], off
	v_or_b32_e32 v30, 56, v34
	v_ashrrev_i32_e32 v31, 31, v30
	v_ashrrev_i32_e32 v39, 31, v38
	v_lshlrev_b64 v[30:31], 12, v[30:31]
	v_lshlrev_b64 v[38:39], 12, v[38:39]
	v_lshl_add_u64 v[30:31], v[36:37], 0, v[30:31]
	v_lshl_add_u64 v[38:39], v[36:37], 0, v[38:39]
	global_load_dword v30, v[30:31], off
	v_lshrrev_b32_e32 v42, 3, v33
	global_load_dword v29, v[38:39], off
	v_or_b32_e32 v38, 60, v34
	v_or_b32_e32 v34, 62, v34
	v_ashrrev_i32_e32 v39, 31, v38
	v_ashrrev_i32_e32 v35, 31, v34
	v_lshlrev_b64 v[38:39], 12, v[38:39]
	v_lshlrev_b64 v[34:35], 12, v[34:35]
	v_lshl_add_u64 v[38:39], v[36:37], 0, v[38:39]
	v_lshl_add_u64 v[34:35], v[36:37], 0, v[34:35]
	global_load_dword v32, v[38:39], off
	global_load_dword v31, v[34:35], off
	v_lshlrev_b32_e32 v33, 3, v33
	v_and_b32_e32 v33, 56, v33
	v_lshlrev_b32_e32 v36, 1, v33
	v_mov_b32_e32 v37, v151
	v_lshl_add_u64 v[36:37], s[0:1], 0, v[36:37]
	s_mov_b64 s[0:1], 0x4100000
	v_mul_u32_u24_e32 v38, 0x84, v33
	v_lshl_add_u64 v[36:37], v[36:37], 0, s[0:1]
	v_lshlrev_b32_e32 v33, 2, v42
	v_readlane_b32 s0, v254, 48
	v_lshl_add_u64 v[34:35], s[4:5], 0, v[150:151]
	v_add3_u32 v33, s7, v38, v33
	v_mul_u32_u24_e32 v38, 0x84, v43
	s_lshl_b32 s5, s0, 5
	v_add3_u32 v44, s7, v38, v150
	s_lshl_b32 s4, s6, 5
	s_mov_b32 s7, s5
	v_readlane_b32 s1, v254, 49
	s_branch .LBB0_408

; __device__ __forceinline__ void xcd_barrier(const XcdBarrier& b) {
;     asm volatile("s_waitcnt vmcnt(0)" ::: "memory");
;     __syncthreads();
;     if (threadIdx.x == 0) {
;         unsigned* bar = b.bar;
;         __builtin_amdgcn_s_waitcnt(0);
;         unsigned nloc = b.st[0], nx = b.st[1];
;         if (nloc == 0u) { xcd_barrier_complete(bar, b.x, nloc, nx); b.st[0] = nloc; b.st[1] = nx; }
.LBB0_410:
	s_mov_b64 s[0:1], src_shared_base
	v_readlane_b32 s0, v254, 4
	s_cmp_lg_u32 s0, -1
	s_cselect_b32 s0, s0, 0
	s_cselect_b32 s1, s1, 0
	s_waitcnt vmcnt(0) lgkmcnt(0)
	s_waitcnt vmcnt(35)
	v_mov_b32_e32 v2, s0
	s_waitcnt vmcnt(32)
	v_mov_b32_e32 v3, s1
	ds_read_b64 v[2:3], v2
	s_waitcnt lgkmcnt(0)
	s_getreg_b32 s6, hwreg(HW_REG_XCC_ID, 0, 4)
	s_waitcnt vmcnt(0)
	s_waitcnt lgkmcnt(0)
	s_barrier
	v_readfirstlane_b32 s5, v3
	v_readfirstlane_b32 s4, v2
	s_mov_b64 s[0:1], exec
	v_readlane_b32 s8, v254, 1
	v_readlane_b32 s9, v254, 2
	s_and_b64 s[8:9], s[0:1], s[8:9]
	s_mov_b64 exec, s[8:9]
	s_cbranch_execz .LBB0_462
	v_readlane_b32 s7, v254, 54
	s_waitcnt vmcnt(0) expcnt(0) lgkmcnt(0)
	s_and_b32 s24, s6, 15
	v_mov_b32_e32 v1, s7
	ds_read_b32 v3, v1
	v_readlane_b32 s7, v254, 55
	s_waitcnt lgkmcnt(0)
	v_cmp_ne_u32_e32 vcc, 0, v3
	v_mov_b32_e32 v1, s7
	ds_read_b32 v2, v1
	s_cbranch_vccnz .LBB0_426
	v_readlane_b32 s6, v254, 5
	v_readlane_b32 s7, v254, 6
	s_load_dwordx2 s[10:11], s[6:7], 0x4
	s_add_u32 s6, s4, 0x1000
	s_addc_u32 s7, s5, 0
	s_add_u32 s8, s4, 0x1100
	s_addc_u32 s9, s5, 0
	v_readlane_b32 s12, v254, 7
	s_waitcnt lgkmcnt(0)
	s_mul_i32 s25, s10, s12
	s_add_u32 s10, s4, 0x1200
	s_mul_i32 s25, s25, s11
	s_addc_u32 s11, s5, 0
	s_add_u32 s12, s4, 0x1300
	s_addc_u32 s13, s5, 0
	s_mov_b32 s26, 1
	s_branch .LBB0_414

; #define LAS __attribute__((address_space(3)))
;     __host__ __device__ bool next(int i, Unit& u) const {
;         const long L = (long)i * G + c; if (L >= nwg) return false;
;         int wgid = (int)L; { const int q = nwg / NXCD, r = nwg % NXCD, xcd = wgid % NXCD, off = wgid / NXCD; wgid = (xcd < r ? xcd * (q + 1) : r * (q + 1) + (xcd - r) * q) + off; }
;         const int nig = WGM * nN, gid = wgid / nig, fm = gid * WGM, gsz = (nM - fm) < WGM ? (nM - fm) : WGM;
;         u.pm = fm + ((wgid % nig) % gsz); u.pn = (wgid % nig) / gsz; return true;
; template <int ID, class E> __device__ __forceinline__ void run_gemm(LAS unsigned char* lds, const bf16* A, const bf16* Bt, int M, int N, int K, const E& e) {
;     asm volatile("" : "+s"(K)); asm volatile("" : "+s"(N));
;     pg8::Gemm g{A, Bt, M, N, K}; pg8::StaticOrder S; S.init(M, N, (int)gridDim.x, (int)blockIdx.x);
.LBB0_462:
	s_or_b64 exec, exec, s[0:1]
	v_readlane_b32 s0, v254, 4
	s_cmp_lg_u32 s0, -1
	s_mov_b64 s[4:5], src_shared_base
	s_cselect_b32 s0, s0, 0
	s_cselect_b32 s1, s5, 0
	s_waitcnt lgkmcnt(0)
	v_mov_b64_e32 v[2:3], s[0:1]
	s_barrier
	ds_read_b64 v[4:5], v2
	s_waitcnt lgkmcnt(0)
	s_movk_i32 s0, 0x180
	ds_read_b64 v[2:3], v2
	s_waitcnt lgkmcnt(0)
	s_movk_i32 s4, 0x600
	s_ashr_i32 s5, s4, 31
	s_lshr_b32 s5, s5, 24
	s_add_i32 s4, s4, s5
	s_ashr_i32 s26, s4, 8
	s_lshl_b32 s10, s26, 6
	v_readlane_b32 s9, v254, 0
	s_cmp_lt_i32 s9, s10
	v_readfirstlane_b32 s11, v147
	s_cselect_b64 s[4:5], -1, 0
	s_cmp_ge_i32 s9, s10
	s_waitcnt lgkmcnt(0)
	v_readfirstlane_b32 s1, v5
	v_readfirstlane_b32 s6, v4
	v_readfirstlane_b32 s7, v3
	v_readfirstlane_b32 s8, v2
	s_cbranch_scc1 .LBB0_464
	s_lshl_b32 s9, s26, 3
	s_abs_i32 s12, s9
	v_cvt_f32_u32_e32 v1, s12
	v_readlane_b32 s13, v254, 24
	s_or_b32 s13, s9, s13
	v_readlane_b32 s14, v254, 37
	v_rcp_iflag_f32_e32 v1, v1
	s_mul_i32 s13, s13, s14
	s_sub_i32 s14, 0, s12
	v_readlane_b32 s15, v254, 23
	v_mul_f32_e32 v1, 0x4f7ffffe, v1
	v_cvt_u32_f32_e32 v1, v1
	s_add_i32 s13, s13, s15
	s_abs_i32 s16, s13
	s_xor_b32 s15, s13, s9
	v_readfirstlane_b32 s17, v1
	s_mul_i32 s14, s14, s17
	s_mul_hi_u32 s14, s17, s14
	s_add_i32 s17, s17, s14
	s_mul_hi_u32 s14, s16, s17
	s_mul_i32 s17, s14, s12
	s_sub_i32 s16, s16, s17
	s_ashr_i32 s15, s15, 31
	s_add_i32 s18, s14, 1
	s_sub_i32 s17, s16, s12
	s_cmp_ge_u32 s16, s12
	s_cselect_b32 s14, s18, s14
	s_cselect_b32 s16, s17, s16
	s_add_i32 s17, s14, 1
	s_cmp_ge_u32 s16, s12
	s_cselect_b32 s12, s17, s14
	s_xor_b32 s12, s12, s15
	s_sub_i32 s12, s12, s15
	s_lshl_b32 s14, s12, 3
	s_sub_i32 s15, 64, s14
	s_min_i32 s15, s15, 8
	s_abs_i32 s16, s15
	v_cvt_f32_u32_e32 v1, s16
	s_sub_i32 s17, 0, s16
	s_mul_i32 s12, s12, s9
	s_sub_i32 s9, s13, s12
	v_rcp_iflag_f32_e32 v1, v1
	s_abs_i32 s12, s9
	s_xor_b32 s13, s9, s15
	s_ashr_i32 s13, s13, 31
	v_mul_f32_e32 v1, 0x4f7ffffe, v1
	v_cvt_u32_f32_e32 v1, v1
	s_nop 0
	v_readfirstlane_b32 s18, v1
	s_mul_i32 s17, s17, s18
	s_mul_hi_u32 s17, s18, s17
	s_add_i32 s18, s18, s17
	s_mul_hi_u32 s17, s12, s18
	s_mul_i32 s18, s17, s16
	s_sub_i32 s12, s12, s18
	s_add_i32 s19, s17, 1
	s_sub_i32 s18, s12, s16
	s_cmp_ge_u32 s12, s16
	s_cselect_b32 s17, s19, s17
	s_cselect_b32 s12, s18, s12
	s_add_i32 s18, s17, 1
	s_cmp_ge_u32 s12, s16
	s_cselect_b32 s12, s18, s17
	s_xor_b32 s12, s12, s13
	s_sub_i32 s30, s12, s13
	s_mul_i32 s12, s30, s15
	s_sub_i32 s9, s9, s12
	s_add_i32 s31, s9, s14

;     for (int i = 0; i < nslot4; ++i) { const f32x4 v = p[i]; s += (v[0] + v[1]) + (v[2] + v[3]); } return rsqrtf(s * invn + EPS); }
.LBB0_481:
	v_readlane_b32 s6, v254, 4
	s_cmp_lg_u32 s6, -1
	s_cselect_b32 s8, s6, 0
	s_mov_b64 s[6:7], src_shared_base
	s_cselect_b32 s6, s7, 0
	v_mov_b32_e32 v138, s8
	v_mov_b32_e32 v139, s6
	ds_read_b64 v[138:139], v138
	s_waitcnt lgkmcnt(0)
	v_lshlrev_b32_e32 v150, 2, v148
	s_waitcnt lgkmcnt(0)
	v_readfirstlane_b32 s6, v138
	v_lshl_add_u32 v138, s31, 8, v1
	v_readfirstlane_b32 s7, v139
	s_add_u32 s34, s6, 0x15e00000
	v_ashrrev_i32_e32 v139, 31, v138
	s_addc_u32 s35, s7, 0
	v_lshlrev_b64 v[144:145], 7, v[138:139]
	v_lshl_add_u64 v[154:155], s[34:35], 0, v[144:145]
	global_load_dwordx4 v[140:143], v[154:155], off offset:32
	global_load_dwordx4 v[158:161], v[154:155], off offset:16
	global_load_dwordx4 v[162:165], v[154:155], off
	s_add_u32 s28, s6, 0x200000
	s_addc_u32 s29, s7, 0
	s_lshl_b32 s8, s30, 8
	s_or_b32 s30, s8, s52
	s_ashr_i32 s33, s30, 5
	s_mul_hi_i32 s8, s33, 0x55555556
	s_lshr_b32 s9, s8, 31
	s_add_i32 s8, s8, s9
	s_mul_i32 s8, s8, 3
	s_sub_i32 s31, s33, s8
	s_cmp_eq_u32 s31, 2
	s_cselect_b64 s[8:9], -1, 0
	s_cmp_lg_u32 s31, 2
	s_waitcnt vmcnt(1)
	v_add_f32_e32 v158, v158, v159
	s_waitcnt vmcnt(0)
	v_mov_b32_e32 v154, v163
	v_mov_b32_e32 v155, v164
	v_mov_b32_e32 v163, v165
	v_pk_add_f32 v[154:155], v[154:155], v[162:163]
	v_add_f32_e32 v160, v160, v161
	v_pk_add_f32 v[154:155], v[154:155], v[154:155] op_sel:[0,1] op_sel_hi:[1,0]
	v_mov_b32_e32 v159, v142
	v_mov_b32_e32 v155, v140
	v_mov_b32_e32 v140, v151
	v_mov_b32_e32 v161, v143
	v_pk_add_f32 v[140:141], v[154:155], v[140:141]
	v_pk_add_f32 v[142:143], v[158:159], v[160:161]
	s_nop 0
	v_pk_add_f32 v[140:141], v[140:141], v[142:143]
	v_lshl_add_u64 v[142:143], s[28:29], 0, v[144:145]
	v_add_f32_e32 v139, v140, v141
	v_fmamk_f32 v139, v139, 0x3b2aaaab, v152
	v_cmp_gt_f32_e32 vcc, s93, v139
	v_mul_f32_e32 v140, 0x4b800000, v139
	v_lshl_add_u64 v[142:143], v[142:143], 0, v[150:151]
	v_cndmask_b32_e32 v139, v139, v140, vcc
	v_rsq_f32_e32 v139, v139
	s_nop 0
	v_mul_f32_e32 v140, 0x45800000, v139
	v_cndmask_b32_e32 v139, v139, v140, vcc
	v_mul_f32_e32 v140, 0x3e16c740, v139
	v_pk_mul_f32 v[124:125], v[124:125], v[140:141] op_sel_hi:[1,0]
	v_pk_mul_f32 v[122:123], v[122:123], v[140:141] op_sel_hi:[1,0]
	v_pk_mul_f32 v[128:129], v[128:129], v[140:141] op_sel_hi:[1,0]
	v_pk_mul_f32 v[144:145], v[126:127], v[140:141] op_sel_hi:[1,0]
	s_cbranch_scc1 .LBB0_483
	global_load_dwordx4 v[158:161], v[142:143], off offset:64
	global_load_dwordx4 v[162:165], v[142:143], off
	s_waitcnt vmcnt(1)
	v_pk_mul_f32 v[126:127], v[128:129], v[160:161]
	v_pk_mul_f32 v[154:155], v[144:145], v[158:159]
	v_pk_mul_f32 v[160:161], v[124:125], v[160:161]
	v_pk_mul_f32 v[158:159], v[122:123], v[158:159]
	s_waitcnt vmcnt(0)
	v_pk_fma_f32 v[124:125], v[124:125], v[164:165], v[126:127] neg_lo:[0,0,1] neg_hi:[0,0,1]
	v_pk_fma_f32 v[122:123], v[122:123], v[162:163], v[154:155] neg_lo:[0,0,1] neg_hi:[0,0,1]
	v_pk_fma_f32 v[128:129], v[128:129], v[164:165], v[160:161]
	v_pk_fma_f32 v[144:145], v[144:145], v[162:163], v[158:159]

; #define LAS __attribute__((address_space(3)))
;     __host__ __device__ bool next(int i, Unit& u) const {
;         const long L = (long)i * G + c; if (L >= nwg) return false;
;         int wgid = (int)L; { const int q = nwg / NXCD, r = nwg % NXCD, xcd = wgid % NXCD, off = wgid / NXCD; wgid = (xcd < r ? xcd * (q + 1) : r * (q + 1) + (xcd - r) * q) + off; }
;         const int nig = WGM * nN, gid = wgid / nig, fm = gid * WGM, gsz = (nM - fm) < WGM ? (nM - fm) : WGM;
;         u.pm = fm + ((wgid % nig) % gsz); u.pn = (wgid % nig) / gsz; return true;
; template <int ID, class E> __device__ __forceinline__ void run_gemm(LAS unsigned char* lds, const bf16* A, const bf16* Bt, int M, int N, int K, const E& e) {
;     asm volatile("" : "+s"(K)); asm volatile("" : "+s"(N));
;     pg8::Gemm g{A, Bt, M, N, K}; pg8::StaticOrder S; S.init(M, N, (int)gridDim.x, (int)blockIdx.x);
.LBB0_517:
	v_readlane_b32 s0, v254, 4
	s_cmp_lg_u32 s0, -1
	s_mov_b64 s[4:5], src_shared_base
	s_cselect_b32 s0, s0, 0
	s_cselect_b32 s1, s5, 0
	v_mov_b64_e32 v[2:3], s[0:1]
	ds_read_b64 v[4:5], v2
	s_waitcnt lgkmcnt(0)
	s_movk_i32 s0, 0x100
	ds_read_b64 v[2:3], v2
	s_waitcnt lgkmcnt(0)
	s_movk_i32 s4, 0x800
	s_ashr_i32 s5, s4, 31
	s_lshr_b32 s5, s5, 24
	s_add_i32 s4, s4, s5
	s_ashr_i32 s26, s4, 8
	s_lshl_b32 s8, s26, 6
	v_readlane_b32 s11, v254, 0
	s_cmp_lt_i32 s11, s8
	v_readfirstlane_b32 s9, v147
	s_cselect_b64 s[4:5], -1, 0
	s_cmp_ge_i32 s11, s8
	s_waitcnt lgkmcnt(0)
	v_readfirstlane_b32 s1, v5
	v_readfirstlane_b32 s6, v4
	v_readfirstlane_b32 s7, v3
	v_readfirstlane_b32 s10, v2
	s_cbranch_scc1 .LBB0_519
	s_lshl_b32 s11, s26, 3
	s_abs_i32 s12, s11
	v_cvt_f32_u32_e32 v1, s12
	v_readlane_b32 s13, v254, 24
	s_or_b32 s13, s11, s13
	v_readlane_b32 s14, v254, 37
	v_rcp_iflag_f32_e32 v1, v1
	s_mul_i32 s13, s13, s14
	s_sub_i32 s14, 0, s12
	v_readlane_b32 s15, v254, 23
	v_mul_f32_e32 v1, 0x4f7ffffe, v1
	v_cvt_u32_f32_e32 v1, v1
	s_add_i32 s13, s13, s15
	s_abs_i32 s16, s13
	s_xor_b32 s15, s13, s11
	v_readfirstlane_b32 s17, v1
	s_mul_i32 s14, s14, s17
	s_mul_hi_u32 s14, s17, s14
	s_add_i32 s17, s17, s14
	s_mul_hi_u32 s14, s16, s17
	s_mul_i32 s17, s14, s12
	s_sub_i32 s16, s16, s17
	s_ashr_i32 s15, s15, 31
	s_add_i32 s18, s14, 1
	s_sub_i32 s17, s16, s12
	s_cmp_ge_u32 s16, s12
	s_cselect_b32 s14, s18, s14
	s_cselect_b32 s16, s17, s16
	s_add_i32 s17, s14, 1
	s_cmp_ge_u32 s16, s12
	s_cselect_b32 s12, s17, s14
	s_xor_b32 s12, s12, s15
	s_sub_i32 s12, s12, s15
	s_lshl_b32 s14, s12, 3
	s_sub_i32 s15, 64, s14
	s_min_i32 s15, s15, 8
	s_abs_i32 s16, s15
	v_cvt_f32_u32_e32 v1, s16
	s_sub_i32 s17, 0, s16
	s_mul_i32 s12, s12, s11
	s_sub_i32 s11, s13, s12
	v_rcp_iflag_f32_e32 v1, v1
	s_abs_i32 s12, s11
	s_xor_b32 s13, s11, s15
	s_ashr_i32 s13, s13, 31
	v_mul_f32_e32 v1, 0x4f7ffffe, v1
	v_cvt_u32_f32_e32 v1, v1
	s_nop 0
	v_readfirstlane_b32 s18, v1
	s_mul_i32 s17, s17, s18
	s_mul_hi_u32 s17, s18, s17
	s_add_i32 s18, s18, s17
	s_mul_hi_u32 s17, s12, s18
	s_mul_i32 s18, s17, s16
	s_sub_i32 s12, s12, s18
	s_add_i32 s19, s17, 1
	s_sub_i32 s18, s12, s16
	s_cmp_ge_u32 s12, s16
	s_cselect_b32 s17, s19, s17
	s_cselect_b32 s12, s18, s12
	s_add_i32 s18, s17, 1
	s_cmp_ge_u32 s12, s16
	s_cselect_b32 s12, s18, s17
	s_xor_b32 s12, s12, s13
	s_sub_i32 s44, s12, s13
	s_mul_i32 s12, s44, s15
	s_sub_i32 s11, s11, s12
	s_add_i32 s33, s11, s14

;     for (int i = 0; i < nslot4; ++i) { const f32x4 v = p[i]; s += (v[0] + v[1]) + (v[2] + v[3]); } return rsqrtf(s * invn + EPS); }
.LBB0_536:
	v_readlane_b32 s0, v254, 4
	s_cmp_lg_u32 s0, -1
	s_cselect_b32 s6, s0, 0
	s_mov_b64 s[0:1], src_shared_base
	s_cselect_b32 s0, s1, 0
	v_mov_b32_e32 v140, s6
	v_mov_b32_e32 v141, s0
	ds_read_b64 v[140:141], v140
	s_waitcnt lgkmcnt(0)
	v_readfirstlane_b32 s1, v140
	v_lshl_add_u32 v140, s33, 8, v1
	v_readfirstlane_b32 s0, v141
	v_ashrrev_i32_e32 v141, 9, v140
	s_add_u32 s36, s1, 0x15e00030
	v_and_b32_e32 v161, -16, v141
	v_ashrrev_i32_e32 v141, 31, v140
	s_addc_u32 s37, s0, 0
	v_lshlrev_b64 v[142:143], 7, v[140:141]
	v_lshl_add_u64 v[154:155], s[36:37], 0, v[142:143]
	global_load_dwordx4 v[142:145], v[154:155], off
	s_nop 0
	global_load_dwordx4 v[154:157], v[154:155], off offset:16
	s_add_u32 s30, s1, 0x9400000
	s_addc_u32 s31, s0, 0
	s_add_u32 s34, s1, 0xb400000
	s_addc_u32 s35, s0, 0
	s_lshl_b32 s41, s44, 1
	s_mov_b64 s[0:1], -1
	s_waitcnt vmcnt(1)
	v_mov_b32_e32 v162, v142
	s_waitcnt vmcnt(0)
	v_mov_b32_e32 v163, v154
	v_mov_b32_e32 v154, v143
	v_pk_add_f32 v[142:143], v[162:163], v[154:155]
	v_mov_b32_e32 v154, v144
	v_mov_b32_e32 v155, v156
	v_mov_b32_e32 v156, v145
	v_pk_add_f32 v[144:145], v[154:155], v[156:157]
	s_nop 0
	v_pk_add_f32 v[142:143], v[142:143], v[144:145]
	v_add_u32_e32 v145, s41, v161
	v_add_f32_e32 v142, 0, v142
	v_add_f32_e32 v142, v142, v143
	v_fmamk_f32 v142, v142, 0x3b800000, v152
	v_cmp_gt_f32_e32 vcc, s93, v142
	v_mul_f32_e32 v143, 0x4b800000, v142
	v_lshl_add_u32 v160, v145, 6, v207
	v_cndmask_b32_e32 v142, v142, v143, vcc
	v_rsq_f32_e32 v142, v142
	s_nop 0
	v_mul_f32_e32 v143, 0x45800000, v142
	v_cndmask_b32_e32 v144, v142, v143, vcc
	v_and_b32_e32 v142, 0x1fcf, v140
	v_lshlrev_b32_e32 v150, 1, v142
	v_lshl_add_u64 v[142:143], s[34:35], 0, v[150:151]
	v_pk_mul_f32 v[128:129], v[128:129], v[144:145] op_sel_hi:[1,0]
	v_pk_mul_f32 v[126:127], v[126:127], v[144:145] op_sel_hi:[1,0]
	s_and_b64 vcc, exec, s[24:25]
	s_cbranch_vccz .LBB0_538
	v_add_u32_e32 v154, v160, v134
	v_ashrrev_i32_e32 v155, 31, v154
	v_lshlrev_b64 v[154:155], 14, v[154:155]
	v_bfe_u32 v145, v126, 16, 1
	s_movk_i32 s0, 0x7fff
	v_lshl_add_u64 v[154:155], v[142:143], 0, v[154:155]
	v_add3_u32 v145, v126, v145, s0
	global_store_short_d16_hi v[154:155], v145, off
	v_bfe_u32 v145, v127, 16, 1
	v_add_co_u32_e32 v156, vcc, 0x4000, v154
	v_add3_u32 v145, v127, v145, s0
	s_nop 0
	v_addc_co_u32_e32 v157, vcc, 0, v155, vcc
	global_store_short_d16_hi v[156:157], v145, off
	v_bfe_u32 v145, v128, 16, 1
	v_add_co_u32_e32 v156, vcc, 0x8000, v154
	v_add3_u32 v145, v128, v145, s0
	s_nop 0
	v_addc_co_u32_e32 v157, vcc, 0, v155, vcc
	global_store_short_d16_hi v[156:157], v145, off
	v_bfe_u32 v145, v129, 16, 1
	v_add_co_u32_e32 v154, vcc, 0xc000, v154
	v_add3_u32 v145, v129, v145, s0
	s_nop 0
	v_addc_co_u32_e32 v155, vcc, 0, v155, vcc
	global_store_short_d16_hi v[154:155], v145, off
	s_mov_b64 s[0:1], 0

; __device__ __forceinline__ void xcd_barrier(const XcdBarrier& b) {
;     asm volatile("s_waitcnt vmcnt(0)" ::: "memory");
;     __syncthreads();
;     if (threadIdx.x == 0) {
;         unsigned* bar = b.bar;
;         __builtin_amdgcn_s_waitcnt(0);
;         unsigned nloc = b.st[0], nx = b.st[1];
;         if (nloc == 0u) { xcd_barrier_complete(bar, b.x, nloc, nx); b.st[0] = nloc; b.st[1] = nx; }
.LBB0_668:
	s_mov_b64 s[0:1], src_shared_base
	v_readlane_b32 s0, v254, 4
	s_cmp_lg_u32 s0, -1
	s_cselect_b32 s0, s0, 0
	s_cselect_b32 s1, s1, 0
	s_waitcnt vmcnt(0) lgkmcnt(0)
	v_mov_b32_e32 v2, s0
	v_mov_b32_e32 v3, s1
	ds_read_b64 v[2:3], v2
	s_waitcnt lgkmcnt(0)
	s_getreg_b32 s6, hwreg(HW_REG_XCC_ID, 0, 4)
	s_waitcnt vmcnt(0)
	s_waitcnt lgkmcnt(0)
	s_barrier
	v_readfirstlane_b32 s5, v3
	v_readfirstlane_b32 s4, v2
	s_mov_b64 s[0:1], exec
	v_readlane_b32 s8, v254, 1
	v_readlane_b32 s9, v254, 2
	s_and_b64 s[8:9], s[0:1], s[8:9]
	s_mov_b64 exec, s[8:9]
	s_cbranch_execz .LBB0_720
	v_readlane_b32 s7, v254, 54
	s_waitcnt vmcnt(0) expcnt(0) lgkmcnt(0)
	s_and_b32 s24, s6, 15
	v_mov_b32_e32 v1, s7
	ds_read_b32 v3, v1
	v_readlane_b32 s7, v254, 55
	s_waitcnt lgkmcnt(0)
	v_cmp_ne_u32_e32 vcc, 0, v3
	v_mov_b32_e32 v1, s7
	ds_read_b32 v2, v1
	s_cbranch_vccnz .LBB0_684
	v_readlane_b32 s6, v254, 5
	v_readlane_b32 s7, v254, 6
	s_load_dwordx2 s[10:11], s[6:7], 0x4
	s_add_u32 s6, s4, 0x1000
	s_addc_u32 s7, s5, 0
	s_add_u32 s8, s4, 0x1100
	s_addc_u32 s9, s5, 0
	v_readlane_b32 s12, v254, 7
	s_waitcnt lgkmcnt(0)
	s_mul_i32 s25, s10, s12
	s_add_u32 s10, s4, 0x1200
	s_mul_i32 s25, s25, s11
	s_addc_u32 s11, s5, 0
	s_add_u32 s12, s4, 0x1300
	s_addc_u32 s13, s5, 0
	s_mov_b32 s26, 1
	s_branch .LBB0_672

; __device__ __forceinline__ void mla_attn_phase(const Ctx&, unsigned char* ws) { const Ctx c = mk_ctx();
;     const bf16* q = (const bf16*)(ws + WS_R + R_Q); const bf16* kn = (const bf16*)(ws + WS_R + R_KN); const bf16* krope = (const bf16*)(ws + WS_R + R_KROPE); const bf16* vt = (const bf16*)(ws + WS_R + R_VT); bf16* o = (bf16*)(ws + WS_R + R_O);
;     bf16* Kl = (bf16*)c.lds; bf16* Vl = Kl + 2 * KTILE_E;
;     const int tid = c.tid, lane = c.lane, wid = c.wid, r = lane & 31, hi = lane >> 5;
;     const int kc0_row = tid / 12, kc0_part = tid % 12, kc1_row = (512 + tid) / 12, kc1_part = (512 + tid) % 12, vd = tid >> 3, vpart = tid & 7;
;     for (int uu = blockIdx.x; uu < 1024; uu += gridDim.x) {
;         const int v0_ = uu & 255, v = (gridDim.x == 256) ? ((v0_ & 7) * 32 + (v0_ >> 3)) : v0_;
;         const int ii = uu >> 8, bh = v >> 3, s8 = v & 7, qb = ii == 0 ? s8 : (ii == 1 ? 15 - s8 : (ii == 2 ? 16 + s8 : 31 - s8));
;         const int b = bh >> 4, h = bh & 15, Q0 = qb * 256, qw0 = Q0 + 32 * wid; const size_t rowbase = (size_t)b * SEQ;
;         bf16x8 qr[6];
; #pragma unroll
;         for (int s = 0; s < 6; ++s) qr[s] = *(const bf16x8*)(q + (rowbase + qw0 + r) * 1536 + h * 96 + 16 * s + 8 * hi);
;         const int ntiles = (Q0 + 256) / 64, my_last = (qw0 + 31) / 64;
;         f32x16 oa[2]; oa[0] = f32x16{}; oa[1] = f32x16{}; float mrun = -INFINITY, lrun = 0.f;
;         v4u kreg0, kreg1 = {0u, 0u, 0u, 0u}, vreg;
.LBB0_725:
	s_mov_b64 s[0:1], src_shared_base
	v_readlane_b32 s0, v254, 4
	s_cmp_lg_u32 s0, -1
	s_cselect_b32 s0, s0, 0
	s_cselect_b32 s1, s1, 0
	v_mov_b32_e32 v2, s0
	v_mov_b32_e32 v3, s1
	ds_read_b64 v[4:5], v2
	s_waitcnt lgkmcnt(0)
	v_mov_b32_e32 v2, v147
	v_readlane_b32 s0, v254, 0
	v_readlane_b32 s4, v254, 28
	v_readlane_b32 s5, v254, 29
	s_andn2_b64 vcc, exec, s[4:5]
	v_readfirstlane_b32 s4, v2
	s_waitcnt lgkmcnt(0)
	v_readfirstlane_b32 s1, v5
	v_readfirstlane_b32 s0, v4
	s_cbranch_vccnz .LBB0_757
	v_add_u32_e32 v3, 0x200, v2
	s_mov_b32 s5, 0x2aaaaaab
	v_mul_hi_i32 v4, v3, s5
	v_lshrrev_b32_e32 v5, 31, v4
	v_ashrrev_i32_e32 v4, 1, v4
	v_add_u32_e32 v104, v4, v5
	s_add_u32 s14, s0, 0x6400000
	v_mul_lo_u32 v4, v104, 12
	s_addc_u32 s15, s1, 0
	v_sub_u32_e32 v3, v3, v4
	v_mul_hi_i32 v4, v2, s5
	s_add_u32 s16, s0, 0x9400000
	v_lshrrev_b32_e32 v5, 31, v4
	v_ashrrev_i32_e32 v4, 1, v4
	s_addc_u32 s17, s1, 0
	v_add_u32_e32 v106, v4, v5
	s_add_u32 s18, s0, 0xd400000
	v_mul_lo_u32 v4, v106, 12
	s_addc_u32 s19, s1, 0
	v_sub_u32_e32 v4, v2, v4
	s_add_u32 s24, s0, 0x6000000
	v_lshlrev_b32_e32 v150, 3, v4
	s_addc_u32 s25, s1, 0
	s_ashr_i32 s26, s4, 1
	v_cmp_gt_i32_e64 s[4:5], 8, v4
	v_cmp_lt_i32_e64 s[6:7], 7, v4
	v_lshlrev_b64 v[4:5], 1, v[150:151]
	v_ashrrev_i32_e32 v113, 31, v150
	v_mov_b32_e32 v112, v150
	v_lshlrev_b32_e32 v150, 3, v3
	v_lshlrev_b32_e32 v9, 3, v2
	v_lshlrev_b64 v[6:7], 1, v[150:151]
	v_and_b32_e32 v9, 56, v9
	v_ashrrev_i32_e32 v1, 3, v2
	v_bfe_u32 v8, v2, 5, 1
	v_lshl_add_u64 v[110:111], s[24:25], 0, v[4:5]
	v_lshl_add_u64 v[114:115], s[24:25], 0, v[6:7]
	s_movk_i32 s25, 0xd0
	s_movk_i32 s24, 0x88
	v_lshlrev_b32_e32 v120, 1, v9
	v_mov_b32_e32 v121, v151
	v_lshlrev_b32_e32 v108, 3, v8
	v_mul_lo_u32 v103, v106, s25
	v_mul_lo_u32 v109, v1, s24
	v_mul_lo_u32 v119, v104, s25
	v_lshlrev_b32_e32 v118, 2, v8
	v_lshl_add_u64 v[8:9], s[0:1], 0, v[120:121]
	s_mov_b64 s[24:25], 0xb400000
	s_movk_i32 s8, 0x100
	v_cmp_gt_i32_e64 s[10:11], 8, v3
	v_cmp_lt_i32_e64 s[12:13], 7, v3
	v_lshlrev_b32_e32 v154, 4, v3
	v_lshl_add_u64 v[122:123], v[8:9], 0, s[24:25]
	v_mov_b32_e32 v3, s26
	s_movk_i32 s24, 0xffe0
	v_and_b32_e32 v102, 31, v2
	v_cmp_gt_i32_e64 s[8:9], s8, v2
	v_ashrrev_i32_e32 v105, 31, v104
	v_bfi_b32 v186, s24, v3, v2
	v_and_b32_e32 v2, 7, v2
	v_mov_b32_e32 v3, 0xb400080
	v_ashrrev_i32_e32 v117, 31, v150
	v_mov_b32_e32 v116, v150
	v_lshl_or_b32 v124, v2, 4, v3
	v_lshlrev_b64 v[2:3], 11, v[104:105]
	v_lshl_add_u64 v[2:3], v[116:117], 1, v[2:3]
	s_mov_b64 s[24:25], 0x9420000
	v_lshl_add_u64 v[126:127], v[2:3], 0, s[24:25]
	v_lshlrev_b64 v[2:3], 6, v[104:105]
	s_and_b32 s30, s26, 0xffffffe0
	v_ashrrev_i32_e32 v107, 31, v106
	v_lshl_add_u64 v[2:3], v[2:3], 0, v[6:7]
	s_mov_b64 s[26:27], 0x6000f80
	v_lshl_add_u64 v[128:129], v[2:3], 0, s[26:27]
	v_lshlrev_b64 v[2:3], 11, v[106:107]
	v_lshl_add_u64 v[2:3], v[112:113], 1, v[2:3]
	v_lshl_add_u64 v[130:131], v[2:3], 0, s[24:25]
	v_lshlrev_b64 v[2:3], 6, v[106:107]
	v_lshl_add_u64 v[2:3], v[2:3], 0, v[4:5]
	v_mul_u32_u24_e32 v155, 0xd0, v102
	v_or_b32_e32 v121, 32, v118
	v_or_b32_e32 v156, 33, v118
	v_or_b32_e32 v157, 2, v118
	v_or_b32_e32 v158, 34, v118
	v_or_b32_e32 v159, 3, v118
	v_or_b32_e32 v160, 35, v118
	v_or_b32_e32 v161, 8, v118
	v_or_b32_e32 v162, 40, v118
	v_or_b32_e32 v163, 9, v118
	v_or_b32_e32 v164, 41, v118
	v_or_b32_e32 v165, 10, v118
	v_or_b32_e32 v166, 42, v118
	v_or_b32_e32 v167, 11, v118
	v_or_b32_e32 v168, 43, v118
	v_or_b32_e32 v169, 16, v118
	v_or_b32_e32 v170, 48, v118
	v_or_b32_e32 v171, 17, v118
	v_or_b32_e32 v172, 49, v118
	v_or_b32_e32 v173, 18, v118
	v_or_b32_e32 v174, 50, v118
	v_or_b32_e32 v175, 19, v118
	v_or_b32_e32 v176, 51, v118
	v_or_b32_e32 v177, 24, v118
	v_or_b32_e32 v178, 56, v118
	v_or_b32_e32 v179, 25, v118
	v_or_b32_e32 v180, 57, v118
	v_or_b32_e32 v181, 26, v118
	v_or_b32_e32 v182, 58, v118
	v_or_b32_e32 v183, 27, v118
	v_or_b32_e32 v184, 59, v118
	v_mul_u32_u24_e32 v185, 0x88, v102
	v_mov_b32_e32 v125, v151
	v_lshl_add_u64 v[132:133], v[2:3], 0, s[26:27]
	v_readlane_b32 s31, v254, 0
	s_branch .LBB0_728

; #define REPLOOP(id) int nrep_ = (REP_PHASE == (id)) ? 2 : 1; asm volatile("" : "+s"(nrep_)); for (int rep_ = 0; rep_ < nrep_; ++rep_)
; #define SYNC() do { asm volatile("s_waitcnt vmcnt(0) lgkmcnt(0)" ::: "memory"); XcdBarrier xb_; xb_.bar = (unsigned*)P_WS; xb_.x = xb_xcc_id(); xb_.st = (volatile LAS unsigned*)(LAS unsigned char*)(g_lds + PTAB_OFF + 384); xcd_barrier(xb_); } while (0)
; __device__ __forceinline__ void xcd_barrier(const XcdBarrier& b) {
;     asm volatile("s_waitcnt vmcnt(0)" ::: "memory");
;     __syncthreads();
;     if (threadIdx.x == 0) {
;         unsigned* bar = b.bar;
;         __builtin_amdgcn_s_waitcnt(0);
;         unsigned nloc = b.st[0], nx = b.st[1];
;         if (nloc == 0u) { xcd_barrier_complete(bar, b.x, nloc, nx); b.st[0] = nloc; b.st[1] = nx; }
; __global__ void __launch_bounds__(512, 2) mega_fwd(Args a) {
;     ...
; { REPLOOP(3) {             if (PH(2)) { mla_attn_phase(c, ws); } if (rep_ + 1 < nrep_) SYNC(); } }
.LBB0_757:
	s_add_i32 s29, s29, 1
	s_cmp_ge_i32 s29, s28
	s_cbranch_scc1 .LBB0_724
	s_mov_b64 s[0:1], src_shared_base
	v_readlane_b32 s0, v254, 4
	s_cmp_lg_u32 s0, -1
	s_cselect_b32 s0, s0, 0
	s_cselect_b32 s1, s1, 0
	s_waitcnt vmcnt(0) lgkmcnt(0)
	v_mov_b32_e32 v2, s0
	v_mov_b32_e32 v3, s1
	ds_read_b64 v[2:3], v2
	s_waitcnt lgkmcnt(0)
	s_getreg_b32 s6, hwreg(HW_REG_XCC_ID, 0, 4)
	s_waitcnt vmcnt(0)
	s_waitcnt lgkmcnt(0)
	s_barrier
	v_readfirstlane_b32 s5, v3
	v_readfirstlane_b32 s4, v2
	s_mov_b64 s[0:1], exec
	v_readlane_b32 s8, v254, 1
	v_readlane_b32 s9, v254, 2
	s_and_b64 s[8:9], s[0:1], s[8:9]
	s_mov_b64 exec, s[8:9]
	s_cbranch_execz .LBB0_723
	v_readlane_b32 s7, v254, 54
	s_waitcnt vmcnt(0) expcnt(0) lgkmcnt(0)
	s_and_b32 s24, s6, 15
	v_mov_b32_e32 v1, s7
	ds_read_b32 v3, v1
	v_readlane_b32 s7, v254, 55
	s_waitcnt lgkmcnt(0)
	v_cmp_ne_u32_e32 vcc, 0, v3
	v_mov_b32_e32 v1, s7
	ds_read_b32 v2, v1
	s_cbranch_vccnz .LBB0_774
	v_readlane_b32 s6, v254, 5
	v_readlane_b32 s7, v254, 6
	s_load_dwordx2 s[10:11], s[6:7], 0x4
	s_add_u32 s6, s4, 0x1000
	s_addc_u32 s7, s5, 0
	s_add_u32 s8, s4, 0x1100
	s_addc_u32 s9, s5, 0
	v_readlane_b32 s12, v254, 7
	s_waitcnt lgkmcnt(0)
	s_mul_i32 s25, s10, s12
	s_add_u32 s10, s4, 0x1200
	s_mul_i32 s25, s25, s11
	s_addc_u32 s11, s5, 0
	s_add_u32 s12, s4, 0x1300
	s_addc_u32 s13, s5, 0
	s_mov_b32 s26, 1
	s_branch .LBB0_762

; #define LAS __attribute__((address_space(3)))
;     __host__ __device__ bool next(int i, Unit& u) const {
;         const long L = (long)i * G + c; if (L >= nwg) return false;
;         int wgid = (int)L; { const int q = nwg / NXCD, r = nwg % NXCD, xcd = wgid % NXCD, off = wgid / NXCD; wgid = (xcd < r ? xcd * (q + 1) : r * (q + 1) + (xcd - r) * q) + off; }
;         const int nig = WGM * nN, gid = wgid / nig, fm = gid * WGM, gsz = (nM - fm) < WGM ? (nM - fm) : WGM;
;         u.pm = fm + ((wgid % nig) % gsz); u.pn = (wgid % nig) / gsz; return true;
; template <int ID, class E> __device__ __forceinline__ void run_gemm(LAS unsigned char* lds, const bf16* A, const bf16* Bt, int M, int N, int K, const E& e) {
;     asm volatile("" : "+s"(K)); asm volatile("" : "+s"(N));
;     pg8::Gemm g{A, Bt, M, N, K}; pg8::StaticOrder S; S.init(M, N, (int)gridDim.x, (int)blockIdx.x);
.LBB0_861:
	s_or_b64 exec, exec, s[0:1]
	v_readlane_b32 s0, v254, 4
	s_cmp_lg_u32 s0, -1
	s_mov_b64 s[4:5], src_shared_base
	s_cselect_b32 s0, s0, 0
	s_cselect_b32 s1, s5, 0
	s_waitcnt lgkmcnt(0)
	v_mov_b64_e32 v[2:3], s[0:1]
	s_barrier
	ds_read_b64 v[4:5], v2
	s_waitcnt lgkmcnt(0)
	s_movk_i32 s0, 0x400
	ds_read_b64 v[2:3], v2
	s_waitcnt lgkmcnt(0)
	s_movk_i32 s4, 0x400
	s_ashr_i32 s5, s4, 31
	s_lshr_b32 s5, s5, 24
	s_add_i32 s4, s4, s5
	s_ashr_i32 s24, s4, 8
	s_lshl_b32 s6, s24, 6
	v_readlane_b32 s11, v254, 0
	s_cmp_lt_i32 s11, s6
	v_readfirstlane_b32 s7, v147
	s_cselect_b64 s[4:5], -1, 0
	s_cmp_ge_i32 s11, s6
	s_waitcnt lgkmcnt(0)
	v_readfirstlane_b32 s1, v5
	v_readfirstlane_b32 s8, v4
	v_readfirstlane_b32 s9, v3
	v_readfirstlane_b32 s10, v2
	s_cbranch_scc1 .LBB0_863
	s_lshl_b32 s11, s24, 3
	s_abs_i32 s12, s11
	v_cvt_f32_u32_e32 v1, s12
	v_readlane_b32 s13, v254, 24
	s_or_b32 s13, s11, s13
	v_readlane_b32 s14, v254, 37
	v_rcp_iflag_f32_e32 v1, v1
	s_mul_i32 s13, s13, s14
	s_sub_i32 s14, 0, s12
	v_readlane_b32 s15, v254, 23
	v_mul_f32_e32 v1, 0x4f7ffffe, v1
	v_cvt_u32_f32_e32 v1, v1
	s_add_i32 s13, s13, s15
	s_abs_i32 s16, s13
	s_xor_b32 s15, s13, s11
	v_readfirstlane_b32 s17, v1
	s_mul_i32 s14, s14, s17
	s_mul_hi_u32 s14, s17, s14
	s_add_i32 s17, s17, s14
	s_mul_hi_u32 s14, s16, s17
	s_mul_i32 s17, s14, s12
	s_sub_i32 s16, s16, s17
	s_ashr_i32 s15, s15, 31
	s_add_i32 s18, s14, 1
	s_sub_i32 s17, s16, s12
	s_cmp_ge_u32 s16, s12
	s_cselect_b32 s14, s18, s14
	s_cselect_b32 s16, s17, s16
	s_add_i32 s17, s14, 1
	s_cmp_ge_u32 s16, s12
	s_cselect_b32 s12, s17, s14
	s_xor_b32 s12, s12, s15
	s_sub_i32 s12, s12, s15
	s_lshl_b32 s14, s12, 3
	s_sub_i32 s15, 64, s14
	s_min_i32 s15, s15, 8
	s_abs_i32 s16, s15
	v_cvt_f32_u32_e32 v1, s16
	s_sub_i32 s17, 0, s16
	s_mul_i32 s12, s12, s11
	s_sub_i32 s11, s13, s12
	v_rcp_iflag_f32_e32 v1, v1
	s_abs_i32 s12, s11
	s_xor_b32 s13, s11, s15
	s_ashr_i32 s13, s13, 31
	v_mul_f32_e32 v1, 0x4f7ffffe, v1
	v_cvt_u32_f32_e32 v1, v1
	s_nop 0
	v_readfirstlane_b32 s18, v1
	s_mul_i32 s17, s17, s18
	s_mul_hi_u32 s17, s18, s17
	s_add_i32 s18, s18, s17
	s_mul_hi_u32 s17, s12, s18
	s_mul_i32 s18, s17, s16
	s_sub_i32 s12, s12, s18
	s_add_i32 s19, s17, 1
	s_sub_i32 s18, s12, s16
	s_cmp_ge_u32 s12, s16
	s_cselect_b32 s17, s19, s17
	s_cselect_b32 s12, s18, s12
	s_add_i32 s18, s17, 1
	s_cmp_ge_u32 s12, s16
	s_cselect_b32 s12, s18, s17
	s_xor_b32 s12, s12, s13
	s_sub_i32 s45, s12, s13
	s_mul_i32 s12, s45, s15
	s_sub_i32 s11, s11, s12
	s_add_i32 s30, s11, s14

.LBB0_880:
	v_readlane_b32 s26, v254, 4
	s_mov_b64 s[34:35], src_shared_base
	s_cmp_lg_u32 s26, -1
	s_cselect_b32 s26, s26, 0
	s_cselect_b32 s27, s35, 0
	v_mov_b32_e32 v136, s26
	v_mov_b32_e32 v137, s27
	ds_read_b64 v[144:145], v136
	s_waitcnt lgkmcnt(0)
	v_readlane_b32 s26, v254, 3
	s_cmp_lg_u32 s26, -1
	s_cselect_b32 s26, s26, 0
	s_cselect_b32 s27, s35, 0
	v_mov_b32_e32 v136, s26
	v_mov_b32_e32 v137, s27
	ds_read_b64 v[154:155], v136
	s_waitcnt lgkmcnt(0)
	v_lshl_add_u32 v138, s30, 8, v1
	v_lshl_or_b32 v136, s45, 8, v141
	v_ashrrev_i32_e32 v139, 31, v138
	v_ashrrev_i32_e32 v137, 31, v136
	v_lshlrev_b64 v[156:157], 12, v[138:139]
	v_lshlrev_b64 v[158:159], 2, v[136:137]
	s_waitcnt lgkmcnt(0)
	v_readfirstlane_b32 s30, v144
	v_readfirstlane_b32 s31, v145
	s_add_u32 s26, s30, 0x400000
	s_addc_u32 s27, s31, 0
	s_add_i32 s33, 0, 0x20020
	s_cmp_lg_u32 s33, -1
	s_cselect_b32 s33, s33, 0
	s_cselect_b32 s34, s35, 0
	v_readfirstlane_b32 s29, v155
	v_readfirstlane_b32 s28, v154
	v_mov_b32_e32 v154, s33
	v_mov_b32_e32 v155, s34
	v_lshl_add_u64 v[144:145], s[28:29], 0, v[156:157]
	ds_read_b64 v[160:161], v154
	s_waitcnt lgkmcnt(0)
	v_lshl_add_u64 v[144:145], v[144:145], 0, v[158:159]
	global_load_dwordx4 v[154:157], v[144:145], off
	s_waitcnt lgkmcnt(0)
	v_readfirstlane_b32 s34, v160
	v_readfirstlane_b32 s33, v161
	s_add_u32 s34, s34, s18
	s_waitcnt vmcnt(0)
	v_pk_add_f32 v[156:157], v[128:129], v[156:157]
	v_pk_add_f32 v[154:155], v[126:127], v[154:155]
	s_addc_u32 s35, s33, s19
	global_store_dwordx4 v[144:145], v[154:157], off
	v_lshl_add_u64 v[126:127], s[34:35], 0, v[158:159]
	global_load_dwordx4 v[158:161], v[126:127], off
	v_lshlrev_b64 v[128:129], 11, v[138:139]
	v_lshl_add_u64 v[128:129], s[26:27], 0, v[128:129]
	v_lshl_add_u64 v[128:129], v[136:137], 1, v[128:129]
	v_mul_f32_e32 v143, v157, v157
	v_fmac_f32_e32 v143, v156, v156
	s_add_u32 s30, s30, 0x15800000
	s_addc_u32 s31, s31, 0
	s_waitcnt vmcnt(0)
	v_pk_mul_f32 v[158:159], v[154:155], v[158:159]
	v_pk_mul_f32 v[160:161], v[156:157], v[160:161]
	v_cvt_pk_bf16_f32 v158, v158, v159
	s_nop 0
	v_cvt_pk_bf16_f32 v159, v160, v161
	global_store_dwordx2 v[128:129], v[158:159], off
	global_load_dwordx4 v[158:161], v[144:145], off offset:64
	s_waitcnt vmcnt(0)
	v_pk_add_f32 v[124:125], v[124:125], v[160:161]
	v_pk_add_f32 v[122:123], v[122:123], v[158:159]
	global_store_dwordx4 v[144:145], v[122:125], off offset:64
	global_load_dwordx4 v[158:161], v[126:127], off offset:64
	s_waitcnt vmcnt(0)
	v_pk_mul_f32 v[158:159], v[122:123], v[158:159]
	v_pk_mul_f32 v[160:161], v[124:125], v[160:161]
	v_cvt_pk_bf16_f32 v158, v158, v159
	v_mul_f32_e32 v123, v123, v123
	v_cvt_pk_bf16_f32 v159, v160, v161
	global_store_dwordx2 v[128:129], v[158:159], off offset:32
	global_load_dwordx4 v[158:161], v[144:145], off offset:512
	v_mul_f32_e32 v125, v125, v125
	v_fmac_f32_e32 v123, v122, v122
	v_fmac_f32_e32 v125, v124, v124
	v_add_f32_e32 v122, v123, v125
	s_waitcnt vmcnt(0)
	v_pk_add_f32 v[120:121], v[120:121], v[160:161]
	v_pk_add_f32 v[118:119], v[118:119], v[158:159]
	global_store_dwordx4 v[144:145], v[118:121], off offset:512
	global_load_dwordx4 v[158:161], v[126:127], off offset:512
	s_waitcnt vmcnt(0)
	v_pk_mul_f32 v[158:159], v[118:119], v[158:159]
	v_pk_mul_f32 v[160:161], v[120:121], v[160:161]
	v_cvt_pk_bf16_f32 v158, v158, v159
	v_mul_f32_e32 v119, v119, v119
	v_cvt_pk_bf16_f32 v159, v160, v161
	global_store_dwordx2 v[128:129], v[158:159], off offset:256
	global_load_dwordx4 v[158:161], v[144:145], off offset:576
	v_mul_f32_e32 v121, v121, v121
	v_fmac_f32_e32 v119, v118, v118
	v_fmac_f32_e32 v121, v120, v120
	v_add_f32_e32 v118, v119, v121
	s_waitcnt vmcnt(0)
	v_pk_add_f32 v[160:161], v[116:117], v[160:161]
	v_pk_add_f32 v[158:159], v[114:115], v[158:159]
	global_store_dwordx4 v[144:145], v[158:161], off offset:576
	global_load_dwordx4 v[162:165], v[126:127], off offset:576
	v_and_b32_e32 v115, 64, v206
	v_xor_b32_e32 v114, 16, v206
	v_add_u32_e32 v115, 64, v115
	v_cmp_lt_i32_e32 vcc, v114, v115
	v_mul_f32_e32 v119, v161, v161
	v_fmac_f32_e32 v119, v160, v160
	v_cndmask_b32_e32 v114, v206, v114, vcc
	v_lshlrev_b32_e32 v116, 2, v114
	v_mul_f32_e32 v114, v155, v155
	v_fmac_f32_e32 v114, v154, v154
	v_add_f32_e32 v114, v114, v143
	v_add_f32_e32 v114, v114, v122
	v_add_f32_e32 v114, v114, v118
	v_mul_f32_e32 v118, v159, v159
	v_fmac_f32_e32 v118, v158, v158
	v_add_f32_e32 v118, v118, v119
	v_add_f32_e32 v114, v114, v118
	ds_bpermute_b32 v118, v116, v114
	v_xor_b32_e32 v117, 32, v206
	v_cmp_lt_i32_e32 vcc, v117, v115
	s_waitcnt lgkmcnt(0)
	v_add_f32_e32 v114, v114, v118
	v_cndmask_b32_e32 v115, v206, v117, vcc
	v_lshlrev_b32_e32 v117, 2, v115
	ds_bpermute_b32 v115, v117, v114
	s_waitcnt vmcnt(0)
	v_pk_mul_f32 v[120:121], v[158:159], v[162:163]
	v_pk_mul_f32 v[118:119], v[160:161], v[164:165]
	v_cvt_pk_bf16_f32 v120, v120, v121
	s_nop 0
	v_cvt_pk_bf16_f32 v121, v118, v119
	global_store_dwordx2 v[128:129], v[120:121], off offset:288
	s_mov_b64 s[34:35], exec
	v_readlane_b32 s62, v254, 25
	v_readlane_b32 s63, v254, 26
	s_and_b64 s[62:63], s[34:35], s[62:63]
	s_mov_b64 exec, s[62:63]
	s_cbranch_execz .LBB0_882
	s_waitcnt lgkmcnt(0)
	v_add_f32_e32 v118, v114, v115
	s_lshl_b32 s62, s45, 2
	v_lshlrev_b64 v[114:115], 7, v[138:139]
	s_ashr_i32 s63, s62, 31
	v_lshl_add_u64 v[114:115], s[30:31], 0, v[114:115]
	v_lshl_add_u64 v[114:115], s[62:63], 2, v[114:115]
	s_lshl_b32 s96, s50, 2
	v_lshl_add_u64 v[114:115], v[114:115], 0, s[96:97]
	global_store_dword v[114:115], v118, off

; __device__ __forceinline__ void xcd_barrier(const XcdBarrier& b) {
;     asm volatile("s_waitcnt vmcnt(0)" ::: "memory");
;     __syncthreads();
;     if (threadIdx.x == 0) {
;         unsigned* bar = b.bar;
;         __builtin_amdgcn_s_waitcnt(0);
;         unsigned nloc = b.st[0], nx = b.st[1];
;         if (nloc == 0u) { xcd_barrier_complete(bar, b.x, nloc, nx); b.st[0] = nloc; b.st[1] = nx; }
.LBB0_900:
	s_mov_b64 s[0:1], src_shared_base
	v_readlane_b32 s0, v254, 4
	s_cmp_lg_u32 s0, -1
	s_cselect_b32 s0, s0, 0
	s_cselect_b32 s1, s1, 0
	s_waitcnt vmcnt(0) lgkmcnt(0)
	v_mov_b32_e32 v2, s0
	s_waitcnt lgkmcnt(0)
	v_mov_b32_e32 v3, s1
	ds_read_b64 v[2:3], v2
	s_waitcnt lgkmcnt(0)
	s_getreg_b32 s6, hwreg(HW_REG_XCC_ID, 0, 4)
	s_waitcnt vmcnt(0)
	s_waitcnt lgkmcnt(0)
	s_barrier
	v_readfirstlane_b32 s5, v3
	v_readfirstlane_b32 s4, v2
	s_mov_b64 s[0:1], exec
	v_readlane_b32 s8, v254, 1
	v_readlane_b32 s9, v254, 2
	s_and_b64 s[8:9], s[0:1], s[8:9]
	s_mov_b64 exec, s[8:9]
	s_cbranch_execz .LBB0_952
	v_readlane_b32 s7, v254, 54
	s_waitcnt vmcnt(0) expcnt(0) lgkmcnt(0)
	s_and_b32 s24, s6, 15
	v_mov_b32_e32 v1, s7
	ds_read_b32 v3, v1
	v_readlane_b32 s7, v254, 55
	s_waitcnt lgkmcnt(0)
	v_cmp_ne_u32_e32 vcc, 0, v3
	v_mov_b32_e32 v1, s7
	ds_read_b32 v2, v1
	s_cbranch_vccnz .LBB0_916
	v_readlane_b32 s6, v254, 5
	v_readlane_b32 s7, v254, 6
	s_load_dwordx2 s[10:11], s[6:7], 0x4
	s_add_u32 s6, s4, 0x1000
	s_addc_u32 s7, s5, 0
	s_add_u32 s8, s4, 0x1100
	s_addc_u32 s9, s5, 0
	v_readlane_b32 s12, v254, 7
	s_waitcnt lgkmcnt(0)
	s_mul_i32 s25, s10, s12
	s_add_u32 s10, s4, 0x1200
	s_mul_i32 s25, s25, s11
	s_addc_u32 s11, s5, 0
	s_add_u32 s12, s4, 0x1300
	s_addc_u32 s13, s5, 0
	s_mov_b32 s26, 1
	s_branch .LBB0_904

; #define LAS __attribute__((address_space(3)))
;     __host__ __device__ bool next(int i, Unit& u) const {
;         const long L = (long)i * G + c; if (L >= nwg) return false;
;         int wgid = (int)L; { const int q = nwg / NXCD, r = nwg % NXCD, xcd = wgid % NXCD, off = wgid / NXCD; wgid = (xcd < r ? xcd * (q + 1) : r * (q + 1) + (xcd - r) * q) + off; }
;         const int nig = WGM * nN, gid = wgid / nig, fm = gid * WGM, gsz = (nM - fm) < WGM ? (nM - fm) : WGM;
;         u.pm = fm + ((wgid % nig) % gsz); u.pn = (wgid % nig) / gsz; return true;
; template <int ID, class E> __device__ __forceinline__ void run_gemm(LAS unsigned char* lds, const bf16* A, const bf16* Bt, int M, int N, int K, const E& e) {
;     asm volatile("" : "+s"(K)); asm volatile("" : "+s"(N));
;     pg8::Gemm g{A, Bt, M, N, K}; pg8::StaticOrder S; S.init(M, N, (int)gridDim.x, (int)blockIdx.x);
.LBB0_959:
	s_mov_b64 s[0:1], src_shared_base
	v_readlane_b32 s0, v254, 4
	s_cmp_lg_u32 s0, -1
	s_cselect_b32 s0, s0, 0
	s_cselect_b32 s1, s1, 0
	v_mov_b64_e32 v[2:3], s[0:1]
	ds_read_b64 v[4:5], v2
	s_waitcnt lgkmcnt(0)
	ds_read_b64 v[2:3], v2
	s_waitcnt lgkmcnt(0)
	s_movk_i32 s0, 0x400
	s_movk_i32 s1, 0xe00
	s_ashr_i32 s4, s1, 31
	s_lshr_b32 s4, s4, 24
	s_add_i32 s1, s1, s4
	s_ashr_i32 s12, s1, 8
	s_lshl_b32 s14, s12, 6
	v_readlane_b32 s1, v254, 0
	s_cmp_lt_i32 s1, s14
	s_cselect_b64 s[4:5], -1, 0
	s_cmp_ge_i32 s1, s14
	v_readfirstlane_b32 s13, v147
	s_waitcnt lgkmcnt(0)
	v_readfirstlane_b32 s1, v5
	v_readfirstlane_b32 s7, v4
	v_readfirstlane_b32 s6, v3
	v_readfirstlane_b32 s8, v2
	s_cbranch_scc0 .LBB0_962
	s_andn2_b64 vcc, exec, s[4:5]
	s_cbranch_vccz .LBB0_963

;     for (int i = 0; i < nslot4; ++i) { const f32x4 v = p[i]; s += (v[0] + v[1]) + (v[2] + v[3]); } return rsqrtf(s * invn + EPS); }
.LBB0_979:
	s_lshl_b32 s73, s11, 8
	s_or_b32 s74, s73, s64
	v_readlane_b32 s6, v254, 4
	s_cmp_lg_u32 s6, -1
	s_cselect_b32 s8, s6, 0
	s_mov_b64 s[6:7], src_shared_base
	s_cselect_b32 s6, s7, 0
	v_mov_b32_e32 v140, s8
	v_mov_b32_e32 v141, s6
	ds_read_b64 v[140:141], v140
	s_waitcnt lgkmcnt(0)
	s_movk_i32 s6, 0xe80
	v_or_b32_e32 v138, s74, v148
	s_waitcnt lgkmcnt(0)
	v_readfirstlane_b32 s38, v140
	v_readfirstlane_b32 s39, v141
	s_add_u32 s34, s38, 0x4c00000
	s_addc_u32 s35, s39, 0
	v_lshl_add_u32 v140, s10, 8, v1
	s_add_u32 s44, s38, 0x15600000
	v_ashrrev_i32_e32 v141, 31, v140
	s_addc_u32 s45, s39, 0
	v_lshlrev_b64 v[142:143], 7, v[140:141]
	v_lshl_add_u64 v[166:167], s[44:45], 0, v[142:143]
	global_load_dwordx4 v[142:145], v[166:167], off offset:48
	global_load_dwordx4 v[154:157], v[166:167], off offset:32
	global_load_dwordx4 v[162:165], v[166:167], off offset:16
	s_nop 0
	global_load_dwordx4 v[166:169], v[166:167], off
	v_ashrrev_i32_e32 v139, 4, v140
	v_and_b32_e32 v139, 0xfffffe00, v139
	v_add_u32_e32 v161, 0xfffffc00, v139
	s_add_u32 s36, s38, 0x6c00000
	s_addc_u32 s37, s39, 0
	s_waitcnt vmcnt(2)
	v_add_f32_e32 v154, v154, v155
	v_add_f32_e32 v156, v156, v157
	s_waitcnt vmcnt(0)
	v_mov_b32_e32 v170, v167
	v_mov_b32_e32 v171, v168
	v_mov_b32_e32 v167, v169
	v_mov_b32_e32 v168, v163
	v_mov_b32_e32 v169, v164
	v_mov_b32_e32 v163, v165
	v_pk_add_f32 v[166:167], v[170:171], v[166:167]
	v_pk_add_f32 v[162:163], v[168:169], v[162:163]
	v_add_f32_e32 v139, v166, v167
	v_pk_add_f32 v[162:163], v[162:163], v[162:163] op_sel:[0,1] op_sel_hi:[1,0]
	v_add_f32_e32 v166, 0, v139
	v_mov_b32_e32 v167, v142
	v_mov_b32_e32 v163, v143
	v_mov_b32_e32 v155, v144
	v_mov_b32_e32 v157, v145
	v_pk_add_f32 v[142:143], v[166:167], v[162:163]
	v_pk_add_f32 v[144:145], v[154:155], v[156:157]
	s_nop 0
	v_pk_add_f32 v[142:143], v[142:143], v[144:145]
	s_nop 0
	v_add_f32_e32 v139, v142, v143
	v_fmamk_f32 v139, v139, 0x3a800000, v152
	v_cmp_gt_f32_e32 vcc, s93, v139
	v_mul_f32_e32 v142, 0x4b800000, v139
	s_nop 0
	v_cndmask_b32_e32 v139, v139, v142, vcc
	v_rsq_f32_e32 v139, v139
	s_nop 0
	v_mul_f32_e32 v142, 0x45800000, v139
	v_cndmask_b32_e32 v144, v139, v142, vcc
	v_mov_b64_e32 v[142:143], s[38:39]
	v_mad_i64_i32 v[142:143], s[6:7], v140, s6, v[142:143]
	v_and_b32_e32 v139, 0x1fcf, v140
	v_lshlrev_b32_e32 v150, 1, v139
	v_add_u32_e32 v139, s74, v161
	s_movk_i32 s6, 0x3ff
	v_lshl_add_u64 v[154:155], s[36:37], 0, v[150:151]
	v_and_b32_e32 v160, 0xffffff40, v139
	v_pk_mul_f32 v[156:157], v[128:129], v[144:145] op_sel_hi:[1,0]
	v_pk_mul_f32 v[126:127], v[126:127], v[144:145] op_sel_hi:[1,0]
	v_cmp_lt_i32_e64 s[12:13], s6, v138
	s_and_saveexec_b64 s[6:7], s[12:13]
	s_xor_b64 s[6:7], exec, s[6:7]
	s_cbranch_execz .LBB0_986
	s_cmpk_gt_u32 s73, 0x5ff
	s_mov_b64 s[8:9], -1
	s_cbranch_scc0 .LBB0_984
	s_cmpk_gt_u32 s74, 0xd1f
	s_cbranch_scc1 .LBB0_983
	v_mov_b32_e32 v139, v151
	v_lshl_add_u64 v[162:163], v[138:139], 1, v[142:143]
	v_add_co_u32_e32 v162, vcc, 0x7bff000, v162
	v_cvt_pk_bf16_f32 v128, v126, v127
	v_cvt_pk_bf16_f32 v129, v156, v157
	s_nop 1
	v_addc_co_u32_e32 v163, vcc, 0, v163, vcc
	global_store_dwordx2 v[162:163], v[128:129], off offset:1024

; __device__ __forceinline__ void transpose_mat(const Ctx& c, const float* W, int K, int N, bf16* WT) {
;     float* scr = (float*)(c.lds + c.wid * 16384); const int items = (K / 64) * (N / 32), nblk = N / 32, lane = c.lane;
;     float tv[32];
;     int it = c.gw;
;     if (it < items) { const int k0 = 64 * (it / nblk), n0 = 32 * (it % nblk);
; #pragma unroll
;         for (int i = 0; i < 32; ++i) tv[i] = W[(size_t)(k0 + 2 * i + (lane >> 5)) * N + n0 + (lane & 31)]; }
; __device__ __forceinline__ void conv_ffn(const Ctx&, const In& in, unsigned char* ws, int layer) { const Ctx c = mk_ctx();
;     ...
;     transpose_mat(c, in[5] + (size_t)layer * 1024 * 5632, 1024, 5632, (bf16*)(W + W_FFNIN));
.LBB0_1322:
	s_cmp_lg_u32 s88, 0
	s_cbranch_scc0 .LBB0_1343
	s_mov_b64 s[0:1], src_shared_base
	v_readlane_b32 s0, v254, 4
	s_cmp_lg_u32 s0, -1
	s_cselect_b32 s0, s0, 0
	s_cselect_b32 s4, s1, 0
	v_mov_b32_e32 v2, s0
	v_mov_b32_e32 v3, s4
	v_mov_b32_e32 v1, v147
	v_readlane_b32 s0, v254, 0
	ds_read_b64 v[2:3], v2
	s_waitcnt lgkmcnt(0)
	s_lshl_b32 s0, s0, 3
	v_readfirstlane_b32 s4, v1
	s_ashr_i32 s7, s4, 6
	s_add_i32 s6, s7, s0
	v_readlane_b32 s0, v254, 14
	s_cmp_lg_u32 s0, -1
	s_cselect_b32 s0, s0, 0
	s_cselect_b32 s1, s1, 0
	v_mov_b32_e32 v4, s0
	v_mov_b32_e32 v5, s1
	ds_read_b64 v[4:5], v4
	s_waitcnt lgkmcnt(0)
	v_and_b32_e32 v45, 63, v1
	v_lshlrev_b32_e32 v1, 2, v1
	v_lshrrev_b32_e32 v33, 5, v45
	v_lshlrev_b32_e32 v6, 3, v45
	s_mov_b32 s89, s97
	v_and_b32_e32 v150, 0x7c, v1
	v_lshrrev_b32_e32 v42, 3, v45
	v_and_b32_e32 v44, 56, v6
	s_cmpk_gt_i32 s6, 0xaff
	v_mul_u32_u24_e32 v43, 0x84, v33
	s_waitcnt lgkmcnt(0)
	v_readfirstlane_b32 s1, v3
	v_readfirstlane_b32 s0, v2
	v_readfirstlane_b32 s5, v5
	v_readfirstlane_b32 s4, v4
	s_cbranch_scc1 .LBB0_1328
	s_mul_i32 s9, s88, 0x1600000
	s_mul_hi_u32 s8, s88, 0x1600000
	s_add_u32 s4, s4, s9
	s_mul_hi_i32 s9, s6, 0x2e8ba2e9
	s_addc_u32 s5, s5, s8
	s_lshr_b32 s10, s9, 31
	s_ashr_i32 s9, s9, 5
	s_add_i32 s9, s9, s10
	s_mul_i32 s10, s9, 0xb0
	s_sub_i32 s10, s6, s10
	s_lshl_b32 s10, s10, 5
	s_lshl_b32 s8, s7, 14
	s_ashr_i32 s11, s10, 31
	s_add_i32 s8, s8, 0
	s_lshl_b64 s[10:11], s[10:11], 2
	s_add_u32 s10, s4, s10
	v_lshl_or_b32 v38, s9, 6, v33
	s_addc_u32 s11, s5, s11
	v_lshl_add_u64 v[34:35], s[10:11], 0, v[150:151]
	s_movk_i32 s9, 0x5800
	v_or_b32_e32 v1, 2, v38
	v_mad_i64_i32 v[2:3], s[10:11], v38, s9, v[34:35]
	v_mad_i64_i32 v[4:5], s[10:11], v1, s9, v[34:35]
	global_load_dword v2, v[2:3], off
	v_lshrrev_b32_e32 v40, 3, v45
	global_load_dword v1, v[4:5], off
	v_or_b32_e32 v3, 4, v38
	v_mad_i64_i32 v[4:5], s[10:11], v3, s9, v[34:35]
	v_or_b32_e32 v3, 6, v38
	v_mad_i64_i32 v[6:7], s[10:11], v3, s9, v[34:35]
	global_load_dword v4, v[4:5], off
	v_lshlrev_b32_e32 v39, 2, v40
	global_load_dword v3, v[6:7], off
	v_or_b32_e32 v5, 8, v38
	v_mad_i64_i32 v[6:7], s[10:11], v5, s9, v[34:35]
	v_or_b32_e32 v5, 10, v38
	v_mad_i64_i32 v[8:9], s[10:11], v5, s9, v[34:35]
	global_load_dword v6, v[6:7], off
	v_add3_u32 v46, s8, v43, v150
	global_load_dword v5, v[8:9], off
	v_or_b32_e32 v7, 12, v38
	v_mad_i64_i32 v[8:9], s[10:11], v7, s9, v[34:35]
	v_or_b32_e32 v7, 14, v38
	v_mad_i64_i32 v[10:11], s[10:11], v7, s9, v[34:35]
	global_load_dword v8, v[8:9], off
	s_mov_b32 s12, s6
	global_load_dword v7, v[10:11], off
	v_or_b32_e32 v9, 16, v38
	v_mad_i64_i32 v[10:11], s[10:11], v9, s9, v[34:35]
	v_or_b32_e32 v9, 18, v38
	v_mad_i64_i32 v[12:13], s[10:11], v9, s9, v[34:35]
	global_load_dword v10, v[10:11], off
	s_nop 0
	global_load_dword v9, v[12:13], off
	v_or_b32_e32 v11, 20, v38
	v_mad_i64_i32 v[12:13], s[10:11], v11, s9, v[34:35]
	v_or_b32_e32 v11, 22, v38
	v_mad_i64_i32 v[14:15], s[10:11], v11, s9, v[34:35]
	global_load_dword v12, v[12:13], off
	s_nop 0
	global_load_dword v11, v[14:15], off
	v_or_b32_e32 v13, 24, v38
	v_mad_i64_i32 v[14:15], s[10:11], v13, s9, v[34:35]
	v_or_b32_e32 v13, 26, v38
	v_mad_i64_i32 v[16:17], s[10:11], v13, s9, v[34:35]
	global_load_dword v14, v[14:15], off
	s_nop 0
	global_load_dword v13, v[16:17], off
	v_or_b32_e32 v15, 28, v38
	v_mad_i64_i32 v[16:17], s[10:11], v15, s9, v[34:35]
	v_or_b32_e32 v15, 30, v38
	v_mad_i64_i32 v[18:19], s[10:11], v15, s9, v[34:35]
	global_load_dword v16, v[16:17], off
	s_nop 0
	global_load_dword v15, v[18:19], off
	v_or_b32_e32 v17, 32, v38
	v_mad_i64_i32 v[18:19], s[10:11], v17, s9, v[34:35]
	v_or_b32_e32 v17, 34, v38
	v_mad_i64_i32 v[20:21], s[10:11], v17, s9, v[34:35]
	global_load_dword v18, v[18:19], off
	s_nop 0
	global_load_dword v17, v[20:21], off
	v_or_b32_e32 v19, 36, v38
	v_mad_i64_i32 v[20:21], s[10:11], v19, s9, v[34:35]
	v_or_b32_e32 v19, 38, v38
	v_mad_i64_i32 v[22:23], s[10:11], v19, s9, v[34:35]
	global_load_dword v20, v[20:21], off
	s_nop 0
	global_load_dword v19, v[22:23], off
	v_or_b32_e32 v21, 40, v38
	v_mad_i64_i32 v[22:23], s[10:11], v21, s9, v[34:35]
	v_or_b32_e32 v21, 42, v38
	v_mad_i64_i32 v[24:25], s[10:11], v21, s9, v[34:35]
	global_load_dword v22, v[22:23], off
	s_nop 0
	global_load_dword v21, v[24:25], off
	v_or_b32_e32 v23, 44, v38
	v_mad_i64_i32 v[24:25], s[10:11], v23, s9, v[34:35]
	v_or_b32_e32 v23, 46, v38
	v_mad_i64_i32 v[26:27], s[10:11], v23, s9, v[34:35]
	global_load_dword v24, v[24:25], off
	s_nop 0
	global_load_dword v23, v[26:27], off
	v_or_b32_e32 v25, 48, v38
	v_mad_i64_i32 v[26:27], s[10:11], v25, s9, v[34:35]
	v_or_b32_e32 v25, 50, v38
	v_mad_i64_i32 v[28:29], s[10:11], v25, s9, v[34:35]
	global_load_dword v26, v[26:27], off
	s_nop 0
	global_load_dword v25, v[28:29], off
	v_or_b32_e32 v27, 52, v38
	v_mad_i64_i32 v[28:29], s[10:11], v27, s9, v[34:35]
	v_or_b32_e32 v27, 54, v38
	v_mad_i64_i32 v[30:31], s[10:11], v27, s9, v[34:35]
	global_load_dword v28, v[28:29], off
	s_nop 0
	global_load_dword v27, v[30:31], off
	v_or_b32_e32 v29, 56, v38
	v_mad_i64_i32 v[30:31], s[10:11], v29, s9, v[34:35]
	v_or_b32_e32 v29, 58, v38
	v_mad_i64_i32 v[36:37], s[10:11], v29, s9, v[34:35]
	global_load_dword v30, v[30:31], off
	s_nop 0
	global_load_dword v29, v[36:37], off
	v_or_b32_e32 v31, 60, v38
	v_mad_i64_i32 v[36:37], s[10:11], v31, s9, v[34:35]
	v_or_b32_e32 v31, 62, v38
	v_mad_i64_i32 v[34:35], s[10:11], v31, s9, v[34:35]
	global_load_dword v32, v[36:37], off
	global_load_dword v31, v[34:35], off
	v_lshlrev_b32_e32 v36, 1, v44
	v_mov_b32_e32 v37, v151
	v_lshl_add_u64 v[34:35], s[4:5], 0, v[150:151]
	v_lshl_add_u64 v[36:37], s[0:1], 0, v[36:37]
	s_mov_b64 s[4:5], 0x3000000
	v_lshl_add_u64 v[36:37], v[36:37], 0, s[4:5]
	v_readlane_b32 s4, v254, 48
	v_mul_u32_u24_e32 v38, 0x84, v44
	s_lshl_b32 s9, s4, 5
	v_add3_u32 v41, s8, v38, v39
	s_lshl_b32 s8, s6, 5
	s_mov_b32 s10, s9
	v_readlane_b32 s5, v254, 49
	s_branch .LBB0_1326

; __device__ __forceinline__ void transpose_mat(const Ctx& c, const float* W, int K, int N, bf16* WT) {
;     float* scr = (float*)(c.lds + c.wid * 16384); const int items = (K / 64) * (N / 32), nblk = N / 32, lane = c.lane;
;     float tv[32];
;     int it = c.gw;
;     if (it < items) { const int k0 = 64 * (it / nblk), n0 = 32 * (it % nblk);
; #pragma unroll
;         for (int i = 0; i < 32; ++i) tv[i] = W[(size_t)(k0 + 2 * i + (lane >> 5)) * N + n0 + (lane & 31)]; }
; __device__ __forceinline__ void conv_ffn(const Ctx&, const In& in, unsigned char* ws, int layer) { const Ctx c = mk_ctx();
;     ...
;     transpose_mat(c, in[8] + (size_t)layer * 2816 * 1024, 2816, 1024, (bf16*)(W + W_FFNOUT));
.LBB0_1328:
	s_mov_b64 s[4:5], src_shared_base
	v_readlane_b32 s4, v254, 15
	s_cmp_lg_u32 s4, -1
	s_cselect_b32 s4, s4, 0
	s_cselect_b32 s5, s5, 0
	s_waitcnt vmcnt(35)
	v_mov_b32_e32 v2, s4
	s_waitcnt vmcnt(32)
	v_mov_b32_e32 v3, s5
	ds_read_b64 v[2:3], v2
	s_waitcnt lgkmcnt(0)
	s_cmpk_gt_i32 s6, 0x57f
	s_waitcnt lgkmcnt(0)
	v_readfirstlane_b32 s5, v3
	v_readfirstlane_b32 s4, v2
	s_cbranch_scc1 .LBB0_1333
; __device__ __forceinline__ void transpose_mat(const Ctx& c, const float* W, int K, int N, bf16* WT) {
;     float* scr = (float*)(c.lds + c.wid * 16384); const int items = (K / 64) * (N / 32), nblk = N / 32, lane = c.lane;
;     float tv[32];
;     int it = c.gw;
;     if (it < items) { const int k0 = 64 * (it / nblk), n0 = 32 * (it % nblk);
; #pragma unroll
;         for (int i = 0; i < 32; ++i) tv[i] = W[(size_t)(k0 + 2 * i + (lane >> 5)) * N + n0 + (lane & 31)]; }
	s_mul_i32 s9, s88, 0xb00000
	s_mul_hi_u32 s8, s88, 0xb00000
	s_add_u32 s4, s4, s9
	s_addc_u32 s5, s5, s8
	s_ashr_i32 s9, s6, 31
	s_lshr_b32 s9, s9, 27
	s_add_i32 s9, s6, s9
	s_lshl_b32 s10, s9, 1
	s_and_b32 s9, s9, 0x7ffffe0
	s_sub_i32 s9, s6, s9
	s_and_b32 s11, s10, 0xffffffc0
	s_lshl_b32 s10, s9, 5
	s_lshl_b32 s8, s7, 14
	v_or_b32_e32 v34, s11, v33
	s_ashr_i32 s11, s10, 31
	s_add_i32 s8, s8, 0
	s_lshl_b64 s[10:11], s[10:11], 2
	s_add_u32 s10, s4, s10
	v_or_b32_e32 v4, 2, v34
	s_addc_u32 s11, s5, s11
	v_ashrrev_i32_e32 v35, 31, v34
	v_ashrrev_i32_e32 v5, 31, v4
	v_lshl_add_u64 v[36:37], s[10:11], 0, v[150:151]
	v_lshlrev_b64 v[2:3], 12, v[34:35]
	v_lshlrev_b64 v[4:5], 12, v[4:5]
	v_lshl_add_u64 v[2:3], v[36:37], 0, v[2:3]
	v_lshl_add_u64 v[4:5], v[36:37], 0, v[4:5]
	global_load_dword v2, v[2:3], off
	v_or_b32_e32 v6, 6, v34
	global_load_dword v1, v[4:5], off
	v_or_b32_e32 v4, 4, v34
	v_ashrrev_i32_e32 v5, 31, v4
	v_ashrrev_i32_e32 v7, 31, v6
	v_lshlrev_b64 v[4:5], 12, v[4:5]
	v_lshlrev_b64 v[6:7], 12, v[6:7]
	v_lshl_add_u64 v[4:5], v[36:37], 0, v[4:5]
	v_lshl_add_u64 v[6:7], v[36:37], 0, v[6:7]
	global_load_dword v4, v[4:5], off
	v_or_b32_e32 v8, 10, v34
	global_load_dword v3, v[6:7], off
	v_or_b32_e32 v6, 8, v34
	v_ashrrev_i32_e32 v7, 31, v6
	v_ashrrev_i32_e32 v9, 31, v8
	v_lshlrev_b64 v[6:7], 12, v[6:7]
	v_lshlrev_b64 v[8:9], 12, v[8:9]
	v_lshl_add_u64 v[6:7], v[36:37], 0, v[6:7]
	v_lshl_add_u64 v[8:9], v[36:37], 0, v[8:9]
	global_load_dword v6, v[6:7], off
	v_or_b32_e32 v10, 14, v34
	global_load_dword v5, v[8:9], off
	v_or_b32_e32 v8, 12, v34
	v_ashrrev_i32_e32 v9, 31, v8
	v_ashrrev_i32_e32 v11, 31, v10
	v_lshlrev_b64 v[8:9], 12, v[8:9]
	v_lshlrev_b64 v[10:11], 12, v[10:11]
	v_lshl_add_u64 v[8:9], v[36:37], 0, v[8:9]
	v_lshl_add_u64 v[10:11], v[36:37], 0, v[10:11]
	global_load_dword v8, v[8:9], off
	v_or_b32_e32 v12, 18, v34
	global_load_dword v7, v[10:11], off
	v_or_b32_e32 v10, 16, v34
	v_ashrrev_i32_e32 v11, 31, v10
	v_ashrrev_i32_e32 v13, 31, v12
	v_lshlrev_b64 v[10:11], 12, v[10:11]
	v_lshlrev_b64 v[12:13], 12, v[12:13]
	v_lshl_add_u64 v[10:11], v[36:37], 0, v[10:11]
	v_lshl_add_u64 v[12:13], v[36:37], 0, v[12:13]
	global_load_dword v10, v[10:11], off
	v_or_b32_e32 v14, 22, v34
	global_load_dword v9, v[12:13], off
	v_or_b32_e32 v12, 20, v34
	v_ashrrev_i32_e32 v13, 31, v12
	v_ashrrev_i32_e32 v15, 31, v14
	v_lshlrev_b64 v[12:13], 12, v[12:13]
	v_lshlrev_b64 v[14:15], 12, v[14:15]
	v_lshl_add_u64 v[12:13], v[36:37], 0, v[12:13]
	v_lshl_add_u64 v[14:15], v[36:37], 0, v[14:15]
	global_load_dword v12, v[12:13], off
	v_or_b32_e32 v16, 26, v34
	global_load_dword v11, v[14:15], off
	v_or_b32_e32 v14, 24, v34
	v_ashrrev_i32_e32 v15, 31, v14
	v_ashrrev_i32_e32 v17, 31, v16
	v_lshlrev_b64 v[14:15], 12, v[14:15]
	v_lshlrev_b64 v[16:17], 12, v[16:17]
	v_lshl_add_u64 v[14:15], v[36:37], 0, v[14:15]
	v_lshl_add_u64 v[16:17], v[36:37], 0, v[16:17]
	global_load_dword v14, v[14:15], off
	v_or_b32_e32 v18, 30, v34
	global_load_dword v13, v[16:17], off
	v_or_b32_e32 v16, 28, v34
	v_ashrrev_i32_e32 v17, 31, v16
	v_ashrrev_i32_e32 v19, 31, v18
	v_lshlrev_b64 v[16:17], 12, v[16:17]
	v_lshlrev_b64 v[18:19], 12, v[18:19]
	v_lshl_add_u64 v[16:17], v[36:37], 0, v[16:17]
	v_lshl_add_u64 v[18:19], v[36:37], 0, v[18:19]
	global_load_dword v16, v[16:17], off
	v_or_b32_e32 v20, 34, v34
	global_load_dword v15, v[18:19], off
	v_or_b32_e32 v18, 32, v34
	v_ashrrev_i32_e32 v19, 31, v18
	v_ashrrev_i32_e32 v21, 31, v20
	v_lshlrev_b64 v[18:19], 12, v[18:19]
	v_lshlrev_b64 v[20:21], 12, v[20:21]
	v_lshl_add_u64 v[18:19], v[36:37], 0, v[18:19]
	v_lshl_add_u64 v[20:21], v[36:37], 0, v[20:21]
	global_load_dword v18, v[18:19], off
	v_or_b32_e32 v22, 38, v34
	global_load_dword v17, v[20:21], off
	v_or_b32_e32 v20, 36, v34
	v_ashrrev_i32_e32 v21, 31, v20
	v_ashrrev_i32_e32 v23, 31, v22
	v_lshlrev_b64 v[20:21], 12, v[20:21]
	v_lshlrev_b64 v[22:23], 12, v[22:23]
	v_lshl_add_u64 v[20:21], v[36:37], 0, v[20:21]
	v_lshl_add_u64 v[22:23], v[36:37], 0, v[22:23]
	global_load_dword v20, v[20:21], off
	v_or_b32_e32 v24, 42, v34
	global_load_dword v19, v[22:23], off
	v_or_b32_e32 v22, 40, v34
	v_ashrrev_i32_e32 v23, 31, v22
	v_ashrrev_i32_e32 v25, 31, v24
	v_lshlrev_b64 v[22:23], 12, v[22:23]
	v_lshlrev_b64 v[24:25], 12, v[24:25]
	v_lshl_add_u64 v[22:23], v[36:37], 0, v[22:23]
	v_lshl_add_u64 v[24:25], v[36:37], 0, v[24:25]
	global_load_dword v22, v[22:23], off
	v_or_b32_e32 v26, 46, v34
	global_load_dword v21, v[24:25], off
	v_or_b32_e32 v24, 44, v34
	v_ashrrev_i32_e32 v25, 31, v24
	v_ashrrev_i32_e32 v27, 31, v26
	v_lshlrev_b64 v[24:25], 12, v[24:25]
	v_lshlrev_b64 v[26:27], 12, v[26:27]
	v_lshl_add_u64 v[24:25], v[36:37], 0, v[24:25]
	v_lshl_add_u64 v[26:27], v[36:37], 0, v[26:27]
	global_load_dword v24, v[24:25], off
	v_or_b32_e32 v28, 50, v34
	global_load_dword v23, v[26:27], off
	v_or_b32_e32 v26, 48, v34
	v_ashrrev_i32_e32 v27, 31, v26
	v_ashrrev_i32_e32 v29, 31, v28
	v_lshlrev_b64 v[26:27], 12, v[26:27]
	v_lshlrev_b64 v[28:29], 12, v[28:29]
	v_lshl_add_u64 v[26:27], v[36:37], 0, v[26:27]
	v_lshl_add_u64 v[28:29], v[36:37], 0, v[28:29]
	global_load_dword v26, v[26:27], off
	v_or_b32_e32 v30, 54, v34
	global_load_dword v25, v[28:29], off
	v_or_b32_e32 v28, 52, v34
	v_ashrrev_i32_e32 v29, 31, v28
	v_ashrrev_i32_e32 v31, 31, v30
	v_lshlrev_b64 v[28:29], 12, v[28:29]
	v_lshlrev_b64 v[30:31], 12, v[30:31]
	v_lshl_add_u64 v[28:29], v[36:37], 0, v[28:29]
	v_lshl_add_u64 v[30:31], v[36:37], 0, v[30:31]
	global_load_dword v28, v[28:29], off
	v_or_b32_e32 v38, 58, v34
	global_load_dword v27, v[30:31], off
	v_or_b32_e32 v30, 56, v34
	v_ashrrev_i32_e32 v31, 31, v30
	v_ashrrev_i32_e32 v39, 31, v38
	v_lshlrev_b64 v[30:31], 12, v[30:31]
	v_lshlrev_b64 v[38:39], 12, v[38:39]
	v_lshl_add_u64 v[30:31], v[36:37], 0, v[30:31]
	v_lshl_add_u64 v[38:39], v[36:37], 0, v[38:39]
	global_load_dword v30, v[30:31], off
	v_readlane_b32 s10, v254, 48
	global_load_dword v29, v[38:39], off
	v_or_b32_e32 v38, 60, v34
	v_or_b32_e32 v34, 62, v34
	v_ashrrev_i32_e32 v39, 31, v38
	v_ashrrev_i32_e32 v35, 31, v34
	v_lshlrev_b64 v[38:39], 12, v[38:39]
	v_lshlrev_b64 v[34:35], 12, v[34:35]
	v_lshl_add_u64 v[38:39], v[36:37], 0, v[38:39]
	v_lshl_add_u64 v[34:35], v[36:37], 0, v[34:35]
	global_load_dword v32, v[38:39], off
	global_load_dword v31, v[34:35], off
	v_lshlrev_b32_e32 v36, 1, v44
	v_mov_b32_e32 v37, v151
	v_lshl_add_u64 v[34:35], s[4:5], 0, v[150:151]
	v_lshrrev_b32_e32 v38, 3, v45
	v_lshl_add_u64 v[36:37], s[0:1], 0, v[36:37]
	s_mov_b64 s[4:5], 0x3b00000
	v_mul_u32_u24_e32 v39, 0x84, v44
	v_lshl_add_u64 v[36:37], v[36:37], 0, s[4:5]
	v_lshlrev_b32_e32 v40, 2, v38
	s_mul_i32 s4, s6, 0x16000
	v_add3_u32 v46, s8, v39, v40
	v_mov_b32_e32 v39, s4
	s_movk_i32 s4, 0xb00
	v_mad_u32_u24 v48, v38, s4, v39
	v_readlane_b32 s11, v254, 49
	s_add_i32 s4, s10, s6
	v_add3_u32 v47, s8, v43, v150
	s_lshl_b32 s8, s4, 5
	s_lshl_b32 s9, s10, 5
	s_mov_b32 s11, s6
	s_branch .LBB0_1331

; __device__ __forceinline__ void transpose_mat(const Ctx& c, const float* W, int K, int N, bf16* WT) {
;     float* scr = (float*)(c.lds + c.wid * 16384); const int items = (K / 64) * (N / 32), nblk = N / 32, lane = c.lane;
;     float tv[32];
;     int it = c.gw;
;     if (it < items) { const int k0 = 64 * (it / nblk), n0 = 32 * (it % nblk);
; #pragma unroll
;         for (int i = 0; i < 32; ++i) tv[i] = W[(size_t)(k0 + 2 * i + (lane >> 5)) * N + n0 + (lane & 31)]; }
; __device__ __forceinline__ void conv_ffn(const Ctx&, const In& in, unsigned char* ws, int layer) { const Ctx c = mk_ctx();
;     ...
;     transpose_mat(c, in[9] + (size_t)layer * 256 * 1024, 256, 1024, (bf16*)(W + W_PLEP));
.LBB0_1333:
	s_mov_b64 s[4:5], src_shared_base
	v_readlane_b32 s4, v254, 17
	s_cmp_lg_u32 s4, -1
	s_cselect_b32 s4, s4, 0
	s_cselect_b32 s5, s5, 0
	s_waitcnt vmcnt(35)
	v_mov_b32_e32 v2, s4
	s_waitcnt vmcnt(32)
	v_mov_b32_e32 v3, s5
	ds_read_b64 v[2:3], v2
	s_waitcnt lgkmcnt(0)
	s_cmpk_gt_i32 s6, 0x7f
	s_waitcnt lgkmcnt(0)
	v_readfirstlane_b32 s5, v3
	v_readfirstlane_b32 s4, v2
	s_cbranch_scc1 .LBB0_1338
; __device__ __forceinline__ void transpose_mat(const Ctx& c, const float* W, int K, int N, bf16* WT) {
;     float* scr = (float*)(c.lds + c.wid * 16384); const int items = (K / 64) * (N / 32), nblk = N / 32, lane = c.lane;
;     float tv[32];
;     int it = c.gw;
;     if (it < items) { const int k0 = 64 * (it / nblk), n0 = 32 * (it % nblk);
; #pragma unroll
;         for (int i = 0; i < 32; ++i) tv[i] = W[(size_t)(k0 + 2 * i + (lane >> 5)) * N + n0 + (lane & 31)]; }
	s_lshl_b64 s[8:9], s[88:89], 20
	s_add_u32 s4, s4, s8
	s_addc_u32 s5, s5, s9
	s_ashr_i32 s9, s6, 31
	s_lshr_b32 s9, s9, 27
	s_add_i32 s9, s6, s9
	s_lshl_b32 s10, s9, 1
	s_and_b32 s9, s9, 0x7ffffe0
	s_sub_i32 s9, s6, s9
	s_and_b32 s11, s10, 0xffffffc0
	s_lshl_b32 s10, s9, 5
	s_lshl_b32 s8, s7, 14
	v_or_b32_e32 v34, s11, v33
	s_ashr_i32 s11, s10, 31
	s_add_i32 s8, s8, 0
	s_lshl_b64 s[10:11], s[10:11], 2
	s_add_u32 s10, s4, s10
	v_or_b32_e32 v4, 2, v34
	s_addc_u32 s11, s5, s11
	v_ashrrev_i32_e32 v35, 31, v34
	v_ashrrev_i32_e32 v5, 31, v4
	v_lshl_add_u64 v[36:37], s[10:11], 0, v[150:151]
	v_lshlrev_b64 v[2:3], 12, v[34:35]
	v_lshlrev_b64 v[4:5], 12, v[4:5]
	v_lshl_add_u64 v[2:3], v[36:37], 0, v[2:3]
	v_lshl_add_u64 v[4:5], v[36:37], 0, v[4:5]
	global_load_dword v2, v[2:3], off
	v_or_b32_e32 v6, 6, v34
	global_load_dword v1, v[4:5], off
	v_or_b32_e32 v4, 4, v34
	v_ashrrev_i32_e32 v5, 31, v4
	v_ashrrev_i32_e32 v7, 31, v6
	v_lshlrev_b64 v[4:5], 12, v[4:5]
	v_lshlrev_b64 v[6:7], 12, v[6:7]
	v_lshl_add_u64 v[4:5], v[36:37], 0, v[4:5]
	v_lshl_add_u64 v[6:7], v[36:37], 0, v[6:7]
	global_load_dword v4, v[4:5], off
	v_or_b32_e32 v8, 10, v34
	global_load_dword v3, v[6:7], off
	v_or_b32_e32 v6, 8, v34
	v_ashrrev_i32_e32 v7, 31, v6
	v_ashrrev_i32_e32 v9, 31, v8
	v_lshlrev_b64 v[6:7], 12, v[6:7]
	v_lshlrev_b64 v[8:9], 12, v[8:9]
	v_lshl_add_u64 v[6:7], v[36:37], 0, v[6:7]
	v_lshl_add_u64 v[8:9], v[36:37], 0, v[8:9]
	global_load_dword v6, v[6:7], off
	v_or_b32_e32 v10, 14, v34
	global_load_dword v5, v[8:9], off
	v_or_b32_e32 v8, 12, v34
	v_ashrrev_i32_e32 v9, 31, v8
	v_ashrrev_i32_e32 v11, 31, v10
	v_lshlrev_b64 v[8:9], 12, v[8:9]
	v_lshlrev_b64 v[10:11], 12, v[10:11]
	v_lshl_add_u64 v[8:9], v[36:37], 0, v[8:9]
	v_lshl_add_u64 v[10:11], v[36:37], 0, v[10:11]
	global_load_dword v8, v[8:9], off
	v_or_b32_e32 v12, 18, v34
	global_load_dword v7, v[10:11], off
	v_or_b32_e32 v10, 16, v34
	v_ashrrev_i32_e32 v11, 31, v10
	v_ashrrev_i32_e32 v13, 31, v12
	v_lshlrev_b64 v[10:11], 12, v[10:11]
	v_lshlrev_b64 v[12:13], 12, v[12:13]
	v_lshl_add_u64 v[10:11], v[36:37], 0, v[10:11]
	v_lshl_add_u64 v[12:13], v[36:37], 0, v[12:13]
	global_load_dword v10, v[10:11], off
	v_or_b32_e32 v14, 22, v34
	global_load_dword v9, v[12:13], off
	v_or_b32_e32 v12, 20, v34
	v_ashrrev_i32_e32 v13, 31, v12
	v_ashrrev_i32_e32 v15, 31, v14
	v_lshlrev_b64 v[12:13], 12, v[12:13]
	v_lshlrev_b64 v[14:15], 12, v[14:15]
	v_lshl_add_u64 v[12:13], v[36:37], 0, v[12:13]
	v_lshl_add_u64 v[14:15], v[36:37], 0, v[14:15]
	global_load_dword v12, v[12:13], off
	v_or_b32_e32 v16, 26, v34
	global_load_dword v11, v[14:15], off
	v_or_b32_e32 v14, 24, v34
	v_ashrrev_i32_e32 v15, 31, v14
	v_ashrrev_i32_e32 v17, 31, v16
	v_lshlrev_b64 v[14:15], 12, v[14:15]
	v_lshlrev_b64 v[16:17], 12, v[16:17]
	v_lshl_add_u64 v[14:15], v[36:37], 0, v[14:15]
	v_lshl_add_u64 v[16:17], v[36:37], 0, v[16:17]
	global_load_dword v14, v[14:15], off
	v_or_b32_e32 v18, 30, v34
	global_load_dword v13, v[16:17], off
	v_or_b32_e32 v16, 28, v34
	v_ashrrev_i32_e32 v17, 31, v16
	v_ashrrev_i32_e32 v19, 31, v18
	v_lshlrev_b64 v[16:17], 12, v[16:17]
	v_lshlrev_b64 v[18:19], 12, v[18:19]
	v_lshl_add_u64 v[16:17], v[36:37], 0, v[16:17]
	v_lshl_add_u64 v[18:19], v[36:37], 0, v[18:19]
	global_load_dword v16, v[16:17], off
	v_or_b32_e32 v20, 34, v34
	global_load_dword v15, v[18:19], off
	v_or_b32_e32 v18, 32, v34
	v_ashrrev_i32_e32 v19, 31, v18
	v_ashrrev_i32_e32 v21, 31, v20
	v_lshlrev_b64 v[18:19], 12, v[18:19]
	v_lshlrev_b64 v[20:21], 12, v[20:21]
	v_lshl_add_u64 v[18:19], v[36:37], 0, v[18:19]
	v_lshl_add_u64 v[20:21], v[36:37], 0, v[20:21]
	global_load_dword v18, v[18:19], off
	v_or_b32_e32 v22, 38, v34
	global_load_dword v17, v[20:21], off
	v_or_b32_e32 v20, 36, v34
	v_ashrrev_i32_e32 v21, 31, v20
	v_ashrrev_i32_e32 v23, 31, v22
	v_lshlrev_b64 v[20:21], 12, v[20:21]
	v_lshlrev_b64 v[22:23], 12, v[22:23]
	v_lshl_add_u64 v[20:21], v[36:37], 0, v[20:21]
	v_lshl_add_u64 v[22:23], v[36:37], 0, v[22:23]
	global_load_dword v20, v[20:21], off
	v_or_b32_e32 v24, 42, v34
	global_load_dword v19, v[22:23], off
	v_or_b32_e32 v22, 40, v34
	v_ashrrev_i32_e32 v23, 31, v22
	v_ashrrev_i32_e32 v25, 31, v24
	v_lshlrev_b64 v[22:23], 12, v[22:23]
	v_lshlrev_b64 v[24:25], 12, v[24:25]
	v_lshl_add_u64 v[22:23], v[36:37], 0, v[22:23]
	v_lshl_add_u64 v[24:25], v[36:37], 0, v[24:25]
	global_load_dword v22, v[22:23], off
	v_or_b32_e32 v26, 46, v34
	global_load_dword v21, v[24:25], off
	v_or_b32_e32 v24, 44, v34
	v_ashrrev_i32_e32 v25, 31, v24
	v_ashrrev_i32_e32 v27, 31, v26
	v_lshlrev_b64 v[24:25], 12, v[24:25]
	v_lshlrev_b64 v[26:27], 12, v[26:27]
	v_lshl_add_u64 v[24:25], v[36:37], 0, v[24:25]
	v_lshl_add_u64 v[26:27], v[36:37], 0, v[26:27]
	global_load_dword v24, v[24:25], off
	v_or_b32_e32 v28, 50, v34
	global_load_dword v23, v[26:27], off
	v_or_b32_e32 v26, 48, v34
	v_ashrrev_i32_e32 v27, 31, v26
	v_ashrrev_i32_e32 v29, 31, v28
	v_lshlrev_b64 v[26:27], 12, v[26:27]
	v_lshlrev_b64 v[28:29], 12, v[28:29]
	v_lshl_add_u64 v[26:27], v[36:37], 0, v[26:27]
	v_lshl_add_u64 v[28:29], v[36:37], 0, v[28:29]
	global_load_dword v26, v[26:27], off
	v_or_b32_e32 v30, 54, v34
	global_load_dword v25, v[28:29], off
	v_or_b32_e32 v28, 52, v34
	v_ashrrev_i32_e32 v29, 31, v28
	v_ashrrev_i32_e32 v31, 31, v30
	v_lshlrev_b64 v[28:29], 12, v[28:29]
	v_lshlrev_b64 v[30:31], 12, v[30:31]
	v_lshl_add_u64 v[28:29], v[36:37], 0, v[28:29]
	v_lshl_add_u64 v[30:31], v[36:37], 0, v[30:31]
	global_load_dword v28, v[28:29], off
	v_or_b32_e32 v38, 58, v34
	global_load_dword v27, v[30:31], off
	v_or_b32_e32 v30, 56, v34
	v_ashrrev_i32_e32 v31, 31, v30
	v_ashrrev_i32_e32 v39, 31, v38
	v_lshlrev_b64 v[30:31], 12, v[30:31]
	v_lshlrev_b64 v[38:39], 12, v[38:39]
	v_lshl_add_u64 v[30:31], v[36:37], 0, v[30:31]
	v_lshl_add_u64 v[38:39], v[36:37], 0, v[38:39]
	global_load_dword v30, v[30:31], off
	v_lshrrev_b32_e32 v45, 3, v45
	global_load_dword v29, v[38:39], off
	v_or_b32_e32 v38, 60, v34
	v_or_b32_e32 v34, 62, v34
	v_ashrrev_i32_e32 v39, 31, v38
	v_ashrrev_i32_e32 v35, 31, v34
	v_lshlrev_b64 v[38:39], 12, v[38:39]
	v_lshlrev_b64 v[34:35], 12, v[34:35]
	v_lshl_add_u64 v[38:39], v[36:37], 0, v[38:39]
	v_lshl_add_u64 v[34:35], v[36:37], 0, v[34:35]
	global_load_dword v32, v[38:39], off
	global_load_dword v31, v[34:35], off
	v_lshlrev_b32_e32 v36, 1, v44
	v_mov_b32_e32 v37, v151
	v_lshl_add_u64 v[34:35], s[4:5], 0, v[150:151]
	v_lshl_add_u64 v[36:37], s[0:1], 0, v[36:37]
	s_mov_b64 s[4:5], 0x4080000
	v_lshl_add_u64 v[36:37], v[36:37], 0, s[4:5]
	v_readlane_b32 s4, v254, 48
	v_mul_u32_u24_e32 v38, 0x84, v44
	v_lshlrev_b32_e32 v39, 2, v45
	s_lshl_b32 s9, s4, 5
	v_add3_u32 v46, s8, v38, v39
	v_add3_u32 v47, s8, v43, v150
	s_lshl_b32 s8, s6, 5
	s_mov_b32 s10, s9
	s_mov_b32 s12, s6
	v_readlane_b32 s5, v254, 49
	s_branch .LBB0_1336

; __device__ __forceinline__ void transpose_mat(const Ctx& c, const float* W, int K, int N, bf16* WT) {
;     float* scr = (float*)(c.lds + c.wid * 16384); const int items = (K / 64) * (N / 32), nblk = N / 32, lane = c.lane;
;     float tv[32];
;     int it = c.gw;
;     if (it < items) { const int k0 = 64 * (it / nblk), n0 = 32 * (it % nblk);
; #pragma unroll
;         for (int i = 0; i < 32; ++i) tv[i] = W[(size_t)(k0 + 2 * i + (lane >> 5)) * N + n0 + (lane & 31)]; }
; __device__ __forceinline__ void conv_ffn(const Ctx&, const In& in, unsigned char* ws, int layer) { const Ctx c = mk_ctx();
;     ...
;     transpose_mat(c, in[12] + (size_t)layer * 1024 * 1024, 1024, 1024, (bf16*)(W + W_PLEG));
.LBB0_1338:
	s_mov_b64 s[4:5], src_shared_base
	v_readlane_b32 s4, v254, 18
	s_cmp_lg_u32 s4, -1
	s_cselect_b32 s4, s4, 0
	s_cselect_b32 s5, s5, 0
	s_waitcnt vmcnt(35)
	v_mov_b32_e32 v2, s4
	s_waitcnt vmcnt(32)
	v_mov_b32_e32 v3, s5
	ds_read_b64 v[2:3], v2
	s_waitcnt lgkmcnt(0)
	s_cmpk_gt_i32 s6, 0x1ff
	s_waitcnt lgkmcnt(0)
	v_readfirstlane_b32 s5, v3
	v_readfirstlane_b32 s4, v2
	s_cbranch_scc1 .LBB0_1343
; __device__ __forceinline__ void transpose_mat(const Ctx& c, const float* W, int K, int N, bf16* WT) {
;     float* scr = (float*)(c.lds + c.wid * 16384); const int items = (K / 64) * (N / 32), nblk = N / 32, lane = c.lane;
;     float tv[32];
;     int it = c.gw;
;     if (it < items) { const int k0 = 64 * (it / nblk), n0 = 32 * (it % nblk);
; #pragma unroll
;         for (int i = 0; i < 32; ++i) tv[i] = W[(size_t)(k0 + 2 * i + (lane >> 5)) * N + n0 + (lane & 31)]; }
	s_lshl_b64 s[8:9], s[88:89], 22
	s_add_u32 s4, s4, s8
	s_addc_u32 s5, s5, s9
	s_ashr_i32 s8, s6, 31
	s_lshr_b32 s8, s8, 27
	s_add_i32 s8, s6, s8
	s_lshl_b32 s9, s8, 1
	s_and_b32 s8, s8, 0x7ffffe0
	s_sub_i32 s8, s6, s8
	s_andn2_b32 s9, s9, 63
	s_lshl_b32 s8, s8, 5
	s_lshl_b32 s7, s7, 14
	v_or_b32_e32 v34, s9, v33
	s_ashr_i32 s9, s8, 31
	s_add_i32 s7, s7, 0
	s_lshl_b64 s[8:9], s[8:9], 2
	s_add_u32 s8, s4, s8
	v_or_b32_e32 v4, 2, v34
	s_addc_u32 s9, s5, s9
	v_ashrrev_i32_e32 v35, 31, v34
	v_ashrrev_i32_e32 v5, 31, v4
	v_lshl_add_u64 v[36:37], s[8:9], 0, v[150:151]
	v_lshlrev_b64 v[2:3], 12, v[34:35]
	v_lshlrev_b64 v[4:5], 12, v[4:5]
	v_lshl_add_u64 v[2:3], v[36:37], 0, v[2:3]
	v_lshl_add_u64 v[4:5], v[36:37], 0, v[4:5]
	global_load_dword v2, v[2:3], off
	v_or_b32_e32 v6, 6, v34
	global_load_dword v1, v[4:5], off
	v_or_b32_e32 v4, 4, v34
	v_ashrrev_i32_e32 v5, 31, v4
	v_ashrrev_i32_e32 v7, 31, v6
	v_lshlrev_b64 v[4:5], 12, v[4:5]
	v_lshlrev_b64 v[6:7], 12, v[6:7]
	v_lshl_add_u64 v[4:5], v[36:37], 0, v[4:5]
	v_lshl_add_u64 v[6:7], v[36:37], 0, v[6:7]
	global_load_dword v4, v[4:5], off
	v_or_b32_e32 v8, 10, v34
	global_load_dword v3, v[6:7], off
	v_or_b32_e32 v6, 8, v34
	v_ashrrev_i32_e32 v7, 31, v6
	v_ashrrev_i32_e32 v9, 31, v8
	v_lshlrev_b64 v[6:7], 12, v[6:7]
	v_lshlrev_b64 v[8:9], 12, v[8:9]
	v_lshl_add_u64 v[6:7], v[36:37], 0, v[6:7]
	v_lshl_add_u64 v[8:9], v[36:37], 0, v[8:9]
	global_load_dword v6, v[6:7], off
	v_or_b32_e32 v10, 14, v34
	global_load_dword v5, v[8:9], off
	v_or_b32_e32 v8, 12, v34
	v_ashrrev_i32_e32 v9, 31, v8
	v_ashrrev_i32_e32 v11, 31, v10
	v_lshlrev_b64 v[8:9], 12, v[8:9]
	v_lshlrev_b64 v[10:11], 12, v[10:11]
	v_lshl_add_u64 v[8:9], v[36:37], 0, v[8:9]
	v_lshl_add_u64 v[10:11], v[36:37], 0, v[10:11]
	global_load_dword v8, v[8:9], off
	v_or_b32_e32 v12, 18, v34
	global_load_dword v7, v[10:11], off
	v_or_b32_e32 v10, 16, v34
	v_ashrrev_i32_e32 v11, 31, v10
	v_ashrrev_i32_e32 v13, 31, v12
	v_lshlrev_b64 v[10:11], 12, v[10:11]
	v_lshlrev_b64 v[12:13], 12, v[12:13]
	v_lshl_add_u64 v[10:11], v[36:37], 0, v[10:11]
	v_lshl_add_u64 v[12:13], v[36:37], 0, v[12:13]
	global_load_dword v10, v[10:11], off
	v_or_b32_e32 v14, 22, v34
	global_load_dword v9, v[12:13], off
	v_or_b32_e32 v12, 20, v34
	v_ashrrev_i32_e32 v13, 31, v12
	v_ashrrev_i32_e32 v15, 31, v14
	v_lshlrev_b64 v[12:13], 12, v[12:13]
	v_lshlrev_b64 v[14:15], 12, v[14:15]
	v_lshl_add_u64 v[12:13], v[36:37], 0, v[12:13]
	v_lshl_add_u64 v[14:15], v[36:37], 0, v[14:15]
	global_load_dword v12, v[12:13], off
	v_or_b32_e32 v16, 26, v34
	global_load_dword v11, v[14:15], off
	v_or_b32_e32 v14, 24, v34
	v_ashrrev_i32_e32 v15, 31, v14
	v_ashrrev_i32_e32 v17, 31, v16
	v_lshlrev_b64 v[14:15], 12, v[14:15]
	v_lshlrev_b64 v[16:17], 12, v[16:17]
	v_lshl_add_u64 v[14:15], v[36:37], 0, v[14:15]
	v_lshl_add_u64 v[16:17], v[36:37], 0, v[16:17]
	global_load_dword v14, v[14:15], off
	v_or_b32_e32 v18, 30, v34
	global_load_dword v13, v[16:17], off
	v_or_b32_e32 v16, 28, v34
	v_ashrrev_i32_e32 v17, 31, v16
	v_ashrrev_i32_e32 v19, 31, v18
	v_lshlrev_b64 v[16:17], 12, v[16:17]
	v_lshlrev_b64 v[18:19], 12, v[18:19]
	v_lshl_add_u64 v[16:17], v[36:37], 0, v[16:17]
	v_lshl_add_u64 v[18:19], v[36:37], 0, v[18:19]
	global_load_dword v16, v[16:17], off
	v_or_b32_e32 v20, 34, v34
	global_load_dword v15, v[18:19], off
	v_or_b32_e32 v18, 32, v34
	v_ashrrev_i32_e32 v19, 31, v18
	v_ashrrev_i32_e32 v21, 31, v20
	v_lshlrev_b64 v[18:19], 12, v[18:19]
	v_lshlrev_b64 v[20:21], 12, v[20:21]
	v_lshl_add_u64 v[18:19], v[36:37], 0, v[18:19]
	v_lshl_add_u64 v[20:21], v[36:37], 0, v[20:21]
	global_load_dword v18, v[18:19], off
	v_or_b32_e32 v22, 38, v34
	global_load_dword v17, v[20:21], off
	v_or_b32_e32 v20, 36, v34
	v_ashrrev_i32_e32 v21, 31, v20
	v_ashrrev_i32_e32 v23, 31, v22
	v_lshlrev_b64 v[20:21], 12, v[20:21]
	v_lshlrev_b64 v[22:23], 12, v[22:23]
	v_lshl_add_u64 v[20:21], v[36:37], 0, v[20:21]
	v_lshl_add_u64 v[22:23], v[36:37], 0, v[22:23]
	global_load_dword v20, v[20:21], off
	v_or_b32_e32 v24, 42, v34
	global_load_dword v19, v[22:23], off
	v_or_b32_e32 v22, 40, v34
	v_ashrrev_i32_e32 v23, 31, v22
	v_ashrrev_i32_e32 v25, 31, v24
	v_lshlrev_b64 v[22:23], 12, v[22:23]
	v_lshlrev_b64 v[24:25], 12, v[24:25]
	v_lshl_add_u64 v[22:23], v[36:37], 0, v[22:23]
	v_lshl_add_u64 v[24:25], v[36:37], 0, v[24:25]
	global_load_dword v22, v[22:23], off
	v_or_b32_e32 v26, 46, v34
	global_load_dword v21, v[24:25], off
	v_or_b32_e32 v24, 44, v34
	v_ashrrev_i32_e32 v25, 31, v24
	v_ashrrev_i32_e32 v27, 31, v26
	v_lshlrev_b64 v[24:25], 12, v[24:25]
	v_lshlrev_b64 v[26:27], 12, v[26:27]
	v_lshl_add_u64 v[24:25], v[36:37], 0, v[24:25]
	v_lshl_add_u64 v[26:27], v[36:37], 0, v[26:27]
	global_load_dword v24, v[24:25], off
	v_or_b32_e32 v28, 50, v34
	global_load_dword v23, v[26:27], off
	v_or_b32_e32 v26, 48, v34
	v_ashrrev_i32_e32 v27, 31, v26
	v_ashrrev_i32_e32 v29, 31, v28
	v_lshlrev_b64 v[26:27], 12, v[26:27]
	v_lshlrev_b64 v[28:29], 12, v[28:29]
	v_lshl_add_u64 v[26:27], v[36:37], 0, v[26:27]
	v_lshl_add_u64 v[28:29], v[36:37], 0, v[28:29]
	global_load_dword v26, v[26:27], off
	v_or_b32_e32 v30, 54, v34
	global_load_dword v25, v[28:29], off
	v_or_b32_e32 v28, 52, v34
	v_ashrrev_i32_e32 v29, 31, v28
	v_ashrrev_i32_e32 v31, 31, v30
	v_lshlrev_b64 v[28:29], 12, v[28:29]
	v_lshlrev_b64 v[30:31], 12, v[30:31]
	v_lshl_add_u64 v[28:29], v[36:37], 0, v[28:29]
	v_lshl_add_u64 v[30:31], v[36:37], 0, v[30:31]
	global_load_dword v28, v[28:29], off
	v_or_b32_e32 v38, 58, v34
	global_load_dword v27, v[30:31], off
	v_or_b32_e32 v30, 56, v34
	v_ashrrev_i32_e32 v31, 31, v30
	v_ashrrev_i32_e32 v39, 31, v38
	v_lshlrev_b64 v[30:31], 12, v[30:31]
	v_lshlrev_b64 v[38:39], 12, v[38:39]
	v_lshl_add_u64 v[30:31], v[36:37], 0, v[30:31]
	v_lshl_add_u64 v[38:39], v[36:37], 0, v[38:39]
	global_load_dword v30, v[30:31], off
	v_add3_u32 v43, s7, v43, v150
	global_load_dword v29, v[38:39], off
	v_or_b32_e32 v38, 60, v34
	v_or_b32_e32 v34, 62, v34
	v_ashrrev_i32_e32 v39, 31, v38
	v_ashrrev_i32_e32 v35, 31, v34
	v_lshlrev_b64 v[38:39], 12, v[38:39]
	v_lshlrev_b64 v[34:35], 12, v[34:35]
	v_lshl_add_u64 v[38:39], v[36:37], 0, v[38:39]
	v_lshl_add_u64 v[34:35], v[36:37], 0, v[34:35]
	global_load_dword v32, v[38:39], off
	global_load_dword v31, v[34:35], off
	v_lshlrev_b32_e32 v36, 1, v44
	v_mov_b32_e32 v37, v151
	v_lshl_add_u64 v[36:37], s[0:1], 0, v[36:37]
	s_mov_b64 s[0:1], 0x4100000
	v_lshl_add_u64 v[36:37], v[36:37], 0, s[0:1]
	v_readlane_b32 s0, v254, 48
	v_lshl_add_u64 v[34:35], s[4:5], 0, v[150:151]
	v_mul_u32_u24_e32 v38, 0x84, v44
	v_lshlrev_b32_e32 v39, 2, v42
	s_lshl_b32 s5, s0, 5
	v_add3_u32 v44, s7, v38, v39
	s_lshl_b32 s4, s6, 5
	s_mov_b32 s7, s5
	v_readlane_b32 s1, v254, 49
	s_branch .LBB0_1341

; __device__ __forceinline__ void rw_prep_phase(const Ctx&, const In& in, unsigned char* ws, int j) { const Ctx c = mk_ctx();
;     const bf16* rwp = (const bf16*)(ws + WS_R + R_RWP); float* scanop = (float*)(ws + WS_R + R_SCAN); bf16* vbf = (bf16*)(ws + WS_HA + HA_VBF); bf16* acat = (bf16*)(ws + WS_HA + HA_ACAT);
;     const float* mu = in[15] + (size_t)j * 1824; const float* k_k = in[21] + (size_t)j * 512;
;     const int lane = c.lane, hh = lane >> 3, n0 = (lane & 7) * 8;
;     for (int row = c.gw; row < T; row += c.NGW) { const int b = row >> 13, t = row & 8191; const bf16* cur = rwp + (size_t)row * RWP_LD; const bool hp = t > 0;
;         float xm[3][8];
; #pragma unroll
;         for (int part = 0; part < 3; ++part) { const int ch = part * 512 + hh * 64 + n0; const v4u cu = *(const v4u*)(cur + ch); v4u pu = {0u, 0u, 0u, 0u}; if (hp) pu = *(const v4u*)(cur - RWP_LD + ch);
.LBB0_1400:
	s_mov_b64 s[4:5], src_shared_base
	v_readlane_b32 s4, v254, 4
	s_cmp_lg_u32 s4, -1
	s_cselect_b32 s4, s4, 0
	s_cselect_b32 s6, s5, 0
	v_mov_b32_e32 v2, s4
	v_mov_b32_e32 v3, s6
	ds_read_b64 v[4:5], v2
	s_waitcnt lgkmcnt(0)
	v_mov_b32_e32 v2, v147
	v_readlane_b32 s4, v254, 0
	v_readfirstlane_b32 s6, v2
	s_ashr_i32 s12, s6, 6
	s_lshl_b32 s13, s4, 3
	s_add_i32 s26, s12, s13
	s_add_i32 s4, 0, 0x20078
	s_cmp_lg_u32 s4, -1
	s_cselect_b32 s4, s4, 0
	s_cselect_b32 s6, s5, 0
	v_mov_b32_e32 v6, s4
	s_add_i32 s4, 0, 0x200a8
	s_cmp_lg_u32 s4, -1
	s_cselect_b32 s4, s4, 0
	s_cselect_b32 s5, s5, 0
	v_mov_b32_e32 v7, s6
	v_mov_b32_e32 v8, s4
	v_mov_b32_e32 v9, s5
	ds_read_b64 v[6:7], v6
	s_waitcnt lgkmcnt(0)
	s_cmpk_gt_i32 s26, 0x3fff
	ds_read_b64 v[8:9], v8
	s_waitcnt lgkmcnt(0)
	v_readfirstlane_b32 s15, v5
	v_readfirstlane_b32 s14, v4
	v_readfirstlane_b32 s6, v7
	v_readfirstlane_b32 s7, v6
	v_readfirstlane_b32 s4, v9
	v_readfirstlane_b32 s5, v8
	s_cbranch_scc1 .LBB0_1465
	s_mul_i32 s8, s90, 0x1c80
	v_and_b32_e32 v4, 63, v2
	v_bfe_u32 v1, v2, 3, 3
	s_add_u32 s16, s7, s8
	s_mul_hi_u32 s7, s90, 0x1c80
	v_lshlrev_b32_e32 v2, 3, v2
	s_addc_u32 s17, s6, s7
	v_and_b32_e32 v5, 56, v2
	s_add_u32 s6, s5, s0
	v_lshlrev_b32_e32 v150, 2, v5
	s_addc_u32 s7, s4, s1
	v_lshl_add_u64 v[2:3], s[14:15], 0, v[150:151]
	s_mov_b64 s[4:5], 0xb600000
	v_lshl_add_u64 v[42:43], v[2:3], 0, s[4:5]
	v_lshlrev_b32_e32 v2, 8, v1
	v_mov_b32_e32 v3, v151
	v_lshl_add_u64 v[2:3], s[6:7], 0, v[2:3]
	v_lshl_add_u64 v[44:45], v[2:3], 0, v[150:151]
	v_and_b32_e32 v3, 64, v206
	v_xor_b32_e32 v2, 1, v206
	v_add_u32_e32 v3, 64, v3
	v_cmp_lt_i32_e32 vcc, v2, v3
	v_lshlrev_b32_e32 v150, 1, v5
	s_mov_b64 s[4:5], 0x400000
	v_cndmask_b32_e32 v2, v206, v2, vcc
	v_lshlrev_b32_e32 v62, 2, v2
	v_xor_b32_e32 v2, 2, v206
	v_cmp_lt_i32_e32 vcc, v2, v3
	v_cmp_gt_u32_e64 s[6:7], 36, v4
	v_cmp_lt_u32_e64 s[8:9], 7, v4
	v_cndmask_b32_e32 v2, v206, v2, vcc
	v_lshlrev_b32_e32 v63, 2, v2
	v_xor_b32_e32 v2, 4, v206
	v_cmp_lt_i32_e32 vcc, v2, v3
	v_cmp_lt_u32_e64 s[10:11], 15, v4
	s_nop 0
	v_cndmask_b32_e32 v2, v206, v2, vcc
	v_lshlrev_b32_e32 v64, 2, v2
	v_lshl_add_u64 v[2:3], s[14:15], 0, v[150:151]
	v_lshl_add_u64 v[46:47], v[2:3], 0, s[4:5]
	v_mov_b32_e32 v2, 0x1800
	v_lshl_or_b32 v150, v4, 5, v2
	v_lshl_or_b32 v2, v1, 6, v5
	v_lshl_add_u64 v[48:49], s[16:17], 0, v[150:151]
	v_lshlrev_b32_e32 v150, 2, v2
	v_lshl_add_u64 v[50:51], s[16:17], 0, v[150:151]
	v_or_b32_e32 v150, 0x1000, v150
	v_lshl_add_u64 v[52:53], s[16:17], 0, v[150:151]
	s_ashr_i32 s16, s12, 31
	s_ashr_i32 s17, s13, 31
	s_add_u32 s18, s12, s13
	s_addc_u32 s16, s16, s17
	s_mul_i32 s12, s16, 0x300
	s_mul_hi_u32 s13, s18, 0x300
	s_add_i32 s13, s13, s12
	s_mul_i32 s12, s18, 0x300
	s_add_u32 s12, s12, 0x1400000
	s_addc_u32 s13, s13, 0
	v_lshlrev_b32_e32 v150, 4, v4
	v_lshl_add_u64 v[54:55], s[12:13], 0, v[150:151]
	v_mad_u64_u32 v[56:57], s[12:13], s18, v209, v[150:151]
	v_lshlrev_b32_e32 v150, 1, v2
	s_mulk_i32 s16, 0xe80
	v_mad_u64_u32 v[58:59], s[12:13], s18, v209, v[150:151]
	v_cmp_gt_u32_e64 s[4:5], 48, v4
	v_add_u32_e32 v57, s16, v57
	v_add_u32_e32 v59, s16, v59
	s_branch .LBB0_1405

; #define REPLOOP(id) int nrep_ = (REP_PHASE == (id)) ? 2 : 1; asm volatile("" : "+s"(nrep_)); for (int rep_ = 0; rep_ < nrep_; ++rep_)
; #define SYNC() do { asm volatile("s_waitcnt vmcnt(0) lgkmcnt(0)" ::: "memory"); XcdBarrier xb_; xb_.bar = (unsigned*)P_WS; xb_.x = xb_xcc_id(); xb_.st = (volatile LAS unsigned*)(LAS unsigned char*)(g_lds + PTAB_OFF + 384); xcd_barrier(xb_); } while (0)
; __device__ __forceinline__ void xcd_barrier(const XcdBarrier& b) {
;     asm volatile("s_waitcnt vmcnt(0)" ::: "memory");
;     __syncthreads();
;     if (threadIdx.x == 0) {
;         unsigned* bar = b.bar;
;         __builtin_amdgcn_s_waitcnt(0);
;         unsigned nloc = b.st[0], nx = b.st[1];
;         if (nloc == 0u) { xcd_barrier_complete(bar, b.x, nloc, nx); b.st[0] = nloc; b.st[1] = nx; }
; __global__ void __launch_bounds__(512, 2) mega_fwd(Args a) {
;     ...
; { REPLOOP(6) {             if (PH(1)) { rw_prep_phase(c, in, ws, jl); } if (rep_ + 1 < nrep_) SYNC(); } }
.LBB0_1465:
	s_add_i32 s31, s31, 1
	s_cmp_ge_i32 s31, s30
	s_cbranch_scc1 .LBB0_1399
	s_mov_b64 s[4:5], src_shared_base
	v_readlane_b32 s4, v254, 4
	s_cmp_lg_u32 s4, -1
	s_cselect_b32 s4, s4, 0
	s_cselect_b32 s5, s5, 0
	s_waitcnt vmcnt(0) lgkmcnt(0)
	v_mov_b32_e32 v2, s4
	v_mov_b32_e32 v3, s5
	ds_read_b64 v[2:3], v2
	s_waitcnt lgkmcnt(0)
	s_getreg_b32 s8, hwreg(HW_REG_XCC_ID, 0, 4)
	s_waitcnt vmcnt(0)
	s_waitcnt lgkmcnt(0)
	s_barrier
	v_readfirstlane_b32 s7, v3
	v_readfirstlane_b32 s6, v2
	s_mov_b64 s[4:5], exec
	v_readlane_b32 s10, v254, 1
	v_readlane_b32 s11, v254, 2
	s_and_b64 s[10:11], s[4:5], s[10:11]
	s_mov_b64 exec, s[10:11]
	s_cbranch_execz .LBB0_1398
	v_readlane_b32 s9, v254, 54
	s_waitcnt vmcnt(0) expcnt(0) lgkmcnt(0)
	s_and_b32 s26, s8, 15
	v_mov_b32_e32 v1, s9
	ds_read_b32 v3, v1
	v_readlane_b32 s9, v254, 55
	s_waitcnt lgkmcnt(0)
	v_cmp_ne_u32_e32 vcc, 0, v3
	v_mov_b32_e32 v1, s9
	ds_read_b32 v2, v1
	s_cbranch_vccnz .LBB0_1482
	v_readlane_b32 s8, v254, 5
	v_readlane_b32 s9, v254, 6
	s_load_dwordx2 s[12:13], s[8:9], 0x4
	s_add_u32 s8, s6, 0x1000
	s_addc_u32 s9, s7, 0
	s_add_u32 s10, s6, 0x1100
	s_addc_u32 s11, s7, 0
	v_readlane_b32 s14, v254, 7
	s_waitcnt lgkmcnt(0)
	s_mul_i32 s27, s12, s14
	s_add_u32 s12, s6, 0x1200
	s_mul_i32 s27, s27, s13
	s_addc_u32 s13, s7, 0
	s_add_u32 s14, s6, 0x1300
	s_addc_u32 s15, s7, 0
	s_mov_b32 s28, 1
	s_branch .LBB0_1470

; #define LAS __attribute__((address_space(3)))
;     __host__ __device__ bool next(int i, Unit& u) const {
;         const long L = (long)i * G + c; if (L >= nwg) return false;
;         int wgid = (int)L; { const int q = nwg / NXCD, r = nwg % NXCD, xcd = wgid % NXCD, off = wgid / NXCD; wgid = (xcd < r ? xcd * (q + 1) : r * (q + 1) + (xcd - r) * q) + off; }
;         const int nig = WGM * nN, gid = wgid / nig, fm = gid * WGM, gsz = (nM - fm) < WGM ? (nM - fm) : WGM;
;         u.pm = fm + ((wgid % nig) % gsz); u.pn = (wgid % nig) / gsz; return true;
; template <int ID, class E> __device__ __forceinline__ void run_gemm(LAS unsigned char* lds, const bf16* A, const bf16* Bt, int M, int N, int K, const E& e) {
;     asm volatile("" : "+s"(K)); asm volatile("" : "+s"(N));
;     pg8::Gemm g{A, Bt, M, N, K}; pg8::StaticOrder S; S.init(M, N, (int)gridDim.x, (int)blockIdx.x);
.LBB0_1569:
	s_or_b64 exec, exec, s[0:1]
	v_readlane_b32 s0, v254, 4
	s_cmp_lg_u32 s0, -1
	s_mov_b64 s[4:5], src_shared_base
	s_cselect_b32 s0, s0, 0
	s_cselect_b32 s1, s5, 0
	s_waitcnt lgkmcnt(0)
	v_mov_b64_e32 v[2:3], s[0:1]
	s_barrier
	ds_read_b64 v[4:5], v2
	s_waitcnt lgkmcnt(0)
	s_movk_i32 s0, 0x180
	ds_read_b64 v[2:3], v2
	s_waitcnt lgkmcnt(0)
	s_movk_i32 s4, 0x600
	s_ashr_i32 s5, s4, 31
	s_lshr_b32 s5, s5, 24
	s_add_i32 s4, s4, s5
	s_ashr_i32 s12, s4, 8
	s_lshl_b32 s14, s12, 6
	v_readlane_b32 s9, v254, 0
	s_cmp_lt_i32 s9, s14
	v_readfirstlane_b32 s13, v147
	s_cselect_b64 s[4:5], -1, 0
	s_cmp_ge_i32 s9, s14
	s_waitcnt lgkmcnt(0)
	v_readfirstlane_b32 s1, v5
	v_readfirstlane_b32 s6, v4
	v_readfirstlane_b32 s7, v3
	v_readfirstlane_b32 s8, v2
	s_cbranch_scc1 .LBB0_1571
	s_lshl_b32 s9, s12, 3
	s_abs_i32 s10, s9
	v_cvt_f32_u32_e32 v1, s10
	v_readlane_b32 s11, v254, 24
	s_or_b32 s11, s9, s11
	v_readlane_b32 s15, v254, 37
	v_rcp_iflag_f32_e32 v1, v1
	s_mul_i32 s11, s11, s15
	s_sub_i32 s15, 0, s10
	v_readlane_b32 s16, v254, 23
	v_mul_f32_e32 v1, 0x4f7ffffe, v1
	v_cvt_u32_f32_e32 v1, v1
	s_add_i32 s11, s11, s16
	s_abs_i32 s17, s11
	s_xor_b32 s16, s11, s9
	v_readfirstlane_b32 s18, v1
	s_mul_i32 s15, s15, s18
	s_mul_hi_u32 s15, s18, s15
	s_add_i32 s18, s18, s15
	s_mul_hi_u32 s15, s17, s18
	s_mul_i32 s18, s15, s10
	s_sub_i32 s17, s17, s18
	s_ashr_i32 s16, s16, 31
	s_add_i32 s19, s15, 1
	s_sub_i32 s18, s17, s10
	s_cmp_ge_u32 s17, s10
	s_cselect_b32 s15, s19, s15
	s_cselect_b32 s17, s18, s17
	s_add_i32 s18, s15, 1
	s_cmp_ge_u32 s17, s10
	s_cselect_b32 s10, s18, s15
	s_xor_b32 s10, s10, s16
	s_sub_i32 s10, s10, s16
	s_lshl_b32 s15, s10, 3
	s_sub_i32 s16, 64, s15
	s_min_i32 s16, s16, 8
	s_abs_i32 s17, s16
	v_cvt_f32_u32_e32 v1, s17
	s_sub_i32 s18, 0, s17
	s_mul_i32 s10, s10, s9
	s_sub_i32 s9, s11, s10
	v_rcp_iflag_f32_e32 v1, v1
	s_abs_i32 s10, s9
	s_xor_b32 s11, s9, s16
	s_ashr_i32 s11, s11, 31
	v_mul_f32_e32 v1, 0x4f7ffffe, v1
	v_cvt_u32_f32_e32 v1, v1
	s_nop 0
	v_readfirstlane_b32 s19, v1
	s_mul_i32 s18, s18, s19
	s_mul_hi_u32 s18, s19, s18
	s_add_i32 s19, s19, s18
	s_mul_hi_u32 s18, s10, s19
	s_mul_i32 s19, s18, s17
	s_sub_i32 s10, s10, s19
	s_add_i32 s24, s18, 1
	s_sub_i32 s19, s10, s17
	s_cmp_ge_u32 s10, s17
	s_cselect_b32 s18, s24, s18
	s_cselect_b32 s10, s19, s10
	s_add_i32 s19, s18, 1
	s_cmp_ge_u32 s10, s17
	s_cselect_b32 s10, s19, s18
	s_xor_b32 s10, s10, s11
	s_sub_i32 s11, s10, s11
	s_mul_i32 s10, s11, s16
	s_sub_i32 s9, s9, s10
	s_add_i32 s10, s9, s15

.LBB0_1588:
	s_lshl_b32 s75, s11, 8
	s_or_b32 s11, s75, s64
	v_readlane_b32 s0, v254, 4
	s_cmp_lg_u32 s0, -1
	s_cselect_b32 s6, s0, 0
	s_mov_b64 s[0:1], src_shared_base
	s_cselect_b32 s0, s1, 0
	v_mov_b32_e32 v130, s6
	v_mov_b32_e32 v131, s0
	ds_read_b64 v[130:131], v130
	s_waitcnt lgkmcnt(0)
	v_lshl_add_u32 v160, s10, 8, v1
	v_ashrrev_i32_e32 v161, 31, v160
	v_or_b32_e32 v158, s11, v148
	v_and_b32_e32 v169, 0x1fcf, v160
	s_waitcnt lgkmcnt(0)
	v_readfirstlane_b32 s50, v130
	v_readfirstlane_b32 s51, v131
	s_add_u32 s48, s50, 0xb600000
	s_addc_u32 s49, s51, 0
	s_add_i32 s0, 0, 0x20080
	s_cmp_lg_u32 s0, -1
	s_cselect_b32 s0, s0, 0
	s_cselect_b32 s6, s1, 0
	v_mov_b32_e32 v130, s0
	v_mov_b32_e32 v131, s6
	ds_read_b64 v[130:131], v130
	s_waitcnt lgkmcnt(0)
	v_readfirstlane_b32 s6, v130
	v_readfirstlane_b32 s0, v131
	s_add_u32 s38, s6, s30
	s_addc_u32 s39, s0, s31
	s_add_i32 s0, 0, 0x20090
	s_cmp_lg_u32 s0, -1
	s_cselect_b32 s0, s0, 0
	s_cselect_b32 s6, s1, 0
	v_mov_b32_e32 v130, s0
	v_mov_b32_e32 v131, s6
	ds_read_b64 v[130:131], v130
	s_waitcnt lgkmcnt(0)
	v_readfirstlane_b32 s6, v130
	v_readfirstlane_b32 s0, v131
	s_add_u32 s44, s6, s30
	s_addc_u32 s45, s0, s31
	s_add_i32 s0, 0, 0x200b0
	s_cmp_lg_u32 s0, -1
	s_cselect_b32 s0, s0, 0
	s_cselect_b32 s1, s1, 0
	v_mov_b32_e32 v130, s0
	v_mov_b32_e32 v131, s1
	ds_read_b64 v[130:131], v130
	s_waitcnt lgkmcnt(0)
	v_readfirstlane_b32 s1, v130
	v_readfirstlane_b32 s0, v131
	s_add_u32 s46, s1, s30
	v_ashrrev_i32_e32 v130, 10, v160
	s_addc_u32 s47, s0, s31
	v_and_b32_e32 v168, -8, v130
	v_lshlrev_b64 v[130:131], 10, v[160:161]
	s_movk_i32 s0, 0x1ff
	v_lshl_add_u64 v[162:163], s[50:51], 0, v[130:131]
	v_cmp_lt_i32_e64 s[6:7], s0, v158
	s_and_saveexec_b64 s[0:1], s[6:7]
	s_xor_b64 s[0:1], exec, s[0:1]
	s_cbranch_execz .LBB0_1593
	s_cmpk_gt_u32 s75, 0x3ff
	s_mov_b64 s[8:9], -1
	s_cbranch_scc0 .LBB0_1591
	v_mov_b32_e32 v159, v151
	v_lshl_add_u64 v[132:133], v[158:159], 1, v[162:163]
	v_add_co_u32_e32 v132, vcc, 0x9bff000, v132
	v_cvt_pk_bf16_f32 v130, v126, v127
	v_cvt_pk_bf16_f32 v131, v128, v129
	s_mov_b64 s[8:9], 0
	s_nop 0
	v_addc_co_u32_e32 v133, vcc, 0, v133, vcc
	global_store_dwordx2 v[132:133], v[130:131], off offset:2048

; __device__ __forceinline__ float softplusf_(float x) { return fmaxf(x, 0.f) + __logf(1.0f + __expf(-fabsf(x))); }
; __device__ __forceinline__ int crow(int r, int hi) { return (r & 3) + 8 * (r >> 2) + 4 * hi; }
; #define MFMA32(a, b, c) __builtin_amdgcn_mfma_f32_32x32x16_bf16((a), (b), (c), 0, 0, 0)
; #define REPLOOP(id) int nrep_ = (REP_PHASE == (id)) ? 2 : 1; asm volatile("" : "+s"(nrep_)); for (int rep_ = 0; rep_ < nrep_; ++rep_)
; #define SYNC() do { asm volatile("s_waitcnt vmcnt(0) lgkmcnt(0)" ::: "memory"); XcdBarrier xb_; xb_.bar = (unsigned*)P_WS; xb_.x = xb_xcc_id(); xb_.st = (volatile LAS unsigned*)(LAS unsigned char*)(g_lds + PTAB_OFF + 384); xcd_barrier(xb_); } while (0)
; __device__ __forceinline__ void sb_attn_phase(const Ctx&, bf16* qk, const bf16* vt) { const Ctx c = mk_ctx();
;     const int r = c.lane & 31, hi = c.lane >> 5;
;     for (int task = (int)blockIdx.x * 4 + (c.wid - 4); task < 16 * 256; task += (int)gridDim.x * 4) {
;         const int chain = task >> 8, qblk = task & 255, b = chain >> 3, h = chain & 7, q0 = qblk * 32; const size_t rowbase = (size_t)b * SEQ;
;         bf16x8 qr[4];
; #pragma unroll
;         for (int s = 0; s < 4; ++s) qr[s] = *(const bf16x8*)(qk + (rowbase + q0 + r) * 1024 + h * 64 + 16 * s + 8 * hi);
;         f32x16 o[2]; o[0] = f32x16{}; o[1] = f32x16{}; float carry = 0.f;
;     ...
;             f32x16 z = f32x16{};
; #pragma unroll
;             for (int s = 0; s < 4; ++s) { const bf16x8 kf = *(const bf16x8*)(qk + (rowbase + k0 + r) * 1024 + 512 + h * 64 + 16 * s + 8 * hi); z = MFMA32(kf, qr[s], z); }
;             const bool diag = (jt == qblk);
;             f32x16 lom;
; #pragma unroll
;             for (int i = 0; i < 16; ++i) { const bool msk = diag && (crow(i, hi) >= r); lom[i] = msk ? 0.f : -softplusf_(z[i]); }
; __global__ void __launch_bounds__(512, 2) mega_fwd(Args a) {
;     ...
; { REPLOOP(1) {             if (PH(3)) { if (__builtin_amdgcn_readfirstlane(threadIdx.x >> 6) < 4) scan_pass1(c, ws, jl); else sb_attn_phase(c, (bf16*)(R + R_QK), (const bf16*)(R + R_VTSB)); } if (rep_ + 1 < nrep_) SYNC(); } }
.LBB0_1873:
	s_mov_b64 s[0:1], src_shared_base
	v_readlane_b32 s0, v254, 4
	s_cmp_lg_u32 s0, -1
	s_cselect_b32 s0, s0, 0
	s_cselect_b32 s1, s1, 0
	v_mov_b32_e32 v2, s0
	v_mov_b32_e32 v3, s1
	s_waitcnt lgkmcnt(0)
	ds_read_b64 v[66:67], v2
	s_waitcnt lgkmcnt(0)
	v_readfirstlane_b32 s0, v147
	s_cmpk_gt_u32 s0, 0xff
	s_mov_b64 s[0:1], -1
	s_cbranch_scc0 .LBB0_1913
	s_mov_b64 s[0:1], src_shared_base
	v_readlane_b32 s0, v254, 4
	s_cmp_lg_u32 s0, -1
	s_cselect_b32 s0, s0, 0
	s_cselect_b32 s1, s1, 0
	v_mov_b32_e32 v2, s0
	v_mov_b32_e32 v3, s1
	ds_read_b64 v[2:3], v2
	s_waitcnt lgkmcnt(0)
	v_mov_b32_e32 v1, v147
	v_readlane_b32 s1, v254, 30
	v_readfirstlane_b32 s6, v1
	s_ashr_i32 s0, s6, 6
	s_add_i32 s52, s1, s0
	s_waitcnt lgkmcnt(0)
	v_readfirstlane_b32 s4, v67
	v_readfirstlane_b32 s5, v66
	v_readlane_b32 s7, v254, 0
	s_cmpk_gt_i32 s52, 0xfff
	v_readfirstlane_b32 s1, v3
	v_readfirstlane_b32 s0, v2
	s_cbranch_scc1 .LBB0_1912
	v_bfe_u32 v6, v1, 5, 1
	s_add_u32 s48, s5, 0x4c00000
	v_and_b32_e32 v3, 63, v1
	v_lshlrev_b32_e32 v2, 2, v6
	s_addc_u32 s49, s4, 0
	v_and_b32_e32 v68, 31, v1
	v_cmp_gt_u32_e64 s[4:5], 32, v3
	v_or_b32_e32 v3, 1, v2
	v_cmp_lt_u32_e64 s[8:9], v3, v68
	v_or_b32_e32 v3, 2, v2
	v_cmp_lt_u32_e64 s[10:11], v3, v68
	v_or_b32_e32 v3, 3, v2
	v_cmp_lt_u32_e64 s[12:13], v3, v68
	v_or_b32_e32 v3, 8, v2
	v_cmp_lt_u32_e64 s[14:15], v3, v68
	v_or_b32_e32 v3, 9, v2
	v_cmp_lt_u32_e64 s[16:17], v3, v68
	v_or_b32_e32 v3, 10, v2
	v_cmp_lt_u32_e64 s[18:19], v3, v68
	v_or_b32_e32 v3, 11, v2
	v_cmp_lt_u32_e64 s[44:45], v3, v68
	v_or_b32_e32 v3, 16, v2
	v_cmp_lt_u32_e64 s[46:47], v3, v68
	v_or_b32_e32 v3, 17, v2
	v_cmp_lt_u32_e64 s[24:25], v3, v68
	v_or_b32_e32 v3, 18, v2
	v_cmp_lt_u32_e64 s[26:27], v3, v68
	v_or_b32_e32 v3, 19, v2
	v_and_b32_e32 v4, 64, v206
	v_cmp_lt_u32_e64 s[28:29], v3, v68
	v_or_b32_e32 v3, 24, v2
	v_lshlrev_b32_e32 v150, 3, v6
	v_xor_b32_e32 v1, 32, v206
	v_add_u32_e32 v4, 64, v4
	v_cmp_lt_u32_e64 s[30:31], v3, v68
	v_or_b32_e32 v3, 25, v2
	v_cmp_lt_i32_e32 vcc, v1, v4
	v_lshl_add_u64 v[4:5], s[0:1], 0, v[150:151]
	s_mov_b64 s[0:1], 0x6c00000
	v_cmp_lt_u32_e64 s[34:35], v3, v68
	v_or_b32_e32 v3, 26, v2
	s_lshr_b32 s33, s6, 6
	v_cndmask_b32_e32 v1, v206, v1, vcc
	v_lshl_add_u64 v[70:71], v[4:5], 0, s[0:1]
	v_cmp_lt_u32_e64 s[36:37], v3, v68
	v_or_b32_e32 v3, 27, v2
	v_lshlrev_b32_e32 v4, 4, v6
	v_mov_b32_e32 v5, v151
	v_readlane_b32 s0, v254, 45
	v_lshlrev_b32_e32 v1, 2, v1
	v_cmp_lt_u32_e64 s[6:7], v2, v68
	v_cmp_lt_u32_e64 s[38:39], v3, v68
	v_lshl_add_u64 v[72:73], s[48:49], 0, v[4:5]
	s_add_i32 s53, s0, s33
	v_lshlrev_b32_e32 v74, 1, v150
	v_lshlrev_b32_e32 v76, 1, v2
	s_branch .LBB0_1877

; __device__ __forceinline__ unsigned xb_add(unsigned* p, unsigned v) { return __hip_atomic_fetch_add(p, v, __ATOMIC_RELAXED, __HIP_MEMORY_SCOPE_AGENT); }
; __device__ __forceinline__ void xcd_barrier(const XcdBarrier& b) {
;     asm volatile("s_waitcnt vmcnt(0)" ::: "memory");
;     __syncthreads();
;     if (threadIdx.x == 0) {
;         unsigned* bar = b.bar;
;         __builtin_amdgcn_s_waitcnt(0);
;         unsigned nloc = b.st[0], nx = b.st[1];
;         if (nloc == 0u) { xcd_barrier_complete(bar, b.x, nloc, nx); b.st[0] = nloc; b.st[1] = nx; }
;         const unsigned old = xb_add(&bar[XB_XSUB(b.x)], 1u);
.LBB0_1923:
	s_add_i32 s57, s57, 1
	s_cmp_ge_i32 s57, s56
	s_cbranch_scc1 .LBB0_1872
	s_mov_b64 s[0:1], src_shared_base
	v_readlane_b32 s0, v254, 4
	s_cmp_lg_u32 s0, -1
	s_cselect_b32 s0, s0, 0
	s_cselect_b32 s1, s1, 0
	s_waitcnt vmcnt(0) lgkmcnt(0)
	v_mov_b32_e32 v2, s0
	v_mov_b32_e32 v3, s1
	ds_read_b64 v[2:3], v2
	s_waitcnt lgkmcnt(0)
	s_getreg_b32 s6, hwreg(HW_REG_XCC_ID, 0, 4)
	s_waitcnt vmcnt(0)
	s_waitcnt lgkmcnt(0)
	s_barrier
	v_readfirstlane_b32 s5, v3
	v_readfirstlane_b32 s4, v2
	s_mov_b64 s[0:1], exec
	v_readlane_b32 s8, v254, 1
	v_readlane_b32 s9, v254, 2
	s_and_b64 s[8:9], s[0:1], s[8:9]
	s_mov_b64 exec, s[8:9]
	s_cbranch_execz .LBB0_1871
	v_readlane_b32 s7, v254, 54
	s_waitcnt vmcnt(0) expcnt(0) lgkmcnt(0)
	s_and_b32 s24, s6, 15
	v_mov_b32_e32 v1, s7
	ds_read_b32 v3, v1
	v_readlane_b32 s7, v254, 55
	s_waitcnt lgkmcnt(0)
	v_cmp_ne_u32_e32 vcc, 0, v3
	v_mov_b32_e32 v1, s7
	ds_read_b32 v2, v1
	s_cbranch_vccnz .LBB0_1940
	v_readlane_b32 s6, v254, 5
	v_readlane_b32 s7, v254, 6
	s_load_dwordx2 s[10:11], s[6:7], 0x4
	s_add_u32 s6, s4, 0x1000
	s_addc_u32 s7, s5, 0
	s_add_u32 s8, s4, 0x1100
	s_addc_u32 s9, s5, 0
	v_readlane_b32 s12, v254, 7
	s_waitcnt lgkmcnt(0)
	s_mul_i32 s25, s10, s12
	s_add_u32 s10, s4, 0x1200
	s_mul_i32 s25, s25, s11
	s_addc_u32 s11, s5, 0
	s_add_u32 s12, s4, 0x1300
	s_addc_u32 s13, s5, 0
	s_mov_b32 s26, 1
	s_branch .LBB0_1928

; __device__ __forceinline__ void scan_pass2(const Ctx&, unsigned char* ws) { const Ctx c = mk_ctx();
;     float* PL = (float*)(ws + WS_R + R_PL); const int lane = c.lane;
;     const int xcd_ = blockIdx.x & 7, tt_ = (blockIdx.x >> 3) * 8 + c.wid;
;     for (int task = (gridDim.x == 256) ? ((tt_ < 128) ? ((xcd_ + 8 * (tt_ >> 6)) * 64 + (tt_ & 63)) : 16 * 64) : c.gw; task < 16 * 64; task += (gridDim.x == 256) ? 16 * 64 : c.NGW) { const int chain = task >> 6, i = task & 63;
.LBB0_2027:
	s_or_b64 exec, exec, s[0:1]
	s_mov_b64 s[0:1], src_shared_base
	v_readlane_b32 s0, v254, 4
	s_cmp_lg_u32 s0, -1
	s_cselect_b32 s0, s0, 0
	s_cselect_b32 s1, s1, 0
	s_waitcnt lgkmcnt(0)
	v_mov_b32_e32 v2, s0
	v_mov_b32_e32 v3, s1
	s_barrier
	ds_read_b64 v[2:3], v2
	s_waitcnt lgkmcnt(0)
	v_mov_b32_e32 v1, v147
	v_readlane_b32 s0, v254, 35
	v_readlane_b32 s1, v254, 36
	v_readlane_b32 s4, v254, 0
	v_readfirstlane_b32 s5, v1
	s_andn2_b64 vcc, exec, s[0:1]
	s_ashr_i32 s5, s5, 6
	s_waitcnt lgkmcnt(0)
	v_readfirstlane_b32 s1, v3
	v_readfirstlane_b32 s0, v2
	s_cbranch_vccnz .LBB0_2029
	v_readlane_b32 s4, v254, 33
	s_add_i32 s5, s5, s4
	s_lshr_b32 s4, s5, 3
	s_and_b32 s4, s4, 0x3fffff8
	v_readlane_b32 s6, v254, 34
	s_or_b32 s4, s4, s6
	s_lshl_b32 s4, s4, 6
	s_and_b32 s6, s5, 63
	s_or_b32 s4, s4, s6
	s_cmpk_lt_i32 s5, 0x80
	s_cselect_b32 s4, s4, 0x400
	s_cmpk_gt_i32 s4, 0x3ff
	s_cbranch_scc0 .LBB0_2030
	s_branch .LBB0_2034

; __device__ __forceinline__ void scan_pass3(const Ctx&, const In& in, unsigned char* ws, int jl, int rot) { const Ctx c = mk_ctx();
;     const float* scanop = (const float*)(ws + WS_R + R_SCAN); const bf16* vbf = (const bf16*)(ws + WS_HA + HA_VBF); const float* PL = (const float*)(ws + WS_R + R_PL);
;     const bf16* gbuf = (const bf16*)(ws + WS_R + R_G); bf16* oc = (bf16*)(ws + WS_R + R_QK);
;     const float* r_k = in[23] + (size_t)jl * 512; const float* ln_w = in[24] + (size_t)jl * 512; const float* ln_b = in[25] + (size_t)jl * 512;
;     const int lane = c.lane; float* yl = (float*)(c.lds + c.wid * 4096); float pfdummy = 0.f;
;     if (c.wid >= 4) return;
;     for (int task = (int)((blockIdx.x + (rot ? gridDim.x / 2 : 0)) % gridDim.x) * 4 + c.wid; task < 16 * NCH; task += gridDim.x * 4) { const int chain = task / NCH, cc = task % NCH, b = chain >> 3, h = chain & 7;
;         f32x2 S[32];
;         if (cc == 0) {
; #pragma unroll
;             for (int j = 0; j < 32; ++j) S[j] = (f32x2){0.f, 0.f};
;         } else { const float* src = PL + (((size_t)chain * NCH + cc - 1) * 2 + 1) * 4096 + lane * 64;
; #pragma unroll
;             for (int j = 0; j < 16; ++j) { const f32x4 v = *(const f32x4*)(src + 4 * j); S[2 * j] = (f32x2){v[0], v[1]}; S[2 * j + 1] = (f32x2){v[2], v[3]}; } }
;         const size_t tb = (size_t)chain * SEQ + (size_t)cc * CHL;
;         cfloat* ob = (cfloat*)(scanop + tb * 320); const bf16* vp = vbf + tb * 64 + lane; const float* og = scanop + tb * 320;
;         f32x4 pfa = {0.f, 0.f, 0.f, 0.f}; float pfb = 0.f; unsigned short vnext = vp[0];
.LBB0_2091:
	s_mov_b64 s[0:1], src_shared_base
	v_readlane_b32 s0, v254, 4
	s_cmp_lg_u32 s0, -1
	s_cselect_b32 s0, s0, 0
	s_cselect_b32 s4, s1, 0
	v_mov_b32_e32 v2, s0
	v_mov_b32_e32 v3, s4
	v_mov_b32_e32 v1, v147
	v_readlane_b32 s0, v254, 0
	ds_read_b64 v[2:3], v2
	s_waitcnt lgkmcnt(0)
	s_add_i32 s4, 0, 0x200b8
	v_readfirstlane_b32 s0, v1
	s_ashr_i32 s0, s0, 6
	s_cmp_lg_u32 s4, -1
	s_cselect_b32 s4, s4, 0
	s_cselect_b32 s5, s1, 0
	v_mov_b32_e32 v4, s4
	s_add_i32 s4, 0, 0x200c0
	s_cmp_lg_u32 s4, -1
	s_cselect_b32 s4, s4, 0
	v_mov_b32_e32 v5, s5
	s_cselect_b32 s5, s1, 0
	v_mov_b32_e32 v6, s4
	s_add_i32 s4, 0, 0x200c8
	s_cmp_lg_u32 s4, -1
	s_cselect_b32 s4, s4, 0
	s_cselect_b32 s1, s1, 0
	v_mov_b32_e32 v7, s5
	v_mov_b32_e32 v8, s4
	v_mov_b32_e32 v9, s1
	ds_read_b64 v[4:5], v4
	s_waitcnt lgkmcnt(0)
	s_cmp_gt_i32 s0, 3
	ds_read_b64 v[6:7], v6
	s_waitcnt lgkmcnt(0)
	v_readfirstlane_b32 s25, v3
	ds_read_b64 v[8:9], v8
	s_waitcnt lgkmcnt(0)
	v_readfirstlane_b32 s24, v2
	v_readfirstlane_b32 s6, v5
	v_readfirstlane_b32 s8, v4
	v_readfirstlane_b32 s4, v7
	v_readfirstlane_b32 s7, v6
	s_waitcnt lgkmcnt(0)
	v_readfirstlane_b32 s1, v9
	v_readfirstlane_b32 s5, v8
	s_cbranch_scc1 .LBB0_2106
	s_add_i32 s43, s31, s0
	s_cmpk_gt_i32 s43, 0x3ff
	s_cbranch_scc1 .LBB0_2106
	s_add_u32 s26, s24, 0xb600000
	s_addc_u32 s27, s25, 0
	v_writelane_b32 v255, s30, 5
	s_add_u32 s10, s24, 0x400000
	s_addc_u32 s11, s25, 0
	v_readlane_b32 s12, v255, 2
	v_readlane_b32 s13, v255, 3
	s_add_u32 s8, s8, s12
	s_addc_u32 s9, s6, s13
	s_add_u32 s6, s7, s12
	s_addc_u32 s7, s4, s13
	s_add_u32 s30, s5, s12
	v_and_b32_e32 v3, 63, v1
	s_addc_u32 s31, s1, s13
	s_lshl_b32 s0, s0, 12
	v_writelane_b32 v255, s6, 6
	s_add_i32 s0, s0, 0
	v_lshlrev_b32_e32 v6, 4, v3
	v_writelane_b32 v255, s7, 7
	s_add_u32 s1, s24, 0x7bfc000
	v_bfe_u32 v1, v1, 2, 4
	v_and_b32_e32 v114, 48, v6
	v_writelane_b32 v255, s1, 8
	s_addc_u32 s1, s25, 0
	v_add_u32_e32 v160, -15, v1
	v_lshlrev_b32_e32 v1, 8, v1
	v_lshlrev_b32_e32 v8, 2, v114
	v_mov_b32_e32 v9, v151
	v_writelane_b32 v255, s1, 9
	v_lshlrev_b32_e32 v4, 2, v3
	v_add3_u32 v161, s0, v1, v8
	v_lshl_add_u64 v[116:117], s[26:27], 0, v[8:9]
	v_lshl_add_u64 v[118:119], s[8:9], 0, v[8:9]
	v_lshlrev_b32_e32 v8, 1, v114
	v_lshlrev_b32_e32 v150, 1, v3
	v_add_u32_e32 v115, s0, v4
	v_writelane_b32 v255, s0, 10
	v_lshl_add_u64 v[120:121], s[10:11], 0, v[8:9]
	v_lshl_add_u64 v[8:9], s[24:25], 0, v[8:9]
	s_mov_b64 s[0:1], 0x9c00000
	v_lshl_add_u64 v[122:123], v[8:9], 0, s[0:1]
	v_lshl_add_u64 v[8:9], s[24:25], 0, v[150:151]
	s_mov_b64 s[0:1], 0x400080
	v_mov_b32_e32 v7, v151
	v_mov_b32_e32 v5, v151
	v_lshl_add_u64 v[124:125], v[8:9], 0, s[0:1]
	v_lshl_add_u64 v[6:7], s[24:25], 0, v[6:7]
	s_mov_b64 s[0:1], 0xb601400
	v_lshlrev_b32_e32 v2, 6, v3
	v_lshl_add_u64 v[126:127], v[6:7], 0, s[0:1]
	v_lshl_add_u64 v[4:5], s[24:25], 0, v[4:5]
	s_mov_b64 s[0:1], 0xb601800
	v_lshl_add_u64 v[112:113], s[10:11], 0, v[150:151]
	v_lshl_add_u64 v[128:129], v[4:5], 0, s[0:1]
	v_mov_b32_e32 v162, 0
	v_lshlrev_b32_e32 v163, 2, v2
	s_branch .LBB0_2095

; __device__ __forceinline__ unsigned xb_add(unsigned* p, unsigned v) { return __hip_atomic_fetch_add(p, v, __ATOMIC_RELAXED, __HIP_MEMORY_SCOPE_AGENT); }
; __device__ __forceinline__ void xcd_barrier(const XcdBarrier& b) {
;     asm volatile("s_waitcnt vmcnt(0)" ::: "memory");
;     __syncthreads();
;     if (threadIdx.x == 0) {
;         unsigned* bar = b.bar;
;         __builtin_amdgcn_s_waitcnt(0);
;         unsigned nloc = b.st[0], nx = b.st[1];
;         if (nloc == 0u) { xcd_barrier_complete(bar, b.x, nloc, nx); b.st[0] = nloc; b.st[1] = nx; }
;         const unsigned old = xb_add(&bar[XB_XSUB(b.x)], 1u);
.LBB0_2106:
	s_add_i32 s30, s30, 1
	s_cmp_ge_i32 s30, s29
	s_cbranch_scc1 .LBB0_2090
	s_mov_b64 s[0:1], src_shared_base
	v_readlane_b32 s0, v254, 4
	s_cmp_lg_u32 s0, -1
	s_cselect_b32 s0, s0, 0
	s_cselect_b32 s1, s1, 0
	s_waitcnt vmcnt(0) lgkmcnt(0)
	v_mov_b32_e32 v2, s0
	v_mov_b32_e32 v3, s1
	ds_read_b64 v[2:3], v2
	s_waitcnt lgkmcnt(0)
	s_getreg_b32 s0, hwreg(HW_REG_XCC_ID, 0, 4)
	s_waitcnt vmcnt(0)
	s_waitcnt lgkmcnt(0)
	s_barrier
	v_readfirstlane_b32 s7, v3
	v_readfirstlane_b32 s6, v2
	s_mov_b64 s[4:5], exec
	v_readlane_b32 s8, v254, 1
	v_readlane_b32 s9, v254, 2
	s_and_b64 s[8:9], s[4:5], s[8:9]
	s_mov_b64 exec, s[8:9]
	s_cbranch_execz .LBB0_2089
	v_readlane_b32 s1, v254, 54
	s_waitcnt vmcnt(0) expcnt(0) lgkmcnt(0)
	s_and_b32 s24, s0, 15
	v_mov_b32_e32 v1, s1
	ds_read_b32 v3, v1
	v_readlane_b32 s1, v254, 55
	s_waitcnt lgkmcnt(0)
	v_cmp_ne_u32_e32 vcc, 0, v3
	v_mov_b32_e32 v1, s1
	ds_read_b32 v2, v1
	s_cbranch_vccnz .LBB0_2123
	v_readlane_b32 s0, v254, 5
	v_readlane_b32 s1, v254, 6
	s_load_dwordx2 s[10:11], s[0:1], 0x4
	s_add_u32 s0, s6, 0x1000
	s_addc_u32 s1, s7, 0
	s_add_u32 s8, s6, 0x1100
	s_addc_u32 s9, s7, 0
	v_readlane_b32 s12, v254, 7
	s_waitcnt lgkmcnt(0)
	s_mul_i32 s25, s10, s12
	s_add_u32 s10, s6, 0x1200
	s_mul_i32 s25, s25, s11
	s_addc_u32 s11, s7, 0
	s_add_u32 s12, s6, 0x1300
	s_addc_u32 s13, s7, 0
	s_mov_b32 s26, 1
	s_branch .LBB0_2111

; #define LAS __attribute__((address_space(3)))
;     __host__ __device__ bool next(int i, Unit& u) const {
;         const long L = (long)i * G + c; if (L >= nwg) return false;
;         int wgid = (int)L; { const int q = nwg / NXCD, r = nwg % NXCD, xcd = wgid % NXCD, off = wgid / NXCD; wgid = (xcd < r ? xcd * (q + 1) : r * (q + 1) + (xcd - r) * q) + off; }
;         const int nig = WGM * nN, gid = wgid / nig, fm = gid * WGM, gsz = (nM - fm) < WGM ? (nM - fm) : WGM;
;         u.pm = fm + ((wgid % nig) % gsz); u.pn = (wgid % nig) / gsz; return true;
; template <int ID, class E> __device__ __forceinline__ void run_gemm(LAS unsigned char* lds, const bf16* A, const bf16* Bt, int M, int N, int K, const E& e) {
;     asm volatile("" : "+s"(K)); asm volatile("" : "+s"(N));
;     pg8::Gemm g{A, Bt, M, N, K}; pg8::StaticOrder S; S.init(M, N, (int)gridDim.x, (int)blockIdx.x);
.LBB0_2210:
	s_or_b64 exec, exec, s[0:1]
	v_readlane_b32 s0, v254, 4
	s_cmp_lg_u32 s0, -1
	s_mov_b64 s[4:5], src_shared_base
	s_cselect_b32 s0, s0, 0
	s_cselect_b32 s1, s5, 0
	s_waitcnt lgkmcnt(0)
	v_mov_b64_e32 v[2:3], s[0:1]
	s_barrier
	ds_read_b64 v[4:5], v2
	s_waitcnt lgkmcnt(0)
	s_movk_i32 s0, 0x400
	ds_read_b64 v[2:3], v2
	s_waitcnt lgkmcnt(0)
	s_movk_i32 s4, 0x400
	s_ashr_i32 s5, s4, 31
	s_lshr_b32 s5, s5, 24
	s_add_i32 s4, s4, s5
	s_ashr_i32 s18, s4, 8
	s_lshl_b32 s6, s18, 6
	v_readlane_b32 s11, v254, 0
	s_cmp_lt_i32 s11, s6
	v_readfirstlane_b32 s7, v147
	s_cselect_b64 s[4:5], -1, 0
	s_cmp_ge_i32 s11, s6
	s_waitcnt lgkmcnt(0)
	v_readfirstlane_b32 s1, v5
	v_readfirstlane_b32 s8, v4
	v_readfirstlane_b32 s9, v3
	v_readfirstlane_b32 s10, v2
	s_cbranch_scc1 .LBB0_2212
	s_lshl_b32 s11, s18, 3
	s_abs_i32 s12, s11
	v_cvt_f32_u32_e32 v1, s12
	v_readlane_b32 s13, v254, 24
	s_or_b32 s13, s11, s13
	v_readlane_b32 s14, v254, 37
	v_rcp_iflag_f32_e32 v1, v1
	s_mul_i32 s13, s13, s14
	s_sub_i32 s14, 0, s12
	v_readlane_b32 s15, v254, 23
	v_mul_f32_e32 v1, 0x4f7ffffe, v1
	v_cvt_u32_f32_e32 v1, v1
	s_add_i32 s13, s13, s15
	s_abs_i32 s16, s13
	s_xor_b32 s15, s13, s11
	v_readfirstlane_b32 s17, v1
	s_mul_i32 s14, s14, s17
	s_mul_hi_u32 s14, s17, s14
	s_add_i32 s17, s17, s14
	s_mul_hi_u32 s14, s16, s17
	s_mul_i32 s17, s14, s12
	s_sub_i32 s16, s16, s17
	s_ashr_i32 s15, s15, 31
	s_add_i32 s19, s14, 1
	s_sub_i32 s17, s16, s12
	s_cmp_ge_u32 s16, s12
	s_cselect_b32 s14, s19, s14
	s_cselect_b32 s16, s17, s16
	s_add_i32 s17, s14, 1
	s_cmp_ge_u32 s16, s12
	s_cselect_b32 s12, s17, s14
	s_xor_b32 s12, s12, s15
	s_sub_i32 s12, s12, s15
	s_lshl_b32 s14, s12, 3
	s_sub_i32 s15, 64, s14
	s_min_i32 s15, s15, 8
	s_abs_i32 s16, s15
	v_cvt_f32_u32_e32 v1, s16
	s_sub_i32 s17, 0, s16
	s_mul_i32 s12, s12, s11
	s_sub_i32 s11, s13, s12
	v_rcp_iflag_f32_e32 v1, v1
	s_abs_i32 s12, s11
	s_xor_b32 s13, s11, s15
	s_ashr_i32 s13, s13, 31
	v_mul_f32_e32 v1, 0x4f7ffffe, v1
	v_cvt_u32_f32_e32 v1, v1
	s_nop 0
	v_readfirstlane_b32 s19, v1
	s_mul_i32 s17, s17, s19
	s_mul_hi_u32 s17, s19, s17
	s_add_i32 s19, s19, s17
	s_mul_hi_u32 s17, s12, s19
	s_mul_i32 s19, s17, s16
	s_sub_i32 s12, s12, s19
	s_add_i32 s24, s17, 1
	s_sub_i32 s19, s12, s16
	s_cmp_ge_u32 s12, s16
	s_cselect_b32 s17, s24, s17
	s_cselect_b32 s12, s19, s12
	s_add_i32 s19, s17, 1
	s_cmp_ge_u32 s12, s16
	s_cselect_b32 s12, s19, s17
	s_xor_b32 s12, s12, s13
	s_sub_i32 s39, s12, s13
	s_mul_i32 s12, s39, s15
	s_sub_i32 s11, s11, s12
	s_add_i32 s28, s11, s14

.LBB0_2229:
	v_readlane_b32 s24, v254, 4
	s_mov_b64 s[30:31], src_shared_base
	s_cmp_lg_u32 s24, -1
	s_cselect_b32 s24, s24, 0
	s_cselect_b32 s25, s31, 0
	v_mov_b32_e32 v138, s24
	v_mov_b32_e32 v139, s25
	ds_read_b64 v[154:155], v138
	s_waitcnt lgkmcnt(0)
	v_readlane_b32 s24, v254, 3
	s_cmp_lg_u32 s24, -1
	s_cselect_b32 s24, s24, 0
	s_cselect_b32 s25, s31, 0
	v_mov_b32_e32 v138, s24
	v_mov_b32_e32 v139, s25
	ds_read_b64 v[156:157], v138
	s_waitcnt lgkmcnt(0)
	v_lshl_add_u32 v140, s28, 8, v1
	v_lshl_or_b32 v138, s39, 8, v143
	v_ashrrev_i32_e32 v141, 31, v140
	v_ashrrev_i32_e32 v139, 31, v138
	v_lshlrev_b64 v[158:159], 12, v[140:141]
	v_lshlrev_b64 v[160:161], 2, v[138:139]
	s_waitcnt lgkmcnt(0)
	v_readfirstlane_b32 s28, v154
	v_readfirstlane_b32 s29, v155
	s_add_u32 s24, s28, 0x400000
	s_addc_u32 s25, s29, 0
	s_add_i32 s30, 0, 0x20020
	s_cmp_lg_u32 s30, -1
	s_cselect_b32 s30, s30, 0
	s_cselect_b32 s31, s31, 0
	v_readfirstlane_b32 s27, v157
	v_readfirstlane_b32 s26, v156
	v_mov_b32_e32 v156, s30
	v_mov_b32_e32 v157, s31
	v_lshl_add_u64 v[154:155], s[26:27], 0, v[158:159]
	ds_read_b64 v[158:159], v156
	s_waitcnt lgkmcnt(0)
	v_lshl_add_u64 v[162:163], v[154:155], 0, v[160:161]
	global_load_dwordx4 v[154:157], v[162:163], off
	s_waitcnt lgkmcnt(0)
	v_readfirstlane_b32 s30, v158
	v_readfirstlane_b32 s31, v159
	s_add_u32 s30, s30, s54
	s_waitcnt vmcnt(0)
	v_pk_add_f32 v[156:157], v[128:129], v[156:157]
	v_pk_add_f32 v[154:155], v[126:127], v[154:155]
	s_addc_u32 s31, s31, 0
	global_store_dwordx4 v[162:163], v[154:157], off
	v_lshl_add_u64 v[126:127], s[30:31], 0, v[160:161]
	global_load_dwordx4 v[158:161], v[126:127], off
	v_lshlrev_b64 v[128:129], 11, v[140:141]
	v_lshl_add_u64 v[128:129], s[24:25], 0, v[128:129]
	v_lshl_add_u64 v[128:129], v[138:139], 1, v[128:129]
	v_mul_f32_e32 v145, v157, v157
	v_fmac_f32_e32 v145, v156, v156
	s_add_u32 s28, s28, 0x15800000
	s_addc_u32 s29, s29, 0
	s_waitcnt vmcnt(0)
	v_pk_mul_f32 v[158:159], v[154:155], v[158:159]
	v_pk_mul_f32 v[160:161], v[156:157], v[160:161]
	v_cvt_pk_bf16_f32 v158, v158, v159
	s_nop 0
	v_cvt_pk_bf16_f32 v159, v160, v161
	global_store_dwordx2 v[128:129], v[158:159], off
	global_load_dwordx4 v[158:161], v[162:163], off offset:64
	s_waitcnt vmcnt(0)
	v_pk_add_f32 v[124:125], v[124:125], v[160:161]
	v_pk_add_f32 v[122:123], v[122:123], v[158:159]
	global_store_dwordx4 v[162:163], v[122:125], off offset:64
	global_load_dwordx4 v[158:161], v[126:127], off offset:64
	s_waitcnt vmcnt(0)
	v_pk_mul_f32 v[158:159], v[122:123], v[158:159]
	v_pk_mul_f32 v[160:161], v[124:125], v[160:161]
	v_cvt_pk_bf16_f32 v158, v158, v159
	v_mul_f32_e32 v123, v123, v123
	v_cvt_pk_bf16_f32 v159, v160, v161
	global_store_dwordx2 v[128:129], v[158:159], off offset:32
	global_load_dwordx4 v[158:161], v[162:163], off offset:512
	v_mul_f32_e32 v125, v125, v125
	v_fmac_f32_e32 v123, v122, v122
	v_fmac_f32_e32 v125, v124, v124
	v_add_f32_e32 v122, v123, v125
	s_waitcnt vmcnt(0)
	v_pk_add_f32 v[120:121], v[120:121], v[160:161]
	v_pk_add_f32 v[118:119], v[118:119], v[158:159]
	global_store_dwordx4 v[162:163], v[118:121], off offset:512
	global_load_dwordx4 v[158:161], v[126:127], off offset:512
	s_waitcnt vmcnt(0)
	v_pk_mul_f32 v[158:159], v[118:119], v[158:159]
	v_pk_mul_f32 v[160:161], v[120:121], v[160:161]
	v_cvt_pk_bf16_f32 v158, v158, v159
	v_mul_f32_e32 v119, v119, v119
	v_cvt_pk_bf16_f32 v159, v160, v161
	global_store_dwordx2 v[128:129], v[158:159], off offset:256
	global_load_dwordx4 v[158:161], v[162:163], off offset:576
	v_mul_f32_e32 v121, v121, v121
	v_fmac_f32_e32 v119, v118, v118
	v_fmac_f32_e32 v121, v120, v120
	v_add_f32_e32 v118, v119, v121
	s_waitcnt vmcnt(0)
	v_pk_add_f32 v[160:161], v[116:117], v[160:161]
	v_pk_add_f32 v[158:159], v[114:115], v[158:159]
	global_store_dwordx4 v[162:163], v[158:161], off offset:576
	global_load_dwordx4 v[162:165], v[126:127], off offset:576
	v_and_b32_e32 v115, 64, v206
	v_xor_b32_e32 v114, 16, v206
	v_add_u32_e32 v115, 64, v115
	v_cmp_lt_i32_e32 vcc, v114, v115
	v_mul_f32_e32 v119, v161, v161
	v_fmac_f32_e32 v119, v160, v160
	v_cndmask_b32_e32 v114, v206, v114, vcc
	v_lshlrev_b32_e32 v116, 2, v114
	v_mul_f32_e32 v114, v155, v155
	v_fmac_f32_e32 v114, v154, v154
	v_add_f32_e32 v114, v114, v145
	v_add_f32_e32 v114, v114, v122
	v_add_f32_e32 v114, v114, v118
	v_mul_f32_e32 v118, v159, v159
	v_fmac_f32_e32 v118, v158, v158
	v_add_f32_e32 v118, v118, v119
	v_add_f32_e32 v114, v114, v118
	ds_bpermute_b32 v118, v116, v114
	v_xor_b32_e32 v117, 32, v206
	v_cmp_lt_i32_e32 vcc, v117, v115
	s_waitcnt lgkmcnt(0)
	v_add_f32_e32 v114, v114, v118
	v_cndmask_b32_e32 v115, v206, v117, vcc
	v_lshlrev_b32_e32 v117, 2, v115
	ds_bpermute_b32 v115, v117, v114
	s_waitcnt vmcnt(0)
	v_pk_mul_f32 v[120:121], v[158:159], v[162:163]
	v_pk_mul_f32 v[118:119], v[160:161], v[164:165]
	v_cvt_pk_bf16_f32 v120, v120, v121
	s_nop 0
	v_cvt_pk_bf16_f32 v121, v118, v119
	global_store_dwordx2 v[128:129], v[120:121], off offset:288
	s_mov_b64 s[30:31], exec
	v_readlane_b32 s62, v254, 25
	v_readlane_b32 s63, v254, 26
	s_and_b64 s[62:63], s[30:31], s[62:63]
	s_mov_b64 exec, s[62:63]
	s_cbranch_execz .LBB0_2231
	s_waitcnt lgkmcnt(0)
	v_add_f32_e32 v118, v114, v115
	s_lshl_b32 s62, s39, 2
	v_lshlrev_b64 v[114:115], 7, v[140:141]
	s_ashr_i32 s63, s62, 31
	v_lshl_add_u64 v[114:115], s[28:29], 0, v[114:115]
	v_lshl_add_u64 v[114:115], s[62:63], 2, v[114:115]
	s_lshl_b32 s96, s48, 2
	v_lshl_add_u64 v[114:115], v[114:115], 0, s[96:97]
	global_store_dword v[114:115], v118, off

; #define LAS __attribute__((address_space(3)))
;     __host__ __device__ bool next(int i, Unit& u) const {
;         const long L = (long)i * G + c; if (L >= nwg) return false;
;         int wgid = (int)L; { const int q = nwg / NXCD, r = nwg % NXCD, xcd = wgid % NXCD, off = wgid / NXCD; wgid = (xcd < r ? xcd * (q + 1) : r * (q + 1) + (xcd - r) * q) + off; }
;         const int nig = WGM * nN, gid = wgid / nig, fm = gid * WGM, gsz = (nM - fm) < WGM ? (nM - fm) : WGM;
;         u.pm = fm + ((wgid % nig) % gsz); u.pn = (wgid % nig) / gsz; return true;
; template <int ID, class E> __device__ __forceinline__ void run_gemm(LAS unsigned char* lds, const bf16* A, const bf16* Bt, int M, int N, int K, const E& e) {
;     asm volatile("" : "+s"(K)); asm volatile("" : "+s"(N));
;     pg8::Gemm g{A, Bt, M, N, K}; pg8::StaticOrder S; S.init(M, N, (int)gridDim.x, (int)blockIdx.x);
.LBB0_2307:
	v_readlane_b32 s0, v254, 4
	s_cmp_lg_u32 s0, -1
	s_mov_b64 s[4:5], src_shared_base
	s_cselect_b32 s0, s0, 0
	s_cselect_b32 s1, s5, 0
	v_mov_b64_e32 v[2:3], s[0:1]
	ds_read_b64 v[4:5], v2
	s_waitcnt lgkmcnt(0)
	s_movk_i32 s0, 0x400
	ds_read_b64 v[2:3], v2
	s_waitcnt lgkmcnt(0)
	s_movk_i32 s4, 0xb00
	s_ashr_i32 s5, s4, 31
	s_lshr_b32 s5, s5, 24
	s_add_i32 s4, s4, s5
	s_ashr_i32 s18, s4, 8
	s_lshl_b32 s6, s18, 6
	v_readlane_b32 s11, v254, 0
	s_cmp_lt_i32 s11, s6
	v_readfirstlane_b32 s7, v147
	s_cselect_b64 s[4:5], -1, 0
	s_cmp_ge_i32 s11, s6
	s_waitcnt lgkmcnt(0)
	v_readfirstlane_b32 s1, v5
	v_readfirstlane_b32 s8, v4
	v_readfirstlane_b32 s9, v3
	v_readfirstlane_b32 s10, v2
	s_cbranch_scc0 .LBB0_2310
	s_andn2_b64 vcc, exec, s[4:5]
	s_cbranch_vccz .LBB0_2311

;     for (int i = 0; i < nslot4; ++i) { const f32x4 v = p[i]; s += (v[0] + v[1]) + (v[2] + v[3]); } return rsqrtf(s * invn + EPS); }
.LBB0_2327:
	v_readlane_b32 s0, v254, 4
	s_cmp_lg_u32 s0, -1
	s_cselect_b32 s26, s0, 0
	s_mov_b64 s[0:1], src_shared_base
	s_cselect_b32 s0, s1, 0
	v_mov_b32_e32 v138, s26
	v_mov_b32_e32 v139, s0
	ds_read_b64 v[138:139], v138
	s_waitcnt lgkmcnt(0)
	v_readfirstlane_b32 s28, v138
	v_lshl_add_u32 v138, s41, 8, v1
	v_readfirstlane_b32 s29, v139
	s_add_u32 s26, s28, 0x15800000
	v_ashrrev_i32_e32 v139, 31, v138
	s_addc_u32 s27, s29, 0
	v_lshlrev_b64 v[140:141], 7, v[138:139]
	v_lshl_add_u64 v[140:141], s[26:27], 0, v[140:141]
	global_load_dwordx4 v[154:157], v[140:141], off offset:48
	global_load_dwordx4 v[158:161], v[140:141], off offset:32
	global_load_dwordx4 v[162:165], v[140:141], off offset:16
	global_load_dwordx4 v[166:169], v[140:141], off
	s_waitcnt vmcnt(2)
	v_add_f32_e32 v158, v158, v159
	v_add_f32_e32 v160, v160, v161
	s_waitcnt vmcnt(0)
	v_mov_b32_e32 v170, v167
	v_mov_b32_e32 v171, v168
	v_mov_b32_e32 v167, v169
	v_mov_b32_e32 v168, v163
	v_mov_b32_e32 v169, v164
	v_mov_b32_e32 v163, v165
	v_pk_add_f32 v[166:167], v[170:171], v[166:167]
	v_pk_add_f32 v[162:163], v[168:169], v[162:163]
	v_add_f32_e32 v139, v166, v167
	v_pk_add_f32 v[162:163], v[162:163], v[162:163] op_sel:[0,1] op_sel_hi:[1,0]
	v_add_f32_e32 v166, 0, v139
	v_mov_b32_e32 v167, v154
	v_mov_b32_e32 v163, v155
	v_mov_b32_e32 v159, v156
	v_mov_b32_e32 v161, v157
	v_pk_add_f32 v[154:155], v[166:167], v[162:163]
	v_pk_add_f32 v[156:157], v[158:159], v[160:161]
	s_nop 0
	v_pk_add_f32 v[154:155], v[154:155], v[156:157]
	s_nop 0
	v_add_f32_e32 v139, v154, v155
	v_fmamk_f32 v139, v139, 0x3a800000, v152
	v_cmp_gt_f32_e32 vcc, s93, v139
	v_mul_f32_e32 v142, 0x4b800000, v139
	s_nop 0
	v_cndmask_b32_e32 v139, v139, v142, vcc
	v_rsq_f32_e32 v139, v139
	s_nop 0
	v_mul_f32_e32 v142, 0x45800000, v139
	v_cndmask_b32_e32 v142, v139, v142, vcc
	v_or_b32_e32 v139, s33, v144
	v_cmp_eq_u32_e32 vcc, 0, v139
	s_and_saveexec_b64 s[0:1], vcc
	s_cbranch_execz .LBB0_2329
	global_store_dword v[140:141], v142, off offset:64

; #define LAS __attribute__((address_space(3)))
;     __host__ __device__ bool next(int i, Unit& u) const {
;         const long L = (long)i * G + c; if (L >= nwg) return false;
;         int wgid = (int)L; { const int q = nwg / NXCD, r = nwg % NXCD, xcd = wgid % NXCD, off = wgid / NXCD; wgid = (xcd < r ? xcd * (q + 1) : r * (q + 1) + (xcd - r) * q) + off; }
;         const int nig = WGM * nN, gid = wgid / nig, fm = gid * WGM, gsz = (nM - fm) < WGM ? (nM - fm) : WGM;
;         u.pm = fm + ((wgid % nig) % gsz); u.pn = (wgid % nig) / gsz; return true;
; template <int ID, class E> __device__ __forceinline__ void run_gemm(LAS unsigned char* lds, const bf16* A, const bf16* Bt, int M, int N, int K, const E& e) {
;     asm volatile("" : "+s"(K)); asm volatile("" : "+s"(N));
;     pg8::Gemm g{A, Bt, M, N, K}; pg8::StaticOrder S; S.init(M, N, (int)gridDim.x, (int)blockIdx.x);
.LBB0_2403:
	v_readlane_b32 s0, v254, 4
	s_cmp_lg_u32 s0, -1
	s_mov_b64 s[4:5], src_shared_base
	s_cselect_b32 s0, s0, 0
	s_cselect_b32 s1, s5, 0
	v_mov_b64_e32 v[2:3], s[0:1]
	ds_read_b64 v[4:5], v2
	s_waitcnt lgkmcnt(0)
	s_movk_i32 s0, 0x100
	ds_read_b64 v[2:3], v2
	s_waitcnt lgkmcnt(0)
	s_movk_i32 s4, 0x400
	s_ashr_i32 s5, s4, 31
	s_lshr_b32 s5, s5, 24
	s_add_i32 s4, s4, s5
	s_ashr_i32 s18, s4, 8
	s_lshl_b32 s6, s18, 6
	v_readlane_b32 s11, v254, 0
	s_cmp_lt_i32 s11, s6
	v_readfirstlane_b32 s7, v147
	s_cselect_b64 s[4:5], -1, 0
	s_cmp_ge_i32 s11, s6
	s_waitcnt lgkmcnt(0)
	v_readfirstlane_b32 s1, v5
	v_readfirstlane_b32 s8, v4
	v_readfirstlane_b32 s9, v3
	v_readfirstlane_b32 s10, v2
	s_cbranch_scc0 .LBB0_2406
	s_andn2_b64 vcc, exec, s[4:5]
	s_cbranch_vccz .LBB0_2407

.LBB0_2423:
	s_mov_b64 s[24:25], src_shared_base
	v_readlane_b32 s24, v254, 4
	s_cmp_lg_u32 s24, -1
	s_cselect_b32 s24, s24, 0
	s_cselect_b32 s25, s25, 0
	v_mov_b32_e32 v138, s24
	v_mov_b32_e32 v139, s25
	ds_read_b64 v[154:155], v138
	s_waitcnt lgkmcnt(0)
	v_mul_f32_e32 v145, v127, v127
	v_mul_f32_e32 v150, v129, v129
	v_mul_f32_e32 v158, v123, v123
	v_mul_f32_e32 v159, v125, v125
	v_mul_f32_e32 v160, v119, v119
	v_mul_f32_e32 v161, v121, v121
	v_and_b32_e32 v156, 64, v206
	v_fmac_f32_e32 v145, v126, v126
	v_fmac_f32_e32 v150, v128, v128
	v_fmac_f32_e32 v158, v122, v122
	v_fmac_f32_e32 v159, v124, v124
	v_mul_f32_e32 v162, v115, v115
	v_mul_f32_e32 v163, v117, v117
	v_xor_b32_e32 v164, 16, v206
	v_fmac_f32_e32 v160, v118, v118
	v_fmac_f32_e32 v161, v120, v120
	v_add_u32_e32 v166, 64, v156
	v_add_f32_e32 v145, v145, v150
	v_add_f32_e32 v150, v158, v159
	v_fmac_f32_e32 v162, v114, v114
	v_fmac_f32_e32 v163, v116, v116
	v_add_f32_e32 v158, v160, v161
	v_cmp_lt_i32_e32 vcc, v164, v166
	v_add_f32_e32 v150, v150, v145
	v_add_f32_e32 v159, v162, v163
	v_cndmask_b32_e32 v160, v206, v164, vcc
	v_add_f32_e32 v150, v158, v150
	v_lshlrev_b32_e32 v145, 2, v160
	v_add_f32_e32 v150, v159, v150
	ds_bpermute_b32 v160, v145, v150
	v_xor_b32_e32 v165, 32, v206
	v_cmp_lt_i32_e32 vcc, v165, v166
	v_cvt_pk_bf16_f32 v158, v126, v127
	v_lshl_add_u32 v140, s28, 8, v1
	s_waitcnt lgkmcnt(0)
	v_add_f32_e32 v127, v150, v160
	v_cndmask_b32_e32 v161, v206, v165, vcc
	v_lshlrev_b32_e32 v126, 2, v161
	v_cvt_pk_bf16_f32 v159, v128, v129
	ds_bpermute_b32 v128, v126, v127
	v_ashrrev_i32_e32 v141, 31, v140
	v_lshl_or_b32 v138, s39, 8, v143
	v_lshlrev_b64 v[156:157], 11, v[140:141]
	v_ashrrev_i32_e32 v139, 31, v138
	v_readfirstlane_b32 s24, v154
	v_readfirstlane_b32 s25, v155
	s_add_u32 s26, s24, 0xfc00000
	s_addc_u32 s27, s25, 0
	s_add_u32 s24, s24, 0x15c00000
	v_lshl_add_u64 v[154:155], s[26:27], 0, v[156:157]
	s_addc_u32 s25, s25, 0
	v_lshl_add_u64 v[154:155], v[138:139], 1, v[154:155]
	global_store_dwordx2 v[154:155], v[158:159], off
	v_cvt_pk_bf16_f32 v122, v122, v123
	v_cvt_pk_bf16_f32 v123, v124, v125
	global_store_dwordx2 v[154:155], v[122:123], off offset:32
	v_cvt_pk_bf16_f32 v118, v118, v119
	v_cvt_pk_bf16_f32 v119, v120, v121
	global_store_dwordx2 v[154:155], v[118:119], off offset:256
	v_cvt_pk_bf16_f32 v114, v114, v115
	v_cvt_pk_bf16_f32 v115, v116, v117
	global_store_dwordx2 v[154:155], v[114:115], off offset:288
	s_mov_b64 s[28:29], exec
	v_readlane_b32 s60, v254, 25
	v_readlane_b32 s61, v254, 26
	s_and_b64 s[60:61], s[28:29], s[60:61]
	s_mov_b64 exec, s[60:61]
	s_cbranch_execz .LBB0_2425
	s_lshl_b32 s60, s39, 2
	v_lshlrev_b64 v[114:115], 7, v[140:141]
	s_ashr_i32 s61, s60, 31
	v_lshl_add_u64 v[114:115], s[24:25], 0, v[114:115]
	v_lshl_add_u64 v[114:115], s[60:61], 2, v[114:115]
	s_lshl_b32 s96, s48, 2
	s_waitcnt lgkmcnt(0)
	v_add_f32_e32 v116, v127, v128
	v_lshl_add_u64 v[114:115], v[114:115], 0, s[96:97]
	global_store_dword v[114:115], v116, off

; __device__ __forceinline__ void transpose_mat(const Ctx& c, const float* W, int K, int N, bf16* WT) {
;     float* scr = (float*)(c.lds + c.wid * 16384); const int items = (K / 64) * (N / 32), nblk = N / 32, lane = c.lane;
;     float tv[32];
;     int it = c.gw;
;     if (it < items) { const int k0 = 64 * (it / nblk), n0 = 32 * (it % nblk);
; #pragma unroll
;         for (int i = 0; i < 32; ++i) tv[i] = W[(size_t)(k0 + 2 * i + (lane >> 5)) * N + n0 + (lane & 31)]; }
; __device__ __forceinline__ void conv_mixer(const Ctx&, const In& in, unsigned char* ws, int layer) { const Ctx c = mk_ctx();
;     const int j = layer >> 1; unsigned char* W = ws + WS_W;
;     if ((layer & 1) == 0) {
;         transpose_mat(c, in[13] + (size_t)j * 1024 * 3360, 1024, 3360, (bf16*)(W + W_HYBIN));
.LBB0_2494:
	s_cmp_eq_u32 s88, 3
	s_cselect_b64 s[14:15], -1, 0
	s_cmp_lg_u32 s88, 3
	s_cselect_b64 s[12:13], -1, 0
	s_and_b64 vcc, exec, s[12:13]
	s_cbranch_vccz .LBB0_2553
	s_mov_b64 s[0:1], src_shared_base
	v_readlane_b32 s0, v254, 4
	s_cmp_lg_u32 s0, -1
	s_cselect_b32 s0, s0, 0
	s_cselect_b32 s1, s1, 0
	v_mov_b32_e32 v2, s0
	v_mov_b32_e32 v3, s1
	ds_read_b64 v[2:3], v2
	s_waitcnt lgkmcnt(0)
	v_mov_b32_e32 v43, v147
	v_readlane_b32 s0, v254, 0
	s_add_i32 s1, s88, 1
	s_lshr_b32 s96, s1, 1
	s_lshl_b32 s0, s0, 3
	v_readfirstlane_b32 s1, v43
	s_ashr_i32 s36, s1, 6
	s_add_i32 s0, s36, s0
	v_readlane_b32 s8, v255, 0
	v_readlane_b32 s9, v255, 1
	v_and_b32_e32 v33, 63, v43
	s_waitcnt lgkmcnt(0)
	v_readfirstlane_b32 s4, v2
	v_readfirstlane_b32 s5, v3
	s_add_u32 s6, s4, 0x2400000
	s_addc_u32 s7, s5, 0
	s_andn2_b64 vcc, exec, s[8:9]
	s_mov_b64 s[8:9], -1
	s_cbranch_vccnz .LBB0_2528
	v_readlane_b32 s1, v254, 9
	s_mov_b64 s[8:9], src_shared_base
	s_cmp_lg_u32 s1, -1
	s_cselect_b32 s1, s1, 0
	s_cselect_b32 s8, s9, 0
	v_mov_b32_e32 v2, s1
	v_mov_b32_e32 v3, s8
	ds_read_b64 v[2:3], v2
	s_waitcnt lgkmcnt(0)
	s_cmpk_gt_i32 s0, 0x68f
	s_waitcnt lgkmcnt(0)
	v_readfirstlane_b32 s1, v3
	v_readfirstlane_b32 s8, v2
	s_cbranch_scc1 .LBB0_2501
	s_mul_i32 s10, s96, 0xd20000
	s_mul_hi_u32 s9, s96, 0xd20000
	s_add_u32 s8, s8, s10
	s_mul_hi_i32 s10, s0, 0x9c09c09d
	s_addc_u32 s9, s1, s9
	s_add_i32 s10, s10, s0
	s_lshr_b32 s11, s10, 31
	s_ashr_i32 s10, s10, 6
	s_add_i32 s11, s10, s11
	s_mul_i32 s10, s11, 0x69
	s_sub_i32 s10, s0, s10
	s_lshl_b32 s10, s10, 5
	v_lshrrev_b32_e32 v40, 5, v33
	s_lshl_b32 s1, s36, 14
	v_lshl_or_b32 v38, s11, 6, v40
	s_ashr_i32 s11, s10, 31
	s_add_i32 s1, s1, 0
	s_lshl_b64 s[10:11], s[10:11], 2
	s_add_u32 s10, s8, s10
	v_lshlrev_b32_e32 v1, 2, v43
	s_addc_u32 s11, s9, s11
	v_and_b32_e32 v150, 0x7c, v1
	v_lshl_add_u64 v[34:35], s[10:11], 0, v[150:151]
	s_movk_i32 s16, 0x3480
	v_or_b32_e32 v1, 2, v38
	v_mad_i64_i32 v[2:3], s[10:11], v38, s16, v[34:35]
	v_mad_i64_i32 v[4:5], s[10:11], v1, s16, v[34:35]
	global_load_dword v2, v[2:3], off
	v_lshrrev_b32_e32 v41, 3, v33
	global_load_dword v1, v[4:5], off
	v_or_b32_e32 v3, 4, v38
	v_mad_i64_i32 v[4:5], s[10:11], v3, s16, v[34:35]
	v_or_b32_e32 v3, 6, v38
	v_mad_i64_i32 v[6:7], s[10:11], v3, s16, v[34:35]
	global_load_dword v4, v[4:5], off
	v_lshlrev_b32_e32 v39, 2, v41
	global_load_dword v3, v[6:7], off
	v_or_b32_e32 v5, 8, v38
	v_mad_i64_i32 v[6:7], s[10:11], v5, s16, v[34:35]
	v_or_b32_e32 v5, 10, v38
	v_mad_i64_i32 v[8:9], s[10:11], v5, s16, v[34:35]
	global_load_dword v6, v[6:7], off
	s_mov_b32 s17, s0
	global_load_dword v5, v[8:9], off
	v_or_b32_e32 v7, 12, v38
	v_mad_i64_i32 v[8:9], s[10:11], v7, s16, v[34:35]
	v_or_b32_e32 v7, 14, v38
	v_mad_i64_i32 v[10:11], s[10:11], v7, s16, v[34:35]
	global_load_dword v8, v[8:9], off
	s_nop 0
	global_load_dword v7, v[10:11], off
	v_or_b32_e32 v9, 16, v38
	v_mad_i64_i32 v[10:11], s[10:11], v9, s16, v[34:35]
	v_or_b32_e32 v9, 18, v38
	v_mad_i64_i32 v[12:13], s[10:11], v9, s16, v[34:35]
	global_load_dword v10, v[10:11], off
	s_nop 0
	global_load_dword v9, v[12:13], off
	v_or_b32_e32 v11, 20, v38
	v_mad_i64_i32 v[12:13], s[10:11], v11, s16, v[34:35]
	v_or_b32_e32 v11, 22, v38
	v_mad_i64_i32 v[14:15], s[10:11], v11, s16, v[34:35]
	global_load_dword v12, v[12:13], off
	s_nop 0
	global_load_dword v11, v[14:15], off
	v_or_b32_e32 v13, 24, v38
	v_mad_i64_i32 v[14:15], s[10:11], v13, s16, v[34:35]
	v_or_b32_e32 v13, 26, v38
	v_mad_i64_i32 v[16:17], s[10:11], v13, s16, v[34:35]
	global_load_dword v14, v[14:15], off
	s_nop 0
	global_load_dword v13, v[16:17], off
	v_or_b32_e32 v15, 28, v38
	v_mad_i64_i32 v[16:17], s[10:11], v15, s16, v[34:35]
	v_or_b32_e32 v15, 30, v38
	v_mad_i64_i32 v[18:19], s[10:11], v15, s16, v[34:35]
	global_load_dword v16, v[16:17], off
	s_nop 0
	global_load_dword v15, v[18:19], off
	v_or_b32_e32 v17, 32, v38
	v_mad_i64_i32 v[18:19], s[10:11], v17, s16, v[34:35]
	v_or_b32_e32 v17, 34, v38
	v_mad_i64_i32 v[20:21], s[10:11], v17, s16, v[34:35]
	global_load_dword v18, v[18:19], off
	s_nop 0
	global_load_dword v17, v[20:21], off
	v_or_b32_e32 v19, 36, v38
	v_mad_i64_i32 v[20:21], s[10:11], v19, s16, v[34:35]
	v_or_b32_e32 v19, 38, v38
	v_mad_i64_i32 v[22:23], s[10:11], v19, s16, v[34:35]
	global_load_dword v20, v[20:21], off
	s_nop 0
	global_load_dword v19, v[22:23], off
	v_or_b32_e32 v21, 40, v38
	v_mad_i64_i32 v[22:23], s[10:11], v21, s16, v[34:35]
	v_or_b32_e32 v21, 42, v38
	v_mad_i64_i32 v[24:25], s[10:11], v21, s16, v[34:35]
	global_load_dword v22, v[22:23], off
	s_nop 0
	global_load_dword v21, v[24:25], off
	v_or_b32_e32 v23, 44, v38
	v_mad_i64_i32 v[24:25], s[10:11], v23, s16, v[34:35]
	v_or_b32_e32 v23, 46, v38
	v_mad_i64_i32 v[26:27], s[10:11], v23, s16, v[34:35]
	global_load_dword v24, v[24:25], off
	s_nop 0
	global_load_dword v23, v[26:27], off
	v_or_b32_e32 v25, 48, v38
	v_mad_i64_i32 v[26:27], s[10:11], v25, s16, v[34:35]
	v_or_b32_e32 v25, 50, v38
	v_mad_i64_i32 v[28:29], s[10:11], v25, s16, v[34:35]
	global_load_dword v26, v[26:27], off
	s_nop 0
	global_load_dword v25, v[28:29], off
	v_or_b32_e32 v27, 52, v38
	v_mad_i64_i32 v[28:29], s[10:11], v27, s16, v[34:35]
	v_or_b32_e32 v27, 54, v38
	v_mad_i64_i32 v[30:31], s[10:11], v27, s16, v[34:35]
	global_load_dword v28, v[28:29], off
	s_nop 0
	global_load_dword v27, v[30:31], off
	v_or_b32_e32 v29, 56, v38
	v_mad_i64_i32 v[30:31], s[10:11], v29, s16, v[34:35]
	v_or_b32_e32 v29, 58, v38
	v_mad_i64_i32 v[36:37], s[10:11], v29, s16, v[34:35]
	global_load_dword v30, v[30:31], off
	s_nop 0
	global_load_dword v29, v[36:37], off
	v_or_b32_e32 v31, 60, v38
	v_mad_i64_i32 v[36:37], s[10:11], v31, s16, v[34:35]
	v_or_b32_e32 v31, 62, v38
	v_mad_i64_i32 v[34:35], s[10:11], v31, s16, v[34:35]
	global_load_dword v32, v[36:37], off
	global_load_dword v31, v[34:35], off
	v_lshlrev_b32_e32 v36, 3, v33
	v_and_b32_e32 v36, 56, v36
	v_lshl_add_u64 v[34:35], s[8:9], 0, v[150:151]
	v_mul_u32_u24_e32 v38, 0x84, v36
	v_readlane_b32 s8, v254, 48
	v_lshlrev_b32_e32 v36, 1, v36
	v_mov_b32_e32 v37, v151
	v_add3_u32 v42, s1, v38, v39
	v_mul_u32_u24_e32 v38, 0x84, v40
	s_lshl_b32 s10, s8, 5
	v_lshl_add_u64 v[36:37], s[6:7], 0, v[36:37]
	v_add3_u32 v44, s1, v38, v150
	s_lshl_b32 s1, s0, 5
	s_mov_b32 s11, s10
	v_readlane_b32 s9, v254, 49
	s_branch .LBB0_2499

; __device__ __forceinline__ void transpose_mat(const Ctx& c, const float* W, int K, int N, bf16* WT) {
;     float* scr = (float*)(c.lds + c.wid * 16384); const int items = (K / 64) * (N / 32), nblk = N / 32, lane = c.lane;
;     float tv[32];
;     int it = c.gw;
;     if (it < items) { const int k0 = 64 * (it / nblk), n0 = 32 * (it % nblk);
; __device__ __forceinline__ void conv_mixer(const Ctx&, const In& in, unsigned char* ws, int layer) { const Ctx c = mk_ctx();
;     ...
;         transpose_mat(c, in[14] + (size_t)j * 1024 * 1024, 1024, 1024, (bf16*)(W + W_HYBOUT));
.LBB0_2505:
	s_mov_b64 s[8:9], src_shared_base
	v_readlane_b32 s8, v254, 10
	s_cmp_lg_u32 s8, -1
	s_cselect_b32 s8, s8, 0
	s_cselect_b32 s9, s9, 0
	v_mov_b32_e32 v2, s8
	v_mov_b32_e32 v3, s9
	ds_read_b64 v[2:3], v2
	s_waitcnt lgkmcnt(0)
	s_cmpk_gt_i32 s0, 0x1ff
	s_waitcnt lgkmcnt(0)
	v_readfirstlane_b32 s9, v3
	v_readfirstlane_b32 s8, v2
	s_cbranch_scc1 .LBB0_2510
; __device__ __forceinline__ void transpose_mat(const Ctx& c, const float* W, int K, int N, bf16* WT) {
;     float* scr = (float*)(c.lds + c.wid * 16384); const int items = (K / 64) * (N / 32), nblk = N / 32, lane = c.lane;
;     float tv[32];
;     int it = c.gw;
;     if (it < items) { const int k0 = 64 * (it / nblk), n0 = 32 * (it % nblk);
; #pragma unroll
;         for (int i = 0; i < 32; ++i) tv[i] = W[(size_t)(k0 + 2 * i + (lane >> 5)) * N + n0 + (lane & 31)]; }
; __device__ __forceinline__ void conv_mixer(const Ctx&, const In& in, unsigned char* ws, int layer) { const Ctx c = mk_ctx();
;     ...
;         transpose_mat(c, in[14] + (size_t)j * 1024 * 1024, 1024, 1024, (bf16*)(W + W_HYBOUT));
	s_lshl_b64 s[10:11], s[96:97], 22
	s_add_u32 s8, s8, s10
	s_addc_u32 s9, s9, s11
	s_lshr_b32 s1, s1, 27
	s_add_i32 s1, s0, s1
	s_lshl_b32 s11, s1, 1
	s_and_b32 s1, s1, 0x7ffffe0
	s_sub_i32 s1, s0, s1
	s_lshl_b32 s16, s1, 5
	s_lshl_b32 s10, s36, 14
	s_andn2_b32 s11, s11, 63
	v_lshrrev_b32_e32 v42, 5, v33
	s_ashr_i32 s17, s16, 31
	s_add_i32 s10, s10, 0
	v_or_b32_e32 v34, s11, v42
	s_lshl_b64 s[16:17], s[16:17], 2
	s_add_u32 s16, s8, s16
	v_lshlrev_b32_e32 v1, 2, v43
	v_or_b32_e32 v4, 2, v34
	s_addc_u32 s17, s9, s17
	v_and_b32_e32 v150, 0x7c, v1
	v_ashrrev_i32_e32 v35, 31, v34
	v_ashrrev_i32_e32 v5, 31, v4
	v_lshl_add_u64 v[36:37], s[16:17], 0, v[150:151]
	v_lshlrev_b64 v[2:3], 12, v[34:35]
	v_lshlrev_b64 v[4:5], 12, v[4:5]
	v_lshl_add_u64 v[2:3], v[36:37], 0, v[2:3]
	v_lshl_add_u64 v[4:5], v[36:37], 0, v[4:5]
	global_load_dword v2, v[2:3], off
	v_or_b32_e32 v6, 6, v34
	global_load_dword v1, v[4:5], off
	v_or_b32_e32 v4, 4, v34
	v_ashrrev_i32_e32 v5, 31, v4
	v_ashrrev_i32_e32 v7, 31, v6
	v_lshlrev_b64 v[4:5], 12, v[4:5]
	v_lshlrev_b64 v[6:7], 12, v[6:7]
	v_lshl_add_u64 v[4:5], v[36:37], 0, v[4:5]
	v_lshl_add_u64 v[6:7], v[36:37], 0, v[6:7]
	global_load_dword v4, v[4:5], off
	v_or_b32_e32 v8, 10, v34
	global_load_dword v3, v[6:7], off
	v_or_b32_e32 v6, 8, v34
	v_ashrrev_i32_e32 v7, 31, v6
	v_ashrrev_i32_e32 v9, 31, v8
	v_lshlrev_b64 v[6:7], 12, v[6:7]
	v_lshlrev_b64 v[8:9], 12, v[8:9]
	v_lshl_add_u64 v[6:7], v[36:37], 0, v[6:7]
	v_lshl_add_u64 v[8:9], v[36:37], 0, v[8:9]
	global_load_dword v6, v[6:7], off
	v_or_b32_e32 v10, 14, v34
	global_load_dword v5, v[8:9], off
	v_or_b32_e32 v8, 12, v34
	v_ashrrev_i32_e32 v9, 31, v8
	v_ashrrev_i32_e32 v11, 31, v10
	v_lshlrev_b64 v[8:9], 12, v[8:9]
	v_lshlrev_b64 v[10:11], 12, v[10:11]
	v_lshl_add_u64 v[8:9], v[36:37], 0, v[8:9]
	v_lshl_add_u64 v[10:11], v[36:37], 0, v[10:11]
	global_load_dword v8, v[8:9], off
	v_or_b32_e32 v12, 18, v34
	global_load_dword v7, v[10:11], off
	v_or_b32_e32 v10, 16, v34
	v_ashrrev_i32_e32 v11, 31, v10
	v_ashrrev_i32_e32 v13, 31, v12
	v_lshlrev_b64 v[10:11], 12, v[10:11]
	v_lshlrev_b64 v[12:13], 12, v[12:13]
	v_lshl_add_u64 v[10:11], v[36:37], 0, v[10:11]
	v_lshl_add_u64 v[12:13], v[36:37], 0, v[12:13]
	global_load_dword v10, v[10:11], off
	v_or_b32_e32 v14, 22, v34
	global_load_dword v9, v[12:13], off
	v_or_b32_e32 v12, 20, v34
	v_ashrrev_i32_e32 v13, 31, v12
	v_ashrrev_i32_e32 v15, 31, v14
	v_lshlrev_b64 v[12:13], 12, v[12:13]
	v_lshlrev_b64 v[14:15], 12, v[14:15]
	v_lshl_add_u64 v[12:13], v[36:37], 0, v[12:13]
	v_lshl_add_u64 v[14:15], v[36:37], 0, v[14:15]
	global_load_dword v12, v[12:13], off
	v_or_b32_e32 v16, 26, v34
	global_load_dword v11, v[14:15], off
	v_or_b32_e32 v14, 24, v34
	v_ashrrev_i32_e32 v15, 31, v14
	v_ashrrev_i32_e32 v17, 31, v16
	v_lshlrev_b64 v[14:15], 12, v[14:15]
	v_lshlrev_b64 v[16:17], 12, v[16:17]
	v_lshl_add_u64 v[14:15], v[36:37], 0, v[14:15]
	v_lshl_add_u64 v[16:17], v[36:37], 0, v[16:17]
	global_load_dword v14, v[14:15], off
	v_or_b32_e32 v18, 30, v34
	global_load_dword v13, v[16:17], off
	v_or_b32_e32 v16, 28, v34
	v_ashrrev_i32_e32 v17, 31, v16
	v_ashrrev_i32_e32 v19, 31, v18
	v_lshlrev_b64 v[16:17], 12, v[16:17]
	v_lshlrev_b64 v[18:19], 12, v[18:19]
	v_lshl_add_u64 v[16:17], v[36:37], 0, v[16:17]
	v_lshl_add_u64 v[18:19], v[36:37], 0, v[18:19]
	global_load_dword v16, v[16:17], off
	v_or_b32_e32 v20, 34, v34
	global_load_dword v15, v[18:19], off
	v_or_b32_e32 v18, 32, v34
	v_ashrrev_i32_e32 v19, 31, v18
	v_ashrrev_i32_e32 v21, 31, v20
	v_lshlrev_b64 v[18:19], 12, v[18:19]
	v_lshlrev_b64 v[20:21], 12, v[20:21]
	v_lshl_add_u64 v[18:19], v[36:37], 0, v[18:19]
	v_lshl_add_u64 v[20:21], v[36:37], 0, v[20:21]
	global_load_dword v18, v[18:19], off
	v_or_b32_e32 v22, 38, v34
	global_load_dword v17, v[20:21], off
	v_or_b32_e32 v20, 36, v34
	v_ashrrev_i32_e32 v21, 31, v20
	v_ashrrev_i32_e32 v23, 31, v22
	v_lshlrev_b64 v[20:21], 12, v[20:21]
	v_lshlrev_b64 v[22:23], 12, v[22:23]
	v_lshl_add_u64 v[20:21], v[36:37], 0, v[20:21]
	v_lshl_add_u64 v[22:23], v[36:37], 0, v[22:23]
	global_load_dword v20, v[20:21], off
	v_or_b32_e32 v24, 42, v34
	global_load_dword v19, v[22:23], off
	v_or_b32_e32 v22, 40, v34
	v_ashrrev_i32_e32 v23, 31, v22
	v_ashrrev_i32_e32 v25, 31, v24
	v_lshlrev_b64 v[22:23], 12, v[22:23]
	v_lshlrev_b64 v[24:25], 12, v[24:25]
	v_lshl_add_u64 v[22:23], v[36:37], 0, v[22:23]
	v_lshl_add_u64 v[24:25], v[36:37], 0, v[24:25]
	global_load_dword v22, v[22:23], off
	v_or_b32_e32 v26, 46, v34
	global_load_dword v21, v[24:25], off
	v_or_b32_e32 v24, 44, v34
	v_ashrrev_i32_e32 v25, 31, v24
	v_ashrrev_i32_e32 v27, 31, v26
	v_lshlrev_b64 v[24:25], 12, v[24:25]
	v_lshlrev_b64 v[26:27], 12, v[26:27]
	v_lshl_add_u64 v[24:25], v[36:37], 0, v[24:25]
	v_lshl_add_u64 v[26:27], v[36:37], 0, v[26:27]
	global_load_dword v24, v[24:25], off
	v_or_b32_e32 v28, 50, v34
	global_load_dword v23, v[26:27], off
	v_or_b32_e32 v26, 48, v34
	v_ashrrev_i32_e32 v27, 31, v26
	v_ashrrev_i32_e32 v29, 31, v28
	v_lshlrev_b64 v[26:27], 12, v[26:27]
	v_lshlrev_b64 v[28:29], 12, v[28:29]
	v_lshl_add_u64 v[26:27], v[36:37], 0, v[26:27]
	v_lshl_add_u64 v[28:29], v[36:37], 0, v[28:29]
	global_load_dword v26, v[26:27], off
	v_or_b32_e32 v30, 54, v34
	global_load_dword v25, v[28:29], off
	v_or_b32_e32 v28, 52, v34
	v_ashrrev_i32_e32 v29, 31, v28
	v_ashrrev_i32_e32 v31, 31, v30
	v_lshlrev_b64 v[28:29], 12, v[28:29]
	v_lshlrev_b64 v[30:31], 12, v[30:31]
	v_lshl_add_u64 v[28:29], v[36:37], 0, v[28:29]
	v_lshl_add_u64 v[30:31], v[36:37], 0, v[30:31]
	global_load_dword v28, v[28:29], off
	v_or_b32_e32 v38, 58, v34
	global_load_dword v27, v[30:31], off
	v_or_b32_e32 v30, 56, v34
	v_ashrrev_i32_e32 v31, 31, v30
	v_ashrrev_i32_e32 v39, 31, v38
	v_lshlrev_b64 v[30:31], 12, v[30:31]
	v_lshlrev_b64 v[38:39], 12, v[38:39]
	v_lshl_add_u64 v[30:31], v[36:37], 0, v[30:31]
	v_lshl_add_u64 v[38:39], v[36:37], 0, v[38:39]
	global_load_dword v30, v[30:31], off
	v_lshrrev_b32_e32 v44, 3, v33
	global_load_dword v29, v[38:39], off
	v_or_b32_e32 v38, 60, v34
	v_or_b32_e32 v34, 62, v34
	v_ashrrev_i32_e32 v39, 31, v38
	v_ashrrev_i32_e32 v35, 31, v34
	v_lshlrev_b64 v[38:39], 12, v[38:39]
	v_lshlrev_b64 v[34:35], 12, v[34:35]
	v_lshl_add_u64 v[38:39], v[36:37], 0, v[38:39]
	v_lshl_add_u64 v[34:35], v[36:37], 0, v[34:35]
	global_load_dword v32, v[38:39], off
	global_load_dword v31, v[34:35], off
	v_lshlrev_b32_e32 v36, 3, v33
	v_and_b32_e32 v36, 56, v36
	v_mul_u32_u24_e32 v38, 0x84, v36
	v_lshlrev_b32_e32 v36, 1, v36
	v_mov_b32_e32 v37, v151
	v_lshl_add_u64 v[34:35], s[8:9], 0, v[150:151]
	v_lshl_add_u64 v[36:37], s[4:5], 0, v[36:37]
	s_mov_b64 s[8:9], 0x2c80000
	v_lshlrev_b32_e32 v39, 2, v44
	v_lshl_add_u64 v[36:37], v[36:37], 0, s[8:9]
	v_add3_u32 v45, s10, v38, v39
	v_mul_u32_u24_e32 v38, 0x84, v42
	v_readlane_b32 s8, v254, 48
	v_add3_u32 v46, s10, v38, v150
	s_lshl_b32 s10, s8, 5
	s_lshl_b32 s1, s0, 5
	s_mov_b32 s11, s10
	s_mov_b32 s17, s0
	v_readlane_b32 s9, v254, 49
	s_branch .LBB0_2508

; __device__ __forceinline__ unsigned f2bf(float f) { unsigned u = __builtin_bit_cast(unsigned, f); return (u + 0x7fffu + ((u >> 16) & 1u)) >> 16; }
; __device__ __forceinline__ void conv_mixer(const Ctx&, const In& in, unsigned char* ws, int layer) { const Ctx c = mk_ctx();
;     ...
;         bf16* L = (bf16*)(W + W_LORA); const float* w2 = in[17] + (size_t)j * 64 * 512; const float* a2 = in[19] + (size_t)j * 64 * 512; const float* g2 = in[20] + (size_t)j * 160 * 512;
;         for (int i = c.gw * 64 + c.lane; i < 1536 * 384; i += c.NGW * 64) { const int n = i / 384, k = i % 384; float v = 0.f;
;             if (n < 512) { if (k < 64) v = w2[k * 512 + n]; } else if (n < 1024) { if (k >= 64 && k < 128) v = a2[(k - 64) * 512 + n - 512]; } else { if (k >= 128 && k < 288) v = g2[(k - 128) * 512 + n - 1024]; }
;             L[i] = (bf16)f2bf(v); }
.LBB0_2510:
	v_readlane_b32 s1, v254, 11
	s_cmp_lg_u32 s1, -1
	s_mov_b64 s[8:9], src_shared_base
	s_cselect_b32 s1, s1, 0
	s_cselect_b32 s8, s9, 0
	s_waitcnt vmcnt(35)
	v_mov_b32_e32 v2, s1
	s_waitcnt vmcnt(32)
	v_mov_b32_e32 v3, s8
	ds_read_b64 v[2:3], v2
	s_waitcnt lgkmcnt(0)
	v_readlane_b32 s8, v254, 12
	s_cmp_lg_u32 s8, -1
	s_cselect_b32 s8, s8, 0
	s_cselect_b32 s10, s9, 0
	s_waitcnt lgkmcnt(0)
	v_readfirstlane_b32 s1, v3
	v_readfirstlane_b32 s16, v2
	v_mov_b32_e32 v2, s8
	v_mov_b32_e32 v3, s10
	ds_read_b64 v[2:3], v2
	s_waitcnt lgkmcnt(0)
	v_readlane_b32 s8, v254, 13
	s_cmp_lg_u32 s8, -1
	s_cselect_b32 s8, s8, 0
	s_cselect_b32 s9, s9, 0
	s_waitcnt lgkmcnt(0)
	v_readfirstlane_b32 s19, v3
	v_readfirstlane_b32 s18, v2
	v_mov_b32_e32 v2, s8
	v_mov_b32_e32 v3, s9
	ds_read_b64 v[2:3], v2
	s_waitcnt lgkmcnt(0)
	s_mov_b32 s8, 0x90000
	s_waitcnt lgkmcnt(0)
	v_readfirstlane_b32 s24, v2
	v_lshl_or_b32 v2, s0, 6, v33
	v_readfirstlane_b32 s25, v3
	v_cmp_gt_i32_e32 vcc, s8, v2
	s_and_saveexec_b64 s[8:9], vcc
	s_cbranch_execz .LBB0_2527
	s_add_u32 s10, s4, 0x2b00000
	s_addc_u32 s11, s5, 0
	s_lshl_b64 s[26:27], s[96:97], 17
	s_add_u32 s16, s16, s26
	s_addc_u32 s17, s1, s27
	s_add_u32 s18, s18, s26
	s_addc_u32 s19, s19, s27
	s_mul_i32 s26, s96, 0x50000
	s_add_u32 s24, s24, s26
	v_readlane_b32 s26, v254, 50
	s_mul_hi_u32 s1, s96, 0x50000
	v_readlane_b32 s27, v254, 51
	s_addc_u32 s25, s25, s1
	v_lshlrev_b32_e32 v1, 9, v2
	s_lshl_b32 s1, s26, 9
	s_mov_b64 s[26:27], 0
	s_branch .LBB0_2514

; __device__ __forceinline__ void transpose_mat(const Ctx& c, const float* W, int K, int N, bf16* WT) {
;     float* scr = (float*)(c.lds + c.wid * 16384); const int items = (K / 64) * (N / 32), nblk = N / 32, lane = c.lane;
;     float tv[32];
;     int it = c.gw;
;     if (it < items) { const int k0 = 64 * (it / nblk), n0 = 32 * (it % nblk);
; #pragma unroll
;         for (int i = 0; i < 32; ++i) tv[i] = W[(size_t)(k0 + 2 * i + (lane >> 5)) * N + n0 + (lane & 31)]; }
; __device__ __forceinline__ void conv_mixer(const Ctx&, const In& in, unsigned char* ws, int layer) { const Ctx c = mk_ctx();
;     ...
;         transpose_mat(c, in[26] + (size_t)j * 1024 * 672, 1024, 672, (bf16*)(W + W_DOWN));
.LBB0_2528:
	s_and_b64 vcc, exec, s[8:9]
	s_cbranch_vccz .LBB0_2553
	s_add_i32 s1, 0, 0x200d0
	s_cmp_lg_u32 s1, -1
	s_mov_b64 s[8:9], src_shared_base
	s_cselect_b32 s1, s1, 0
	s_cselect_b32 s8, s9, 0
	v_mov_b32_e32 v2, s1
	v_mov_b32_e32 v3, s8
	ds_read_b64 v[2:3], v2
	s_waitcnt lgkmcnt(0)
	v_lshrrev_b32_e32 v42, 5, v33
	v_lshlrev_b32_e32 v1, 2, v43
	s_cmpk_gt_i32 s0, 0x14f
	v_and_b32_e32 v150, 0x7c, v1
	v_lshrrev_b32_e32 v43, 3, v33
	v_mul_u32_u24_e32 v45, 0x84, v42
	s_waitcnt lgkmcnt(0)
	v_readfirstlane_b32 s8, v2
	v_lshlrev_b32_e32 v2, 3, v33
	v_readfirstlane_b32 s1, v3
	v_and_b32_e32 v44, 56, v2
	s_cbranch_scc1 .LBB0_2534
	s_mul_i32 s10, s96, 0x2a0000
	s_mul_hi_u32 s9, s96, 0x2a0000
	s_add_u32 s8, s8, s10
	s_mul_hi_i32 s10, s0, 0x30c30c31
	s_addc_u32 s9, s1, s9
	s_lshr_b32 s11, s10, 31
	s_ashr_i32 s10, s10, 2
	s_add_i32 s11, s10, s11
	s_mul_i32 s10, s11, 21
	s_sub_i32 s10, s0, s10
	s_lshl_b32 s10, s10, 5
	s_lshl_b32 s1, s36, 14
	v_lshl_or_b32 v38, s11, 6, v42
	s_ashr_i32 s11, s10, 31
	s_add_i32 s1, s1, 0
	s_lshl_b64 s[10:11], s[10:11], 2
	s_add_u32 s10, s8, s10
	s_addc_u32 s11, s9, s11
	v_lshl_add_u64 v[34:35], s[10:11], 0, v[150:151]
	s_movk_i32 s16, 0xa80
	v_or_b32_e32 v1, 2, v38
	v_mad_i64_i32 v[2:3], s[10:11], v38, s16, v[34:35]
	v_mad_i64_i32 v[4:5], s[10:11], v1, s16, v[34:35]
	global_load_dword v2, v[2:3], off
	v_lshrrev_b32_e32 v40, 3, v33
	global_load_dword v1, v[4:5], off
	v_or_b32_e32 v3, 4, v38
	v_mad_i64_i32 v[4:5], s[10:11], v3, s16, v[34:35]
	v_or_b32_e32 v3, 6, v38
	v_mad_i64_i32 v[6:7], s[10:11], v3, s16, v[34:35]
	global_load_dword v4, v[4:5], off
	v_lshlrev_b32_e32 v39, 2, v40
	global_load_dword v3, v[6:7], off
	v_or_b32_e32 v5, 8, v38
	v_mad_i64_i32 v[6:7], s[10:11], v5, s16, v[34:35]
	v_or_b32_e32 v5, 10, v38
	v_mad_i64_i32 v[8:9], s[10:11], v5, s16, v[34:35]
	global_load_dword v6, v[6:7], off
	v_add3_u32 v46, s1, v45, v150
	global_load_dword v5, v[8:9], off
	v_or_b32_e32 v7, 12, v38
	v_mad_i64_i32 v[8:9], s[10:11], v7, s16, v[34:35]
	v_or_b32_e32 v7, 14, v38
	v_mad_i64_i32 v[10:11], s[10:11], v7, s16, v[34:35]
	global_load_dword v8, v[8:9], off
	s_nop 0
	global_load_dword v7, v[10:11], off
	v_or_b32_e32 v9, 16, v38
	v_mad_i64_i32 v[10:11], s[10:11], v9, s16, v[34:35]
	v_or_b32_e32 v9, 18, v38
	v_mad_i64_i32 v[12:13], s[10:11], v9, s16, v[34:35]
	global_load_dword v10, v[10:11], off
	s_nop 0
	global_load_dword v9, v[12:13], off
	v_or_b32_e32 v11, 20, v38
	v_mad_i64_i32 v[12:13], s[10:11], v11, s16, v[34:35]
	v_or_b32_e32 v11, 22, v38
	v_mad_i64_i32 v[14:15], s[10:11], v11, s16, v[34:35]
	global_load_dword v12, v[12:13], off
	s_nop 0
	global_load_dword v11, v[14:15], off
	v_or_b32_e32 v13, 24, v38
	v_mad_i64_i32 v[14:15], s[10:11], v13, s16, v[34:35]
	v_or_b32_e32 v13, 26, v38
	v_mad_i64_i32 v[16:17], s[10:11], v13, s16, v[34:35]
	global_load_dword v14, v[14:15], off
	s_nop 0
	global_load_dword v13, v[16:17], off
	v_or_b32_e32 v15, 28, v38
	v_mad_i64_i32 v[16:17], s[10:11], v15, s16, v[34:35]
	v_or_b32_e32 v15, 30, v38
	v_mad_i64_i32 v[18:19], s[10:11], v15, s16, v[34:35]
	global_load_dword v16, v[16:17], off
	s_nop 0
	global_load_dword v15, v[18:19], off
	v_or_b32_e32 v17, 32, v38
	v_mad_i64_i32 v[18:19], s[10:11], v17, s16, v[34:35]
	v_or_b32_e32 v17, 34, v38
	v_mad_i64_i32 v[20:21], s[10:11], v17, s16, v[34:35]
	global_load_dword v18, v[18:19], off
	s_nop 0
	global_load_dword v17, v[20:21], off
	v_or_b32_e32 v19, 36, v38
	v_mad_i64_i32 v[20:21], s[10:11], v19, s16, v[34:35]
	v_or_b32_e32 v19, 38, v38
	v_mad_i64_i32 v[22:23], s[10:11], v19, s16, v[34:35]
	global_load_dword v20, v[20:21], off
	s_nop 0
	global_load_dword v19, v[22:23], off
	v_or_b32_e32 v21, 40, v38
	v_mad_i64_i32 v[22:23], s[10:11], v21, s16, v[34:35]
	v_or_b32_e32 v21, 42, v38
	v_mad_i64_i32 v[24:25], s[10:11], v21, s16, v[34:35]
	global_load_dword v22, v[22:23], off
	s_nop 0
	global_load_dword v21, v[24:25], off
	v_or_b32_e32 v23, 44, v38
	v_mad_i64_i32 v[24:25], s[10:11], v23, s16, v[34:35]
	v_or_b32_e32 v23, 46, v38
	v_mad_i64_i32 v[26:27], s[10:11], v23, s16, v[34:35]
	global_load_dword v24, v[24:25], off
	s_nop 0
	global_load_dword v23, v[26:27], off
	v_or_b32_e32 v25, 48, v38
	v_mad_i64_i32 v[26:27], s[10:11], v25, s16, v[34:35]
	v_or_b32_e32 v25, 50, v38
	v_mad_i64_i32 v[28:29], s[10:11], v25, s16, v[34:35]
	global_load_dword v26, v[26:27], off
	s_nop 0
	global_load_dword v25, v[28:29], off
	v_or_b32_e32 v27, 52, v38
	v_mad_i64_i32 v[28:29], s[10:11], v27, s16, v[34:35]
	v_or_b32_e32 v27, 54, v38
	v_mad_i64_i32 v[30:31], s[10:11], v27, s16, v[34:35]
	global_load_dword v28, v[28:29], off
	s_nop 0
	global_load_dword v27, v[30:31], off
	v_or_b32_e32 v29, 56, v38
	v_mad_i64_i32 v[30:31], s[10:11], v29, s16, v[34:35]
	v_or_b32_e32 v29, 58, v38
	v_mad_i64_i32 v[36:37], s[10:11], v29, s16, v[34:35]
	global_load_dword v30, v[30:31], off
	s_nop 0
	global_load_dword v29, v[36:37], off
	v_or_b32_e32 v31, 60, v38
	v_mad_i64_i32 v[36:37], s[10:11], v31, s16, v[34:35]
	v_or_b32_e32 v31, 62, v38
	v_mad_i64_i32 v[34:35], s[10:11], v31, s16, v[34:35]
	global_load_dword v32, v[36:37], off
	global_load_dword v31, v[34:35], off
	v_lshlrev_b32_e32 v36, 1, v44
	v_mov_b32_e32 v37, v151
	v_lshl_add_u64 v[36:37], s[6:7], 0, v[36:37]
	v_readlane_b32 s6, v254, 48
	v_lshl_add_u64 v[34:35], s[8:9], 0, v[150:151]
	v_mul_u32_u24_e32 v38, 0x84, v44
	s_lshl_b32 s8, s6, 5
	v_add3_u32 v41, s1, v38, v39
	s_lshl_b32 s1, s0, 5
	s_mov_b32 s9, s8
	s_mov_b32 s11, s0
	v_readlane_b32 s7, v254, 49
	s_branch .LBB0_2532

; __device__ __forceinline__ void transpose_mat(const Ctx& c, const float* W, int K, int N, bf16* WT) {
;     float* scr = (float*)(c.lds + c.wid * 16384); const int items = (K / 64) * (N / 32), nblk = N / 32, lane = c.lane;
;     float tv[32];
;     int it = c.gw;
;     if (it < items) { const int k0 = 64 * (it / nblk), n0 = 32 * (it % nblk);
; #pragma unroll
;         for (int i = 0; i < 32; ++i) tv[i] = W[(size_t)(k0 + 2 * i + (lane >> 5)) * N + n0 + (lane & 31)]; }
; __device__ __forceinline__ void conv_mixer(const Ctx&, const In& in, unsigned char* ws, int layer) { const Ctx c = mk_ctx();
;     ...
;         transpose_mat(c, in[29] + (size_t)j * 384 * 1536, 384, 1536, (bf16*)(W + W_UQ));
.LBB0_2538:
	s_mov_b64 s[6:7], src_shared_base
	s_add_i32 s6, 0, 0x200e8
	s_cmp_lg_u32 s6, -1
	s_cselect_b32 s6, s6, 0
	s_cselect_b32 s7, s7, 0
	v_mov_b32_e32 v2, s6
	v_mov_b32_e32 v3, s7
	ds_read_b64 v[2:3], v2
	s_waitcnt lgkmcnt(0)
	s_cmpk_gt_i32 s0, 0x11f
	s_waitcnt lgkmcnt(0)
	v_readfirstlane_b32 s7, v3
	v_readfirstlane_b32 s6, v2
	s_cbranch_scc1 .LBB0_2543
	s_mul_i32 s9, s96, 0x240000
	s_mul_hi_u32 s8, s96, 0x240000
	s_add_u32 s6, s6, s9
	s_mul_hi_i32 s9, s0, 0x2aaaaaab
	s_addc_u32 s7, s7, s8
	s_lshr_b32 s10, s9, 31
	s_ashr_i32 s9, s9, 3
	s_add_i32 s9, s9, s10
	s_mul_i32 s10, s9, 48
	s_sub_i32 s10, s0, s10
	s_lshl_b32 s10, s10, 5
	s_lshl_b32 s8, s36, 14
	s_ashr_i32 s11, s10, 31
	s_add_i32 s8, s8, 0
	s_lshl_b64 s[10:11], s[10:11], 2
	s_add_u32 s10, s6, s10
	v_lshl_or_b32 v38, s9, 6, v42
	s_addc_u32 s11, s7, s11
	v_lshl_add_u64 v[34:35], s[10:11], 0, v[150:151]
	s_movk_i32 s9, 0x1800
	v_or_b32_e32 v1, 2, v38
	v_mad_i64_i32 v[2:3], s[10:11], v38, s9, v[34:35]
	v_mad_i64_i32 v[4:5], s[10:11], v1, s9, v[34:35]
	global_load_dword v2, v[2:3], off
	v_lshrrev_b32_e32 v40, 3, v33
	global_load_dword v1, v[4:5], off
	v_or_b32_e32 v3, 4, v38
	v_mad_i64_i32 v[4:5], s[10:11], v3, s9, v[34:35]
	v_or_b32_e32 v3, 6, v38
	v_mad_i64_i32 v[6:7], s[10:11], v3, s9, v[34:35]
	global_load_dword v4, v[4:5], off
	v_lshlrev_b32_e32 v39, 2, v40
	global_load_dword v3, v[6:7], off
	v_or_b32_e32 v5, 8, v38
	v_mad_i64_i32 v[6:7], s[10:11], v5, s9, v[34:35]
	v_or_b32_e32 v5, 10, v38
	v_mad_i64_i32 v[8:9], s[10:11], v5, s9, v[34:35]
	global_load_dword v6, v[6:7], off
	v_mul_u32_u24_e32 v40, 0x180, v40
	global_load_dword v5, v[8:9], off
	v_or_b32_e32 v7, 12, v38
	v_mad_i64_i32 v[8:9], s[10:11], v7, s9, v[34:35]
	v_or_b32_e32 v7, 14, v38
	v_mad_i64_i32 v[10:11], s[10:11], v7, s9, v[34:35]
	global_load_dword v8, v[8:9], off
	v_readlane_b32 s16, v254, 48
	global_load_dword v7, v[10:11], off
	v_or_b32_e32 v9, 16, v38
	v_mad_i64_i32 v[10:11], s[10:11], v9, s9, v[34:35]
	v_or_b32_e32 v9, 18, v38
	v_mad_i64_i32 v[12:13], s[10:11], v9, s9, v[34:35]
	global_load_dword v10, v[10:11], off
	v_readlane_b32 s17, v254, 49
	global_load_dword v9, v[12:13], off
	v_or_b32_e32 v11, 20, v38
	v_mad_i64_i32 v[12:13], s[10:11], v11, s9, v[34:35]
	v_or_b32_e32 v11, 22, v38
	v_mad_i64_i32 v[14:15], s[10:11], v11, s9, v[34:35]
	global_load_dword v12, v[12:13], off
	s_nop 0
	global_load_dword v11, v[14:15], off
	v_or_b32_e32 v13, 24, v38
	v_mad_i64_i32 v[14:15], s[10:11], v13, s9, v[34:35]
	v_or_b32_e32 v13, 26, v38
	v_mad_i64_i32 v[16:17], s[10:11], v13, s9, v[34:35]
	global_load_dword v14, v[14:15], off
	s_nop 0
	global_load_dword v13, v[16:17], off
	v_or_b32_e32 v15, 28, v38
	v_mad_i64_i32 v[16:17], s[10:11], v15, s9, v[34:35]
	v_or_b32_e32 v15, 30, v38
	v_mad_i64_i32 v[18:19], s[10:11], v15, s9, v[34:35]
	global_load_dword v16, v[16:17], off
	s_nop 0
	global_load_dword v15, v[18:19], off
	v_or_b32_e32 v17, 32, v38
	v_mad_i64_i32 v[18:19], s[10:11], v17, s9, v[34:35]
	v_or_b32_e32 v17, 34, v38
	v_mad_i64_i32 v[20:21], s[10:11], v17, s9, v[34:35]
	global_load_dword v18, v[18:19], off
	s_nop 0
	global_load_dword v17, v[20:21], off
	v_or_b32_e32 v19, 36, v38
	v_mad_i64_i32 v[20:21], s[10:11], v19, s9, v[34:35]
	v_or_b32_e32 v19, 38, v38
	v_mad_i64_i32 v[22:23], s[10:11], v19, s9, v[34:35]
	global_load_dword v20, v[20:21], off
	s_nop 0
	global_load_dword v19, v[22:23], off
	v_or_b32_e32 v21, 40, v38
	v_mad_i64_i32 v[22:23], s[10:11], v21, s9, v[34:35]
	v_or_b32_e32 v21, 42, v38
	v_mad_i64_i32 v[24:25], s[10:11], v21, s9, v[34:35]
	global_load_dword v22, v[22:23], off
	s_nop 0
	global_load_dword v21, v[24:25], off
	v_or_b32_e32 v23, 44, v38
	v_mad_i64_i32 v[24:25], s[10:11], v23, s9, v[34:35]
	v_or_b32_e32 v23, 46, v38
	v_mad_i64_i32 v[26:27], s[10:11], v23, s9, v[34:35]
	global_load_dword v24, v[24:25], off
	s_nop 0
	global_load_dword v23, v[26:27], off
	v_or_b32_e32 v25, 48, v38
	v_mad_i64_i32 v[26:27], s[10:11], v25, s9, v[34:35]
	v_or_b32_e32 v25, 50, v38
	v_mad_i64_i32 v[28:29], s[10:11], v25, s9, v[34:35]
	global_load_dword v26, v[26:27], off
	s_nop 0
	global_load_dword v25, v[28:29], off
	v_or_b32_e32 v27, 52, v38
	v_mad_i64_i32 v[28:29], s[10:11], v27, s9, v[34:35]
	v_or_b32_e32 v27, 54, v38
	v_mad_i64_i32 v[30:31], s[10:11], v27, s9, v[34:35]
	global_load_dword v28, v[28:29], off
	s_nop 0
	global_load_dword v27, v[30:31], off
	v_or_b32_e32 v29, 56, v38
	v_mad_i64_i32 v[30:31], s[10:11], v29, s9, v[34:35]
	v_or_b32_e32 v29, 58, v38
	v_mad_i64_i32 v[36:37], s[10:11], v29, s9, v[34:35]
	global_load_dword v30, v[30:31], off
	s_nop 0
	global_load_dword v29, v[36:37], off
	v_or_b32_e32 v31, 60, v38
	v_mad_i64_i32 v[36:37], s[10:11], v31, s9, v[34:35]
	v_or_b32_e32 v31, 62, v38
	v_mad_i64_i32 v[34:35], s[10:11], v31, s9, v[34:35]
	global_load_dword v32, v[36:37], off
	global_load_dword v31, v[34:35], off
	v_lshlrev_b32_e32 v36, 1, v44
	v_mov_b32_e32 v37, v151
	v_lshl_add_u64 v[34:35], s[6:7], 0, v[150:151]
	v_lshl_add_u64 v[36:37], s[4:5], 0, v[36:37]
	s_mov_b64 s[6:7], 0x2600000
	v_lshl_add_u64 v[36:37], v[36:37], 0, s[6:7]
	s_mul_i32 s6, s0, 0x3000
	v_mul_u32_u24_e32 v38, 0x84, v44
	v_or_b32_e32 v40, s6, v40
	s_add_i32 s6, s16, s0
	v_add3_u32 v38, s8, v38, v39
	v_add3_u32 v39, s8, v45, v150
	s_lshl_b32 s8, s6, 5
	s_lshl_b32 s9, s16, 5
	s_mov_b32 s11, s0
	s_branch .LBB0_2541

; __device__ __forceinline__ void transpose_mat(const Ctx& c, const float* W, int K, int N, bf16* WT) {
;     float* scr = (float*)(c.lds + c.wid * 16384); const int items = (K / 64) * (N / 32), nblk = N / 32, lane = c.lane;
;     float tv[32];
;     int it = c.gw;
;     if (it < items) { const int k0 = 64 * (it / nblk), n0 = 32 * (it % nblk);
; __device__ __forceinline__ void conv_mixer(const Ctx&, const In& in, unsigned char* ws, int layer) { const Ctx c = mk_ctx();
;     ...
;         transpose_mat(c, in[30] + (size_t)j * 256 * 2048, 256, 2048, (bf16*)(W + W_UKV));
.LBB0_2543:
	s_mov_b64 s[6:7], src_shared_base
	s_add_i32 s6, 0, 0x200f0
	s_cmp_lg_u32 s6, -1
	s_cselect_b32 s6, s6, 0
	s_cselect_b32 s7, s7, 0
	s_waitcnt vmcnt(35)
	v_mov_b32_e32 v2, s6
	s_waitcnt vmcnt(32)
	v_mov_b32_e32 v3, s7
	ds_read_b64 v[2:3], v2
	s_waitcnt lgkmcnt(0)
	s_cmpk_gt_i32 s0, 0xff
	s_waitcnt lgkmcnt(0)
	v_readfirstlane_b32 s7, v3
	v_readfirstlane_b32 s6, v2
	s_cbranch_scc1 .LBB0_2548
; __device__ __forceinline__ void transpose_mat(const Ctx& c, const float* W, int K, int N, bf16* WT) {
;     float* scr = (float*)(c.lds + c.wid * 16384); const int items = (K / 64) * (N / 32), nblk = N / 32, lane = c.lane;
;     float tv[32];
;     int it = c.gw;
;     if (it < items) { const int k0 = 64 * (it / nblk), n0 = 32 * (it % nblk);
; #pragma unroll
;         for (int i = 0; i < 32; ++i) tv[i] = W[(size_t)(k0 + 2 * i + (lane >> 5)) * N + n0 + (lane & 31)]; }
; __device__ __forceinline__ void conv_mixer(const Ctx&, const In& in, unsigned char* ws, int layer) { const Ctx c = mk_ctx();
;     ...
;         transpose_mat(c, in[30] + (size_t)j * 256 * 2048, 256, 2048, (bf16*)(W + W_UKV));
	s_lshl_b64 s[8:9], s[96:97], 21
	s_add_u32 s6, s6, s8
	s_addc_u32 s7, s7, s9
	s_lshr_b32 s9, s1, 26
	s_add_i32 s9, s0, s9
	s_andn2_b32 s9, s9, 63
	s_sub_i32 s10, s0, s9
	s_lshl_b32 s10, s10, 5
	s_lshl_b32 s8, s36, 14
	s_ashr_i32 s11, s10, 31
	s_add_i32 s8, s8, 0
	v_or_b32_e32 v34, s9, v42
	s_lshl_b64 s[10:11], s[10:11], 2
	s_add_u32 s10, s6, s10
	v_or_b32_e32 v4, 2, v34
	s_addc_u32 s11, s7, s11
	v_ashrrev_i32_e32 v35, 31, v34
	v_ashrrev_i32_e32 v5, 31, v4
	v_lshl_add_u64 v[36:37], s[10:11], 0, v[150:151]
	v_lshlrev_b64 v[2:3], 13, v[34:35]
	v_lshlrev_b64 v[4:5], 13, v[4:5]
	v_lshl_add_u64 v[2:3], v[36:37], 0, v[2:3]
	v_lshl_add_u64 v[4:5], v[36:37], 0, v[4:5]
	global_load_dword v2, v[2:3], off
	v_or_b32_e32 v6, 6, v34
	global_load_dword v1, v[4:5], off
	v_or_b32_e32 v4, 4, v34
	v_ashrrev_i32_e32 v5, 31, v4
	v_ashrrev_i32_e32 v7, 31, v6
	v_lshlrev_b64 v[4:5], 13, v[4:5]
	v_lshlrev_b64 v[6:7], 13, v[6:7]
	v_lshl_add_u64 v[4:5], v[36:37], 0, v[4:5]
	v_lshl_add_u64 v[6:7], v[36:37], 0, v[6:7]
	global_load_dword v4, v[4:5], off
	v_or_b32_e32 v8, 10, v34
	global_load_dword v3, v[6:7], off
	v_or_b32_e32 v6, 8, v34
	v_ashrrev_i32_e32 v7, 31, v6
	v_ashrrev_i32_e32 v9, 31, v8
	v_lshlrev_b64 v[6:7], 13, v[6:7]
	v_lshlrev_b64 v[8:9], 13, v[8:9]
	v_lshl_add_u64 v[6:7], v[36:37], 0, v[6:7]
	v_lshl_add_u64 v[8:9], v[36:37], 0, v[8:9]
	global_load_dword v6, v[6:7], off
	v_or_b32_e32 v10, 14, v34
	global_load_dword v5, v[8:9], off
	v_or_b32_e32 v8, 12, v34
	v_ashrrev_i32_e32 v9, 31, v8
	v_ashrrev_i32_e32 v11, 31, v10
	v_lshlrev_b64 v[8:9], 13, v[8:9]
	v_lshlrev_b64 v[10:11], 13, v[10:11]
	v_lshl_add_u64 v[8:9], v[36:37], 0, v[8:9]
	v_lshl_add_u64 v[10:11], v[36:37], 0, v[10:11]
	global_load_dword v8, v[8:9], off
	v_or_b32_e32 v12, 18, v34
	global_load_dword v7, v[10:11], off
	v_or_b32_e32 v10, 16, v34
	v_ashrrev_i32_e32 v11, 31, v10
	v_ashrrev_i32_e32 v13, 31, v12
	v_lshlrev_b64 v[10:11], 13, v[10:11]
	v_lshlrev_b64 v[12:13], 13, v[12:13]
	v_lshl_add_u64 v[10:11], v[36:37], 0, v[10:11]
	v_lshl_add_u64 v[12:13], v[36:37], 0, v[12:13]
	global_load_dword v10, v[10:11], off
	v_or_b32_e32 v14, 22, v34
	global_load_dword v9, v[12:13], off
	v_or_b32_e32 v12, 20, v34
	v_ashrrev_i32_e32 v13, 31, v12
	v_ashrrev_i32_e32 v15, 31, v14
	v_lshlrev_b64 v[12:13], 13, v[12:13]
	v_lshlrev_b64 v[14:15], 13, v[14:15]
	v_lshl_add_u64 v[12:13], v[36:37], 0, v[12:13]
	v_lshl_add_u64 v[14:15], v[36:37], 0, v[14:15]
	global_load_dword v12, v[12:13], off
	v_or_b32_e32 v16, 26, v34
	global_load_dword v11, v[14:15], off
	v_or_b32_e32 v14, 24, v34
	v_ashrrev_i32_e32 v15, 31, v14
	v_ashrrev_i32_e32 v17, 31, v16
	v_lshlrev_b64 v[14:15], 13, v[14:15]
	v_lshlrev_b64 v[16:17], 13, v[16:17]
	v_lshl_add_u64 v[14:15], v[36:37], 0, v[14:15]
	v_lshl_add_u64 v[16:17], v[36:37], 0, v[16:17]
	global_load_dword v14, v[14:15], off
	v_or_b32_e32 v18, 30, v34
	global_load_dword v13, v[16:17], off
	v_or_b32_e32 v16, 28, v34
	v_ashrrev_i32_e32 v17, 31, v16
	v_ashrrev_i32_e32 v19, 31, v18
	v_lshlrev_b64 v[16:17], 13, v[16:17]
	v_lshlrev_b64 v[18:19], 13, v[18:19]
	v_lshl_add_u64 v[16:17], v[36:37], 0, v[16:17]
	v_lshl_add_u64 v[18:19], v[36:37], 0, v[18:19]
	global_load_dword v16, v[16:17], off
	v_or_b32_e32 v20, 34, v34
	global_load_dword v15, v[18:19], off
	v_or_b32_e32 v18, 32, v34
	v_ashrrev_i32_e32 v19, 31, v18
	v_ashrrev_i32_e32 v21, 31, v20
	v_lshlrev_b64 v[18:19], 13, v[18:19]
	v_lshlrev_b64 v[20:21], 13, v[20:21]
	v_lshl_add_u64 v[18:19], v[36:37], 0, v[18:19]
	v_lshl_add_u64 v[20:21], v[36:37], 0, v[20:21]
	global_load_dword v18, v[18:19], off
	v_or_b32_e32 v22, 38, v34
	global_load_dword v17, v[20:21], off
	v_or_b32_e32 v20, 36, v34
	v_ashrrev_i32_e32 v21, 31, v20
	v_ashrrev_i32_e32 v23, 31, v22
	v_lshlrev_b64 v[20:21], 13, v[20:21]
	v_lshlrev_b64 v[22:23], 13, v[22:23]
	v_lshl_add_u64 v[20:21], v[36:37], 0, v[20:21]
	v_lshl_add_u64 v[22:23], v[36:37], 0, v[22:23]
	global_load_dword v20, v[20:21], off
	v_or_b32_e32 v24, 42, v34
	global_load_dword v19, v[22:23], off
	v_or_b32_e32 v22, 40, v34
	v_ashrrev_i32_e32 v23, 31, v22
	v_ashrrev_i32_e32 v25, 31, v24
	v_lshlrev_b64 v[22:23], 13, v[22:23]
	v_lshlrev_b64 v[24:25], 13, v[24:25]
	v_lshl_add_u64 v[22:23], v[36:37], 0, v[22:23]
	v_lshl_add_u64 v[24:25], v[36:37], 0, v[24:25]
	global_load_dword v22, v[22:23], off
	v_or_b32_e32 v26, 46, v34
	global_load_dword v21, v[24:25], off
	v_or_b32_e32 v24, 44, v34
	v_ashrrev_i32_e32 v25, 31, v24
	v_ashrrev_i32_e32 v27, 31, v26
	v_lshlrev_b64 v[24:25], 13, v[24:25]
	v_lshlrev_b64 v[26:27], 13, v[26:27]
	v_lshl_add_u64 v[24:25], v[36:37], 0, v[24:25]
	v_lshl_add_u64 v[26:27], v[36:37], 0, v[26:27]
	global_load_dword v24, v[24:25], off
	v_or_b32_e32 v28, 50, v34
	global_load_dword v23, v[26:27], off
	v_or_b32_e32 v26, 48, v34
	v_ashrrev_i32_e32 v27, 31, v26
	v_ashrrev_i32_e32 v29, 31, v28
	v_lshlrev_b64 v[26:27], 13, v[26:27]
	v_lshlrev_b64 v[28:29], 13, v[28:29]
	v_lshl_add_u64 v[26:27], v[36:37], 0, v[26:27]
	v_lshl_add_u64 v[28:29], v[36:37], 0, v[28:29]
	global_load_dword v26, v[26:27], off
	v_or_b32_e32 v30, 54, v34
	global_load_dword v25, v[28:29], off
	v_or_b32_e32 v28, 52, v34
	v_ashrrev_i32_e32 v29, 31, v28
	v_ashrrev_i32_e32 v31, 31, v30
	v_lshlrev_b64 v[28:29], 13, v[28:29]
	v_lshlrev_b64 v[30:31], 13, v[30:31]
	v_lshl_add_u64 v[28:29], v[36:37], 0, v[28:29]
	v_lshl_add_u64 v[30:31], v[36:37], 0, v[30:31]
	global_load_dword v28, v[28:29], off
	v_or_b32_e32 v38, 58, v34
	global_load_dword v27, v[30:31], off
	v_or_b32_e32 v30, 56, v34
	v_ashrrev_i32_e32 v31, 31, v30
	v_ashrrev_i32_e32 v39, 31, v38
	v_lshlrev_b64 v[30:31], 13, v[30:31]
	v_lshlrev_b64 v[38:39], 13, v[38:39]
	v_lshl_add_u64 v[30:31], v[36:37], 0, v[30:31]
	v_lshl_add_u64 v[38:39], v[36:37], 0, v[38:39]
	global_load_dword v30, v[30:31], off
	v_lshrrev_b32_e32 v33, 3, v33
	global_load_dword v29, v[38:39], off
	v_or_b32_e32 v38, 60, v34
	v_or_b32_e32 v34, 62, v34
	v_ashrrev_i32_e32 v39, 31, v38
	v_ashrrev_i32_e32 v35, 31, v34
	v_lshlrev_b64 v[38:39], 13, v[38:39]
	v_lshlrev_b64 v[34:35], 13, v[34:35]
	v_lshl_add_u64 v[38:39], v[36:37], 0, v[38:39]
	v_lshl_add_u64 v[34:35], v[36:37], 0, v[34:35]
	global_load_dword v32, v[38:39], off
	global_load_dword v31, v[34:35], off
	v_lshlrev_b32_e32 v36, 1, v44
	v_mov_b32_e32 v37, v151
	v_lshl_add_u64 v[34:35], s[6:7], 0, v[150:151]
	v_lshl_add_u64 v[36:37], s[4:5], 0, v[36:37]
	s_mov_b64 s[6:7], 0x2800000
	v_lshl_add_u64 v[36:37], v[36:37], 0, s[6:7]
	v_readlane_b32 s6, v254, 48
	v_mul_u32_u24_e32 v38, 0x84, v44
	v_lshlrev_b32_e32 v39, 2, v33
	s_lshl_b32 s9, s6, 5
	v_add3_u32 v46, s8, v38, v39
	v_add3_u32 v47, s8, v45, v150
	s_lshl_b32 s8, s0, 5
	s_mov_b32 s10, s9
	s_mov_b32 s16, s0
	v_readlane_b32 s7, v254, 49
	s_branch .LBB0_2546

; __device__ __forceinline__ void transpose_mat(const Ctx& c, const float* W, int K, int N, bf16* WT) {
;     float* scr = (float*)(c.lds + c.wid * 16384); const int items = (K / 64) * (N / 32), nblk = N / 32, lane = c.lane;
;     float tv[32];
;     int it = c.gw;
;     if (it < items) { const int k0 = 64 * (it / nblk), n0 = 32 * (it % nblk);
; __device__ __forceinline__ void conv_mixer(const Ctx&, const In& in, unsigned char* ws, int layer) { const Ctx c = mk_ctx();
;     ...
;         transpose_mat(c, in[31] + (size_t)j * 1024 * 1024, 1024, 1024, (bf16*)(W + W_WO));
.LBB0_2548:
	s_mov_b64 s[6:7], src_shared_base
	s_add_i32 s6, 0, 0x200f8
	s_cmp_lg_u32 s6, -1
	s_cselect_b32 s6, s6, 0
	s_cselect_b32 s7, s7, 0
	s_waitcnt vmcnt(35)
	v_mov_b32_e32 v2, s6
	s_waitcnt vmcnt(32)
	v_mov_b32_e32 v3, s7
	ds_read_b64 v[2:3], v2
	s_waitcnt lgkmcnt(0)
	s_cmpk_gt_i32 s0, 0x1ff
	s_waitcnt lgkmcnt(0)
	v_readfirstlane_b32 s7, v3
	v_readfirstlane_b32 s6, v2
	s_cbranch_scc1 .LBB0_2553
; __device__ __forceinline__ void transpose_mat(const Ctx& c, const float* W, int K, int N, bf16* WT) {
;     float* scr = (float*)(c.lds + c.wid * 16384); const int items = (K / 64) * (N / 32), nblk = N / 32, lane = c.lane;
;     float tv[32];
;     int it = c.gw;
;     if (it < items) { const int k0 = 64 * (it / nblk), n0 = 32 * (it % nblk);
; #pragma unroll
;         for (int i = 0; i < 32; ++i) tv[i] = W[(size_t)(k0 + 2 * i + (lane >> 5)) * N + n0 + (lane & 31)]; }
; __device__ __forceinline__ void conv_mixer(const Ctx&, const In& in, unsigned char* ws, int layer) { const Ctx c = mk_ctx();
;     ...
;         transpose_mat(c, in[31] + (size_t)j * 1024 * 1024, 1024, 1024, (bf16*)(W + W_WO));
	s_lshl_b64 s[8:9], s[96:97], 22
	s_add_u32 s6, s6, s8
	s_addc_u32 s7, s7, s9
	s_lshr_b32 s1, s1, 27
	s_add_i32 s1, s0, s1
	s_lshl_b32 s9, s1, 1
	s_and_b32 s1, s1, 0x7ffffe0
	s_sub_i32 s1, s0, s1
	s_lshl_b32 s10, s1, 5
	s_lshl_b32 s8, s36, 14
	s_andn2_b32 s9, s9, 63
	s_ashr_i32 s11, s10, 31
	s_add_i32 s8, s8, 0
	v_or_b32_e32 v34, s9, v42
	s_lshl_b64 s[10:11], s[10:11], 2
	s_add_u32 s10, s6, s10
	v_or_b32_e32 v4, 2, v34
	s_addc_u32 s11, s7, s11
	v_ashrrev_i32_e32 v35, 31, v34
	v_ashrrev_i32_e32 v5, 31, v4
	v_lshl_add_u64 v[36:37], s[10:11], 0, v[150:151]
	v_lshlrev_b64 v[2:3], 12, v[34:35]
	v_lshlrev_b64 v[4:5], 12, v[4:5]
	v_lshl_add_u64 v[2:3], v[36:37], 0, v[2:3]
	v_lshl_add_u64 v[4:5], v[36:37], 0, v[4:5]
	global_load_dword v2, v[2:3], off
	v_or_b32_e32 v6, 6, v34
	global_load_dword v1, v[4:5], off
	v_or_b32_e32 v4, 4, v34
	v_ashrrev_i32_e32 v5, 31, v4
	v_ashrrev_i32_e32 v7, 31, v6
	v_lshlrev_b64 v[4:5], 12, v[4:5]
	v_lshlrev_b64 v[6:7], 12, v[6:7]
	v_lshl_add_u64 v[4:5], v[36:37], 0, v[4:5]
	v_lshl_add_u64 v[6:7], v[36:37], 0, v[6:7]
	global_load_dword v4, v[4:5], off
	v_or_b32_e32 v8, 10, v34
	global_load_dword v3, v[6:7], off
	v_or_b32_e32 v6, 8, v34
	v_ashrrev_i32_e32 v7, 31, v6
	v_ashrrev_i32_e32 v9, 31, v8
	v_lshlrev_b64 v[6:7], 12, v[6:7]
	v_lshlrev_b64 v[8:9], 12, v[8:9]
	v_lshl_add_u64 v[6:7], v[36:37], 0, v[6:7]
	v_lshl_add_u64 v[8:9], v[36:37], 0, v[8:9]
	global_load_dword v6, v[6:7], off
	v_or_b32_e32 v10, 14, v34
	global_load_dword v5, v[8:9], off
	v_or_b32_e32 v8, 12, v34
	v_ashrrev_i32_e32 v9, 31, v8
	v_ashrrev_i32_e32 v11, 31, v10
	v_lshlrev_b64 v[8:9], 12, v[8:9]
	v_lshlrev_b64 v[10:11], 12, v[10:11]
	v_lshl_add_u64 v[8:9], v[36:37], 0, v[8:9]
	v_lshl_add_u64 v[10:11], v[36:37], 0, v[10:11]
	global_load_dword v8, v[8:9], off
	v_or_b32_e32 v12, 18, v34
	global_load_dword v7, v[10:11], off
	v_or_b32_e32 v10, 16, v34
	v_ashrrev_i32_e32 v11, 31, v10
	v_ashrrev_i32_e32 v13, 31, v12
	v_lshlrev_b64 v[10:11], 12, v[10:11]
	v_lshlrev_b64 v[12:13], 12, v[12:13]
	v_lshl_add_u64 v[10:11], v[36:37], 0, v[10:11]
	v_lshl_add_u64 v[12:13], v[36:37], 0, v[12:13]
	global_load_dword v10, v[10:11], off
	v_or_b32_e32 v14, 22, v34
	global_load_dword v9, v[12:13], off
	v_or_b32_e32 v12, 20, v34
	v_ashrrev_i32_e32 v13, 31, v12
	v_ashrrev_i32_e32 v15, 31, v14
	v_lshlrev_b64 v[12:13], 12, v[12:13]
	v_lshlrev_b64 v[14:15], 12, v[14:15]
	v_lshl_add_u64 v[12:13], v[36:37], 0, v[12:13]
	v_lshl_add_u64 v[14:15], v[36:37], 0, v[14:15]
	global_load_dword v12, v[12:13], off
	v_or_b32_e32 v16, 26, v34
	global_load_dword v11, v[14:15], off
	v_or_b32_e32 v14, 24, v34
	v_ashrrev_i32_e32 v15, 31, v14
	v_ashrrev_i32_e32 v17, 31, v16
	v_lshlrev_b64 v[14:15], 12, v[14:15]
	v_lshlrev_b64 v[16:17], 12, v[16:17]
	v_lshl_add_u64 v[14:15], v[36:37], 0, v[14:15]
	v_lshl_add_u64 v[16:17], v[36:37], 0, v[16:17]
	global_load_dword v14, v[14:15], off
	v_or_b32_e32 v18, 30, v34
	global_load_dword v13, v[16:17], off
	v_or_b32_e32 v16, 28, v34
	v_ashrrev_i32_e32 v17, 31, v16
	v_ashrrev_i32_e32 v19, 31, v18
	v_lshlrev_b64 v[16:17], 12, v[16:17]
	v_lshlrev_b64 v[18:19], 12, v[18:19]
	v_lshl_add_u64 v[16:17], v[36:37], 0, v[16:17]
	v_lshl_add_u64 v[18:19], v[36:37], 0, v[18:19]
	global_load_dword v16, v[16:17], off
	v_or_b32_e32 v20, 34, v34
	global_load_dword v15, v[18:19], off
	v_or_b32_e32 v18, 32, v34
	v_ashrrev_i32_e32 v19, 31, v18
	v_ashrrev_i32_e32 v21, 31, v20
	v_lshlrev_b64 v[18:19], 12, v[18:19]
	v_lshlrev_b64 v[20:21], 12, v[20:21]
	v_lshl_add_u64 v[18:19], v[36:37], 0, v[18:19]
	v_lshl_add_u64 v[20:21], v[36:37], 0, v[20:21]
	global_load_dword v18, v[18:19], off
	v_or_b32_e32 v22, 38, v34
	global_load_dword v17, v[20:21], off
	v_or_b32_e32 v20, 36, v34
	v_ashrrev_i32_e32 v21, 31, v20
	v_ashrrev_i32_e32 v23, 31, v22
	v_lshlrev_b64 v[20:21], 12, v[20:21]
	v_lshlrev_b64 v[22:23], 12, v[22:23]
	v_lshl_add_u64 v[20:21], v[36:37], 0, v[20:21]
	v_lshl_add_u64 v[22:23], v[36:37], 0, v[22:23]
	global_load_dword v20, v[20:21], off
	v_or_b32_e32 v24, 42, v34
	global_load_dword v19, v[22:23], off
	v_or_b32_e32 v22, 40, v34
	v_ashrrev_i32_e32 v23, 31, v22
	v_ashrrev_i32_e32 v25, 31, v24
	v_lshlrev_b64 v[22:23], 12, v[22:23]
	v_lshlrev_b64 v[24:25], 12, v[24:25]
	v_lshl_add_u64 v[22:23], v[36:37], 0, v[22:23]
	v_lshl_add_u64 v[24:25], v[36:37], 0, v[24:25]
	global_load_dword v22, v[22:23], off
	v_or_b32_e32 v26, 46, v34
	global_load_dword v21, v[24:25], off
	v_or_b32_e32 v24, 44, v34
	v_ashrrev_i32_e32 v25, 31, v24
	v_ashrrev_i32_e32 v27, 31, v26
	v_lshlrev_b64 v[24:25], 12, v[24:25]
	v_lshlrev_b64 v[26:27], 12, v[26:27]
	v_lshl_add_u64 v[24:25], v[36:37], 0, v[24:25]
	v_lshl_add_u64 v[26:27], v[36:37], 0, v[26:27]
	global_load_dword v24, v[24:25], off
	v_or_b32_e32 v28, 50, v34
	global_load_dword v23, v[26:27], off
	v_or_b32_e32 v26, 48, v34
	v_ashrrev_i32_e32 v27, 31, v26
	v_ashrrev_i32_e32 v29, 31, v28
	v_lshlrev_b64 v[26:27], 12, v[26:27]
	v_lshlrev_b64 v[28:29], 12, v[28:29]
	v_lshl_add_u64 v[26:27], v[36:37], 0, v[26:27]
	v_lshl_add_u64 v[28:29], v[36:37], 0, v[28:29]
	global_load_dword v26, v[26:27], off
	v_or_b32_e32 v30, 54, v34
	global_load_dword v25, v[28:29], off
	v_or_b32_e32 v28, 52, v34
	v_ashrrev_i32_e32 v29, 31, v28
	v_ashrrev_i32_e32 v31, 31, v30
	v_lshlrev_b64 v[28:29], 12, v[28:29]
	v_lshlrev_b64 v[30:31], 12, v[30:31]
	v_lshl_add_u64 v[28:29], v[36:37], 0, v[28:29]
	v_lshl_add_u64 v[30:31], v[36:37], 0, v[30:31]
	global_load_dword v28, v[28:29], off
	v_or_b32_e32 v32, 58, v34
	global_load_dword v27, v[30:31], off
	v_or_b32_e32 v30, 56, v34
	v_ashrrev_i32_e32 v31, 31, v30
	v_ashrrev_i32_e32 v33, 31, v32
	v_lshlrev_b64 v[30:31], 12, v[30:31]
	v_lshlrev_b64 v[32:33], 12, v[32:33]
	v_lshl_add_u64 v[30:31], v[36:37], 0, v[30:31]
	v_lshl_add_u64 v[32:33], v[36:37], 0, v[32:33]
	global_load_dword v30, v[30:31], off
	v_lshlrev_b32_e32 v38, 2, v43
	global_load_dword v29, v[32:33], off
	v_or_b32_e32 v32, 60, v34
	v_or_b32_e32 v34, 62, v34
	v_ashrrev_i32_e32 v33, 31, v32
	v_ashrrev_i32_e32 v35, 31, v34
	v_lshlrev_b64 v[32:33], 12, v[32:33]
	v_lshlrev_b64 v[34:35], 12, v[34:35]
	v_lshl_add_u64 v[32:33], v[36:37], 0, v[32:33]
	v_lshl_add_u64 v[34:35], v[36:37], 0, v[34:35]
	global_load_dword v32, v[32:33], off
	v_lshlrev_b32_e32 v36, 1, v44
	global_load_dword v31, v[34:35], off
	v_mov_b32_e32 v37, v151
	v_lshl_add_u64 v[36:37], s[4:5], 0, v[36:37]
	s_mov_b64 s[4:5], 0x2a00000
	v_lshl_add_u64 v[36:37], v[36:37], 0, s[4:5]
	v_readlane_b32 s4, v254, 48
	v_lshl_add_u64 v[34:35], s[6:7], 0, v[150:151]
	v_mul_u32_u24_e32 v33, 0x84, v44
	s_lshl_b32 s6, s4, 5
	v_add3_u32 v33, s8, v33, v38
	v_add3_u32 v44, s8, v45, v150
	s_lshl_b32 s1, s0, 5
	s_mov_b32 s7, s6
	v_readlane_b32 s5, v254, 49
	s_branch .LBB0_2551

; __device__ __forceinline__ unsigned xb_add(unsigned* p, unsigned v) { return __hip_atomic_fetch_add(p, v, __ATOMIC_RELAXED, __HIP_MEMORY_SCOPE_AGENT); }
; __device__ __forceinline__ void xcd_barrier(const XcdBarrier& b) {
;     asm volatile("s_waitcnt vmcnt(0)" ::: "memory");
;     __syncthreads();
;     if (threadIdx.x == 0) {
;         unsigned* bar = b.bar;
;         __builtin_amdgcn_s_waitcnt(0);
;         unsigned nloc = b.st[0], nx = b.st[1];
;         if (nloc == 0u) { xcd_barrier_complete(bar, b.x, nloc, nx); b.st[0] = nloc; b.st[1] = nx; }
;         const unsigned old = xb_add(&bar[XB_XSUB(b.x)], 1u);
.LBB0_2553:
	v_readlane_b32 s0, v254, 4
	v_readlane_b32 s4, v254, 20
	s_cmp_lg_u32 s0, -1
	v_readlane_b32 s5, v254, 21
	s_cselect_b32 s0, s0, 0
	s_cselect_b32 s1, s5, 0
	s_waitcnt vmcnt(0) lgkmcnt(0)
	s_waitcnt vmcnt(35)
	v_mov_b32_e32 v2, s0
	s_waitcnt vmcnt(32)
	v_mov_b32_e32 v3, s1
	ds_read_b64 v[2:3], v2
	s_waitcnt lgkmcnt(0)
	s_getreg_b32 s6, hwreg(HW_REG_XCC_ID, 0, 4)
	s_waitcnt vmcnt(0)
	s_waitcnt lgkmcnt(0)
	s_barrier
	v_readfirstlane_b32 s5, v3
	v_readfirstlane_b32 s4, v2
	s_mov_b64 s[0:1], exec
	v_readlane_b32 s8, v254, 1
	v_readlane_b32 s9, v254, 2
	s_and_b64 s[8:9], s[0:1], s[8:9]
	s_mov_b64 exec, s[8:9]
	s_cbranch_execz .LBB0_2605
	v_readlane_b32 s7, v254, 54
	s_waitcnt vmcnt(0) expcnt(0) lgkmcnt(0)
	s_and_b32 s28, s6, 15
	v_mov_b32_e32 v1, s7
	ds_read_b32 v3, v1
	v_readlane_b32 s7, v254, 55
	s_waitcnt lgkmcnt(0)
	v_cmp_ne_u32_e32 vcc, 0, v3
	v_mov_b32_e32 v1, s7
	ds_read_b32 v2, v1
	s_cbranch_vccnz .LBB0_2569
	v_readlane_b32 s6, v254, 5
	v_readlane_b32 s7, v254, 6
	s_load_dwordx2 s[10:11], s[6:7], 0x4
	s_add_u32 s6, s4, 0x1000
	s_addc_u32 s7, s5, 0
	s_add_u32 s8, s4, 0x1100
	s_addc_u32 s9, s5, 0
	v_readlane_b32 s16, v254, 7
	s_waitcnt lgkmcnt(0)
	s_mul_i32 s29, s10, s16
	s_add_u32 s10, s4, 0x1200
	s_mul_i32 s29, s29, s11
	s_addc_u32 s11, s5, 0
	s_add_u32 s16, s4, 0x1300
	s_addc_u32 s17, s5, 0
	s_mov_b32 s30, 1
	s_branch .LBB0_2557

; #define LAS __attribute__((address_space(3)))
;     __host__ __device__ bool next(int i, Unit& u) const {
;         const long L = (long)i * G + c; if (L >= nwg) return false;
;         int wgid = (int)L; { const int q = nwg / NXCD, r = nwg % NXCD, xcd = wgid % NXCD, off = wgid / NXCD; wgid = (xcd < r ? xcd * (q + 1) : r * (q + 1) + (xcd - r) * q) + off; }
;         const int nig = WGM * nN, gid = wgid / nig, fm = gid * WGM, gsz = (nM - fm) < WGM ? (nM - fm) : WGM;
;         u.pm = fm + ((wgid % nig) % gsz); u.pn = (wgid % nig) / gsz; return true;
; template <int ID, class E> __device__ __forceinline__ void run_gemm(LAS unsigned char* lds, const bf16* A, const bf16* Bt, int M, int N, int K, const E& e) {
;     asm volatile("" : "+s"(K)); asm volatile("" : "+s"(N));
;     pg8::Gemm g{A, Bt, M, N, K}; pg8::StaticOrder S; S.init(M, N, (int)gridDim.x, (int)blockIdx.x);
.LBB0_2610:
	v_readlane_b32 s0, v254, 4
	v_readlane_b32 s4, v254, 20
	s_cmp_lg_u32 s0, -1
	v_readlane_b32 s5, v254, 21
	s_cselect_b32 s0, s0, 0
	s_cselect_b32 s1, s5, 0
	v_mov_b64_e32 v[2:3], s[0:1]
	ds_read_b64 v[4:5], v2
	s_waitcnt lgkmcnt(0)
	s_movk_i32 s0, 0x400
	ds_read_b64 v[2:3], v2
	s_waitcnt lgkmcnt(0)
	s_movk_i32 s5, 0xb00
	s_ashr_i32 s8, s5, 31
	s_lshr_b32 s8, s8, 24
	s_add_i32 s5, s5, s8
	s_ashr_i32 s5, s5, 8
	s_lshl_b32 s16, s5, 6
	v_readlane_b32 s8, v254, 0
	v_readfirstlane_b32 s17, v147
	s_cmp_ge_i32 s8, s16
	s_waitcnt lgkmcnt(0)
	v_readfirstlane_b32 s1, v5
	v_readfirstlane_b32 s4, v4
	v_readfirstlane_b32 s6, v3
	v_readfirstlane_b32 s7, v2
	s_cbranch_scc0 .LBB0_2612
	s_add_i32 s53, s53, 1
	s_cmp_ge_i32 s53, s52
	s_cbranch_scc1 .LBB0_2609
	s_branch .LBB0_2632

; __device__ __forceinline__ f32x2 gelu_pk(f32x2 v) {
;     const f32x2 av = __builtin_elementwise_abs(v), d = av * 0.2316418882f + 1.0f;
;     f32x2 t; t.x = __builtin_amdgcn_rcpf(d.x); t.y = __builtin_amdgcn_rcpf(d.y);
;     f32x2 q = t * 0.5307027145f + (-0.7265760135f); q = q * t + 0.7107068705f; q = q * t + (-0.142248368f); q = q * t + 0.127414796f; q = q * t;
;     const f32x2 s = (v * v) * (-0.72134752044f);
;     f32x2 e; e.x = __builtin_amdgcn_exp2f(s.x); e.y = __builtin_amdgcn_exp2f(s.y);
;     const f32x2 m = v * (q * e), r = v - m;
;     f32x2 o; o.x = v.x < 0.f ? m.x : r.x; o.y = v.y < 0.f ? m.y : r.y; return o;
.LBB0_2628:
	v_readlane_b32 s0, v254, 4
	v_readlane_b32 s6, v254, 20
	s_cmp_lg_u32 s0, -1
	v_readlane_b32 s7, v254, 21
	s_cselect_b32 s0, s0, 0
	s_cselect_b32 s1, s7, 0
	v_mov_b32_e32 v106, s0
	v_mov_b32_e32 v107, s1
	ds_read_b64 v[106:107], v106
	s_waitcnt lgkmcnt(0)
	s_mul_i32 s6, s88, 0x8400
	s_mul_i32 s33, s88, 0x2c00
	v_lshl_or_b32 v164, s11, 8, v214
	v_lshl_add_u32 v176, s10, 8, v1
	v_ashrrev_i32_e32 v165, 31, v164
	v_lshlrev_b64 v[118:119], 2, v[164:165]
	v_lshlrev_b64 v[162:163], 1, v[164:165]
	v_and_b32_e32 v165, 0x1fcf, v176
	v_cmp_lt_u32_e32 vcc, 1, v165
	v_ashrrev_i32_e32 v177, 31, v176
	v_cmp_gt_u32_e64 s[10:11], 2, v165
	v_cndmask_b32_e64 v189, 0, -1, vcc
	v_cndmask_b32_e32 v188, 0, v213, vcc
	s_mov_b32 s20, 0x3e027906
	s_waitcnt lgkmcnt(0)
	v_readfirstlane_b32 s9, v106
	v_readfirstlane_b32 s8, v107
	s_add_u32 s48, s9, 0x4c00000
	s_addc_u32 s49, s8, 0
	s_add_u32 s46, s9, 0xa400000
	s_addc_u32 s47, s8, 0
	s_add_i32 s0, 0, 0x20030
	s_cmp_lg_u32 s0, -1
	s_cselect_b32 s0, s0, 0
	s_cselect_b32 s1, s7, 0
	v_mov_b32_e32 v106, s0
	v_mov_b32_e32 v107, s1
	ds_read_b64 v[106:107], v106
	s_waitcnt lgkmcnt(0)
	v_lshl_add_u64 v[190:191], s[48:49], 0, v[162:163]
	v_lshl_add_u64 v[186:187], s[46:47], 0, v[162:163]
	s_waitcnt lgkmcnt(0)
	v_readfirstlane_b32 s0, v106
	v_readfirstlane_b32 s1, v107
	s_add_u32 s0, s0, s6
	s_mul_hi_u32 s6, s88, 0x8400
	s_addc_u32 s1, s1, s6
	s_add_i32 s6, 0, 0x20038
	s_cmp_lg_u32 s6, -1
	s_cselect_b32 s6, s6, 0
	s_cselect_b32 s7, s7, 0
	v_mov_b32_e32 v106, s6
	v_mov_b32_e32 v107, s7
	ds_read_b64 v[106:107], v106
	s_waitcnt lgkmcnt(0)
	v_lshl_add_u64 v[166:167], s[0:1], 0, v[118:119]
	s_waitcnt lgkmcnt(0)
	v_readfirstlane_b32 s6, v106
	v_readfirstlane_b32 s7, v107
	s_add_u32 s6, s6, s33
	s_mul_hi_u32 s33, s88, 0x2c00
	s_addc_u32 s7, s7, s33
	s_add_u32 s38, s0, 0x2c00
	s_addc_u32 s39, s1, 0
	s_add_u32 s44, s0, 0x5800
	v_lshl_add_u64 v[168:169], s[6:7], 0, v[118:119]
	s_movk_i32 s33, 0x1600
	v_cmp_eq_u32_e64 s[6:7], 0, v165
	s_addc_u32 s45, s1, 0
	v_mad_i64_i32 v[162:163], s[0:1], v176, s33, v[190:191]
	v_cndmask_b32_e64 v185, -1, 0, s[6:7]
	v_cndmask_b32_e64 v184, v212, 0, s[6:7]
	global_load_dwordx2 v[170:171], v[162:163], off
	v_lshl_add_u64 v[172:173], v[162:163], 0, v[184:185]
	v_lshl_add_u64 v[162:163], v[162:163], 0, v[188:189]
	s_add_u32 s50, s9, 0x15800040
	global_load_dwordx2 v[172:173], v[172:173], off
	s_addc_u32 s51, s8, 0
	global_load_dwordx2 v[174:175], v[162:163], off
	v_lshlrev_b64 v[162:163], 7, v[176:177]
	global_load_dwordx4 v[106:109], v[166:167], off
	v_lshl_add_u64 v[110:111], s[38:39], 0, v[118:119]
	v_lshl_add_u64 v[162:163], s[50:51], 0, v[162:163]
	global_load_dwordx4 v[110:113], v[110:111], off
	v_lshl_add_u64 v[114:115], s[44:45], 0, v[118:119]
	global_load_dword v178, v[162:163], off
	global_load_dwordx4 v[118:121], v[168:169], off
	s_mov_b32 s0, 0xbf3a00e3
	global_load_dwordx4 v[114:117], v[114:115], off
	s_waitcnt vmcnt(6)
	v_lshlrev_b32_e32 v180, 16, v173
	v_and_b32_e32 v181, 0xffff0000, v173
	s_waitcnt vmcnt(5)
	v_lshlrev_b32_e32 v182, 16, v174
	v_and_b32_e32 v183, 0xffff0000, v174
	v_lshlrev_b32_e32 v177, 16, v172
	v_and_b32_e32 v172, 0xffff0000, v172
	v_lshlrev_b32_e32 v192, 16, v175
	v_and_b32_e32 v193, 0xffff0000, v175
	v_cndmask_b32_e64 v175, v181, 0, s[6:7]
	v_cndmask_b32_e64 v174, v180, 0, s[6:7]
	v_cndmask_b32_e64 v181, v183, 0, s[10:11]
	v_cndmask_b32_e64 v180, v182, 0, s[10:11]
	v_cndmask_b32_e64 v173, v172, 0, s[6:7]
	v_cndmask_b32_e64 v172, v177, 0, s[6:7]
	s_waitcnt vmcnt(4)
	v_pk_mul_f32 v[180:181], v[106:107], v[180:181]
	s_waitcnt vmcnt(2)
	v_pk_mul_f32 v[144:145], v[144:145], v[178:179] op_sel_hi:[1,0]
	v_pk_mul_f32 v[178:179], v[142:143], v[178:179] op_sel_hi:[1,0]
	v_lshlrev_b32_e32 v142, 16, v170
	v_and_b32_e32 v143, 0xffff0000, v170
	v_pk_fma_f32 v[172:173], v[110:111], v[172:173], v[180:181]
	v_cndmask_b32_e64 v183, v193, 0, s[10:11]
	s_waitcnt vmcnt(0)
	v_pk_fma_f32 v[142:143], v[114:115], v[142:143], v[172:173]
	v_cndmask_b32_e64 v182, v192, 0, s[10:11]
	v_pk_add_f32 v[172:173], v[118:119], v[142:143]
	v_pk_mul_f32 v[182:183], v[108:109], v[182:183]
	v_and_b32_e32 v143, 0x7fffffff, v173
	v_and_b32_e32 v142, 0x7fffffff, v172
	v_lshlrev_b32_e32 v170, 16, v171
	v_and_b32_e32 v171, 0xffff0000, v171
	v_pk_fma_f32 v[174:175], v[112:113], v[174:175], v[182:183]
	v_pk_fma_f32 v[142:143], v[142:143], s[2:3], 1.0 op_sel_hi:[1,0,0]
	v_pk_fma_f32 v[170:171], v[116:117], v[170:171], v[174:175]
	v_rcp_f32_e32 v174, v142
	v_rcp_f32_e32 v175, v143
	v_mov_b64_e32 v[142:143], s[0:1]
	v_pk_mul_f32 v[182:183], v[172:173], v[172:173]
	v_pk_add_f32 v[170:171], v[120:121], v[170:171]
	v_pk_fma_f32 v[180:181], v[174:175], s[42:43], v[142:143] op_sel_hi:[1,0,0]
	v_pk_mul_f32 v[182:183], v[182:183], s[22:23] op_sel_hi:[1,0]
	v_pk_fma_f32 v[180:181], v[174:175], v[180:181], s[40:41] op_sel_hi:[1,1,0]
	v_exp_f32_e32 v182, v182
	v_exp_f32_e32 v183, v183
	v_pk_fma_f32 v[180:181], v[174:175], v[180:181], s[92:93] op_sel_hi:[1,1,0]
	v_cmp_gt_f32_e32 vcc, 0, v172
	v_pk_fma_f32 v[180:181], v[174:175], v[180:181], s[20:21] op_sel_hi:[1,1,0]
	s_nop 0
	v_pk_mul_f32 v[174:175], v[174:175], v[180:181]
	v_pk_mul_f32 v[180:181], v[170:171], v[170:171]
	v_pk_mul_f32 v[174:175], v[182:183], v[174:175]
	s_nop 0
	v_pk_mul_f32 v[182:183], v[172:173], v[174:175]
	v_pk_fma_f32 v[174:175], v[172:173], v[174:175], v[172:173] neg_lo:[1,0,0] neg_hi:[1,0,0]
	v_and_b32_e32 v172, 0x7fffffff, v170
	v_cndmask_b32_e32 v165, v174, v182, vcc
	v_cmp_gt_f32_e32 vcc, 0, v173
	v_and_b32_e32 v173, 0x7fffffff, v171
	v_pk_fma_f32 v[172:173], v[172:173], s[2:3], 1.0 op_sel_hi:[1,0,0]
	v_cndmask_b32_e32 v177, v175, v183, vcc
; __device__ __forceinline__ f32x2 gelu_pk(f32x2 v) {
;     const f32x2 av = __builtin_elementwise_abs(v), d = av * 0.2316418882f + 1.0f;
;     f32x2 t; t.x = __builtin_amdgcn_rcpf(d.x); t.y = __builtin_amdgcn_rcpf(d.y);
;     f32x2 q = t * 0.5307027145f + (-0.7265760135f); q = q * t + 0.7107068705f; q = q * t + (-0.142248368f); q = q * t + 0.127414796f; q = q * t;
;     const f32x2 s = (v * v) * (-0.72134752044f);
;     f32x2 e; e.x = __builtin_amdgcn_exp2f(s.x); e.y = __builtin_amdgcn_exp2f(s.y);
;     const f32x2 m = v * (q * e), r = v - m;
;     f32x2 o; o.x = v.x < 0.f ? m.x : r.x; o.y = v.y < 0.f ? m.y : r.y; return o;
	v_rcp_f32_e32 v172, v172
	v_rcp_f32_e32 v173, v173
	v_cmp_gt_f32_e32 vcc, 0, v170
	v_mul_f32_e32 v165, v178, v165
	v_pk_fma_f32 v[174:175], v[172:173], s[42:43], v[142:143] op_sel_hi:[1,0,0]
	s_nop 0
	v_pk_fma_f32 v[174:175], v[172:173], v[174:175], s[40:41] op_sel_hi:[1,1,0]
	s_movk_i32 s41, 0xf000
	v_pk_fma_f32 v[174:175], v[172:173], v[174:175], s[92:93] op_sel_hi:[1,1,0]
	s_movk_i32 s43, 0xe000
	v_pk_fma_f32 v[174:175], v[172:173], v[174:175], s[20:21] op_sel_hi:[1,1,0]
	s_nop 0
	v_pk_mul_f32 v[172:173], v[172:173], v[174:175]
	v_pk_mul_f32 v[174:175], v[180:181], s[22:23] op_sel_hi:[1,0]
	s_nop 0
	v_exp_f32_e32 v174, v174
	v_exp_f32_e32 v175, v175
	s_nop 0
	v_pk_mul_f32 v[172:173], v[174:175], v[172:173]
	s_nop 0
	v_pk_mul_f32 v[174:175], v[170:171], v[172:173]
	v_pk_fma_f32 v[172:173], v[170:171], v[172:173], v[170:171] neg_lo:[1,0,0] neg_hi:[1,0,0]
	v_mul_f32_e32 v170, v179, v177
	v_cndmask_b32_e32 v172, v172, v174, vcc
	v_cmp_gt_f32_e32 vcc, 0, v171
	v_mul_f32_e32 v144, v144, v172
	v_cvt_pk_bf16_f32 v170, v165, v170
	s_nop 0
	v_cndmask_b32_e32 v171, v173, v175, vcc
	v_mul_f32_e32 v145, v145, v171
	v_cvt_pk_bf16_f32 v171, v144, v145
	v_mad_i64_i32 v[144:145], s[0:1], v176, s33, v[186:187]
	global_store_dwordx2 v[144:145], v[170:171], off
	v_or_b32_e32 v170, 16, v176
	v_mad_i64_i32 v[144:145], s[0:1], v170, s33, v[190:191]
	v_add_co_u32_e32 v174, vcc, s41, v144
	global_load_dwordx2 v[172:173], v[144:145], off
	s_nop 0
	v_addc_co_u32_e32 v175, vcc, -1, v145, vcc
	v_add_co_u32_e32 v144, vcc, s43, v144
	v_ashrrev_i32_e32 v171, 31, v170
	s_nop 0
	v_addc_co_u32_e32 v145, vcc, -1, v145, vcc
	global_load_dwordx2 v[174:175], v[174:175], off offset:-1536
	s_nop 0
	global_load_dwordx2 v[178:179], v[144:145], off offset:-3072
	v_lshlrev_b64 v[144:145], 7, v[170:171]
	v_lshl_add_u64 v[144:145], s[50:51], 0, v[144:145]
	global_load_dword v180, v[144:145], off
	s_waitcnt vmcnt(2)
	v_lshlrev_b32_e32 v182, 16, v174
	v_and_b32_e32 v183, 0xffff0000, v174
	s_waitcnt vmcnt(1)
	v_lshlrev_b32_e32 v192, 16, v178
	v_and_b32_e32 v193, 0xffff0000, v178
	v_lshlrev_b32_e32 v178, 16, v179
	v_and_b32_e32 v179, 0xffff0000, v179
	v_lshlrev_b32_e32 v174, 16, v175
	v_and_b32_e32 v175, 0xffff0000, v175
	v_pk_mul_f32 v[192:193], v[106:107], v[192:193]
	v_pk_mul_f32 v[178:179], v[108:109], v[178:179]
	s_waitcnt vmcnt(0)
	v_pk_mul_f32 v[140:141], v[140:141], v[180:181] op_sel_hi:[1,0]
	v_pk_mul_f32 v[138:139], v[138:139], v[180:181] op_sel_hi:[1,0]
	v_lshlrev_b32_e32 v180, 16, v172
	v_and_b32_e32 v181, 0xffff0000, v172
	v_pk_fma_f32 v[174:175], v[112:113], v[174:175], v[178:179]
	v_pk_fma_f32 v[178:179], v[110:111], v[182:183], v[192:193]
	v_lshlrev_b32_e32 v172, 16, v173
	v_and_b32_e32 v173, 0xffff0000, v173
	v_pk_fma_f32 v[178:179], v[114:115], v[180:181], v[178:179]
	v_pk_fma_f32 v[172:173], v[116:117], v[172:173], v[174:175]
	v_pk_add_f32 v[174:175], v[118:119], v[178:179]
	v_pk_add_f32 v[172:173], v[120:121], v[172:173]
	v_and_b32_e32 v179, 0x7fffffff, v175
	v_and_b32_e32 v178, 0x7fffffff, v174
	v_pk_fma_f32 v[178:179], v[178:179], s[2:3], 1.0 op_sel_hi:[1,0,0]
	v_pk_mul_f32 v[182:183], v[174:175], v[174:175]
	v_rcp_f32_e32 v178, v178
	v_rcp_f32_e32 v179, v179
	v_pk_mul_f32 v[182:183], v[182:183], s[22:23] op_sel_hi:[1,0]
	v_cmp_gt_f32_e32 vcc, 0, v174
	v_exp_f32_e32 v182, v182
	v_pk_fma_f32 v[180:181], v[178:179], s[42:43], v[142:143] op_sel_hi:[1,0,0]
	v_exp_f32_e32 v183, v183
	v_pk_fma_f32 v[180:181], v[178:179], v[180:181], s[40:41] op_sel_hi:[1,1,0]
	s_nop 0
	v_pk_fma_f32 v[180:181], v[178:179], v[180:181], s[92:93] op_sel_hi:[1,1,0]
	s_nop 0
	v_pk_fma_f32 v[180:181], v[178:179], v[180:181], s[20:21] op_sel_hi:[1,1,0]
	s_nop 0
	v_pk_mul_f32 v[178:179], v[178:179], v[180:181]
	v_pk_mul_f32 v[180:181], v[172:173], v[172:173]
	v_pk_mul_f32 v[178:179], v[182:183], v[178:179]
	s_nop 0
	v_pk_mul_f32 v[182:183], v[174:175], v[178:179]
	v_pk_fma_f32 v[178:179], v[174:175], v[178:179], v[174:175] neg_lo:[1,0,0] neg_hi:[1,0,0]
	v_and_b32_e32 v174, 0x7fffffff, v172
	v_cndmask_b32_e32 v165, v178, v182, vcc
	v_cmp_gt_f32_e32 vcc, 0, v175
	v_and_b32_e32 v175, 0x7fffffff, v173
	v_pk_fma_f32 v[174:175], v[174:175], s[2:3], 1.0 op_sel_hi:[1,0,0]
	v_cndmask_b32_e32 v171, v179, v183, vcc
	v_rcp_f32_e32 v174, v174
	v_rcp_f32_e32 v175, v175
	v_cmp_gt_f32_e32 vcc, 0, v172
	v_mul_f32_e32 v138, v138, v165
	v_mul_f32_e32 v139, v139, v171
	v_pk_fma_f32 v[178:179], v[174:175], s[42:43], v[142:143] op_sel_hi:[1,0,0]
	v_cvt_pk_bf16_f32 v138, v138, v139
	s_nop 0
	v_pk_fma_f32 v[178:179], v[174:175], v[178:179], s[40:41] op_sel_hi:[1,1,0]
	s_nop 0
	v_pk_fma_f32 v[178:179], v[174:175], v[178:179], s[92:93] op_sel_hi:[1,1,0]
	s_nop 0
	v_pk_fma_f32 v[178:179], v[174:175], v[178:179], s[20:21] op_sel_hi:[1,1,0]
	s_nop 0
	v_pk_mul_f32 v[174:175], v[174:175], v[178:179]
	v_pk_mul_f32 v[178:179], v[180:181], s[22:23] op_sel_hi:[1,0]
	s_nop 0
	v_exp_f32_e32 v178, v178
	v_exp_f32_e32 v179, v179
	s_nop 0
	v_pk_mul_f32 v[174:175], v[178:179], v[174:175]
	s_nop 0
	v_pk_mul_f32 v[178:179], v[172:173], v[174:175]
	v_pk_fma_f32 v[174:175], v[172:173], v[174:175], v[172:173] neg_lo:[1,0,0] neg_hi:[1,0,0]
	s_nop 0
	v_cndmask_b32_e32 v172, v174, v178, vcc
	v_cmp_gt_f32_e32 vcc, 0, v173
	v_mul_f32_e32 v139, v140, v172
	v_or_b32_e32 v174, 32, v176
	v_cndmask_b32_e32 v173, v175, v179, vcc
	v_mul_f32_e32 v140, v141, v173
	v_cvt_pk_bf16_f32 v139, v139, v140
	v_mad_i64_i32 v[140:141], s[0:1], v170, s33, v[186:187]
	global_store_dwordx2 v[140:141], v[138:139], off
	v_mad_i64_i32 v[138:139], s[0:1], v174, s33, v[190:191]
	v_add_co_u32_e32 v172, vcc, s41, v138
	global_load_dwordx2 v[140:141], v[138:139], off
	s_nop 0
	v_addc_co_u32_e32 v173, vcc, -1, v139, vcc
	v_add_co_u32_e32 v138, vcc, s43, v138
	v_ashrrev_i32_e32 v175, 31, v174
	s_nop 0
	v_addc_co_u32_e32 v139, vcc, -1, v139, vcc
	global_load_dwordx2 v[172:173], v[172:173], off offset:-1536
	s_nop 0
	global_load_dwordx2 v[178:179], v[138:139], off offset:-3072
	v_lshlrev_b64 v[138:139], 7, v[174:175]
	v_lshl_add_u64 v[138:139], s[50:51], 0, v[138:139]
	global_load_dword v180, v[138:139], off
	s_waitcnt vmcnt(2)
; __device__ __forceinline__ f32x2 gelu_pk(f32x2 v) {
;     const f32x2 av = __builtin_elementwise_abs(v), d = av * 0.2316418882f + 1.0f;
;     f32x2 t; t.x = __builtin_amdgcn_rcpf(d.x); t.y = __builtin_amdgcn_rcpf(d.y);
;     f32x2 q = t * 0.5307027145f + (-0.7265760135f); q = q * t + 0.7107068705f; q = q * t + (-0.142248368f); q = q * t + 0.127414796f; q = q * t;
;     const f32x2 s = (v * v) * (-0.72134752044f);
;     f32x2 e; e.x = __builtin_amdgcn_exp2f(s.x); e.y = __builtin_amdgcn_exp2f(s.y);
;     const f32x2 m = v * (q * e), r = v - m;
;     f32x2 o; o.x = v.x < 0.f ? m.x : r.x; o.y = v.y < 0.f ? m.y : r.y; return o;
	v_lshlrev_b32_e32 v182, 16, v172
	v_and_b32_e32 v183, 0xffff0000, v172
	s_waitcnt vmcnt(1)
	v_lshlrev_b32_e32 v192, 16, v178
	v_and_b32_e32 v193, 0xffff0000, v178
	v_lshlrev_b32_e32 v178, 16, v179
	v_and_b32_e32 v179, 0xffff0000, v179
	v_lshlrev_b32_e32 v172, 16, v173
	v_and_b32_e32 v173, 0xffff0000, v173
	v_pk_mul_f32 v[192:193], v[106:107], v[192:193]
	v_pk_mul_f32 v[178:179], v[108:109], v[178:179]
	s_waitcnt vmcnt(0)
	v_pk_mul_f32 v[136:137], v[136:137], v[180:181] op_sel_hi:[1,0]
	v_pk_mul_f32 v[134:135], v[134:135], v[180:181] op_sel_hi:[1,0]
	v_lshlrev_b32_e32 v180, 16, v140
	v_and_b32_e32 v181, 0xffff0000, v140
	v_pk_fma_f32 v[172:173], v[112:113], v[172:173], v[178:179]
	v_pk_fma_f32 v[178:179], v[110:111], v[182:183], v[192:193]
	v_lshlrev_b32_e32 v140, 16, v141
	v_and_b32_e32 v141, 0xffff0000, v141
	v_pk_fma_f32 v[178:179], v[114:115], v[180:181], v[178:179]
	v_pk_fma_f32 v[140:141], v[116:117], v[140:141], v[172:173]
	v_pk_add_f32 v[172:173], v[118:119], v[178:179]
	v_pk_add_f32 v[140:141], v[120:121], v[140:141]
	v_and_b32_e32 v179, 0x7fffffff, v173
	v_and_b32_e32 v178, 0x7fffffff, v172
	v_pk_fma_f32 v[178:179], v[178:179], s[2:3], 1.0 op_sel_hi:[1,0,0]
	v_pk_mul_f32 v[182:183], v[172:173], v[172:173]
	v_rcp_f32_e32 v178, v178
	v_rcp_f32_e32 v179, v179
	v_pk_mul_f32 v[182:183], v[182:183], s[22:23] op_sel_hi:[1,0]
	v_cmp_gt_f32_e32 vcc, 0, v172
	v_exp_f32_e32 v182, v182
	v_pk_fma_f32 v[180:181], v[178:179], s[42:43], v[142:143] op_sel_hi:[1,0,0]
	v_exp_f32_e32 v183, v183
	v_pk_fma_f32 v[180:181], v[178:179], v[180:181], s[40:41] op_sel_hi:[1,1,0]
	s_nop 0
	v_pk_fma_f32 v[180:181], v[178:179], v[180:181], s[92:93] op_sel_hi:[1,1,0]
	s_nop 0
	v_pk_fma_f32 v[180:181], v[178:179], v[180:181], s[20:21] op_sel_hi:[1,1,0]
	s_nop 0
	v_pk_mul_f32 v[178:179], v[178:179], v[180:181]
	v_pk_mul_f32 v[180:181], v[140:141], v[140:141]
	v_pk_mul_f32 v[178:179], v[182:183], v[178:179]
	s_nop 0
	v_pk_mul_f32 v[182:183], v[172:173], v[178:179]
	v_pk_fma_f32 v[178:179], v[172:173], v[178:179], v[172:173] neg_lo:[1,0,0] neg_hi:[1,0,0]
	v_and_b32_e32 v172, 0x7fffffff, v140
	v_cndmask_b32_e32 v165, v178, v182, vcc
	v_cmp_gt_f32_e32 vcc, 0, v173
	v_and_b32_e32 v173, 0x7fffffff, v141
	v_pk_fma_f32 v[172:173], v[172:173], s[2:3], 1.0 op_sel_hi:[1,0,0]
	v_cndmask_b32_e32 v171, v179, v183, vcc
	v_rcp_f32_e32 v172, v172
	v_rcp_f32_e32 v173, v173
	v_cmp_gt_f32_e32 vcc, 0, v140
	v_mul_f32_e32 v134, v134, v165
	v_mul_f32_e32 v135, v135, v171
	v_pk_fma_f32 v[178:179], v[172:173], s[42:43], v[142:143] op_sel_hi:[1,0,0]
	v_cvt_pk_bf16_f32 v134, v134, v135
	s_nop 0
	v_pk_fma_f32 v[178:179], v[172:173], v[178:179], s[40:41] op_sel_hi:[1,1,0]
	s_nop 0
	v_pk_fma_f32 v[178:179], v[172:173], v[178:179], s[92:93] op_sel_hi:[1,1,0]
	s_nop 0
	v_pk_fma_f32 v[178:179], v[172:173], v[178:179], s[20:21] op_sel_hi:[1,1,0]
	s_nop 0
	v_pk_mul_f32 v[172:173], v[172:173], v[178:179]
	v_pk_mul_f32 v[178:179], v[180:181], s[22:23] op_sel_hi:[1,0]
	s_nop 0
	v_exp_f32_e32 v178, v178
	v_exp_f32_e32 v179, v179
	s_nop 0
	v_pk_mul_f32 v[172:173], v[178:179], v[172:173]
	s_nop 0
	v_pk_mul_f32 v[178:179], v[140:141], v[172:173]
	v_pk_fma_f32 v[172:173], v[140:141], v[172:173], v[140:141] neg_lo:[1,0,0] neg_hi:[1,0,0]
	s_nop 0
	v_cndmask_b32_e32 v140, v172, v178, vcc
	v_cmp_gt_f32_e32 vcc, 0, v141
	v_mul_f32_e32 v135, v136, v140
	s_nop 0
	v_cndmask_b32_e32 v141, v173, v179, vcc
	v_mul_f32_e32 v136, v137, v141
	v_cvt_pk_bf16_f32 v135, v135, v136
	v_mad_i64_i32 v[136:137], s[0:1], v174, s33, v[186:187]
	global_store_dwordx2 v[136:137], v[134:135], off
	v_or_b32_e32 v136, 48, v176
	v_mad_i64_i32 v[134:135], s[0:1], v136, s33, v[190:191]
	v_add_co_u32_e32 v172, vcc, s41, v134
	global_load_dwordx2 v[140:141], v[134:135], off
	s_nop 0
	v_addc_co_u32_e32 v173, vcc, -1, v135, vcc
	v_add_co_u32_e32 v134, vcc, s43, v134
	v_ashrrev_i32_e32 v137, 31, v136
	s_nop 0
	v_addc_co_u32_e32 v135, vcc, -1, v135, vcc
	global_load_dwordx2 v[172:173], v[172:173], off offset:-1536
	s_nop 0
	global_load_dwordx2 v[178:179], v[134:135], off offset:-3072
	v_lshlrev_b64 v[134:135], 7, v[136:137]
	v_lshl_add_u64 v[134:135], s[50:51], 0, v[134:135]
	global_load_dword v180, v[134:135], off
	s_waitcnt vmcnt(2)
	v_lshlrev_b32_e32 v182, 16, v172
	v_and_b32_e32 v183, 0xffff0000, v172
	s_waitcnt vmcnt(1)
	v_lshlrev_b32_e32 v192, 16, v178
	v_and_b32_e32 v193, 0xffff0000, v178
	v_lshlrev_b32_e32 v178, 16, v179
	v_and_b32_e32 v179, 0xffff0000, v179
	v_lshlrev_b32_e32 v172, 16, v173
	v_and_b32_e32 v173, 0xffff0000, v173
	v_pk_mul_f32 v[192:193], v[106:107], v[192:193]
	v_pk_mul_f32 v[178:179], v[108:109], v[178:179]
	s_waitcnt vmcnt(0)
; __device__ __forceinline__ f32x2 gelu_pk(f32x2 v) {
;     const f32x2 av = __builtin_elementwise_abs(v), d = av * 0.2316418882f + 1.0f;
;     f32x2 t; t.x = __builtin_amdgcn_rcpf(d.x); t.y = __builtin_amdgcn_rcpf(d.y);
;     f32x2 q = t * 0.5307027145f + (-0.7265760135f); q = q * t + 0.7107068705f; q = q * t + (-0.142248368f); q = q * t + 0.127414796f; q = q * t;
;     const f32x2 s = (v * v) * (-0.72134752044f);
;     f32x2 e; e.x = __builtin_amdgcn_exp2f(s.x); e.y = __builtin_amdgcn_exp2f(s.y);
;     const f32x2 m = v * (q * e), r = v - m;
;     f32x2 o; o.x = v.x < 0.f ? m.x : r.x; o.y = v.y < 0.f ? m.y : r.y; return o;
	v_pk_mul_f32 v[132:133], v[132:133], v[180:181] op_sel_hi:[1,0]
	v_pk_mul_f32 v[130:131], v[130:131], v[180:181] op_sel_hi:[1,0]
	v_lshlrev_b32_e32 v180, 16, v140
	v_and_b32_e32 v181, 0xffff0000, v140
	v_pk_fma_f32 v[172:173], v[112:113], v[172:173], v[178:179]
	v_pk_fma_f32 v[178:179], v[110:111], v[182:183], v[192:193]
	v_lshlrev_b32_e32 v140, 16, v141
	v_and_b32_e32 v141, 0xffff0000, v141
	v_pk_fma_f32 v[178:179], v[114:115], v[180:181], v[178:179]
	v_pk_fma_f32 v[140:141], v[116:117], v[140:141], v[172:173]
	v_pk_add_f32 v[172:173], v[118:119], v[178:179]
	v_pk_add_f32 v[140:141], v[120:121], v[140:141]
	v_and_b32_e32 v179, 0x7fffffff, v173
	v_and_b32_e32 v178, 0x7fffffff, v172
	v_pk_fma_f32 v[178:179], v[178:179], s[2:3], 1.0 op_sel_hi:[1,0,0]
	v_pk_mul_f32 v[182:183], v[172:173], v[172:173]
	v_rcp_f32_e32 v178, v178
	v_rcp_f32_e32 v179, v179
	v_pk_mul_f32 v[182:183], v[182:183], s[22:23] op_sel_hi:[1,0]
	v_cmp_gt_f32_e32 vcc, 0, v172
	v_exp_f32_e32 v182, v182
	v_pk_fma_f32 v[180:181], v[178:179], s[42:43], v[142:143] op_sel_hi:[1,0,0]
	v_exp_f32_e32 v183, v183
	v_pk_fma_f32 v[180:181], v[178:179], v[180:181], s[40:41] op_sel_hi:[1,1,0]
	s_nop 0
	v_pk_fma_f32 v[180:181], v[178:179], v[180:181], s[92:93] op_sel_hi:[1,1,0]
	s_nop 0
	v_pk_fma_f32 v[180:181], v[178:179], v[180:181], s[20:21] op_sel_hi:[1,1,0]
	s_nop 0
	v_pk_mul_f32 v[178:179], v[178:179], v[180:181]
	v_pk_mul_f32 v[180:181], v[140:141], v[140:141]
	v_pk_mul_f32 v[178:179], v[182:183], v[178:179]
	s_nop 0
	v_pk_mul_f32 v[182:183], v[172:173], v[178:179]
	v_pk_fma_f32 v[178:179], v[172:173], v[178:179], v[172:173] neg_lo:[1,0,0] neg_hi:[1,0,0]
	v_and_b32_e32 v172, 0x7fffffff, v140
	v_cndmask_b32_e32 v137, v178, v182, vcc
	v_cmp_gt_f32_e32 vcc, 0, v173
	v_and_b32_e32 v173, 0x7fffffff, v141
	v_pk_fma_f32 v[172:173], v[172:173], s[2:3], 1.0 op_sel_hi:[1,0,0]
	v_cndmask_b32_e32 v165, v179, v183, vcc
	v_rcp_f32_e32 v172, v172
	v_rcp_f32_e32 v173, v173
	v_cmp_gt_f32_e32 vcc, 0, v140
	v_mul_f32_e32 v130, v130, v137
	v_mul_f32_e32 v131, v131, v165
	v_pk_fma_f32 v[178:179], v[172:173], s[42:43], v[142:143] op_sel_hi:[1,0,0]
	v_cvt_pk_bf16_f32 v130, v130, v131
	s_nop 0
	v_pk_fma_f32 v[178:179], v[172:173], v[178:179], s[40:41] op_sel_hi:[1,1,0]
	s_nop 0
	v_pk_fma_f32 v[178:179], v[172:173], v[178:179], s[92:93] op_sel_hi:[1,1,0]
	s_nop 0
	v_pk_fma_f32 v[178:179], v[172:173], v[178:179], s[20:21] op_sel_hi:[1,1,0]
	s_nop 0
	v_pk_mul_f32 v[172:173], v[172:173], v[178:179]
	v_pk_mul_f32 v[178:179], v[180:181], s[22:23] op_sel_hi:[1,0]
	s_nop 0
	v_exp_f32_e32 v178, v178
	v_exp_f32_e32 v179, v179
	s_nop 0
	v_pk_mul_f32 v[172:173], v[178:179], v[172:173]
	s_nop 0
	v_pk_mul_f32 v[178:179], v[140:141], v[172:173]
	v_pk_fma_f32 v[172:173], v[140:141], v[172:173], v[140:141] neg_lo:[1,0,0] neg_hi:[1,0,0]
	s_nop 0
	v_cndmask_b32_e32 v140, v172, v178, vcc
	v_cmp_gt_f32_e32 vcc, 0, v141
	v_mul_f32_e32 v131, v132, v140
	s_nop 0
	v_cndmask_b32_e32 v141, v173, v179, vcc
	v_mul_f32_e32 v132, v133, v141
	v_cvt_pk_bf16_f32 v131, v131, v132
	v_mad_i64_i32 v[132:133], s[0:1], v136, s33, v[186:187]
	global_store_dwordx2 v[132:133], v[130:131], off
	v_add_u32_e32 v132, 0x80, v176
	v_and_b32_e32 v137, 0x1fcf, v132
	v_mad_i64_i32 v[130:131], s[0:1], v132, s33, v[190:191]
	v_cmp_eq_u32_e32 vcc, 0, v137
	v_cmp_lt_u32_e64 s[0:1], 1, v137
	global_load_dwordx2 v[140:141], v[130:131], off
	v_cndmask_b32_e64 v183, -1, 0, vcc
	v_cndmask_b32_e64 v182, v212, 0, vcc
	v_lshl_add_u64 v[172:173], v[130:131], 0, v[182:183]
	v_cndmask_b32_e64 v181, 0, -1, s[0:1]
	v_cndmask_b32_e64 v180, 0, v213, s[0:1]
	global_load_dwordx2 v[172:173], v[172:173], off
	v_lshl_add_u64 v[130:131], v[130:131], 0, v[180:181]
	v_ashrrev_i32_e32 v133, 31, v132
	global_load_dwordx2 v[178:179], v[130:131], off
	v_lshlrev_b64 v[130:131], 7, v[132:133]
	v_lshl_add_u64 v[130:131], s[50:51], 0, v[130:131]
	global_load_dword v192, v[130:131], off
	v_cmp_gt_u32_e64 s[8:9], 2, v137
	s_waitcnt vmcnt(2)
	v_lshlrev_b32_e32 v133, 16, v172
	v_and_b32_e32 v165, 0xffff0000, v172
	v_lshlrev_b32_e32 v171, 16, v173
	s_waitcnt vmcnt(1)
	v_lshlrev_b32_e32 v177, 16, v178
	v_and_b32_e32 v216, 0xffff0000, v178
	v_cndmask_b32_e64 v217, v216, 0, s[8:9]
	v_cndmask_b32_e64 v216, v177, 0, s[8:9]
	v_and_b32_e32 v175, 0xffff0000, v173
	v_lshlrev_b32_e32 v218, 16, v179
	v_and_b32_e32 v219, 0xffff0000, v179
	v_cndmask_b32_e64 v173, v165, 0, vcc
	v_cndmask_b32_e64 v172, v133, 0, vcc
	v_pk_mul_f32 v[216:217], v[106:107], v[216:217]
	s_waitcnt vmcnt(0)
; __device__ __forceinline__ f32x2 gelu_pk(f32x2 v) {
;     const f32x2 av = __builtin_elementwise_abs(v), d = av * 0.2316418882f + 1.0f;
;     f32x2 t; t.x = __builtin_amdgcn_rcpf(d.x); t.y = __builtin_amdgcn_rcpf(d.y);
;     f32x2 q = t * 0.5307027145f + (-0.7265760135f); q = q * t + 0.7107068705f; q = q * t + (-0.142248368f); q = q * t + 0.127414796f; q = q * t;
;     const f32x2 s = (v * v) * (-0.72134752044f);
;     f32x2 e; e.x = __builtin_amdgcn_exp2f(s.x); e.y = __builtin_amdgcn_exp2f(s.y);
;     const f32x2 m = v * (q * e), r = v - m;
;     f32x2 o; o.x = v.x < 0.f ? m.x : r.x; o.y = v.y < 0.f ? m.y : r.y; return o;
	v_pk_mul_f32 v[128:129], v[128:129], v[192:193] op_sel_hi:[1,0]
	v_pk_mul_f32 v[126:127], v[126:127], v[192:193] op_sel_hi:[1,0]
	v_lshlrev_b32_e32 v192, 16, v140
	v_and_b32_e32 v193, 0xffff0000, v140
	v_cndmask_b32_e64 v219, v219, 0, s[8:9]
	v_cndmask_b32_e64 v218, v218, 0, s[8:9]
	v_pk_fma_f32 v[172:173], v[110:111], v[172:173], v[216:217]
	v_cndmask_b32_e64 v179, v175, 0, vcc
	v_cndmask_b32_e64 v178, v171, 0, vcc
	v_pk_mul_f32 v[218:219], v[108:109], v[218:219]
	v_pk_fma_f32 v[172:173], v[114:115], v[192:193], v[172:173]
	v_lshlrev_b32_e32 v140, 16, v141
	v_and_b32_e32 v141, 0xffff0000, v141
	v_pk_fma_f32 v[178:179], v[112:113], v[178:179], v[218:219]
	v_pk_add_f32 v[172:173], v[118:119], v[172:173]
	v_pk_fma_f32 v[140:141], v[116:117], v[140:141], v[178:179]
	v_and_b32_e32 v179, 0x7fffffff, v173
	v_and_b32_e32 v178, 0x7fffffff, v172
	v_pk_fma_f32 v[178:179], v[178:179], s[2:3], 1.0 op_sel_hi:[1,0,0]
	v_pk_mul_f32 v[216:217], v[172:173], v[172:173]
	v_rcp_f32_e32 v178, v178
	v_rcp_f32_e32 v179, v179
	v_pk_mul_f32 v[216:217], v[216:217], s[22:23] op_sel_hi:[1,0]
	v_pk_add_f32 v[140:141], v[120:121], v[140:141]
	v_exp_f32_e32 v216, v216
	v_pk_fma_f32 v[192:193], v[178:179], s[42:43], v[142:143] op_sel_hi:[1,0,0]
	v_exp_f32_e32 v217, v217
	v_pk_fma_f32 v[192:193], v[178:179], v[192:193], s[40:41] op_sel_hi:[1,1,0]
	v_cmp_gt_f32_e64 s[0:1], 0, v172
	v_pk_fma_f32 v[192:193], v[178:179], v[192:193], s[92:93] op_sel_hi:[1,1,0]
	s_nop 0
	v_pk_fma_f32 v[192:193], v[178:179], v[192:193], s[20:21] op_sel_hi:[1,1,0]
	s_nop 0
	v_pk_mul_f32 v[178:179], v[178:179], v[192:193]
	v_pk_mul_f32 v[192:193], v[140:141], v[140:141]
	v_pk_mul_f32 v[178:179], v[216:217], v[178:179]
	s_nop 0
	v_pk_mul_f32 v[216:217], v[172:173], v[178:179]
	v_pk_fma_f32 v[178:179], v[172:173], v[178:179], v[172:173] neg_lo:[1,0,0] neg_hi:[1,0,0]
	v_and_b32_e32 v172, 0x7fffffff, v140
	v_cndmask_b32_e64 v133, v178, v216, s[0:1]
	v_cmp_gt_f32_e64 s[0:1], 0, v173
	v_and_b32_e32 v173, 0x7fffffff, v141
	v_pk_fma_f32 v[172:173], v[172:173], s[2:3], 1.0 op_sel_hi:[1,0,0]
	v_cndmask_b32_e64 v137, v179, v217, s[0:1]
	v_rcp_f32_e32 v172, v172
	v_rcp_f32_e32 v173, v173
	v_cmp_gt_f32_e64 s[0:1], 0, v140
	v_mul_f32_e32 v126, v126, v133
	v_mul_f32_e32 v127, v127, v137
	v_pk_fma_f32 v[178:179], v[172:173], s[42:43], v[142:143] op_sel_hi:[1,0,0]
	v_cvt_pk_bf16_f32 v126, v126, v127
	s_nop 0
	v_pk_fma_f32 v[178:179], v[172:173], v[178:179], s[40:41] op_sel_hi:[1,1,0]
	s_nop 0
	v_pk_fma_f32 v[178:179], v[172:173], v[178:179], s[92:93] op_sel_hi:[1,1,0]
	s_nop 0
	v_pk_fma_f32 v[178:179], v[172:173], v[178:179], s[20:21] op_sel_hi:[1,1,0]
	s_nop 0
	v_pk_mul_f32 v[172:173], v[172:173], v[178:179]
	v_pk_mul_f32 v[178:179], v[192:193], s[22:23] op_sel_hi:[1,0]
	s_nop 0
	v_exp_f32_e32 v178, v178
	v_exp_f32_e32 v179, v179
	s_nop 0
	v_pk_mul_f32 v[172:173], v[178:179], v[172:173]
	s_nop 0
	v_pk_mul_f32 v[178:179], v[140:141], v[172:173]
	v_pk_fma_f32 v[172:173], v[140:141], v[172:173], v[140:141] neg_lo:[1,0,0] neg_hi:[1,0,0]
	s_nop 0
	v_cndmask_b32_e64 v140, v172, v178, s[0:1]
	v_cmp_gt_f32_e64 s[0:1], 0, v141
	v_mul_f32_e32 v127, v128, v140
	v_add_u32_e32 v140, 0x90, v176
	v_cndmask_b32_e64 v141, v173, v179, s[0:1]
	v_mul_f32_e32 v128, v129, v141
	v_cvt_pk_bf16_f32 v127, v127, v128
	v_mad_i64_i32 v[128:129], s[0:1], v132, s33, v[186:187]
	global_store_dwordx2 v[128:129], v[126:127], off
	v_mad_i64_i32 v[126:127], s[0:1], v140, s33, v[190:191]
	v_add_co_u32_e64 v172, s[0:1], s41, v126
	global_load_dwordx2 v[128:129], v[126:127], off
	s_nop 0
	v_addc_co_u32_e64 v173, s[0:1], -1, v127, s[0:1]
	v_add_co_u32_e64 v126, s[0:1], s43, v126
	v_ashrrev_i32_e32 v141, 31, v140
	s_nop 0
	v_addc_co_u32_e64 v127, s[0:1], -1, v127, s[0:1]
	global_load_dwordx2 v[172:173], v[172:173], off offset:-1536
	s_nop 0
	global_load_dwordx2 v[178:179], v[126:127], off offset:-3072
	v_lshlrev_b64 v[126:127], 7, v[140:141]
	v_lshl_add_u64 v[126:127], s[50:51], 0, v[126:127]
	global_load_dword v192, v[126:127], off
	s_waitcnt vmcnt(2)
	v_lshlrev_b32_e32 v216, 16, v172
	v_and_b32_e32 v217, 0xffff0000, v172
	s_waitcnt vmcnt(1)
	v_lshlrev_b32_e32 v218, 16, v178
	v_and_b32_e32 v219, 0xffff0000, v178
	v_lshlrev_b32_e32 v178, 16, v179
	v_and_b32_e32 v179, 0xffff0000, v179
	v_lshlrev_b32_e32 v172, 16, v173
	v_and_b32_e32 v173, 0xffff0000, v173
	v_pk_mul_f32 v[218:219], v[106:107], v[218:219]
	v_pk_mul_f32 v[178:179], v[108:109], v[178:179]
	s_waitcnt vmcnt(0)
; __device__ __forceinline__ f32x2 gelu_pk(f32x2 v) {
;     const f32x2 av = __builtin_elementwise_abs(v), d = av * 0.2316418882f + 1.0f;
;     f32x2 t; t.x = __builtin_amdgcn_rcpf(d.x); t.y = __builtin_amdgcn_rcpf(d.y);
;     f32x2 q = t * 0.5307027145f + (-0.7265760135f); q = q * t + 0.7107068705f; q = q * t + (-0.142248368f); q = q * t + 0.127414796f; q = q * t;
;     const f32x2 s = (v * v) * (-0.72134752044f);
;     f32x2 e; e.x = __builtin_amdgcn_exp2f(s.x); e.y = __builtin_amdgcn_exp2f(s.y);
;     const f32x2 m = v * (q * e), r = v - m;
;     f32x2 o; o.x = v.x < 0.f ? m.x : r.x; o.y = v.y < 0.f ? m.y : r.y; return o;
	v_pk_mul_f32 v[124:125], v[124:125], v[192:193] op_sel_hi:[1,0]
	v_pk_mul_f32 v[122:123], v[122:123], v[192:193] op_sel_hi:[1,0]
	v_lshlrev_b32_e32 v192, 16, v128
	v_and_b32_e32 v193, 0xffff0000, v128
	v_pk_fma_f32 v[172:173], v[112:113], v[172:173], v[178:179]
	v_pk_fma_f32 v[178:179], v[110:111], v[216:217], v[218:219]
	v_lshlrev_b32_e32 v128, 16, v129
	v_and_b32_e32 v129, 0xffff0000, v129
	v_pk_fma_f32 v[178:179], v[114:115], v[192:193], v[178:179]
	v_pk_fma_f32 v[128:129], v[116:117], v[128:129], v[172:173]
	v_pk_add_f32 v[172:173], v[118:119], v[178:179]
	v_pk_add_f32 v[128:129], v[120:121], v[128:129]
	v_and_b32_e32 v179, 0x7fffffff, v173
	v_and_b32_e32 v178, 0x7fffffff, v172
	v_pk_fma_f32 v[178:179], v[178:179], s[2:3], 1.0 op_sel_hi:[1,0,0]
	v_pk_mul_f32 v[216:217], v[172:173], v[172:173]
	v_rcp_f32_e32 v178, v178
	v_rcp_f32_e32 v179, v179
	v_pk_mul_f32 v[216:217], v[216:217], s[22:23] op_sel_hi:[1,0]
	v_cmp_gt_f32_e64 s[0:1], 0, v172
	v_exp_f32_e32 v216, v216
	v_pk_fma_f32 v[192:193], v[178:179], s[42:43], v[142:143] op_sel_hi:[1,0,0]
	v_exp_f32_e32 v217, v217
	v_pk_fma_f32 v[192:193], v[178:179], v[192:193], s[40:41] op_sel_hi:[1,1,0]
	s_nop 0
	v_pk_fma_f32 v[192:193], v[178:179], v[192:193], s[92:93] op_sel_hi:[1,1,0]
	s_nop 0
	v_pk_fma_f32 v[192:193], v[178:179], v[192:193], s[20:21] op_sel_hi:[1,1,0]
	s_nop 0
	v_pk_mul_f32 v[178:179], v[178:179], v[192:193]
	v_pk_mul_f32 v[192:193], v[128:129], v[128:129]
	v_pk_mul_f32 v[178:179], v[216:217], v[178:179]
	s_nop 0
	v_pk_mul_f32 v[216:217], v[172:173], v[178:179]
	v_pk_fma_f32 v[178:179], v[172:173], v[178:179], v[172:173] neg_lo:[1,0,0] neg_hi:[1,0,0]
	v_and_b32_e32 v172, 0x7fffffff, v128
	v_cndmask_b32_e64 v133, v178, v216, s[0:1]
	v_cmp_gt_f32_e64 s[0:1], 0, v173
	v_and_b32_e32 v173, 0x7fffffff, v129
	v_pk_fma_f32 v[172:173], v[172:173], s[2:3], 1.0 op_sel_hi:[1,0,0]
	v_cndmask_b32_e64 v137, v179, v217, s[0:1]
	v_rcp_f32_e32 v172, v172
	v_rcp_f32_e32 v173, v173
	v_cmp_gt_f32_e64 s[0:1], 0, v128
	v_mul_f32_e32 v122, v122, v133
	v_mul_f32_e32 v123, v123, v137
	v_pk_fma_f32 v[178:179], v[172:173], s[42:43], v[142:143] op_sel_hi:[1,0,0]
	v_cvt_pk_bf16_f32 v122, v122, v123
	s_nop 0
	v_pk_fma_f32 v[178:179], v[172:173], v[178:179], s[40:41] op_sel_hi:[1,1,0]
	s_nop 0
	v_pk_fma_f32 v[178:179], v[172:173], v[178:179], s[92:93] op_sel_hi:[1,1,0]
	s_nop 0
	v_pk_fma_f32 v[178:179], v[172:173], v[178:179], s[20:21] op_sel_hi:[1,1,0]
	s_nop 0
	v_pk_mul_f32 v[172:173], v[172:173], v[178:179]
	v_pk_mul_f32 v[178:179], v[192:193], s[22:23] op_sel_hi:[1,0]
	s_nop 0
	v_exp_f32_e32 v178, v178
	v_exp_f32_e32 v179, v179
	s_nop 0
	v_pk_mul_f32 v[172:173], v[178:179], v[172:173]
	s_nop 0
	v_pk_mul_f32 v[178:179], v[128:129], v[172:173]
	v_pk_fma_f32 v[172:173], v[128:129], v[172:173], v[128:129] neg_lo:[1,0,0] neg_hi:[1,0,0]
	s_nop 0
	v_cndmask_b32_e64 v128, v172, v178, s[0:1]
	v_cmp_gt_f32_e64 s[0:1], 0, v129
	v_mul_f32_e32 v123, v124, v128
	v_add_u32_e32 v172, 0xa0, v176
	v_cndmask_b32_e64 v129, v173, v179, s[0:1]
	v_mul_f32_e32 v124, v125, v129
	v_cvt_pk_bf16_f32 v123, v123, v124
	v_mad_i64_i32 v[124:125], s[0:1], v140, s33, v[186:187]
	global_store_dwordx2 v[124:125], v[122:123], off
	v_mad_i64_i32 v[122:123], s[0:1], v172, s33, v[190:191]
	v_add_co_u32_e64 v124, s[0:1], s41, v122
	global_load_dwordx2 v[128:129], v[122:123], off
	s_nop 0
	v_addc_co_u32_e64 v125, s[0:1], -1, v123, s[0:1]
	v_add_co_u32_e64 v122, s[0:1], s43, v122
	v_ashrrev_i32_e32 v173, 31, v172
	s_nop 0
	v_addc_co_u32_e64 v123, s[0:1], -1, v123, s[0:1]
	global_load_dwordx2 v[178:179], v[124:125], off offset:-1536
	s_nop 0
	global_load_dwordx2 v[122:123], v[122:123], off offset:-3072
	v_lshlrev_b64 v[124:125], 7, v[172:173]
	v_lshl_add_u64 v[124:125], s[50:51], 0, v[124:125]
	global_load_dword v192, v[124:125], off
	s_waitcnt vmcnt(2)
	v_lshlrev_b32_e32 v216, 16, v178
	v_and_b32_e32 v217, 0xffff0000, v178
	s_waitcnt vmcnt(1)
	v_lshlrev_b32_e32 v218, 16, v122
	v_and_b32_e32 v219, 0xffff0000, v122
	v_lshlrev_b32_e32 v122, 16, v123
	v_and_b32_e32 v123, 0xffff0000, v123
	v_lshlrev_b32_e32 v178, 16, v179
	v_and_b32_e32 v179, 0xffff0000, v179
	v_pk_mul_f32 v[218:219], v[106:107], v[218:219]
	v_pk_mul_f32 v[122:123], v[108:109], v[122:123]
	s_waitcnt vmcnt(0)
; __device__ __forceinline__ f32x2 gelu_pk(f32x2 v) {
;     const f32x2 av = __builtin_elementwise_abs(v), d = av * 0.2316418882f + 1.0f;
;     f32x2 t; t.x = __builtin_amdgcn_rcpf(d.x); t.y = __builtin_amdgcn_rcpf(d.y);
;     f32x2 q = t * 0.5307027145f + (-0.7265760135f); q = q * t + 0.7107068705f; q = q * t + (-0.142248368f); q = q * t + 0.127414796f; q = q * t;
;     const f32x2 s = (v * v) * (-0.72134752044f);
;     f32x2 e; e.x = __builtin_amdgcn_exp2f(s.x); e.y = __builtin_amdgcn_exp2f(s.y);
;     const f32x2 m = v * (q * e), r = v - m;
;     f32x2 o; o.x = v.x < 0.f ? m.x : r.x; o.y = v.y < 0.f ? m.y : r.y; return o;
	v_pk_mul_f32 v[104:105], v[104:105], v[192:193] op_sel_hi:[1,0]
	v_pk_mul_f32 v[102:103], v[102:103], v[192:193] op_sel_hi:[1,0]
	v_lshlrev_b32_e32 v192, 16, v128
	v_and_b32_e32 v193, 0xffff0000, v128
	v_pk_fma_f32 v[122:123], v[112:113], v[178:179], v[122:123]
	v_pk_fma_f32 v[178:179], v[110:111], v[216:217], v[218:219]
	v_lshlrev_b32_e32 v128, 16, v129
	v_and_b32_e32 v129, 0xffff0000, v129
	v_pk_fma_f32 v[178:179], v[114:115], v[192:193], v[178:179]
	v_pk_fma_f32 v[122:123], v[116:117], v[128:129], v[122:123]
	v_pk_add_f32 v[128:129], v[118:119], v[178:179]
	v_pk_add_f32 v[122:123], v[120:121], v[122:123]
	v_and_b32_e32 v179, 0x7fffffff, v129
	v_and_b32_e32 v178, 0x7fffffff, v128
	v_pk_fma_f32 v[178:179], v[178:179], s[2:3], 1.0 op_sel_hi:[1,0,0]
	v_pk_mul_f32 v[216:217], v[128:129], v[128:129]
	v_rcp_f32_e32 v178, v178
	v_rcp_f32_e32 v179, v179
	v_pk_mul_f32 v[216:217], v[216:217], s[22:23] op_sel_hi:[1,0]
	v_cmp_gt_f32_e64 s[0:1], 0, v128
	v_exp_f32_e32 v216, v216
	v_pk_fma_f32 v[192:193], v[178:179], s[42:43], v[142:143] op_sel_hi:[1,0,0]
	v_exp_f32_e32 v217, v217
	v_pk_fma_f32 v[192:193], v[178:179], v[192:193], s[40:41] op_sel_hi:[1,1,0]
	s_nop 0
	v_pk_fma_f32 v[192:193], v[178:179], v[192:193], s[92:93] op_sel_hi:[1,1,0]
	s_nop 0
	v_pk_fma_f32 v[192:193], v[178:179], v[192:193], s[20:21] op_sel_hi:[1,1,0]
	s_nop 0
	v_pk_mul_f32 v[178:179], v[178:179], v[192:193]
	v_pk_mul_f32 v[192:193], v[122:123], v[122:123]
	v_pk_mul_f32 v[178:179], v[216:217], v[178:179]
	s_nop 0
	v_pk_mul_f32 v[216:217], v[128:129], v[178:179]
	v_pk_fma_f32 v[178:179], v[128:129], v[178:179], v[128:129] neg_lo:[1,0,0] neg_hi:[1,0,0]
	v_and_b32_e32 v128, 0x7fffffff, v122
	v_cndmask_b32_e64 v133, v178, v216, s[0:1]
	v_cmp_gt_f32_e64 s[0:1], 0, v129
	v_and_b32_e32 v129, 0x7fffffff, v123
	v_pk_fma_f32 v[128:129], v[128:129], s[2:3], 1.0 op_sel_hi:[1,0,0]
	v_cndmask_b32_e64 v137, v179, v217, s[0:1]
	v_rcp_f32_e32 v128, v128
	v_rcp_f32_e32 v129, v129
	v_cmp_gt_f32_e64 s[0:1], 0, v122
	v_mul_f32_e32 v102, v102, v133
	v_mul_f32_e32 v103, v103, v137
	v_pk_fma_f32 v[178:179], v[128:129], s[42:43], v[142:143] op_sel_hi:[1,0,0]
	v_cvt_pk_bf16_f32 v102, v102, v103
	s_nop 0
	v_pk_fma_f32 v[178:179], v[128:129], v[178:179], s[40:41] op_sel_hi:[1,1,0]
	s_nop 0
	v_pk_fma_f32 v[178:179], v[128:129], v[178:179], s[92:93] op_sel_hi:[1,1,0]
	s_nop 0
	v_pk_fma_f32 v[178:179], v[128:129], v[178:179], s[20:21] op_sel_hi:[1,1,0]
	s_nop 0
	v_pk_mul_f32 v[128:129], v[128:129], v[178:179]
	v_pk_mul_f32 v[178:179], v[192:193], s[22:23] op_sel_hi:[1,0]
	s_nop 0
	v_exp_f32_e32 v178, v178
	v_exp_f32_e32 v179, v179
	s_nop 0
	v_pk_mul_f32 v[128:129], v[178:179], v[128:129]
	s_nop 0
	v_pk_mul_f32 v[178:179], v[122:123], v[128:129]
	v_pk_fma_f32 v[128:129], v[122:123], v[128:129], v[122:123] neg_lo:[1,0,0] neg_hi:[1,0,0]
	s_nop 0
	v_cndmask_b32_e64 v122, v128, v178, s[0:1]
	v_cmp_gt_f32_e64 s[0:1], 0, v123
	v_mul_f32_e32 v103, v104, v122
	v_add_u32_e32 v178, 0xb0, v176
	v_cndmask_b32_e64 v123, v129, v179, s[0:1]
	v_mul_f32_e32 v104, v105, v123
	v_cvt_pk_bf16_f32 v103, v103, v104
	v_mad_i64_i32 v[104:105], s[0:1], v172, s33, v[186:187]
	global_store_dwordx2 v[104:105], v[102:103], off
	v_mad_i64_i32 v[102:103], s[0:1], v178, s33, v[190:191]
	v_add_co_u32_e64 v122, s[0:1], s41, v102
	global_load_dwordx2 v[104:105], v[102:103], off
	s_nop 0
	v_addc_co_u32_e64 v123, s[0:1], -1, v103, s[0:1]
	v_add_co_u32_e64 v102, s[0:1], s43, v102
	v_ashrrev_i32_e32 v179, 31, v178
	s_nop 0
	v_addc_co_u32_e64 v103, s[0:1], -1, v103, s[0:1]
	global_load_dwordx2 v[128:129], v[122:123], off offset:-1536
	s_nop 0
	global_load_dwordx2 v[102:103], v[102:103], off offset:-3072
	v_lshlrev_b64 v[122:123], 7, v[178:179]
	v_lshl_add_u64 v[122:123], s[50:51], 0, v[122:123]
	global_load_dword v190, v[122:123], off
	s_waitcnt vmcnt(2)
	v_lshlrev_b32_e32 v192, 16, v128
	v_and_b32_e32 v193, 0xffff0000, v128
	s_waitcnt vmcnt(1)
	v_lshlrev_b32_e32 v216, 16, v102
	v_and_b32_e32 v217, 0xffff0000, v102
	v_lshlrev_b32_e32 v102, 16, v103
	v_and_b32_e32 v103, 0xffff0000, v103
	v_pk_mul_f32 v[106:107], v[106:107], v[216:217]
	s_waitcnt vmcnt(0)
	v_pk_mul_f32 v[100:101], v[100:101], v[190:191] op_sel_hi:[1,0]
	v_pk_mul_f32 v[98:99], v[98:99], v[190:191] op_sel_hi:[1,0]
	v_lshlrev_b32_e32 v190, 16, v104
	v_and_b32_e32 v191, 0xffff0000, v104
	v_lshlrev_b32_e32 v128, 16, v129
	v_and_b32_e32 v129, 0xffff0000, v129
	v_pk_mul_f32 v[102:103], v[108:109], v[102:103]
	v_pk_fma_f32 v[106:107], v[110:111], v[192:193], v[106:107]
	v_lshlrev_b32_e32 v104, 16, v105
	v_and_b32_e32 v105, 0xffff0000, v105
	v_pk_fma_f32 v[102:103], v[112:113], v[128:129], v[102:103]
	v_pk_fma_f32 v[106:107], v[114:115], v[190:191], v[106:107]
	v_pk_fma_f32 v[102:103], v[116:117], v[104:105], v[102:103]
	v_pk_add_f32 v[104:105], v[118:119], v[106:107]
	v_pk_add_f32 v[102:103], v[120:121], v[102:103]
	v_and_b32_e32 v107, 0x7fffffff, v105
	v_and_b32_e32 v106, 0x7fffffff, v104
	v_pk_fma_f32 v[106:107], v[106:107], s[2:3], 1.0 op_sel_hi:[1,0,0]
	v_pk_mul_f32 v[110:111], v[104:105], v[104:105]
	v_rcp_f32_e32 v106, v106
	v_rcp_f32_e32 v107, v107
	v_pk_mul_f32 v[110:111], v[110:111], s[22:23] op_sel_hi:[1,0]
	v_cmp_gt_f32_e64 s[0:1], 0, v104
	v_exp_f32_e32 v110, v110
	v_pk_fma_f32 v[108:109], v[106:107], s[42:43], v[142:143] op_sel_hi:[1,0,0]
	v_exp_f32_e32 v111, v111
	v_pk_fma_f32 v[108:109], v[106:107], v[108:109], s[40:41] op_sel_hi:[1,1,0]
	v_or_b32_e32 v116, 16, v164
	v_pk_fma_f32 v[108:109], v[106:107], v[108:109], s[92:93] op_sel_hi:[1,1,0]
	v_ashrrev_i32_e32 v117, 31, v116
	v_pk_fma_f32 v[108:109], v[106:107], v[108:109], s[20:21] op_sel_hi:[1,1,0]
	v_mov_b64_e32 v[190:191], s[48:49]
	v_pk_mul_f32 v[106:107], v[106:107], v[108:109]
	v_pk_mul_f32 v[108:109], v[102:103], v[102:103]
	v_pk_mul_f32 v[106:107], v[110:111], v[106:107]
	s_nop 0
	v_pk_mul_f32 v[110:111], v[104:105], v[106:107]
	v_pk_fma_f32 v[106:107], v[104:105], v[106:107], v[104:105] neg_lo:[1,0,0] neg_hi:[1,0,0]
	v_and_b32_e32 v104, 0x7fffffff, v102
	v_cndmask_b32_e64 v110, v106, v110, s[0:1]
	v_cmp_gt_f32_e64 s[0:1], 0, v105
	v_and_b32_e32 v105, 0x7fffffff, v103
	v_pk_fma_f32 v[104:105], v[104:105], s[2:3], 1.0 op_sel_hi:[1,0,0]
	v_cndmask_b32_e64 v111, v107, v111, s[0:1]
	v_rcp_f32_e32 v104, v104
	v_rcp_f32_e32 v105, v105
	v_cmp_gt_f32_e64 s[0:1], 0, v102
	v_mul_f32_e32 v98, v98, v110
	v_mul_f32_e32 v99, v99, v111
	v_pk_fma_f32 v[106:107], v[104:105], s[42:43], v[142:143] op_sel_hi:[1,0,0]
	v_cvt_pk_bf16_f32 v98, v98, v99
	s_nop 0
	v_pk_fma_f32 v[106:107], v[104:105], v[106:107], s[40:41] op_sel_hi:[1,1,0]
	s_nop 0
	v_pk_fma_f32 v[106:107], v[104:105], v[106:107], s[92:93] op_sel_hi:[1,1,0]
	s_nop 0
	v_pk_fma_f32 v[106:107], v[104:105], v[106:107], s[20:21] op_sel_hi:[1,1,0]
	s_nop 0
	v_pk_mul_f32 v[104:105], v[104:105], v[106:107]
	v_pk_mul_f32 v[106:107], v[108:109], s[22:23] op_sel_hi:[1,0]
	s_nop 0
	v_exp_f32_e32 v106, v106
	v_exp_f32_e32 v107, v107
	s_nop 0
	v_pk_mul_f32 v[104:105], v[106:107], v[104:105]
	s_nop 0
	v_pk_mul_f32 v[106:107], v[102:103], v[104:105]
	v_pk_fma_f32 v[104:105], v[102:103], v[104:105], v[102:103] neg_lo:[1,0,0] neg_hi:[1,0,0]
	s_nop 0
	v_cndmask_b32_e64 v102, v104, v106, s[0:1]
	v_cmp_gt_f32_e64 s[0:1], 0, v103
	v_mul_f32_e32 v99, v100, v102
	s_nop 0
	v_cndmask_b32_e64 v103, v105, v107, s[0:1]
	v_mul_f32_e32 v100, v101, v103
	v_cvt_pk_bf16_f32 v99, v99, v100
	v_mad_i64_i32 v[100:101], s[0:1], v178, s33, v[186:187]
	global_store_dwordx2 v[100:101], v[98:99], off
	v_lshlrev_b64 v[102:103], 2, v[116:117]
	v_mad_i64_i32 v[114:115], s[0:1], v176, s33, v[190:191]
	v_lshlrev_b64 v[186:187], 1, v[116:117]
	v_lshl_add_u64 v[104:105], s[38:39], 0, v[102:103]
	v_lshl_add_u64 v[102:103], s[44:45], 0, v[102:103]
	v_lshl_add_u64 v[116:117], v[114:115], 0, v[186:187]
	global_load_dwordx4 v[98:101], v[166:167], off offset:64
	global_load_dwordx4 v[110:113], v[104:105], off
	global_load_dwordx4 v[106:109], v[102:103], off
	s_nop 0
	global_load_dwordx4 v[102:105], v[168:169], off offset:64
	global_load_dwordx2 v[192:193], v[116:117], off
	v_lshl_add_u64 v[116:117], v[114:115], 0, v[184:185]
	v_lshl_add_u64 v[118:119], v[116:117], 0, v[186:187]
	global_load_dwordx2 v[128:129], v[118:119], off
	v_lshl_add_u64 v[118:119], v[114:115], 0, v[188:189]
	v_lshl_add_u64 v[120:121], v[118:119], 0, v[186:187]
	global_load_dwordx2 v[120:121], v[120:121], off
	s_nop 0
	global_load_dword v184, v[162:163], off
	s_waitcnt vmcnt(3)
	v_lshlrev_b32_e32 v188, 16, v193
	v_and_b32_e32 v189, 0xffff0000, v193
	s_waitcnt vmcnt(2)
	v_lshlrev_b32_e32 v133, 16, v128
	v_and_b32_e32 v128, 0xffff0000, v128
	s_waitcnt vmcnt(1)
	v_lshlrev_b32_e32 v141, 16, v120
	v_and_b32_e32 v165, 0xffff0000, v120
	s_waitcnt vmcnt(0)
	v_pk_mul_f32 v[96:97], v[96:97], v[184:185] op_sel_hi:[1,0]
	v_pk_mul_f32 v[94:95], v[94:95], v[184:185] op_sel_hi:[1,0]
	v_lshlrev_b32_e32 v184, 16, v192
	v_and_b32_e32 v185, 0xffff0000, v192
	v_cndmask_b32_e64 v193, v165, 0, s[10:11]
	v_cndmask_b32_e64 v192, v141, 0, s[10:11]
	v_lshlrev_b32_e32 v171, 16, v121
	v_and_b32_e32 v173, 0xffff0000, v121
	v_cndmask_b32_e64 v121, v128, 0, s[6:7]
	v_cndmask_b32_e64 v120, v133, 0, s[6:7]
	v_pk_mul_f32 v[192:193], v[98:99], v[192:193]
	v_lshlrev_b32_e32 v137, 16, v129
	v_pk_fma_f32 v[120:121], v[110:111], v[120:121], v[192:193]
	v_and_b32_e32 v129, 0xffff0000, v129
	v_pk_fma_f32 v[120:121], v[106:107], v[184:185], v[120:121]
	v_cndmask_b32_e64 v217, v173, 0, s[10:11]
	v_pk_add_f32 v[120:121], v[102:103], v[120:121]
	v_cndmask_b32_e64 v216, v171, 0, s[10:11]
	v_and_b32_e32 v185, 0x7fffffff, v121
	v_and_b32_e32 v184, 0x7fffffff, v120
	v_pk_fma_f32 v[184:185], v[184:185], s[2:3], 1.0 op_sel_hi:[1,0,0]
	v_cndmask_b32_e64 v129, v129, 0, s[6:7]
	v_rcp_f32_e32 v184, v184
	v_rcp_f32_e32 v185, v185
	v_cndmask_b32_e64 v128, v137, 0, s[6:7]
	v_pk_mul_f32 v[216:217], v[100:101], v[216:217]
	v_pk_mul_f32 v[192:193], v[120:121], v[120:121]
	v_pk_fma_f32 v[128:129], v[112:113], v[128:129], v[216:217]
	v_pk_mul_f32 v[192:193], v[192:193], s[22:23] op_sel_hi:[1,0]
	v_pk_fma_f32 v[128:129], v[108:109], v[188:189], v[128:129]
	v_pk_fma_f32 v[188:189], v[184:185], s[42:43], v[142:143] op_sel_hi:[1,0,0]
	v_exp_f32_e32 v192, v192
	v_pk_fma_f32 v[188:189], v[184:185], v[188:189], s[40:41] op_sel_hi:[1,1,0]
	v_exp_f32_e32 v193, v193
	v_pk_fma_f32 v[188:189], v[184:185], v[188:189], s[92:93] op_sel_hi:[1,1,0]
	v_pk_add_f32 v[128:129], v[104:105], v[128:129]
	v_pk_fma_f32 v[188:189], v[184:185], v[188:189], s[20:21] op_sel_hi:[1,1,0]
	v_cmp_gt_f32_e64 s[0:1], 0, v120
	v_pk_mul_f32 v[184:185], v[184:185], v[188:189]
	v_pk_mul_f32 v[188:189], v[128:129], v[128:129]
	v_pk_mul_f32 v[184:185], v[192:193], v[184:185]
	s_nop 0
	v_pk_mul_f32 v[192:193], v[120:121], v[184:185]
	v_pk_fma_f32 v[184:185], v[120:121], v[184:185], v[120:121] neg_lo:[1,0,0] neg_hi:[1,0,0]
	v_and_b32_e32 v120, 0x7fffffff, v128
	v_cndmask_b32_e64 v133, v184, v192, s[0:1]
	v_cmp_gt_f32_e64 s[0:1], 0, v121
	v_and_b32_e32 v121, 0x7fffffff, v129
	v_pk_fma_f32 v[120:121], v[120:121], s[2:3], 1.0 op_sel_hi:[1,0,0]
	v_cndmask_b32_e64 v137, v185, v193, s[0:1]
	v_rcp_f32_e32 v120, v120
	v_rcp_f32_e32 v121, v121
	v_cmp_gt_f32_e64 s[0:1], 0, v128
	v_mul_f32_e32 v94, v94, v133
	v_mul_f32_e32 v95, v95, v137
	v_pk_fma_f32 v[184:185], v[120:121], s[42:43], v[142:143] op_sel_hi:[1,0,0]
; __device__ __forceinline__ f32x2 gelu_pk(f32x2 v) {
;     const f32x2 av = __builtin_elementwise_abs(v), d = av * 0.2316418882f + 1.0f;
;     f32x2 t; t.x = __builtin_amdgcn_rcpf(d.x); t.y = __builtin_amdgcn_rcpf(d.y);
;     f32x2 q = t * 0.5307027145f + (-0.7265760135f); q = q * t + 0.7107068705f; q = q * t + (-0.142248368f); q = q * t + 0.127414796f; q = q * t;
;     const f32x2 s = (v * v) * (-0.72134752044f);
;     f32x2 e; e.x = __builtin_amdgcn_exp2f(s.x); e.y = __builtin_amdgcn_exp2f(s.y);
;     const f32x2 m = v * (q * e), r = v - m;
;     f32x2 o; o.x = v.x < 0.f ? m.x : r.x; o.y = v.y < 0.f ? m.y : r.y; return o;
	s_nop 0
	v_pk_fma_f32 v[184:185], v[120:121], v[184:185], s[40:41] op_sel_hi:[1,1,0]
	s_nop 0
	v_pk_fma_f32 v[184:185], v[120:121], v[184:185], s[92:93] op_sel_hi:[1,1,0]
	s_nop 0
	v_pk_fma_f32 v[184:185], v[120:121], v[184:185], s[20:21] op_sel_hi:[1,1,0]
	s_nop 0
	v_pk_mul_f32 v[120:121], v[120:121], v[184:185]
	v_pk_mul_f32 v[184:185], v[188:189], s[22:23] op_sel_hi:[1,0]
	s_nop 0
	v_exp_f32_e32 v184, v184
	v_exp_f32_e32 v185, v185
	s_nop 0
	v_pk_mul_f32 v[120:121], v[184:185], v[120:121]
	s_nop 0
	v_pk_mul_f32 v[184:185], v[128:129], v[120:121]
	v_pk_fma_f32 v[120:121], v[128:129], v[120:121], v[128:129] neg_lo:[1,0,0] neg_hi:[1,0,0]
	s_nop 0
	v_cndmask_b32_e64 v128, v120, v184, s[0:1]
	v_cmp_gt_f32_e64 s[0:1], 0, v129
	v_cvt_pk_bf16_f32 v120, v94, v95
	v_mul_f32_e32 v94, v96, v128
	s_nop 0
	v_cndmask_b32_e64 v121, v121, v185, s[0:1]
	v_mul_f32_e32 v95, v97, v121
	v_mov_b64_e32 v[184:185], s[46:47]
	v_cvt_pk_bf16_f32 v121, v94, v95
	v_mad_i64_i32 v[94:95], s[0:1], v176, s33, v[184:185]
	v_lshl_add_u64 v[96:97], v[94:95], 0, v[186:187]
	global_store_dwordx2 v[96:97], v[120:121], off
	v_mad_i64_i32 v[96:97], s[0:1], v170, s33, v[190:191]
	v_lshl_add_u64 v[176:177], v[96:97], 0, v[186:187]
	v_add_co_u32_e64 v128, s[0:1], s43, v176
	global_load_dword v120, v[144:145], off
	s_nop 0
	v_addc_co_u32_e64 v129, s[0:1], -1, v177, s[0:1]
	v_add_co_u32_e64 v188, s[0:1], s41, v176
	global_load_dwordx2 v[128:129], v[128:129], off offset:-3072
	s_nop 0
	v_addc_co_u32_e64 v189, s[0:1], -1, v177, s[0:1]
	global_load_dwordx2 v[188:189], v[188:189], off offset:-1536
	s_nop 0
	global_load_dwordx2 v[176:177], v[176:177], off
	s_waitcnt vmcnt(3)
	v_pk_mul_f32 v[92:93], v[92:93], v[120:121] op_sel_hi:[1,0]
	v_pk_mul_f32 v[90:91], v[90:91], v[120:121] op_sel_hi:[1,0]
	s_waitcnt vmcnt(2)
	v_lshlrev_b32_e32 v216, 16, v128
	v_and_b32_e32 v217, 0xffff0000, v128
	s_waitcnt vmcnt(1)
	v_lshlrev_b32_e32 v192, 16, v188
	v_and_b32_e32 v193, 0xffff0000, v188
	v_lshlrev_b32_e32 v188, 16, v189
	v_and_b32_e32 v189, 0xffff0000, v189
	v_lshlrev_b32_e32 v128, 16, v129
	v_and_b32_e32 v129, 0xffff0000, v129
	v_pk_mul_f32 v[192:193], v[110:111], v[192:193]
	v_pk_mul_f32 v[188:189], v[112:113], v[188:189]
	s_waitcnt vmcnt(0)
	v_lshlrev_b32_e32 v120, 16, v176
	v_and_b32_e32 v121, 0xffff0000, v176
	v_pk_fma_f32 v[128:129], v[100:101], v[128:129], v[188:189]
	v_pk_fma_f32 v[188:189], v[98:99], v[216:217], v[192:193]
	v_lshlrev_b32_e32 v176, 16, v177
	v_pk_fma_f32 v[120:121], v[106:107], v[120:121], v[188:189]
	v_and_b32_e32 v177, 0xffff0000, v177
	v_pk_add_f32 v[120:121], v[102:103], v[120:121]
	v_pk_fma_f32 v[128:129], v[108:109], v[176:177], v[128:129]
	v_and_b32_e32 v177, 0x7fffffff, v121
	v_and_b32_e32 v176, 0x7fffffff, v120
	v_pk_fma_f32 v[176:177], v[176:177], s[2:3], 1.0 op_sel_hi:[1,0,0]
	v_pk_mul_f32 v[192:193], v[120:121], v[120:121]
	v_rcp_f32_e32 v176, v176
	v_rcp_f32_e32 v177, v177
	v_pk_mul_f32 v[192:193], v[192:193], s[22:23] op_sel_hi:[1,0]
	v_pk_add_f32 v[128:129], v[104:105], v[128:129]
	v_exp_f32_e32 v192, v192
	v_pk_fma_f32 v[188:189], v[176:177], s[42:43], v[142:143] op_sel_hi:[1,0,0]
	v_exp_f32_e32 v193, v193
	v_pk_fma_f32 v[188:189], v[176:177], v[188:189], s[40:41] op_sel_hi:[1,1,0]
	v_cmp_gt_f32_e64 s[0:1], 0, v120
	v_pk_fma_f32 v[188:189], v[176:177], v[188:189], s[92:93] op_sel_hi:[1,1,0]
	s_nop 0
	v_pk_fma_f32 v[188:189], v[176:177], v[188:189], s[20:21] op_sel_hi:[1,1,0]
	s_nop 0
	v_pk_mul_f32 v[176:177], v[176:177], v[188:189]
	v_pk_mul_f32 v[188:189], v[128:129], v[128:129]
	v_pk_mul_f32 v[176:177], v[192:193], v[176:177]
	s_nop 0
	v_pk_mul_f32 v[192:193], v[120:121], v[176:177]
	v_pk_fma_f32 v[176:177], v[120:121], v[176:177], v[120:121] neg_lo:[1,0,0] neg_hi:[1,0,0]
	v_and_b32_e32 v120, 0x7fffffff, v128
	v_cndmask_b32_e64 v133, v176, v192, s[0:1]
	v_cmp_gt_f32_e64 s[0:1], 0, v121
	v_and_b32_e32 v121, 0x7fffffff, v129
	v_pk_fma_f32 v[120:121], v[120:121], s[2:3], 1.0 op_sel_hi:[1,0,0]
	v_cndmask_b32_e64 v137, v177, v193, s[0:1]
	v_rcp_f32_e32 v120, v120
	v_rcp_f32_e32 v121, v121
	v_cmp_gt_f32_e64 s[0:1], 0, v128
	v_mul_f32_e32 v90, v90, v133
	v_mul_f32_e32 v91, v91, v137
	v_pk_fma_f32 v[176:177], v[120:121], s[42:43], v[142:143] op_sel_hi:[1,0,0]
	s_nop 0
	v_pk_fma_f32 v[176:177], v[120:121], v[176:177], s[40:41] op_sel_hi:[1,1,0]
	s_nop 0
	v_pk_fma_f32 v[176:177], v[120:121], v[176:177], s[92:93] op_sel_hi:[1,1,0]
	s_nop 0
	v_pk_fma_f32 v[176:177], v[120:121], v[176:177], s[20:21] op_sel_hi:[1,1,0]
	s_nop 0
	v_pk_mul_f32 v[120:121], v[120:121], v[176:177]
	v_pk_mul_f32 v[176:177], v[188:189], s[22:23] op_sel_hi:[1,0]
	s_nop 0
	v_exp_f32_e32 v176, v176
	v_exp_f32_e32 v177, v177
	s_nop 0
	v_pk_mul_f32 v[120:121], v[176:177], v[120:121]
	s_nop 0
	v_pk_mul_f32 v[176:177], v[128:129], v[120:121]
	v_pk_fma_f32 v[120:121], v[128:129], v[120:121], v[128:129] neg_lo:[1,0,0] neg_hi:[1,0,0]
	s_nop 0
	v_cndmask_b32_e64 v128, v120, v176, s[0:1]
	v_cmp_gt_f32_e64 s[0:1], 0, v129
	v_cvt_pk_bf16_f32 v120, v90, v91
	v_mul_f32_e32 v90, v92, v128
	s_nop 0
	v_cndmask_b32_e64 v121, v121, v177, s[0:1]
	v_mul_f32_e32 v91, v93, v121
	v_cvt_pk_bf16_f32 v121, v90, v91
	v_mad_i64_i32 v[90:91], s[0:1], v170, s33, v[184:185]
	v_lshl_add_u64 v[92:93], v[90:91], 0, v[186:187]
	global_store_dwordx2 v[92:93], v[120:121], off
	v_mad_i64_i32 v[92:93], s[0:1], v174, s33, v[190:191]
	v_lshl_add_u64 v[170:171], v[92:93], 0, v[186:187]
	v_add_co_u32_e64 v128, s[0:1], s43, v170
	global_load_dword v120, v[138:139], off
	s_nop 0
	v_addc_co_u32_e64 v129, s[0:1], -1, v171, s[0:1]
	v_add_co_u32_e64 v176, s[0:1], s41, v170
	global_load_dwordx2 v[128:129], v[128:129], off offset:-3072
	s_nop 0
	v_addc_co_u32_e64 v177, s[0:1], -1, v171, s[0:1]
	global_load_dwordx2 v[176:177], v[176:177], off offset:-1536
	s_nop 0
	global_load_dwordx2 v[170:171], v[170:171], off
	s_waitcnt vmcnt(3)
; __device__ __forceinline__ f32x2 gelu_pk(f32x2 v) {
;     const f32x2 av = __builtin_elementwise_abs(v), d = av * 0.2316418882f + 1.0f;
;     f32x2 t; t.x = __builtin_amdgcn_rcpf(d.x); t.y = __builtin_amdgcn_rcpf(d.y);
;     f32x2 q = t * 0.5307027145f + (-0.7265760135f); q = q * t + 0.7107068705f; q = q * t + (-0.142248368f); q = q * t + 0.127414796f; q = q * t;
;     const f32x2 s = (v * v) * (-0.72134752044f);
;     f32x2 e; e.x = __builtin_amdgcn_exp2f(s.x); e.y = __builtin_amdgcn_exp2f(s.y);
;     const f32x2 m = v * (q * e), r = v - m;
;     f32x2 o; o.x = v.x < 0.f ? m.x : r.x; o.y = v.y < 0.f ? m.y : r.y; return o;
	v_pk_mul_f32 v[88:89], v[88:89], v[120:121] op_sel_hi:[1,0]
	v_pk_mul_f32 v[86:87], v[86:87], v[120:121] op_sel_hi:[1,0]
	s_waitcnt vmcnt(2)
	v_lshlrev_b32_e32 v192, 16, v128
	v_and_b32_e32 v193, 0xffff0000, v128
	s_waitcnt vmcnt(1)
	v_lshlrev_b32_e32 v188, 16, v176
	v_and_b32_e32 v189, 0xffff0000, v176
	v_lshlrev_b32_e32 v176, 16, v177
	v_and_b32_e32 v177, 0xffff0000, v177
	v_lshlrev_b32_e32 v128, 16, v129
	v_and_b32_e32 v129, 0xffff0000, v129
	v_pk_mul_f32 v[188:189], v[110:111], v[188:189]
	v_pk_mul_f32 v[176:177], v[112:113], v[176:177]
	s_waitcnt vmcnt(0)
	v_lshlrev_b32_e32 v120, 16, v170
	v_and_b32_e32 v121, 0xffff0000, v170
	v_pk_fma_f32 v[128:129], v[100:101], v[128:129], v[176:177]
	v_pk_fma_f32 v[176:177], v[98:99], v[192:193], v[188:189]
	v_lshlrev_b32_e32 v170, 16, v171
	v_pk_fma_f32 v[120:121], v[106:107], v[120:121], v[176:177]
	v_and_b32_e32 v171, 0xffff0000, v171
	v_pk_add_f32 v[120:121], v[102:103], v[120:121]
	v_pk_fma_f32 v[128:129], v[108:109], v[170:171], v[128:129]
	v_and_b32_e32 v171, 0x7fffffff, v121
	v_and_b32_e32 v170, 0x7fffffff, v120
	v_pk_fma_f32 v[170:171], v[170:171], s[2:3], 1.0 op_sel_hi:[1,0,0]
	v_pk_mul_f32 v[188:189], v[120:121], v[120:121]
	v_rcp_f32_e32 v170, v170
	v_rcp_f32_e32 v171, v171
	v_pk_mul_f32 v[188:189], v[188:189], s[22:23] op_sel_hi:[1,0]
	v_pk_add_f32 v[128:129], v[104:105], v[128:129]
	v_exp_f32_e32 v188, v188
	v_pk_fma_f32 v[176:177], v[170:171], s[42:43], v[142:143] op_sel_hi:[1,0,0]
	v_exp_f32_e32 v189, v189
	v_pk_fma_f32 v[176:177], v[170:171], v[176:177], s[40:41] op_sel_hi:[1,1,0]
	v_cmp_gt_f32_e64 s[0:1], 0, v120
	v_pk_fma_f32 v[176:177], v[170:171], v[176:177], s[92:93] op_sel_hi:[1,1,0]
	s_nop 0
	v_pk_fma_f32 v[176:177], v[170:171], v[176:177], s[20:21] op_sel_hi:[1,1,0]
	s_nop 0
	v_pk_mul_f32 v[170:171], v[170:171], v[176:177]
	v_pk_mul_f32 v[176:177], v[128:129], v[128:129]
	v_pk_mul_f32 v[170:171], v[188:189], v[170:171]
	s_nop 0
	v_pk_mul_f32 v[188:189], v[120:121], v[170:171]
	v_pk_fma_f32 v[170:171], v[120:121], v[170:171], v[120:121] neg_lo:[1,0,0] neg_hi:[1,0,0]
	v_and_b32_e32 v120, 0x7fffffff, v128
	v_cndmask_b32_e64 v133, v170, v188, s[0:1]
	v_cmp_gt_f32_e64 s[0:1], 0, v121
	v_and_b32_e32 v121, 0x7fffffff, v129
	v_pk_fma_f32 v[120:121], v[120:121], s[2:3], 1.0 op_sel_hi:[1,0,0]
	v_cndmask_b32_e64 v137, v171, v189, s[0:1]
	v_rcp_f32_e32 v120, v120
	v_rcp_f32_e32 v121, v121
	v_cmp_gt_f32_e64 s[0:1], 0, v128
	v_mul_f32_e32 v86, v86, v133
	v_mul_f32_e32 v87, v87, v137
	v_pk_fma_f32 v[170:171], v[120:121], s[42:43], v[142:143] op_sel_hi:[1,0,0]
	s_nop 0
	v_pk_fma_f32 v[170:171], v[120:121], v[170:171], s[40:41] op_sel_hi:[1,1,0]
	s_nop 0
	v_pk_fma_f32 v[170:171], v[120:121], v[170:171], s[92:93] op_sel_hi:[1,1,0]
	s_nop 0
	v_pk_fma_f32 v[170:171], v[120:121], v[170:171], s[20:21] op_sel_hi:[1,1,0]
	s_nop 0
	v_pk_mul_f32 v[120:121], v[120:121], v[170:171]
	v_pk_mul_f32 v[170:171], v[176:177], s[22:23] op_sel_hi:[1,0]
	s_nop 0
	v_exp_f32_e32 v170, v170
	v_exp_f32_e32 v171, v171
	s_nop 0
	v_pk_mul_f32 v[120:121], v[170:171], v[120:121]
	s_nop 0
	v_pk_mul_f32 v[170:171], v[128:129], v[120:121]
	v_pk_fma_f32 v[120:121], v[128:129], v[120:121], v[128:129] neg_lo:[1,0,0] neg_hi:[1,0,0]
	s_nop 0
	v_cndmask_b32_e64 v128, v120, v170, s[0:1]
	v_cmp_gt_f32_e64 s[0:1], 0, v129
	v_cvt_pk_bf16_f32 v120, v86, v87
	v_mul_f32_e32 v86, v88, v128
	s_nop 0
	v_cndmask_b32_e64 v121, v121, v171, s[0:1]
	v_mul_f32_e32 v87, v89, v121
	v_cvt_pk_bf16_f32 v121, v86, v87
	v_mad_i64_i32 v[86:87], s[0:1], v174, s33, v[184:185]
	v_lshl_add_u64 v[88:89], v[86:87], 0, v[186:187]
	global_store_dwordx2 v[88:89], v[120:121], off
	v_mad_i64_i32 v[88:89], s[0:1], v136, s33, v[190:191]
	v_lshl_add_u64 v[170:171], v[88:89], 0, v[186:187]
	v_add_co_u32_e64 v128, s[0:1], s43, v170
	global_load_dword v120, v[134:135], off
	s_nop 0
	v_addc_co_u32_e64 v129, s[0:1], -1, v171, s[0:1]
	v_add_co_u32_e64 v174, s[0:1], s41, v170
	global_load_dwordx2 v[128:129], v[128:129], off offset:-3072
	s_nop 0
	v_addc_co_u32_e64 v175, s[0:1], -1, v171, s[0:1]
	global_load_dwordx2 v[174:175], v[174:175], off offset:-1536
	s_nop 0
	global_load_dwordx2 v[170:171], v[170:171], off
	s_waitcnt vmcnt(3)
	v_pk_mul_f32 v[84:85], v[84:85], v[120:121] op_sel_hi:[1,0]
	v_pk_mul_f32 v[82:83], v[82:83], v[120:121] op_sel_hi:[1,0]
	s_waitcnt vmcnt(2)
	v_lshlrev_b32_e32 v188, 16, v128
	v_and_b32_e32 v189, 0xffff0000, v128
	s_waitcnt vmcnt(1)
	v_lshlrev_b32_e32 v176, 16, v174
	v_and_b32_e32 v177, 0xffff0000, v174
	v_lshlrev_b32_e32 v174, 16, v175
	v_and_b32_e32 v175, 0xffff0000, v175
	v_lshlrev_b32_e32 v128, 16, v129
	v_and_b32_e32 v129, 0xffff0000, v129
	v_pk_mul_f32 v[176:177], v[110:111], v[176:177]
	v_pk_mul_f32 v[174:175], v[112:113], v[174:175]
	s_waitcnt vmcnt(0)
	v_lshlrev_b32_e32 v120, 16, v170
	v_and_b32_e32 v121, 0xffff0000, v170
	v_pk_fma_f32 v[128:129], v[100:101], v[128:129], v[174:175]
	v_pk_fma_f32 v[174:175], v[98:99], v[188:189], v[176:177]
	v_lshlrev_b32_e32 v170, 16, v171
	v_pk_fma_f32 v[120:121], v[106:107], v[120:121], v[174:175]
	v_and_b32_e32 v171, 0xffff0000, v171
	v_pk_add_f32 v[120:121], v[102:103], v[120:121]
	v_pk_fma_f32 v[128:129], v[108:109], v[170:171], v[128:129]
	v_and_b32_e32 v171, 0x7fffffff, v121
	v_and_b32_e32 v170, 0x7fffffff, v120
	v_pk_fma_f32 v[170:171], v[170:171], s[2:3], 1.0 op_sel_hi:[1,0,0]
	v_pk_mul_f32 v[176:177], v[120:121], v[120:121]
	v_rcp_f32_e32 v170, v170
	v_rcp_f32_e32 v171, v171
	v_pk_mul_f32 v[176:177], v[176:177], s[22:23] op_sel_hi:[1,0]
	v_pk_add_f32 v[128:129], v[104:105], v[128:129]
	v_exp_f32_e32 v176, v176
	v_pk_fma_f32 v[174:175], v[170:171], s[42:43], v[142:143] op_sel_hi:[1,0,0]
	v_exp_f32_e32 v177, v177
	v_pk_fma_f32 v[174:175], v[170:171], v[174:175], s[40:41] op_sel_hi:[1,1,0]
	v_cmp_gt_f32_e64 s[0:1], 0, v120
	v_pk_fma_f32 v[174:175], v[170:171], v[174:175], s[92:93] op_sel_hi:[1,1,0]
	s_nop 0
	v_pk_fma_f32 v[174:175], v[170:171], v[174:175], s[20:21] op_sel_hi:[1,1,0]
	s_nop 0
	v_pk_mul_f32 v[170:171], v[170:171], v[174:175]
	v_pk_mul_f32 v[174:175], v[128:129], v[128:129]
	v_pk_mul_f32 v[170:171], v[176:177], v[170:171]
	s_nop 0
	v_pk_mul_f32 v[176:177], v[120:121], v[170:171]
	v_pk_fma_f32 v[170:171], v[120:121], v[170:171], v[120:121] neg_lo:[1,0,0] neg_hi:[1,0,0]
	v_and_b32_e32 v120, 0x7fffffff, v128
	v_cndmask_b32_e64 v133, v170, v176, s[0:1]
	v_cmp_gt_f32_e64 s[0:1], 0, v121
	v_and_b32_e32 v121, 0x7fffffff, v129
	v_pk_fma_f32 v[120:121], v[120:121], s[2:3], 1.0 op_sel_hi:[1,0,0]
	v_cndmask_b32_e64 v137, v171, v177, s[0:1]
	v_rcp_f32_e32 v120, v120
	v_rcp_f32_e32 v121, v121
	v_cmp_gt_f32_e64 s[0:1], 0, v128
	v_mul_f32_e32 v82, v82, v133
	v_mul_f32_e32 v83, v83, v137
	v_pk_fma_f32 v[170:171], v[120:121], s[42:43], v[142:143] op_sel_hi:[1,0,0]
	v_cvt_pk_bf16_f32 v82, v82, v83
	s_nop 0
	v_pk_fma_f32 v[170:171], v[120:121], v[170:171], s[40:41] op_sel_hi:[1,1,0]
	s_nop 0
	v_pk_fma_f32 v[170:171], v[120:121], v[170:171], s[92:93] op_sel_hi:[1,1,0]
	s_nop 0
	v_pk_fma_f32 v[170:171], v[120:121], v[170:171], s[20:21] op_sel_hi:[1,1,0]
	s_nop 0
	v_pk_mul_f32 v[120:121], v[120:121], v[170:171]
	v_pk_mul_f32 v[170:171], v[174:175], s[22:23] op_sel_hi:[1,0]
	s_nop 0
	v_exp_f32_e32 v170, v170
	v_exp_f32_e32 v171, v171
	s_nop 0
	v_pk_mul_f32 v[120:121], v[170:171], v[120:121]
	s_nop 0
	v_pk_mul_f32 v[170:171], v[128:129], v[120:121]
	v_pk_fma_f32 v[120:121], v[128:129], v[120:121], v[128:129] neg_lo:[1,0,0] neg_hi:[1,0,0]
	s_nop 0
	v_cndmask_b32_e64 v120, v120, v170, s[0:1]
	v_cmp_gt_f32_e64 s[0:1], 0, v129
	v_mul_f32_e32 v83, v84, v120
	s_nop 0
	v_cndmask_b32_e64 v121, v121, v171, s[0:1]
	v_mul_f32_e32 v84, v85, v121
	v_cvt_pk_bf16_f32 v83, v83, v84
	v_mad_i64_i32 v[84:85], s[0:1], v136, s33, v[184:185]
	v_lshl_add_u64 v[120:121], v[84:85], 0, v[186:187]
	v_mad_i64_i32 v[176:177], s[0:1], v132, s33, v[190:191]
	global_store_dwordx2 v[120:121], v[82:83], off
	v_lshl_add_u64 v[136:137], v[176:177], 0, v[182:183]
	v_lshl_add_u64 v[170:171], v[176:177], 0, v[180:181]
	v_lshl_add_u64 v[82:83], v[176:177], 0, v[186:187]
	v_lshl_add_u64 v[120:121], v[136:137], 0, v[186:187]
	v_lshl_add_u64 v[128:129], v[170:171], 0, v[186:187]
	global_load_dwordx2 v[82:83], v[82:83], off
	s_nop 0
	global_load_dwordx2 v[120:121], v[120:121], off
	s_nop 0
	global_load_dwordx2 v[128:129], v[128:129], off
	s_nop 0
	global_load_dword v174, v[130:131], off
	s_waitcnt vmcnt(1)
	v_lshlrev_b32_e32 v173, 16, v128
	v_and_b32_e32 v179, 0xffff0000, v128
	v_lshlrev_b32_e32 v133, 16, v120
	v_and_b32_e32 v120, 0xffff0000, v120
	v_cndmask_b32_e64 v181, v179, 0, s[8:9]
	v_cndmask_b32_e64 v180, v173, 0, s[8:9]
	v_lshlrev_b32_e32 v141, 16, v121
	v_and_b32_e32 v165, 0xffff0000, v121
	v_lshlrev_b32_e32 v182, 16, v129
	v_and_b32_e32 v183, 0xffff0000, v129
	v_cndmask_b32_e64 v121, v120, 0, vcc
	v_cndmask_b32_e64 v120, v133, 0, vcc
	v_pk_mul_f32 v[180:181], v[98:99], v[180:181]
	s_waitcnt vmcnt(0)
	v_pk_mul_f32 v[80:81], v[80:81], v[174:175] op_sel_hi:[1,0]
	v_pk_mul_f32 v[78:79], v[78:79], v[174:175] op_sel_hi:[1,0]
	v_lshlrev_b32_e32 v174, 16, v82
	v_and_b32_e32 v175, 0xffff0000, v82
	v_cndmask_b32_e64 v183, v183, 0, s[8:9]
	v_cndmask_b32_e64 v182, v182, 0, s[8:9]
	v_pk_fma_f32 v[120:121], v[110:111], v[120:121], v[180:181]
	v_cndmask_b32_e64 v129, v165, 0, vcc
	v_cndmask_b32_e64 v128, v141, 0, vcc
	v_pk_mul_f32 v[182:183], v[100:101], v[182:183]
	v_pk_fma_f32 v[120:121], v[106:107], v[174:175], v[120:121]
	v_lshlrev_b32_e32 v82, 16, v83
	v_and_b32_e32 v83, 0xffff0000, v83
	v_pk_fma_f32 v[128:129], v[112:113], v[128:129], v[182:183]
	v_pk_add_f32 v[120:121], v[102:103], v[120:121]
	v_pk_fma_f32 v[82:83], v[108:109], v[82:83], v[128:129]
	v_and_b32_e32 v129, 0x7fffffff, v121
	v_and_b32_e32 v128, 0x7fffffff, v120
	v_pk_fma_f32 v[128:129], v[128:129], s[2:3], 1.0 op_sel_hi:[1,0,0]
	v_pk_mul_f32 v[180:181], v[120:121], v[120:121]
	v_rcp_f32_e32 v128, v128
	v_rcp_f32_e32 v129, v129
	v_pk_mul_f32 v[180:181], v[180:181], s[22:23] op_sel_hi:[1,0]
	v_pk_add_f32 v[82:83], v[104:105], v[82:83]
	v_exp_f32_e32 v180, v180
	v_pk_fma_f32 v[174:175], v[128:129], s[42:43], v[142:143] op_sel_hi:[1,0,0]
	v_exp_f32_e32 v181, v181
	v_pk_fma_f32 v[174:175], v[128:129], v[174:175], s[40:41] op_sel_hi:[1,1,0]
	v_cmp_gt_f32_e64 s[0:1], 0, v120
	v_pk_fma_f32 v[174:175], v[128:129], v[174:175], s[92:93] op_sel_hi:[1,1,0]
	s_nop 0
	v_pk_fma_f32 v[174:175], v[128:129], v[174:175], s[20:21] op_sel_hi:[1,1,0]
	s_nop 0
	v_pk_mul_f32 v[128:129], v[128:129], v[174:175]
	v_pk_mul_f32 v[174:175], v[82:83], v[82:83]
	v_pk_mul_f32 v[128:129], v[180:181], v[128:129]
	s_nop 0
	v_pk_mul_f32 v[180:181], v[120:121], v[128:129]
	v_pk_fma_f32 v[128:129], v[120:121], v[128:129], v[120:121] neg_lo:[1,0,0] neg_hi:[1,0,0]
	v_and_b32_e32 v120, 0x7fffffff, v82
	v_cndmask_b32_e64 v133, v128, v180, s[0:1]
	v_cmp_gt_f32_e64 s[0:1], 0, v121
	v_and_b32_e32 v121, 0x7fffffff, v83
	v_pk_fma_f32 v[120:121], v[120:121], s[2:3], 1.0 op_sel_hi:[1,0,0]
	v_cndmask_b32_e64 v141, v129, v181, s[0:1]
	v_rcp_f32_e32 v120, v120
	v_rcp_f32_e32 v121, v121
	v_cmp_gt_f32_e64 s[0:1], 0, v82
	v_mul_f32_e32 v78, v78, v133
	v_mul_f32_e32 v79, v79, v141
	v_pk_fma_f32 v[128:129], v[120:121], s[42:43], v[142:143] op_sel_hi:[1,0,0]
	v_cvt_pk_bf16_f32 v78, v78, v79
	s_nop 0
	v_pk_fma_f32 v[128:129], v[120:121], v[128:129], s[40:41] op_sel_hi:[1,1,0]
	s_nop 0
	v_pk_fma_f32 v[128:129], v[120:121], v[128:129], s[92:93] op_sel_hi:[1,1,0]
	s_nop 0
	v_pk_fma_f32 v[128:129], v[120:121], v[128:129], s[20:21] op_sel_hi:[1,1,0]
	s_nop 0
	v_pk_mul_f32 v[120:121], v[120:121], v[128:129]
	v_pk_mul_f32 v[128:129], v[174:175], s[22:23] op_sel_hi:[1,0]
	s_nop 0
	v_exp_f32_e32 v128, v128
	v_exp_f32_e32 v129, v129
	s_nop 0
	v_pk_mul_f32 v[120:121], v[128:129], v[120:121]
	s_nop 0
	v_pk_mul_f32 v[128:129], v[82:83], v[120:121]
	v_pk_fma_f32 v[120:121], v[82:83], v[120:121], v[82:83] neg_lo:[1,0,0] neg_hi:[1,0,0]
	s_nop 0
	v_cndmask_b32_e64 v82, v120, v128, s[0:1]
	v_cmp_gt_f32_e64 s[0:1], 0, v83
	v_mul_f32_e32 v79, v80, v82
	s_nop 0
	v_cndmask_b32_e64 v83, v121, v129, s[0:1]
	v_mul_f32_e32 v80, v81, v83
	v_mad_i64_i32 v[120:121], s[0:1], v132, s33, v[184:185]
	v_mad_i64_i32 v[128:129], s[0:1], v140, s33, v[190:191]
	v_cvt_pk_bf16_f32 v79, v79, v80
	v_lshl_add_u64 v[80:81], v[120:121], 0, v[186:187]
	v_lshl_add_u64 v[82:83], v[128:129], 0, v[186:187]
	global_store_dwordx2 v[80:81], v[78:79], off
	v_add_co_u32_e64 v80, s[0:1], s43, v82
	global_load_dword v78, v[126:127], off
	s_nop 0
	v_addc_co_u32_e64 v81, s[0:1], -1, v83, s[0:1]
	v_add_co_u32_e64 v132, s[0:1], s41, v82
	global_load_dwordx2 v[80:81], v[80:81], off offset:-3072
	s_nop 0
	v_addc_co_u32_e64 v133, s[0:1], -1, v83, s[0:1]
	global_load_dwordx2 v[132:133], v[132:133], off offset:-1536
	s_nop 0
	global_load_dwordx2 v[82:83], v[82:83], off
	s_waitcnt vmcnt(3)
	v_pk_mul_f32 v[76:77], v[76:77], v[78:79] op_sel_hi:[1,0]
	v_pk_mul_f32 v[74:75], v[74:75], v[78:79] op_sel_hi:[1,0]
	s_waitcnt vmcnt(2)
	v_lshlrev_b32_e32 v180, 16, v80
	v_and_b32_e32 v181, 0xffff0000, v80
	s_waitcnt vmcnt(1)
	v_lshlrev_b32_e32 v174, 16, v132
	v_and_b32_e32 v175, 0xffff0000, v132
	v_lshlrev_b32_e32 v132, 16, v133
	v_and_b32_e32 v133, 0xffff0000, v133
	v_lshlrev_b32_e32 v80, 16, v81
	v_and_b32_e32 v81, 0xffff0000, v81
	v_pk_mul_f32 v[174:175], v[110:111], v[174:175]
	v_pk_mul_f32 v[132:133], v[112:113], v[132:133]
	s_waitcnt vmcnt(0)
	v_lshlrev_b32_e32 v78, 16, v82
	v_and_b32_e32 v79, 0xffff0000, v82
	v_pk_fma_f32 v[80:81], v[100:101], v[80:81], v[132:133]
	v_pk_fma_f32 v[132:133], v[98:99], v[180:181], v[174:175]
	v_lshlrev_b32_e32 v82, 16, v83
	v_pk_fma_f32 v[78:79], v[106:107], v[78:79], v[132:133]
	v_and_b32_e32 v83, 0xffff0000, v83
	v_pk_add_f32 v[78:79], v[102:103], v[78:79]
	v_pk_fma_f32 v[80:81], v[108:109], v[82:83], v[80:81]
	v_and_b32_e32 v83, 0x7fffffff, v79
	v_and_b32_e32 v82, 0x7fffffff, v78
	v_pk_fma_f32 v[82:83], v[82:83], s[2:3], 1.0 op_sel_hi:[1,0,0]
	v_pk_mul_f32 v[174:175], v[78:79], v[78:79]
	v_rcp_f32_e32 v82, v82
	v_rcp_f32_e32 v83, v83
	v_pk_mul_f32 v[174:175], v[174:175], s[22:23] op_sel_hi:[1,0]
	v_pk_add_f32 v[80:81], v[104:105], v[80:81]
	v_exp_f32_e32 v174, v174
	v_pk_fma_f32 v[132:133], v[82:83], s[42:43], v[142:143] op_sel_hi:[1,0,0]
	v_exp_f32_e32 v175, v175
	v_pk_fma_f32 v[132:133], v[82:83], v[132:133], s[40:41] op_sel_hi:[1,1,0]
	v_cmp_gt_f32_e64 s[0:1], 0, v78
	v_pk_fma_f32 v[132:133], v[82:83], v[132:133], s[92:93] op_sel_hi:[1,1,0]
	s_nop 0
	v_pk_fma_f32 v[132:133], v[82:83], v[132:133], s[20:21] op_sel_hi:[1,1,0]
	s_nop 0
	v_pk_mul_f32 v[82:83], v[82:83], v[132:133]
	v_pk_mul_f32 v[132:133], v[80:81], v[80:81]
	v_pk_mul_f32 v[82:83], v[174:175], v[82:83]
	s_nop 0
	v_pk_mul_f32 v[174:175], v[78:79], v[82:83]
	v_pk_fma_f32 v[82:83], v[78:79], v[82:83], v[78:79] neg_lo:[1,0,0] neg_hi:[1,0,0]
	v_and_b32_e32 v78, 0x7fffffff, v80
	v_cndmask_b32_e64 v141, v82, v174, s[0:1]
	v_cmp_gt_f32_e64 s[0:1], 0, v79
	v_and_b32_e32 v79, 0x7fffffff, v81
	v_pk_fma_f32 v[78:79], v[78:79], s[2:3], 1.0 op_sel_hi:[1,0,0]
	v_cndmask_b32_e64 v165, v83, v175, s[0:1]
	v_rcp_f32_e32 v78, v78
	v_rcp_f32_e32 v79, v79
	v_cmp_gt_f32_e64 s[0:1], 0, v80
	v_mul_f32_e32 v74, v74, v141
	v_mul_f32_e32 v75, v75, v165
	v_pk_fma_f32 v[82:83], v[78:79], s[42:43], v[142:143] op_sel_hi:[1,0,0]
	v_cvt_pk_bf16_f32 v74, v74, v75
	s_nop 0
	v_pk_fma_f32 v[82:83], v[78:79], v[82:83], s[40:41] op_sel_hi:[1,1,0]
	s_nop 0
	v_pk_fma_f32 v[82:83], v[78:79], v[82:83], s[92:93] op_sel_hi:[1,1,0]
	s_nop 0
	v_pk_fma_f32 v[82:83], v[78:79], v[82:83], s[20:21] op_sel_hi:[1,1,0]
	s_nop 0
	v_pk_mul_f32 v[78:79], v[78:79], v[82:83]
	v_pk_mul_f32 v[82:83], v[132:133], s[22:23] op_sel_hi:[1,0]
	s_nop 0
	v_exp_f32_e32 v82, v82
	v_exp_f32_e32 v83, v83
	s_nop 0
	v_pk_mul_f32 v[78:79], v[82:83], v[78:79]
	s_nop 0
	v_pk_mul_f32 v[82:83], v[80:81], v[78:79]
	v_pk_fma_f32 v[78:79], v[80:81], v[78:79], v[80:81] neg_lo:[1,0,0] neg_hi:[1,0,0]
	s_nop 0
	v_cndmask_b32_e64 v78, v78, v82, s[0:1]
	v_cmp_gt_f32_e64 s[0:1], 0, v81
	v_mul_f32_e32 v75, v76, v78
	s_nop 0
	v_cndmask_b32_e64 v79, v79, v83, s[0:1]
	v_mul_f32_e32 v76, v77, v79
	v_mad_i64_i32 v[132:133], s[0:1], v140, s33, v[184:185]
	v_mad_i64_i32 v[140:141], s[0:1], v172, s33, v[190:191]
	v_cvt_pk_bf16_f32 v75, v75, v76
	v_lshl_add_u64 v[76:77], v[132:133], 0, v[186:187]
	v_lshl_add_u64 v[78:79], v[140:141], 0, v[186:187]
	global_store_dwordx2 v[76:77], v[74:75], off
	v_add_co_u32_e64 v76, s[0:1], s43, v78
	global_load_dword v74, v[124:125], off
	s_nop 0
	v_addc_co_u32_e64 v77, s[0:1], -1, v79, s[0:1]
	v_add_co_u32_e64 v80, s[0:1], s41, v78
	global_load_dwordx2 v[76:77], v[76:77], off offset:-3072
	s_nop 0
	v_addc_co_u32_e64 v81, s[0:1], -1, v79, s[0:1]
	global_load_dwordx2 v[80:81], v[80:81], off offset:-1536
	s_nop 0
	global_load_dwordx2 v[78:79], v[78:79], off
	s_waitcnt vmcnt(3)
	v_pk_mul_f32 v[72:73], v[72:73], v[74:75] op_sel_hi:[1,0]
	v_pk_mul_f32 v[70:71], v[70:71], v[74:75] op_sel_hi:[1,0]
	s_waitcnt vmcnt(2)
	v_lshlrev_b32_e32 v174, 16, v76
	v_and_b32_e32 v175, 0xffff0000, v76
	s_waitcnt vmcnt(1)
	v_lshlrev_b32_e32 v82, 16, v80
	v_and_b32_e32 v83, 0xffff0000, v80
	v_lshlrev_b32_e32 v80, 16, v81
	v_and_b32_e32 v81, 0xffff0000, v81
	v_lshlrev_b32_e32 v76, 16, v77
	v_and_b32_e32 v77, 0xffff0000, v77
	v_pk_mul_f32 v[82:83], v[110:111], v[82:83]
	v_pk_mul_f32 v[80:81], v[112:113], v[80:81]
	s_waitcnt vmcnt(0)
	v_lshlrev_b32_e32 v74, 16, v78
	v_and_b32_e32 v75, 0xffff0000, v78
	v_pk_fma_f32 v[76:77], v[100:101], v[76:77], v[80:81]
	v_pk_fma_f32 v[80:81], v[98:99], v[174:175], v[82:83]
	v_lshlrev_b32_e32 v78, 16, v79
	v_pk_fma_f32 v[74:75], v[106:107], v[74:75], v[80:81]
	v_and_b32_e32 v79, 0xffff0000, v79
	v_pk_add_f32 v[74:75], v[102:103], v[74:75]
	v_pk_fma_f32 v[76:77], v[108:109], v[78:79], v[76:77]
	v_and_b32_e32 v79, 0x7fffffff, v75
	v_and_b32_e32 v78, 0x7fffffff, v74
	v_pk_fma_f32 v[78:79], v[78:79], s[2:3], 1.0 op_sel_hi:[1,0,0]
	v_pk_mul_f32 v[82:83], v[74:75], v[74:75]
	v_rcp_f32_e32 v78, v78
	v_rcp_f32_e32 v79, v79
	v_pk_mul_f32 v[82:83], v[82:83], s[22:23] op_sel_hi:[1,0]
	v_pk_add_f32 v[76:77], v[104:105], v[76:77]
	v_exp_f32_e32 v82, v82
	v_pk_fma_f32 v[80:81], v[78:79], s[42:43], v[142:143] op_sel_hi:[1,0,0]
	v_exp_f32_e32 v83, v83
	v_pk_fma_f32 v[80:81], v[78:79], v[80:81], s[40:41] op_sel_hi:[1,1,0]
	v_cmp_gt_f32_e64 s[0:1], 0, v74
	v_pk_fma_f32 v[80:81], v[78:79], v[80:81], s[92:93] op_sel_hi:[1,1,0]
	s_nop 0
	v_pk_fma_f32 v[80:81], v[78:79], v[80:81], s[20:21] op_sel_hi:[1,1,0]
	s_nop 0
	v_pk_mul_f32 v[78:79], v[78:79], v[80:81]
	v_pk_mul_f32 v[80:81], v[76:77], v[76:77]
	v_pk_mul_f32 v[78:79], v[82:83], v[78:79]
	s_nop 0
	v_pk_mul_f32 v[82:83], v[74:75], v[78:79]
	v_pk_fma_f32 v[78:79], v[74:75], v[78:79], v[74:75] neg_lo:[1,0,0] neg_hi:[1,0,0]
	v_and_b32_e32 v74, 0x7fffffff, v76
	v_cndmask_b32_e64 v82, v78, v82, s[0:1]
	v_cmp_gt_f32_e64 s[0:1], 0, v75
	v_and_b32_e32 v75, 0x7fffffff, v77
	v_pk_fma_f32 v[74:75], v[74:75], s[2:3], 1.0 op_sel_hi:[1,0,0]
	v_cndmask_b32_e64 v83, v79, v83, s[0:1]
	v_rcp_f32_e32 v74, v74
	v_rcp_f32_e32 v75, v75
	v_cmp_gt_f32_e64 s[0:1], 0, v76
	v_mul_f32_e32 v70, v70, v82
	v_mul_f32_e32 v71, v71, v83
	v_pk_fma_f32 v[78:79], v[74:75], s[42:43], v[142:143] op_sel_hi:[1,0,0]
	v_cvt_pk_bf16_f32 v70, v70, v71
	s_nop 0
	v_pk_fma_f32 v[78:79], v[74:75], v[78:79], s[40:41] op_sel_hi:[1,1,0]
	s_nop 0
	v_pk_fma_f32 v[78:79], v[74:75], v[78:79], s[92:93] op_sel_hi:[1,1,0]
	s_nop 0
	v_pk_fma_f32 v[78:79], v[74:75], v[78:79], s[20:21] op_sel_hi:[1,1,0]
	s_nop 0
	v_pk_mul_f32 v[74:75], v[74:75], v[78:79]
	v_pk_mul_f32 v[78:79], v[80:81], s[22:23] op_sel_hi:[1,0]
	s_nop 0
	v_exp_f32_e32 v78, v78
	v_exp_f32_e32 v79, v79
	s_nop 0
	v_pk_mul_f32 v[74:75], v[78:79], v[74:75]
	s_nop 0
	v_pk_mul_f32 v[78:79], v[76:77], v[74:75]
	v_pk_fma_f32 v[74:75], v[76:77], v[74:75], v[76:77] neg_lo:[1,0,0] neg_hi:[1,0,0]
	s_nop 0
	v_cndmask_b32_e64 v74, v74, v78, s[0:1]
	v_cmp_gt_f32_e64 s[0:1], 0, v77
	v_mul_f32_e32 v71, v72, v74
	s_nop 0
	v_cndmask_b32_e64 v75, v75, v79, s[0:1]
	v_mul_f32_e32 v72, v73, v75
	v_mad_i64_i32 v[172:173], s[0:1], v172, s33, v[184:185]
	v_mad_i64_i32 v[174:175], s[0:1], v178, s33, v[190:191]
	v_cvt_pk_bf16_f32 v71, v71, v72
	v_lshl_add_u64 v[72:73], v[172:173], 0, v[186:187]
	v_lshl_add_u64 v[74:75], v[174:175], 0, v[186:187]
	global_store_dwordx2 v[72:73], v[70:71], off
	v_add_co_u32_e64 v72, s[0:1], s43, v74
	global_load_dword v70, v[122:123], off
	s_nop 0
	v_addc_co_u32_e64 v73, s[0:1], -1, v75, s[0:1]
	v_add_co_u32_e64 v76, s[0:1], s41, v74
	global_load_dwordx2 v[72:73], v[72:73], off offset:-3072
	s_nop 0
	v_addc_co_u32_e64 v77, s[0:1], -1, v75, s[0:1]
	global_load_dwordx2 v[76:77], v[76:77], off offset:-1536
	s_nop 0
	global_load_dwordx2 v[74:75], v[74:75], off
	s_waitcnt vmcnt(3)
	v_pk_mul_f32 v[68:69], v[68:69], v[70:71] op_sel_hi:[1,0]
	v_pk_mul_f32 v[66:67], v[66:67], v[70:71] op_sel_hi:[1,0]
	s_waitcnt vmcnt(2)
	v_lshlrev_b32_e32 v80, 16, v72
	v_and_b32_e32 v81, 0xffff0000, v72
	s_waitcnt vmcnt(1)
	v_lshlrev_b32_e32 v78, 16, v76
	v_and_b32_e32 v79, 0xffff0000, v76
	v_lshlrev_b32_e32 v76, 16, v77
	v_and_b32_e32 v77, 0xffff0000, v77
	v_lshlrev_b32_e32 v72, 16, v73
	v_and_b32_e32 v73, 0xffff0000, v73
	v_pk_mul_f32 v[78:79], v[110:111], v[78:79]
	v_pk_mul_f32 v[76:77], v[112:113], v[76:77]
	s_waitcnt vmcnt(0)
	v_lshlrev_b32_e32 v70, 16, v74
	v_and_b32_e32 v71, 0xffff0000, v74
	v_pk_fma_f32 v[72:73], v[100:101], v[72:73], v[76:77]
	v_pk_fma_f32 v[76:77], v[98:99], v[80:81], v[78:79]
	v_lshlrev_b32_e32 v74, 16, v75
	v_pk_fma_f32 v[70:71], v[106:107], v[70:71], v[76:77]
	v_and_b32_e32 v75, 0xffff0000, v75
	v_pk_add_f32 v[70:71], v[102:103], v[70:71]
	v_pk_fma_f32 v[72:73], v[108:109], v[74:75], v[72:73]
	v_and_b32_e32 v75, 0x7fffffff, v71
	v_and_b32_e32 v74, 0x7fffffff, v70
	v_pk_fma_f32 v[74:75], v[74:75], s[2:3], 1.0 op_sel_hi:[1,0,0]
	v_pk_mul_f32 v[78:79], v[70:71], v[70:71]
	v_rcp_f32_e32 v74, v74
	v_rcp_f32_e32 v75, v75
	v_pk_mul_f32 v[78:79], v[78:79], s[22:23] op_sel_hi:[1,0]
	v_pk_add_f32 v[72:73], v[104:105], v[72:73]
	v_exp_f32_e32 v78, v78
	v_pk_fma_f32 v[76:77], v[74:75], s[42:43], v[142:143] op_sel_hi:[1,0,0]
	v_exp_f32_e32 v79, v79
	v_pk_fma_f32 v[76:77], v[74:75], v[76:77], s[40:41] op_sel_hi:[1,1,0]
	v_cmp_gt_f32_e64 s[0:1], 0, v70
	v_pk_fma_f32 v[76:77], v[74:75], v[76:77], s[92:93] op_sel_hi:[1,1,0]
	v_or_b32_e32 v98, 0x80, v164
	v_pk_fma_f32 v[76:77], v[74:75], v[76:77], s[20:21] op_sel_hi:[1,1,0]
	v_ashrrev_i32_e32 v99, 31, v98
	v_pk_mul_f32 v[74:75], v[74:75], v[76:77]
	v_pk_mul_f32 v[76:77], v[72:73], v[72:73]
	v_pk_mul_f32 v[74:75], v[78:79], v[74:75]
	s_nop 0
	v_pk_mul_f32 v[78:79], v[70:71], v[74:75]
	v_pk_fma_f32 v[74:75], v[70:71], v[74:75], v[70:71] neg_lo:[1,0,0] neg_hi:[1,0,0]
	v_and_b32_e32 v70, 0x7fffffff, v72
	v_cndmask_b32_e64 v78, v74, v78, s[0:1]
	v_cmp_gt_f32_e64 s[0:1], 0, v71
	v_and_b32_e32 v71, 0x7fffffff, v73
	v_pk_fma_f32 v[70:71], v[70:71], s[2:3], 1.0 op_sel_hi:[1,0,0]
	v_cndmask_b32_e64 v79, v75, v79, s[0:1]
	v_rcp_f32_e32 v70, v70
	v_rcp_f32_e32 v71, v71
	v_cmp_gt_f32_e64 s[0:1], 0, v72
	v_mul_f32_e32 v66, v66, v78
	v_mul_f32_e32 v67, v67, v79
	v_pk_fma_f32 v[74:75], v[70:71], s[42:43], v[142:143] op_sel_hi:[1,0,0]
	v_cvt_pk_bf16_f32 v66, v66, v67
	s_nop 0
	v_pk_fma_f32 v[74:75], v[70:71], v[74:75], s[40:41] op_sel_hi:[1,1,0]
	s_nop 0
	v_pk_fma_f32 v[74:75], v[70:71], v[74:75], s[92:93] op_sel_hi:[1,1,0]
	s_nop 0
	v_pk_fma_f32 v[74:75], v[70:71], v[74:75], s[20:21] op_sel_hi:[1,1,0]
	s_nop 0
	v_pk_mul_f32 v[70:71], v[70:71], v[74:75]
	v_pk_mul_f32 v[74:75], v[76:77], s[22:23] op_sel_hi:[1,0]
	s_nop 0
	v_exp_f32_e32 v74, v74
	v_exp_f32_e32 v75, v75
	s_nop 0
	v_pk_mul_f32 v[70:71], v[74:75], v[70:71]
	s_nop 0
	v_pk_mul_f32 v[74:75], v[72:73], v[70:71]
	v_pk_fma_f32 v[70:71], v[72:73], v[70:71], v[72:73] neg_lo:[1,0,0] neg_hi:[1,0,0]
	s_nop 0
	v_cndmask_b32_e64 v70, v70, v74, s[0:1]
	v_cmp_gt_f32_e64 s[0:1], 0, v73
	v_mul_f32_e32 v67, v68, v70
	s_nop 0
	v_cndmask_b32_e64 v71, v71, v75, s[0:1]
	v_mul_f32_e32 v68, v69, v71
	v_mad_i64_i32 v[82:83], s[0:1], v178, s33, v[184:185]
	v_cvt_pk_bf16_f32 v67, v67, v68
	v_lshl_add_u64 v[68:69], v[82:83], 0, v[186:187]
	global_store_dwordx2 v[68:69], v[66:67], off
	v_lshlrev_b64 v[70:71], 2, v[98:99]
	v_lshlrev_b64 v[98:99], 1, v[98:99]
	v_lshl_add_u64 v[72:73], s[38:39], 0, v[70:71]
	v_lshl_add_u64 v[70:71], s[44:45], 0, v[70:71]
	v_lshl_add_u64 v[100:101], v[114:115], 0, v[98:99]
	global_load_dwordx4 v[66:69], v[166:167], off offset:512
	global_load_dwordx4 v[78:81], v[72:73], off
	global_load_dwordx4 v[74:77], v[70:71], off
	s_nop 0
	global_load_dwordx4 v[70:73], v[168:169], off offset:512
	global_load_dwordx2 v[104:105], v[100:101], off
	v_lshl_add_u64 v[100:101], v[116:117], 0, v[98:99]
	global_load_dwordx2 v[102:103], v[100:101], off
	v_lshl_add_u64 v[100:101], v[118:119], 0, v[98:99]
	global_load_dwordx2 v[100:101], v[100:101], off
	s_nop 0
	global_load_dword v106, v[162:163], off
	s_waitcnt vmcnt(2)
	v_lshlrev_b32_e32 v108, 16, v102
	v_and_b32_e32 v102, 0xffff0000, v102
	v_lshlrev_b32_e32 v109, 16, v103
	s_waitcnt vmcnt(1)
	v_lshlrev_b32_e32 v110, 16, v100
	v_and_b32_e32 v111, 0xffff0000, v100
	v_lshlrev_b32_e32 v112, 16, v101
	v_and_b32_e32 v113, 0xffff0000, v101
	v_cndmask_b32_e64 v101, v102, 0, s[6:7]
	v_cndmask_b32_e64 v100, v108, 0, s[6:7]
	v_cndmask_b32_e64 v102, v109, 0, s[6:7]
	v_cndmask_b32_e64 v109, v111, 0, s[10:11]
	v_cndmask_b32_e64 v108, v110, 0, s[10:11]
	v_pk_mul_f32 v[108:109], v[66:67], v[108:109]
	s_waitcnt vmcnt(0)
	v_pk_mul_f32 v[64:65], v[64:65], v[106:107] op_sel_hi:[1,0]
	v_pk_mul_f32 v[62:63], v[62:63], v[106:107] op_sel_hi:[1,0]
	v_lshlrev_b32_e32 v106, 16, v104
	v_and_b32_e32 v107, 0xffff0000, v104
	v_and_b32_e32 v103, 0xffff0000, v103
	v_cndmask_b32_e64 v111, v113, 0, s[10:11]
	v_cndmask_b32_e64 v110, v112, 0, s[10:11]
	v_pk_fma_f32 v[100:101], v[78:79], v[100:101], v[108:109]
	v_cndmask_b32_e64 v103, v103, 0, s[6:7]
	v_pk_mul_f32 v[110:111], v[68:69], v[110:111]
	v_pk_fma_f32 v[100:101], v[74:75], v[106:107], v[100:101]
	v_lshlrev_b32_e32 v104, 16, v105
	v_and_b32_e32 v105, 0xffff0000, v105
	v_pk_fma_f32 v[102:103], v[80:81], v[102:103], v[110:111]
	v_pk_add_f32 v[100:101], v[70:71], v[100:101]
	v_pk_fma_f32 v[102:103], v[76:77], v[104:105], v[102:103]
	v_and_b32_e32 v105, 0x7fffffff, v101
	v_and_b32_e32 v104, 0x7fffffff, v100
	v_pk_fma_f32 v[104:105], v[104:105], s[2:3], 1.0 op_sel_hi:[1,0,0]
	v_pk_mul_f32 v[108:109], v[100:101], v[100:101]
	v_rcp_f32_e32 v104, v104
	v_rcp_f32_e32 v105, v105
	v_pk_mul_f32 v[108:109], v[108:109], s[22:23] op_sel_hi:[1,0]
	v_pk_add_f32 v[102:103], v[72:73], v[102:103]
	v_exp_f32_e32 v108, v108
	v_pk_fma_f32 v[106:107], v[104:105], s[42:43], v[142:143] op_sel_hi:[1,0,0]
	v_exp_f32_e32 v109, v109
	v_pk_fma_f32 v[106:107], v[104:105], v[106:107], s[40:41] op_sel_hi:[1,1,0]
	v_cmp_gt_f32_e64 s[0:1], 0, v100
	v_pk_fma_f32 v[106:107], v[104:105], v[106:107], s[92:93] op_sel_hi:[1,1,0]
	s_nop 0
	v_pk_fma_f32 v[106:107], v[104:105], v[106:107], s[20:21] op_sel_hi:[1,1,0]
	s_nop 0
	v_pk_mul_f32 v[104:105], v[104:105], v[106:107]
	v_pk_mul_f32 v[106:107], v[102:103], v[102:103]
	v_pk_mul_f32 v[104:105], v[108:109], v[104:105]
	s_nop 0
	v_pk_mul_f32 v[108:109], v[100:101], v[104:105]
	v_pk_fma_f32 v[104:105], v[100:101], v[104:105], v[100:101] neg_lo:[1,0,0] neg_hi:[1,0,0]
	v_and_b32_e32 v100, 0x7fffffff, v102
	v_cndmask_b32_e64 v108, v104, v108, s[0:1]
	v_cmp_gt_f32_e64 s[0:1], 0, v101
	v_and_b32_e32 v101, 0x7fffffff, v103
	v_pk_fma_f32 v[100:101], v[100:101], s[2:3], 1.0 op_sel_hi:[1,0,0]
	v_cndmask_b32_e64 v109, v105, v109, s[0:1]
	v_rcp_f32_e32 v100, v100
	v_rcp_f32_e32 v101, v101
	v_cmp_gt_f32_e64 s[0:1], 0, v102
	v_mul_f32_e32 v62, v62, v108
	v_mul_f32_e32 v63, v63, v109
	v_pk_fma_f32 v[104:105], v[100:101], s[42:43], v[142:143] op_sel_hi:[1,0,0]
	v_cvt_pk_bf16_f32 v62, v62, v63
	s_nop 0
	v_pk_fma_f32 v[104:105], v[100:101], v[104:105], s[40:41] op_sel_hi:[1,1,0]
	s_nop 0
	v_pk_fma_f32 v[104:105], v[100:101], v[104:105], s[92:93] op_sel_hi:[1,1,0]
	s_nop 0
	v_pk_fma_f32 v[104:105], v[100:101], v[104:105], s[20:21] op_sel_hi:[1,1,0]
	s_nop 0
	v_pk_mul_f32 v[100:101], v[100:101], v[104:105]
	v_pk_mul_f32 v[104:105], v[106:107], s[22:23] op_sel_hi:[1,0]
	s_nop 0
	v_exp_f32_e32 v104, v104
	v_exp_f32_e32 v105, v105
	s_nop 0
	v_pk_mul_f32 v[100:101], v[104:105], v[100:101]
	s_nop 0
	v_pk_mul_f32 v[104:105], v[102:103], v[100:101]
	v_pk_fma_f32 v[100:101], v[102:103], v[100:101], v[102:103] neg_lo:[1,0,0] neg_hi:[1,0,0]
	s_nop 0
	v_cndmask_b32_e64 v100, v100, v104, s[0:1]
	v_cmp_gt_f32_e64 s[0:1], 0, v103
	v_mul_f32_e32 v63, v64, v100
	s_nop 0
	v_cndmask_b32_e64 v101, v101, v105, s[0:1]
	v_mul_f32_e32 v64, v65, v101
	v_cvt_pk_bf16_f32 v63, v63, v64
	v_lshl_add_u64 v[64:65], v[94:95], 0, v[98:99]
	v_lshl_add_u64 v[100:101], v[96:97], 0, v[98:99]
	global_store_dwordx2 v[64:65], v[62:63], off
	v_add_co_u32_e64 v64, s[0:1], s43, v100
	global_load_dword v62, v[144:145], off
	s_nop 0
	v_addc_co_u32_e64 v65, s[0:1], -1, v101, s[0:1]
	v_add_co_u32_e64 v102, s[0:1], s41, v100
	global_load_dwordx2 v[64:65], v[64:65], off offset:-3072
	s_nop 0
	v_addc_co_u32_e64 v103, s[0:1], -1, v101, s[0:1]
	global_load_dwordx2 v[102:103], v[102:103], off offset:-1536
	s_nop 0
	global_load_dwordx2 v[100:101], v[100:101], off
	s_waitcnt vmcnt(3)
	v_pk_mul_f32 v[60:61], v[60:61], v[62:63] op_sel_hi:[1,0]
	v_pk_mul_f32 v[58:59], v[58:59], v[62:63] op_sel_hi:[1,0]
	s_waitcnt vmcnt(2)
	v_lshlrev_b32_e32 v106, 16, v64
	v_and_b32_e32 v107, 0xffff0000, v64
	s_waitcnt vmcnt(1)
	v_lshlrev_b32_e32 v104, 16, v102
	v_and_b32_e32 v105, 0xffff0000, v102
	v_lshlrev_b32_e32 v102, 16, v103
	v_and_b32_e32 v103, 0xffff0000, v103
	v_lshlrev_b32_e32 v64, 16, v65
	v_and_b32_e32 v65, 0xffff0000, v65
	v_pk_mul_f32 v[104:105], v[78:79], v[104:105]
	v_pk_mul_f32 v[102:103], v[80:81], v[102:103]
	s_waitcnt vmcnt(0)
	v_lshlrev_b32_e32 v62, 16, v100
	v_and_b32_e32 v63, 0xffff0000, v100
	v_pk_fma_f32 v[64:65], v[68:69], v[64:65], v[102:103]
	v_pk_fma_f32 v[102:103], v[66:67], v[106:107], v[104:105]
	v_lshlrev_b32_e32 v100, 16, v101
	v_pk_fma_f32 v[62:63], v[74:75], v[62:63], v[102:103]
	v_and_b32_e32 v101, 0xffff0000, v101
	v_pk_add_f32 v[62:63], v[70:71], v[62:63]
	v_pk_fma_f32 v[64:65], v[76:77], v[100:101], v[64:65]
	v_and_b32_e32 v101, 0x7fffffff, v63
	v_and_b32_e32 v100, 0x7fffffff, v62
	v_pk_fma_f32 v[100:101], v[100:101], s[2:3], 1.0 op_sel_hi:[1,0,0]
	v_pk_mul_f32 v[104:105], v[62:63], v[62:63]
	v_rcp_f32_e32 v100, v100
	v_rcp_f32_e32 v101, v101
	v_pk_mul_f32 v[104:105], v[104:105], s[22:23] op_sel_hi:[1,0]
	v_pk_add_f32 v[64:65], v[72:73], v[64:65]
	v_exp_f32_e32 v104, v104
	v_pk_fma_f32 v[102:103], v[100:101], s[42:43], v[142:143] op_sel_hi:[1,0,0]
	v_exp_f32_e32 v105, v105
	v_pk_fma_f32 v[102:103], v[100:101], v[102:103], s[40:41] op_sel_hi:[1,1,0]
	v_cmp_gt_f32_e64 s[0:1], 0, v62
	v_pk_fma_f32 v[102:103], v[100:101], v[102:103], s[92:93] op_sel_hi:[1,1,0]
	s_nop 0
	v_pk_fma_f32 v[102:103], v[100:101], v[102:103], s[20:21] op_sel_hi:[1,1,0]
	s_nop 0
	v_pk_mul_f32 v[100:101], v[100:101], v[102:103]
	v_pk_mul_f32 v[102:103], v[64:65], v[64:65]
	v_pk_mul_f32 v[100:101], v[104:105], v[100:101]
	s_nop 0
	v_pk_mul_f32 v[104:105], v[62:63], v[100:101]
	v_pk_fma_f32 v[100:101], v[62:63], v[100:101], v[62:63] neg_lo:[1,0,0] neg_hi:[1,0,0]
	v_and_b32_e32 v62, 0x7fffffff, v64
	v_cndmask_b32_e64 v104, v100, v104, s[0:1]
	v_cmp_gt_f32_e64 s[0:1], 0, v63
	v_and_b32_e32 v63, 0x7fffffff, v65
	v_pk_fma_f32 v[62:63], v[62:63], s[2:3], 1.0 op_sel_hi:[1,0,0]
	v_cndmask_b32_e64 v105, v101, v105, s[0:1]
	v_rcp_f32_e32 v62, v62
	v_rcp_f32_e32 v63, v63
	v_cmp_gt_f32_e64 s[0:1], 0, v64
	v_mul_f32_e32 v58, v58, v104
	v_mul_f32_e32 v59, v59, v105
	v_pk_fma_f32 v[100:101], v[62:63], s[42:43], v[142:143] op_sel_hi:[1,0,0]
	v_cvt_pk_bf16_f32 v58, v58, v59
	s_nop 0
	v_pk_fma_f32 v[100:101], v[62:63], v[100:101], s[40:41] op_sel_hi:[1,1,0]
	s_nop 0
	v_pk_fma_f32 v[100:101], v[62:63], v[100:101], s[92:93] op_sel_hi:[1,1,0]
	s_nop 0
	v_pk_fma_f32 v[100:101], v[62:63], v[100:101], s[20:21] op_sel_hi:[1,1,0]
	s_nop 0
	v_pk_mul_f32 v[62:63], v[62:63], v[100:101]
	v_pk_mul_f32 v[100:101], v[102:103], s[22:23] op_sel_hi:[1,0]
	s_nop 0
	v_exp_f32_e32 v100, v100
	v_exp_f32_e32 v101, v101
	s_nop 0
	v_pk_mul_f32 v[62:63], v[100:101], v[62:63]
	s_nop 0
	v_pk_mul_f32 v[100:101], v[64:65], v[62:63]
	v_pk_fma_f32 v[62:63], v[64:65], v[62:63], v[64:65] neg_lo:[1,0,0] neg_hi:[1,0,0]
	s_nop 0
	v_cndmask_b32_e64 v62, v62, v100, s[0:1]
	v_cmp_gt_f32_e64 s[0:1], 0, v65
	v_mul_f32_e32 v59, v60, v62
	s_nop 0
	v_cndmask_b32_e64 v63, v63, v101, s[0:1]
	v_mul_f32_e32 v60, v61, v63
	v_cvt_pk_bf16_f32 v59, v59, v60
	v_lshl_add_u64 v[60:61], v[90:91], 0, v[98:99]
	v_lshl_add_u64 v[62:63], v[92:93], 0, v[98:99]
	global_store_dwordx2 v[60:61], v[58:59], off
	v_add_co_u32_e64 v60, s[0:1], s43, v62
	global_load_dword v58, v[138:139], off
	s_nop 0
	v_addc_co_u32_e64 v61, s[0:1], -1, v63, s[0:1]
	v_add_co_u32_e64 v64, s[0:1], s41, v62
	global_load_dwordx2 v[60:61], v[60:61], off offset:-3072
	s_nop 0
	v_addc_co_u32_e64 v65, s[0:1], -1, v63, s[0:1]
	global_load_dwordx2 v[64:65], v[64:65], off offset:-1536
	s_nop 0
	global_load_dwordx2 v[62:63], v[62:63], off
	s_waitcnt vmcnt(3)
	v_pk_mul_f32 v[56:57], v[56:57], v[58:59] op_sel_hi:[1,0]
	v_pk_mul_f32 v[54:55], v[54:55], v[58:59] op_sel_hi:[1,0]
	s_waitcnt vmcnt(2)
	v_lshlrev_b32_e32 v102, 16, v60
	v_and_b32_e32 v103, 0xffff0000, v60
	s_waitcnt vmcnt(1)
	v_lshlrev_b32_e32 v100, 16, v64
	v_and_b32_e32 v101, 0xffff0000, v64
	v_lshlrev_b32_e32 v64, 16, v65
	v_and_b32_e32 v65, 0xffff0000, v65
	v_lshlrev_b32_e32 v60, 16, v61
	v_and_b32_e32 v61, 0xffff0000, v61
	v_pk_mul_f32 v[100:101], v[78:79], v[100:101]
	v_pk_mul_f32 v[64:65], v[80:81], v[64:65]
	s_waitcnt vmcnt(0)
	v_lshlrev_b32_e32 v58, 16, v62
	v_and_b32_e32 v59, 0xffff0000, v62
	v_pk_fma_f32 v[60:61], v[68:69], v[60:61], v[64:65]
	v_pk_fma_f32 v[64:65], v[66:67], v[102:103], v[100:101]
	v_lshlrev_b32_e32 v62, 16, v63
	v_pk_fma_f32 v[58:59], v[74:75], v[58:59], v[64:65]
	v_and_b32_e32 v63, 0xffff0000, v63
	v_pk_add_f32 v[58:59], v[70:71], v[58:59]
	v_pk_fma_f32 v[60:61], v[76:77], v[62:63], v[60:61]
	v_and_b32_e32 v63, 0x7fffffff, v59
	v_and_b32_e32 v62, 0x7fffffff, v58
	v_pk_fma_f32 v[62:63], v[62:63], s[2:3], 1.0 op_sel_hi:[1,0,0]
	v_pk_mul_f32 v[100:101], v[58:59], v[58:59]
	v_rcp_f32_e32 v62, v62
	v_rcp_f32_e32 v63, v63
	v_pk_mul_f32 v[100:101], v[100:101], s[22:23] op_sel_hi:[1,0]
	v_pk_add_f32 v[60:61], v[72:73], v[60:61]
	v_exp_f32_e32 v100, v100
	v_pk_fma_f32 v[64:65], v[62:63], s[42:43], v[142:143] op_sel_hi:[1,0,0]
	v_exp_f32_e32 v101, v101
	v_pk_fma_f32 v[64:65], v[62:63], v[64:65], s[40:41] op_sel_hi:[1,1,0]
	v_cmp_gt_f32_e64 s[0:1], 0, v58
	v_pk_fma_f32 v[64:65], v[62:63], v[64:65], s[92:93] op_sel_hi:[1,1,0]
	s_nop 0
	v_pk_fma_f32 v[64:65], v[62:63], v[64:65], s[20:21] op_sel_hi:[1,1,0]
	s_nop 0
	v_pk_mul_f32 v[62:63], v[62:63], v[64:65]
	v_pk_mul_f32 v[64:65], v[60:61], v[60:61]
	v_pk_mul_f32 v[62:63], v[100:101], v[62:63]
	s_nop 0
	v_pk_mul_f32 v[100:101], v[58:59], v[62:63]
	v_pk_fma_f32 v[62:63], v[58:59], v[62:63], v[58:59] neg_lo:[1,0,0] neg_hi:[1,0,0]
	v_and_b32_e32 v58, 0x7fffffff, v60
	v_cndmask_b32_e64 v100, v62, v100, s[0:1]
	v_cmp_gt_f32_e64 s[0:1], 0, v59
	v_and_b32_e32 v59, 0x7fffffff, v61
	v_pk_fma_f32 v[58:59], v[58:59], s[2:3], 1.0 op_sel_hi:[1,0,0]
	v_cndmask_b32_e64 v101, v63, v101, s[0:1]
	v_rcp_f32_e32 v58, v58
	v_rcp_f32_e32 v59, v59
	v_cmp_gt_f32_e64 s[0:1], 0, v60
	v_mul_f32_e32 v54, v54, v100
	v_mul_f32_e32 v55, v55, v101
	v_pk_fma_f32 v[62:63], v[58:59], s[42:43], v[142:143] op_sel_hi:[1,0,0]
	v_cvt_pk_bf16_f32 v54, v54, v55
	s_nop 0
	v_pk_fma_f32 v[62:63], v[58:59], v[62:63], s[40:41] op_sel_hi:[1,1,0]
	s_nop 0
	v_pk_fma_f32 v[62:63], v[58:59], v[62:63], s[92:93] op_sel_hi:[1,1,0]
	s_nop 0
	v_pk_fma_f32 v[62:63], v[58:59], v[62:63], s[20:21] op_sel_hi:[1,1,0]
	s_nop 0
	v_pk_mul_f32 v[58:59], v[58:59], v[62:63]
	v_pk_mul_f32 v[62:63], v[64:65], s[22:23] op_sel_hi:[1,0]
	s_nop 0
	v_exp_f32_e32 v62, v62
	v_exp_f32_e32 v63, v63
	s_nop 0
	v_pk_mul_f32 v[58:59], v[62:63], v[58:59]
	s_nop 0
	v_pk_mul_f32 v[62:63], v[60:61], v[58:59]
	v_pk_fma_f32 v[58:59], v[60:61], v[58:59], v[60:61] neg_lo:[1,0,0] neg_hi:[1,0,0]
	s_nop 0
	v_cndmask_b32_e64 v58, v58, v62, s[0:1]
	v_cmp_gt_f32_e64 s[0:1], 0, v61
	v_mul_f32_e32 v55, v56, v58
	s_nop 0
	v_cndmask_b32_e64 v59, v59, v63, s[0:1]
	v_mul_f32_e32 v56, v57, v59
	v_cvt_pk_bf16_f32 v55, v55, v56
	v_lshl_add_u64 v[56:57], v[86:87], 0, v[98:99]
	v_lshl_add_u64 v[58:59], v[88:89], 0, v[98:99]
	global_store_dwordx2 v[56:57], v[54:55], off
	v_add_co_u32_e64 v56, s[0:1], s43, v58
	global_load_dword v54, v[134:135], off
	s_nop 0
	v_addc_co_u32_e64 v57, s[0:1], -1, v59, s[0:1]
	v_add_co_u32_e64 v60, s[0:1], s41, v58
	global_load_dwordx2 v[56:57], v[56:57], off offset:-3072
	s_nop 0
	v_addc_co_u32_e64 v61, s[0:1], -1, v59, s[0:1]
	global_load_dwordx2 v[60:61], v[60:61], off offset:-1536
	s_nop 0
	global_load_dwordx2 v[58:59], v[58:59], off
	s_waitcnt vmcnt(3)
	v_pk_mul_f32 v[52:53], v[52:53], v[54:55] op_sel_hi:[1,0]
	v_pk_mul_f32 v[50:51], v[50:51], v[54:55] op_sel_hi:[1,0]
	s_waitcnt vmcnt(2)
	v_lshlrev_b32_e32 v64, 16, v56
	v_and_b32_e32 v65, 0xffff0000, v56
	s_waitcnt vmcnt(1)
	v_lshlrev_b32_e32 v62, 16, v60
	v_and_b32_e32 v63, 0xffff0000, v60
	v_lshlrev_b32_e32 v60, 16, v61
	v_and_b32_e32 v61, 0xffff0000, v61
	v_lshlrev_b32_e32 v56, 16, v57
	v_and_b32_e32 v57, 0xffff0000, v57
	v_pk_mul_f32 v[62:63], v[78:79], v[62:63]
	v_pk_mul_f32 v[60:61], v[80:81], v[60:61]
	s_waitcnt vmcnt(0)
	v_lshlrev_b32_e32 v54, 16, v58
	v_and_b32_e32 v55, 0xffff0000, v58
	v_pk_fma_f32 v[56:57], v[68:69], v[56:57], v[60:61]
	v_pk_fma_f32 v[60:61], v[66:67], v[64:65], v[62:63]
	v_lshlrev_b32_e32 v58, 16, v59
	v_pk_fma_f32 v[54:55], v[74:75], v[54:55], v[60:61]
	v_and_b32_e32 v59, 0xffff0000, v59
	v_pk_add_f32 v[54:55], v[70:71], v[54:55]
	v_pk_fma_f32 v[56:57], v[76:77], v[58:59], v[56:57]
	v_and_b32_e32 v59, 0x7fffffff, v55
	v_and_b32_e32 v58, 0x7fffffff, v54
	v_pk_fma_f32 v[58:59], v[58:59], s[2:3], 1.0 op_sel_hi:[1,0,0]
	v_pk_mul_f32 v[62:63], v[54:55], v[54:55]
	v_rcp_f32_e32 v58, v58
	v_rcp_f32_e32 v59, v59
	v_pk_mul_f32 v[62:63], v[62:63], s[22:23] op_sel_hi:[1,0]
	v_pk_add_f32 v[56:57], v[72:73], v[56:57]
	v_exp_f32_e32 v62, v62
	v_pk_fma_f32 v[60:61], v[58:59], s[42:43], v[142:143] op_sel_hi:[1,0,0]
	v_exp_f32_e32 v63, v63
	v_pk_fma_f32 v[60:61], v[58:59], v[60:61], s[40:41] op_sel_hi:[1,1,0]
	v_cmp_gt_f32_e64 s[0:1], 0, v54
	v_pk_fma_f32 v[60:61], v[58:59], v[60:61], s[92:93] op_sel_hi:[1,1,0]
	s_nop 0
	v_pk_fma_f32 v[60:61], v[58:59], v[60:61], s[20:21] op_sel_hi:[1,1,0]
	s_nop 0
	v_pk_mul_f32 v[58:59], v[58:59], v[60:61]
	v_pk_mul_f32 v[60:61], v[56:57], v[56:57]
	v_pk_mul_f32 v[58:59], v[62:63], v[58:59]
	s_nop 0
	v_pk_mul_f32 v[62:63], v[54:55], v[58:59]
	v_pk_fma_f32 v[58:59], v[54:55], v[58:59], v[54:55] neg_lo:[1,0,0] neg_hi:[1,0,0]
	v_and_b32_e32 v54, 0x7fffffff, v56
	v_cndmask_b32_e64 v62, v58, v62, s[0:1]
	v_cmp_gt_f32_e64 s[0:1], 0, v55
	v_and_b32_e32 v55, 0x7fffffff, v57
	v_pk_fma_f32 v[54:55], v[54:55], s[2:3], 1.0 op_sel_hi:[1,0,0]
	v_cndmask_b32_e64 v63, v59, v63, s[0:1]
	v_rcp_f32_e32 v54, v54
	v_rcp_f32_e32 v55, v55
	v_cmp_gt_f32_e64 s[0:1], 0, v56
	v_mul_f32_e32 v50, v50, v62
	v_mul_f32_e32 v51, v51, v63
	v_pk_fma_f32 v[58:59], v[54:55], s[42:43], v[142:143] op_sel_hi:[1,0,0]
	v_cvt_pk_bf16_f32 v50, v50, v51
	s_nop 0
	v_pk_fma_f32 v[58:59], v[54:55], v[58:59], s[40:41] op_sel_hi:[1,1,0]
	s_nop 0
	v_pk_fma_f32 v[58:59], v[54:55], v[58:59], s[92:93] op_sel_hi:[1,1,0]
	s_nop 0
	v_pk_fma_f32 v[58:59], v[54:55], v[58:59], s[20:21] op_sel_hi:[1,1,0]
	s_nop 0
	v_pk_mul_f32 v[54:55], v[54:55], v[58:59]
	v_pk_mul_f32 v[58:59], v[60:61], s[22:23] op_sel_hi:[1,0]
	s_nop 0
	v_exp_f32_e32 v58, v58
	v_exp_f32_e32 v59, v59
	s_nop 0
	v_pk_mul_f32 v[54:55], v[58:59], v[54:55]
	s_nop 0
	v_pk_mul_f32 v[58:59], v[56:57], v[54:55]
	v_pk_fma_f32 v[54:55], v[56:57], v[54:55], v[56:57] neg_lo:[1,0,0] neg_hi:[1,0,0]
	s_nop 0
	v_cndmask_b32_e64 v54, v54, v58, s[0:1]
	v_cmp_gt_f32_e64 s[0:1], 0, v57
	v_mul_f32_e32 v51, v52, v54
	s_nop 0
	v_cndmask_b32_e64 v55, v55, v59, s[0:1]
	v_mul_f32_e32 v52, v53, v55
	v_cvt_pk_bf16_f32 v51, v51, v52
	v_lshl_add_u64 v[52:53], v[84:85], 0, v[98:99]
	global_store_dwordx2 v[52:53], v[50:51], off
	v_lshl_add_u64 v[50:51], v[176:177], 0, v[98:99]
	v_lshl_add_u64 v[52:53], v[136:137], 0, v[98:99]
	global_load_dwordx2 v[50:51], v[50:51], off
	v_lshl_add_u64 v[54:55], v[170:171], 0, v[98:99]
	global_load_dwordx2 v[52:53], v[52:53], off
	s_nop 0
	global_load_dwordx2 v[54:55], v[54:55], off
	s_nop 0
	global_load_dword v56, v[130:131], off
	s_waitcnt vmcnt(2)
	v_lshlrev_b32_e32 v58, 16, v52
	v_and_b32_e32 v52, 0xffff0000, v52
	v_lshlrev_b32_e32 v59, 16, v53
	s_waitcnt vmcnt(1)
	v_lshlrev_b32_e32 v61, 16, v54
	v_and_b32_e32 v62, 0xffff0000, v54
	v_and_b32_e32 v60, 0xffff0000, v53
	v_cndmask_b32_e64 v53, v52, 0, vcc
	v_cndmask_b32_e64 v52, v58, 0, vcc
	v_cndmask_b32_e64 v54, v59, 0, vcc
	v_cndmask_b32_e64 v59, v62, 0, s[8:9]
	v_cndmask_b32_e64 v58, v61, 0, s[8:9]
	v_lshlrev_b32_e32 v63, 16, v55
	v_and_b32_e32 v64, 0xffff0000, v55
	v_pk_mul_f32 v[58:59], v[66:67], v[58:59]
	s_waitcnt vmcnt(0)
	v_pk_mul_f32 v[48:49], v[48:49], v[56:57] op_sel_hi:[1,0]
	v_pk_mul_f32 v[46:47], v[46:47], v[56:57] op_sel_hi:[1,0]
	v_lshlrev_b32_e32 v56, 16, v50
	v_and_b32_e32 v57, 0xffff0000, v50
	v_cndmask_b32_e64 v55, v60, 0, vcc
	v_cndmask_b32_e64 v61, v64, 0, s[8:9]
	v_cndmask_b32_e64 v60, v63, 0, s[8:9]
	v_pk_fma_f32 v[52:53], v[78:79], v[52:53], v[58:59]
	v_pk_mul_f32 v[60:61], v[68:69], v[60:61]
	v_pk_fma_f32 v[52:53], v[74:75], v[56:57], v[52:53]
	v_lshlrev_b32_e32 v50, 16, v51
	v_and_b32_e32 v51, 0xffff0000, v51
	v_pk_fma_f32 v[54:55], v[80:81], v[54:55], v[60:61]
	v_pk_add_f32 v[52:53], v[70:71], v[52:53]
	v_pk_fma_f32 v[50:51], v[76:77], v[50:51], v[54:55]
	v_and_b32_e32 v55, 0x7fffffff, v53
	v_and_b32_e32 v54, 0x7fffffff, v52
	v_pk_fma_f32 v[54:55], v[54:55], s[2:3], 1.0 op_sel_hi:[1,0,0]
	v_pk_mul_f32 v[58:59], v[52:53], v[52:53]
	v_rcp_f32_e32 v54, v54
	v_rcp_f32_e32 v55, v55
	v_pk_mul_f32 v[58:59], v[58:59], s[22:23] op_sel_hi:[1,0]
	v_pk_add_f32 v[50:51], v[72:73], v[50:51]
	v_exp_f32_e32 v58, v58
	v_pk_fma_f32 v[56:57], v[54:55], s[42:43], v[142:143] op_sel_hi:[1,0,0]
	v_exp_f32_e32 v59, v59
	v_pk_fma_f32 v[56:57], v[54:55], v[56:57], s[40:41] op_sel_hi:[1,1,0]
	v_cmp_gt_f32_e64 s[0:1], 0, v52
	v_pk_fma_f32 v[56:57], v[54:55], v[56:57], s[92:93] op_sel_hi:[1,1,0]
	s_nop 0
	v_pk_fma_f32 v[56:57], v[54:55], v[56:57], s[20:21] op_sel_hi:[1,1,0]
	s_nop 0
	v_pk_mul_f32 v[54:55], v[54:55], v[56:57]
	v_pk_mul_f32 v[56:57], v[50:51], v[50:51]
	v_pk_mul_f32 v[54:55], v[58:59], v[54:55]
	s_nop 0
	v_pk_mul_f32 v[58:59], v[52:53], v[54:55]
	v_pk_fma_f32 v[54:55], v[52:53], v[54:55], v[52:53] neg_lo:[1,0,0] neg_hi:[1,0,0]
	v_and_b32_e32 v52, 0x7fffffff, v50
	v_cndmask_b32_e64 v58, v54, v58, s[0:1]
	v_cmp_gt_f32_e64 s[0:1], 0, v53
	v_and_b32_e32 v53, 0x7fffffff, v51
	v_pk_fma_f32 v[52:53], v[52:53], s[2:3], 1.0 op_sel_hi:[1,0,0]
	v_cndmask_b32_e64 v59, v55, v59, s[0:1]
	v_rcp_f32_e32 v52, v52
	v_rcp_f32_e32 v53, v53
	v_cmp_gt_f32_e64 s[0:1], 0, v50
	v_mul_f32_e32 v46, v46, v58
	v_mul_f32_e32 v47, v47, v59
	v_pk_fma_f32 v[54:55], v[52:53], s[42:43], v[142:143] op_sel_hi:[1,0,0]
	v_cvt_pk_bf16_f32 v46, v46, v47
	s_nop 0
	v_pk_fma_f32 v[54:55], v[52:53], v[54:55], s[40:41] op_sel_hi:[1,1,0]
	s_nop 0
	v_pk_fma_f32 v[54:55], v[52:53], v[54:55], s[92:93] op_sel_hi:[1,1,0]
	s_nop 0
	v_pk_fma_f32 v[54:55], v[52:53], v[54:55], s[20:21] op_sel_hi:[1,1,0]
	s_nop 0
	v_pk_mul_f32 v[52:53], v[52:53], v[54:55]
	v_pk_mul_f32 v[54:55], v[56:57], s[22:23] op_sel_hi:[1,0]
	s_nop 0
	v_exp_f32_e32 v54, v54
	v_exp_f32_e32 v55, v55
	s_nop 0
	v_pk_mul_f32 v[52:53], v[54:55], v[52:53]
	s_nop 0
	v_pk_mul_f32 v[54:55], v[50:51], v[52:53]
	v_pk_fma_f32 v[52:53], v[50:51], v[52:53], v[50:51] neg_lo:[1,0,0] neg_hi:[1,0,0]
	s_nop 0
	v_cndmask_b32_e64 v50, v52, v54, s[0:1]
	v_cmp_gt_f32_e64 s[0:1], 0, v51
	v_mul_f32_e32 v47, v48, v50
	s_nop 0
	v_cndmask_b32_e64 v51, v53, v55, s[0:1]
	v_mul_f32_e32 v48, v49, v51
	v_cvt_pk_bf16_f32 v47, v47, v48
	v_lshl_add_u64 v[48:49], v[120:121], 0, v[98:99]
	v_lshl_add_u64 v[50:51], v[128:129], 0, v[98:99]
	global_store_dwordx2 v[48:49], v[46:47], off
	v_add_co_u32_e64 v48, s[0:1], s43, v50
	global_load_dword v46, v[126:127], off
	s_nop 0
	v_addc_co_u32_e64 v49, s[0:1], -1, v51, s[0:1]
	v_add_co_u32_e64 v52, s[0:1], s41, v50
	global_load_dwordx2 v[48:49], v[48:49], off offset:-3072
	s_nop 0
	v_addc_co_u32_e64 v53, s[0:1], -1, v51, s[0:1]
	global_load_dwordx2 v[52:53], v[52:53], off offset:-1536
	s_nop 0
	global_load_dwordx2 v[50:51], v[50:51], off
	s_waitcnt vmcnt(3)
	v_pk_mul_f32 v[44:45], v[44:45], v[46:47] op_sel_hi:[1,0]
	v_pk_mul_f32 v[42:43], v[42:43], v[46:47] op_sel_hi:[1,0]
	s_waitcnt vmcnt(2)
	v_lshlrev_b32_e32 v56, 16, v48
	v_and_b32_e32 v57, 0xffff0000, v48
	s_waitcnt vmcnt(1)
	v_lshlrev_b32_e32 v54, 16, v52
	v_and_b32_e32 v55, 0xffff0000, v52
	v_lshlrev_b32_e32 v52, 16, v53
	v_and_b32_e32 v53, 0xffff0000, v53
	v_lshlrev_b32_e32 v48, 16, v49
	v_and_b32_e32 v49, 0xffff0000, v49
	v_pk_mul_f32 v[54:55], v[78:79], v[54:55]
	v_pk_mul_f32 v[52:53], v[80:81], v[52:53]
	s_waitcnt vmcnt(0)
	v_lshlrev_b32_e32 v46, 16, v50
	v_and_b32_e32 v47, 0xffff0000, v50
	v_pk_fma_f32 v[48:49], v[68:69], v[48:49], v[52:53]
	v_pk_fma_f32 v[52:53], v[66:67], v[56:57], v[54:55]
	v_lshlrev_b32_e32 v50, 16, v51
	v_pk_fma_f32 v[46:47], v[74:75], v[46:47], v[52:53]
	v_and_b32_e32 v51, 0xffff0000, v51
	v_pk_add_f32 v[46:47], v[70:71], v[46:47]
	v_pk_fma_f32 v[48:49], v[76:77], v[50:51], v[48:49]
	v_and_b32_e32 v51, 0x7fffffff, v47
	v_and_b32_e32 v50, 0x7fffffff, v46
	v_pk_fma_f32 v[50:51], v[50:51], s[2:3], 1.0 op_sel_hi:[1,0,0]
	v_pk_mul_f32 v[54:55], v[46:47], v[46:47]
	v_rcp_f32_e32 v50, v50
	v_rcp_f32_e32 v51, v51
	v_pk_mul_f32 v[54:55], v[54:55], s[22:23] op_sel_hi:[1,0]
	v_pk_add_f32 v[48:49], v[72:73], v[48:49]
	v_exp_f32_e32 v54, v54
	v_pk_fma_f32 v[52:53], v[50:51], s[42:43], v[142:143] op_sel_hi:[1,0,0]
	v_exp_f32_e32 v55, v55
	v_pk_fma_f32 v[52:53], v[50:51], v[52:53], s[40:41] op_sel_hi:[1,1,0]
	v_cmp_gt_f32_e64 s[0:1], 0, v46
	v_pk_fma_f32 v[52:53], v[50:51], v[52:53], s[92:93] op_sel_hi:[1,1,0]
	s_nop 0
	v_pk_fma_f32 v[52:53], v[50:51], v[52:53], s[20:21] op_sel_hi:[1,1,0]
	s_nop 0
	v_pk_mul_f32 v[50:51], v[50:51], v[52:53]
	v_pk_mul_f32 v[52:53], v[48:49], v[48:49]
	v_pk_mul_f32 v[50:51], v[54:55], v[50:51]
	s_nop 0
	v_pk_mul_f32 v[54:55], v[46:47], v[50:51]
	v_pk_fma_f32 v[50:51], v[46:47], v[50:51], v[46:47] neg_lo:[1,0,0] neg_hi:[1,0,0]
	v_and_b32_e32 v46, 0x7fffffff, v48
	v_cndmask_b32_e64 v54, v50, v54, s[0:1]
	v_cmp_gt_f32_e64 s[0:1], 0, v47
	v_and_b32_e32 v47, 0x7fffffff, v49
	v_pk_fma_f32 v[46:47], v[46:47], s[2:3], 1.0 op_sel_hi:[1,0,0]
	v_cndmask_b32_e64 v55, v51, v55, s[0:1]
	v_rcp_f32_e32 v46, v46
	v_rcp_f32_e32 v47, v47
	v_cmp_gt_f32_e64 s[0:1], 0, v48
	v_mul_f32_e32 v42, v42, v54
	v_mul_f32_e32 v43, v43, v55
	v_pk_fma_f32 v[50:51], v[46:47], s[42:43], v[142:143] op_sel_hi:[1,0,0]
	v_cvt_pk_bf16_f32 v42, v42, v43
	s_nop 0
	v_pk_fma_f32 v[50:51], v[46:47], v[50:51], s[40:41] op_sel_hi:[1,1,0]
	s_nop 0
	v_pk_fma_f32 v[50:51], v[46:47], v[50:51], s[92:93] op_sel_hi:[1,1,0]
	s_nop 0
	v_pk_fma_f32 v[50:51], v[46:47], v[50:51], s[20:21] op_sel_hi:[1,1,0]
	s_nop 0
	v_pk_mul_f32 v[46:47], v[46:47], v[50:51]
	v_pk_mul_f32 v[50:51], v[52:53], s[22:23] op_sel_hi:[1,0]
	s_nop 0
	v_exp_f32_e32 v50, v50
	v_exp_f32_e32 v51, v51
	s_nop 0
	v_pk_mul_f32 v[46:47], v[50:51], v[46:47]
	s_nop 0
	v_pk_mul_f32 v[50:51], v[48:49], v[46:47]
	v_pk_fma_f32 v[46:47], v[48:49], v[46:47], v[48:49] neg_lo:[1,0,0] neg_hi:[1,0,0]
	s_nop 0
	v_cndmask_b32_e64 v46, v46, v50, s[0:1]
	v_cmp_gt_f32_e64 s[0:1], 0, v49
	v_mul_f32_e32 v43, v44, v46
	s_nop 0
	v_cndmask_b32_e64 v47, v47, v51, s[0:1]
	v_mul_f32_e32 v44, v45, v47
	v_cvt_pk_bf16_f32 v43, v43, v44
	v_lshl_add_u64 v[44:45], v[132:133], 0, v[98:99]
	v_lshl_add_u64 v[46:47], v[140:141], 0, v[98:99]
	global_store_dwordx2 v[44:45], v[42:43], off
	v_add_co_u32_e64 v44, s[0:1], s43, v46
	global_load_dword v42, v[124:125], off
	s_nop 0
	v_addc_co_u32_e64 v45, s[0:1], -1, v47, s[0:1]
	v_add_co_u32_e64 v48, s[0:1], s41, v46
	global_load_dwordx2 v[44:45], v[44:45], off offset:-3072
	s_nop 0
	v_addc_co_u32_e64 v49, s[0:1], -1, v47, s[0:1]
	global_load_dwordx2 v[48:49], v[48:49], off offset:-1536
	s_nop 0
	global_load_dwordx2 v[46:47], v[46:47], off
	s_waitcnt vmcnt(3)
	v_pk_mul_f32 v[40:41], v[40:41], v[42:43] op_sel_hi:[1,0]
	v_pk_mul_f32 v[38:39], v[38:39], v[42:43] op_sel_hi:[1,0]
	s_waitcnt vmcnt(2)
	v_lshlrev_b32_e32 v52, 16, v44
	v_and_b32_e32 v53, 0xffff0000, v44
	s_waitcnt vmcnt(1)
	v_lshlrev_b32_e32 v50, 16, v48
	v_and_b32_e32 v51, 0xffff0000, v48
	v_lshlrev_b32_e32 v48, 16, v49
	v_and_b32_e32 v49, 0xffff0000, v49
	v_lshlrev_b32_e32 v44, 16, v45
	v_and_b32_e32 v45, 0xffff0000, v45
	v_pk_mul_f32 v[50:51], v[78:79], v[50:51]
	v_pk_mul_f32 v[48:49], v[80:81], v[48:49]
	s_waitcnt vmcnt(0)
	v_lshlrev_b32_e32 v42, 16, v46
	v_and_b32_e32 v43, 0xffff0000, v46
	v_pk_fma_f32 v[44:45], v[68:69], v[44:45], v[48:49]
	v_pk_fma_f32 v[48:49], v[66:67], v[52:53], v[50:51]
	v_lshlrev_b32_e32 v46, 16, v47
	v_pk_fma_f32 v[42:43], v[74:75], v[42:43], v[48:49]
	v_and_b32_e32 v47, 0xffff0000, v47
	v_pk_add_f32 v[42:43], v[70:71], v[42:43]
	v_pk_fma_f32 v[44:45], v[76:77], v[46:47], v[44:45]
	v_and_b32_e32 v47, 0x7fffffff, v43
	v_and_b32_e32 v46, 0x7fffffff, v42
	v_pk_fma_f32 v[46:47], v[46:47], s[2:3], 1.0 op_sel_hi:[1,0,0]
	v_pk_mul_f32 v[50:51], v[42:43], v[42:43]
	v_rcp_f32_e32 v46, v46
	v_rcp_f32_e32 v47, v47
	v_pk_mul_f32 v[50:51], v[50:51], s[22:23] op_sel_hi:[1,0]
	v_pk_add_f32 v[44:45], v[72:73], v[44:45]
	v_exp_f32_e32 v50, v50
	v_pk_fma_f32 v[48:49], v[46:47], s[42:43], v[142:143] op_sel_hi:[1,0,0]
	v_exp_f32_e32 v51, v51
	v_pk_fma_f32 v[48:49], v[46:47], v[48:49], s[40:41] op_sel_hi:[1,1,0]
	v_cmp_gt_f32_e64 s[0:1], 0, v42
	v_pk_fma_f32 v[48:49], v[46:47], v[48:49], s[92:93] op_sel_hi:[1,1,0]
	s_nop 0
	v_pk_fma_f32 v[48:49], v[46:47], v[48:49], s[20:21] op_sel_hi:[1,1,0]
	s_nop 0
	v_pk_mul_f32 v[46:47], v[46:47], v[48:49]
	v_pk_mul_f32 v[48:49], v[44:45], v[44:45]
	v_pk_mul_f32 v[46:47], v[50:51], v[46:47]
	s_nop 0
	v_pk_mul_f32 v[50:51], v[42:43], v[46:47]
	v_pk_fma_f32 v[46:47], v[42:43], v[46:47], v[42:43] neg_lo:[1,0,0] neg_hi:[1,0,0]
	v_and_b32_e32 v42, 0x7fffffff, v44
	v_cndmask_b32_e64 v50, v46, v50, s[0:1]
	v_cmp_gt_f32_e64 s[0:1], 0, v43
	v_and_b32_e32 v43, 0x7fffffff, v45
	v_pk_fma_f32 v[42:43], v[42:43], s[2:3], 1.0 op_sel_hi:[1,0,0]
	v_cndmask_b32_e64 v51, v47, v51, s[0:1]
	v_rcp_f32_e32 v42, v42
	v_rcp_f32_e32 v43, v43
	v_cmp_gt_f32_e64 s[0:1], 0, v44
	v_mul_f32_e32 v38, v38, v50
	v_mul_f32_e32 v39, v39, v51
	v_pk_fma_f32 v[46:47], v[42:43], s[42:43], v[142:143] op_sel_hi:[1,0,0]
	v_cvt_pk_bf16_f32 v38, v38, v39
	v_or_b32_e32 v50, 0x90, v164
	v_pk_fma_f32 v[46:47], v[42:43], v[46:47], s[40:41] op_sel_hi:[1,1,0]
	v_ashrrev_i32_e32 v51, 31, v50
	v_pk_fma_f32 v[46:47], v[42:43], v[46:47], s[92:93] op_sel_hi:[1,1,0]
	s_nop 0
	v_pk_fma_f32 v[46:47], v[42:43], v[46:47], s[20:21] op_sel_hi:[1,1,0]
	s_nop 0
	v_pk_mul_f32 v[42:43], v[42:43], v[46:47]
	v_pk_mul_f32 v[46:47], v[48:49], s[22:23] op_sel_hi:[1,0]
	s_nop 0
	v_exp_f32_e32 v46, v46
	v_exp_f32_e32 v47, v47
	s_nop 0
	v_pk_mul_f32 v[42:43], v[46:47], v[42:43]
	s_nop 0
	v_pk_mul_f32 v[46:47], v[44:45], v[42:43]
	v_pk_fma_f32 v[42:43], v[44:45], v[42:43], v[44:45] neg_lo:[1,0,0] neg_hi:[1,0,0]
	s_nop 0
	v_cndmask_b32_e64 v42, v42, v46, s[0:1]
	v_cmp_gt_f32_e64 s[0:1], 0, v45
	v_mul_f32_e32 v39, v40, v42
	s_nop 0
	v_cndmask_b32_e64 v43, v43, v47, s[0:1]
	v_mul_f32_e32 v40, v41, v43
	v_cvt_pk_bf16_f32 v39, v39, v40
	v_lshl_add_u64 v[40:41], v[172:173], 0, v[98:99]
	v_lshl_add_u64 v[42:43], v[174:175], 0, v[98:99]
	global_store_dwordx2 v[40:41], v[38:39], off
	v_add_co_u32_e64 v40, s[0:1], s43, v42
	global_load_dword v38, v[122:123], off
	s_nop 0
	v_addc_co_u32_e64 v41, s[0:1], -1, v43, s[0:1]
	v_add_co_u32_e64 v44, s[0:1], s41, v42
	global_load_dwordx2 v[40:41], v[40:41], off offset:-3072
	s_nop 0
	v_addc_co_u32_e64 v45, s[0:1], -1, v43, s[0:1]
	global_load_dwordx2 v[44:45], v[44:45], off offset:-1536
	s_nop 0
	global_load_dwordx2 v[42:43], v[42:43], off
	s_waitcnt vmcnt(3)
	v_pk_mul_f32 v[36:37], v[36:37], v[38:39] op_sel_hi:[1,0]
	v_pk_mul_f32 v[34:35], v[34:35], v[38:39] op_sel_hi:[1,0]
	s_waitcnt vmcnt(2)
	v_lshlrev_b32_e32 v48, 16, v40
	v_and_b32_e32 v49, 0xffff0000, v40
	s_waitcnt vmcnt(1)
	v_lshlrev_b32_e32 v46, 16, v44
	v_and_b32_e32 v47, 0xffff0000, v44
	v_lshlrev_b32_e32 v44, 16, v45
	v_and_b32_e32 v45, 0xffff0000, v45
	v_lshlrev_b32_e32 v40, 16, v41
	v_and_b32_e32 v41, 0xffff0000, v41
	v_pk_mul_f32 v[46:47], v[78:79], v[46:47]
	v_pk_mul_f32 v[44:45], v[80:81], v[44:45]
	s_waitcnt vmcnt(0)
	v_lshlrev_b32_e32 v38, 16, v42
	v_and_b32_e32 v39, 0xffff0000, v42
	v_pk_fma_f32 v[40:41], v[68:69], v[40:41], v[44:45]
	v_pk_fma_f32 v[44:45], v[66:67], v[48:49], v[46:47]
	v_lshlrev_b32_e32 v42, 16, v43
	v_pk_fma_f32 v[38:39], v[74:75], v[38:39], v[44:45]
	v_and_b32_e32 v43, 0xffff0000, v43
	v_pk_add_f32 v[38:39], v[70:71], v[38:39]
	v_pk_fma_f32 v[40:41], v[76:77], v[42:43], v[40:41]
	v_and_b32_e32 v43, 0x7fffffff, v39
	v_and_b32_e32 v42, 0x7fffffff, v38
	v_pk_fma_f32 v[42:43], v[42:43], s[2:3], 1.0 op_sel_hi:[1,0,0]
	v_pk_mul_f32 v[46:47], v[38:39], v[38:39]
	v_rcp_f32_e32 v42, v42
	v_rcp_f32_e32 v43, v43
	v_pk_mul_f32 v[46:47], v[46:47], s[22:23] op_sel_hi:[1,0]
	v_pk_add_f32 v[40:41], v[72:73], v[40:41]
	v_exp_f32_e32 v46, v46
	v_pk_fma_f32 v[44:45], v[42:43], s[42:43], v[142:143] op_sel_hi:[1,0,0]
	v_exp_f32_e32 v47, v47
	v_pk_fma_f32 v[44:45], v[42:43], v[44:45], s[40:41] op_sel_hi:[1,1,0]
	v_cmp_gt_f32_e64 s[0:1], 0, v38
	v_pk_fma_f32 v[44:45], v[42:43], v[44:45], s[92:93] op_sel_hi:[1,1,0]
	s_nop 0
	v_pk_fma_f32 v[44:45], v[42:43], v[44:45], s[20:21] op_sel_hi:[1,1,0]
	s_nop 0
	v_pk_mul_f32 v[42:43], v[42:43], v[44:45]
	v_pk_mul_f32 v[44:45], v[40:41], v[40:41]
	v_pk_mul_f32 v[42:43], v[46:47], v[42:43]
	s_nop 0
	v_pk_mul_f32 v[46:47], v[38:39], v[42:43]
	v_pk_fma_f32 v[42:43], v[38:39], v[42:43], v[38:39] neg_lo:[1,0,0] neg_hi:[1,0,0]
	v_and_b32_e32 v38, 0x7fffffff, v40
	v_cndmask_b32_e64 v46, v42, v46, s[0:1]
	v_cmp_gt_f32_e64 s[0:1], 0, v39
	v_and_b32_e32 v39, 0x7fffffff, v41
	v_pk_fma_f32 v[38:39], v[38:39], s[2:3], 1.0 op_sel_hi:[1,0,0]
	v_cndmask_b32_e64 v47, v43, v47, s[0:1]
	v_rcp_f32_e32 v38, v38
	v_rcp_f32_e32 v39, v39
	v_cmp_gt_f32_e64 s[0:1], 0, v40
	v_mul_f32_e32 v34, v34, v46
	v_mul_f32_e32 v35, v35, v47
	v_pk_fma_f32 v[42:43], v[38:39], s[42:43], v[142:143] op_sel_hi:[1,0,0]
	v_cvt_pk_bf16_f32 v34, v34, v35
	s_nop 0
	v_pk_fma_f32 v[42:43], v[38:39], v[42:43], s[40:41] op_sel_hi:[1,1,0]
	s_nop 0
	v_pk_fma_f32 v[42:43], v[38:39], v[42:43], s[92:93] op_sel_hi:[1,1,0]
	s_nop 0
	v_pk_fma_f32 v[42:43], v[38:39], v[42:43], s[20:21] op_sel_hi:[1,1,0]
	s_nop 0
	v_pk_mul_f32 v[38:39], v[38:39], v[42:43]
	v_pk_mul_f32 v[42:43], v[44:45], s[22:23] op_sel_hi:[1,0]
	s_nop 0
	v_exp_f32_e32 v42, v42
	v_exp_f32_e32 v43, v43
	s_nop 0
	v_pk_mul_f32 v[38:39], v[42:43], v[38:39]
	s_nop 0
	v_pk_mul_f32 v[42:43], v[40:41], v[38:39]
	v_pk_fma_f32 v[38:39], v[40:41], v[38:39], v[40:41] neg_lo:[1,0,0] neg_hi:[1,0,0]
	s_nop 0
	v_cndmask_b32_e64 v38, v38, v42, s[0:1]
	v_cmp_gt_f32_e64 s[0:1], 0, v41
	v_mul_f32_e32 v35, v36, v38
	s_nop 0
	v_cndmask_b32_e64 v39, v39, v43, s[0:1]
	v_mul_f32_e32 v36, v37, v39
	v_cvt_pk_bf16_f32 v35, v35, v36
	v_lshl_add_u64 v[36:37], v[82:83], 0, v[98:99]
	global_store_dwordx2 v[36:37], v[34:35], off
	v_lshlrev_b64 v[34:35], 2, v[50:51]
	v_lshlrev_b64 v[50:51], 1, v[50:51]
	v_lshl_add_u64 v[36:37], s[38:39], 0, v[34:35]
	v_lshl_add_u64 v[34:35], s[44:45], 0, v[34:35]
	v_lshl_add_u64 v[52:53], v[114:115], 0, v[50:51]
	global_load_dwordx4 v[42:45], v[166:167], off offset:576
	global_load_dwordx4 v[46:49], v[36:37], off
	global_load_dwordx4 v[38:41], v[34:35], off
	s_nop 0
	global_load_dwordx4 v[34:37], v[168:169], off offset:576
	global_load_dwordx2 v[56:57], v[52:53], off
	v_lshl_add_u64 v[52:53], v[116:117], 0, v[50:51]
	global_load_dwordx2 v[54:55], v[52:53], off
	v_lshl_add_u64 v[52:53], v[118:119], 0, v[50:51]
	global_load_dwordx2 v[52:53], v[52:53], off
	s_nop 0
	global_load_dword v58, v[162:163], off
	s_waitcnt vmcnt(2)
	v_lshlrev_b32_e32 v60, 16, v54
	v_and_b32_e32 v54, 0xffff0000, v54
	v_lshlrev_b32_e32 v61, 16, v55
	s_waitcnt vmcnt(1)
	v_lshlrev_b32_e32 v62, 16, v52
	v_and_b32_e32 v63, 0xffff0000, v52
	v_lshlrev_b32_e32 v64, 16, v53
	v_and_b32_e32 v65, 0xffff0000, v53
	v_cndmask_b32_e64 v53, v54, 0, s[6:7]
	v_cndmask_b32_e64 v52, v60, 0, s[6:7]
	v_cndmask_b32_e64 v54, v61, 0, s[6:7]
	v_cndmask_b32_e64 v61, v63, 0, s[10:11]
	v_cndmask_b32_e64 v60, v62, 0, s[10:11]
	v_pk_mul_f32 v[60:61], v[42:43], v[60:61]
	s_waitcnt vmcnt(0)
	v_pk_mul_f32 v[32:33], v[32:33], v[58:59] op_sel_hi:[1,0]
	v_pk_mul_f32 v[30:31], v[30:31], v[58:59] op_sel_hi:[1,0]
	v_lshlrev_b32_e32 v58, 16, v56
	v_and_b32_e32 v59, 0xffff0000, v56
	v_and_b32_e32 v55, 0xffff0000, v55
	v_cndmask_b32_e64 v63, v65, 0, s[10:11]
	v_cndmask_b32_e64 v62, v64, 0, s[10:11]
	v_pk_fma_f32 v[52:53], v[46:47], v[52:53], v[60:61]
	v_cndmask_b32_e64 v55, v55, 0, s[6:7]
	v_pk_mul_f32 v[62:63], v[44:45], v[62:63]
	v_pk_fma_f32 v[52:53], v[38:39], v[58:59], v[52:53]
	v_lshlrev_b32_e32 v56, 16, v57
	v_and_b32_e32 v57, 0xffff0000, v57
	v_pk_fma_f32 v[54:55], v[48:49], v[54:55], v[62:63]
	v_pk_add_f32 v[52:53], v[34:35], v[52:53]
	v_pk_fma_f32 v[54:55], v[40:41], v[56:57], v[54:55]
	v_and_b32_e32 v57, 0x7fffffff, v53
	v_and_b32_e32 v56, 0x7fffffff, v52
	v_pk_fma_f32 v[56:57], v[56:57], s[2:3], 1.0 op_sel_hi:[1,0,0]
	v_pk_mul_f32 v[60:61], v[52:53], v[52:53]
	v_rcp_f32_e32 v56, v56
	v_rcp_f32_e32 v57, v57
	v_pk_mul_f32 v[60:61], v[60:61], s[22:23] op_sel_hi:[1,0]
	v_pk_add_f32 v[54:55], v[36:37], v[54:55]
	v_exp_f32_e32 v60, v60
	v_pk_fma_f32 v[58:59], v[56:57], s[42:43], v[142:143] op_sel_hi:[1,0,0]
	v_exp_f32_e32 v61, v61
	v_pk_fma_f32 v[58:59], v[56:57], v[58:59], s[40:41] op_sel_hi:[1,1,0]
	v_cmp_gt_f32_e64 s[0:1], 0, v52
	v_pk_fma_f32 v[58:59], v[56:57], v[58:59], s[92:93] op_sel_hi:[1,1,0]
	s_nop 0
	v_pk_fma_f32 v[58:59], v[56:57], v[58:59], s[20:21] op_sel_hi:[1,1,0]
	s_nop 0
	v_pk_mul_f32 v[56:57], v[56:57], v[58:59]
	v_pk_mul_f32 v[58:59], v[54:55], v[54:55]
	v_pk_mul_f32 v[56:57], v[60:61], v[56:57]
	s_nop 0
	v_pk_mul_f32 v[60:61], v[52:53], v[56:57]
	v_pk_fma_f32 v[56:57], v[52:53], v[56:57], v[52:53] neg_lo:[1,0,0] neg_hi:[1,0,0]
	v_and_b32_e32 v52, 0x7fffffff, v54
	v_cndmask_b32_e64 v60, v56, v60, s[0:1]
	v_cmp_gt_f32_e64 s[0:1], 0, v53
	v_and_b32_e32 v53, 0x7fffffff, v55
	v_pk_fma_f32 v[52:53], v[52:53], s[2:3], 1.0 op_sel_hi:[1,0,0]
	v_cndmask_b32_e64 v61, v57, v61, s[0:1]
	v_rcp_f32_e32 v52, v52
	v_rcp_f32_e32 v53, v53
	v_cmp_gt_f32_e64 s[0:1], 0, v54
	v_mul_f32_e32 v30, v30, v60
	v_mul_f32_e32 v31, v31, v61
	v_pk_fma_f32 v[56:57], v[52:53], s[42:43], v[142:143] op_sel_hi:[1,0,0]
	v_cvt_pk_bf16_f32 v30, v30, v31
	s_nop 0
	v_pk_fma_f32 v[56:57], v[52:53], v[56:57], s[40:41] op_sel_hi:[1,1,0]
	s_nop 0
	v_pk_fma_f32 v[56:57], v[52:53], v[56:57], s[92:93] op_sel_hi:[1,1,0]
	s_nop 0
	v_pk_fma_f32 v[56:57], v[52:53], v[56:57], s[20:21] op_sel_hi:[1,1,0]
	s_nop 0
	v_pk_mul_f32 v[52:53], v[52:53], v[56:57]
	v_pk_mul_f32 v[56:57], v[58:59], s[22:23] op_sel_hi:[1,0]
	s_nop 0
	v_exp_f32_e32 v56, v56
	v_exp_f32_e32 v57, v57
	s_nop 0
	v_pk_mul_f32 v[52:53], v[56:57], v[52:53]
	s_nop 0
	v_pk_mul_f32 v[56:57], v[54:55], v[52:53]
	v_pk_fma_f32 v[52:53], v[54:55], v[52:53], v[54:55] neg_lo:[1,0,0] neg_hi:[1,0,0]
	s_nop 0
	v_cndmask_b32_e64 v52, v52, v56, s[0:1]
	v_cmp_gt_f32_e64 s[0:1], 0, v55
	v_mul_f32_e32 v31, v32, v52
	s_nop 0
	v_cndmask_b32_e64 v53, v53, v57, s[0:1]
	v_mul_f32_e32 v32, v33, v53
	v_cvt_pk_bf16_f32 v31, v31, v32
	v_lshl_add_u64 v[32:33], v[94:95], 0, v[50:51]
	v_lshl_add_u64 v[52:53], v[96:97], 0, v[50:51]
	global_store_dwordx2 v[32:33], v[30:31], off
	v_add_co_u32_e64 v32, s[0:1], s43, v52
	global_load_dword v30, v[144:145], off
	s_nop 0
	v_addc_co_u32_e64 v33, s[0:1], -1, v53, s[0:1]
	v_add_co_u32_e64 v54, s[0:1], s41, v52
	global_load_dwordx2 v[32:33], v[32:33], off offset:-3072
	s_nop 0
	v_addc_co_u32_e64 v55, s[0:1], -1, v53, s[0:1]
	global_load_dwordx2 v[54:55], v[54:55], off offset:-1536
	s_nop 0
	global_load_dwordx2 v[52:53], v[52:53], off
	s_waitcnt vmcnt(3)
	v_pk_mul_f32 v[28:29], v[28:29], v[30:31] op_sel_hi:[1,0]
	v_pk_mul_f32 v[26:27], v[26:27], v[30:31] op_sel_hi:[1,0]
	s_waitcnt vmcnt(2)
	v_lshlrev_b32_e32 v58, 16, v32
	v_and_b32_e32 v59, 0xffff0000, v32
	s_waitcnt vmcnt(1)
	v_lshlrev_b32_e32 v56, 16, v54
	v_and_b32_e32 v57, 0xffff0000, v54
	v_lshlrev_b32_e32 v54, 16, v55
	v_and_b32_e32 v55, 0xffff0000, v55
	v_lshlrev_b32_e32 v32, 16, v33
	v_and_b32_e32 v33, 0xffff0000, v33
	v_pk_mul_f32 v[56:57], v[46:47], v[56:57]
	v_pk_mul_f32 v[54:55], v[48:49], v[54:55]
	s_waitcnt vmcnt(0)
	v_lshlrev_b32_e32 v30, 16, v52
	v_and_b32_e32 v31, 0xffff0000, v52
	v_pk_fma_f32 v[32:33], v[44:45], v[32:33], v[54:55]
	v_pk_fma_f32 v[54:55], v[42:43], v[58:59], v[56:57]
	v_lshlrev_b32_e32 v52, 16, v53
	v_pk_fma_f32 v[30:31], v[38:39], v[30:31], v[54:55]
	v_and_b32_e32 v53, 0xffff0000, v53
	v_pk_add_f32 v[30:31], v[34:35], v[30:31]
	v_pk_fma_f32 v[32:33], v[40:41], v[52:53], v[32:33]
	v_and_b32_e32 v53, 0x7fffffff, v31
	v_and_b32_e32 v52, 0x7fffffff, v30
	v_pk_fma_f32 v[52:53], v[52:53], s[2:3], 1.0 op_sel_hi:[1,0,0]
	v_pk_mul_f32 v[56:57], v[30:31], v[30:31]
	v_rcp_f32_e32 v52, v52
	v_rcp_f32_e32 v53, v53
	v_pk_mul_f32 v[56:57], v[56:57], s[22:23] op_sel_hi:[1,0]
	v_pk_add_f32 v[32:33], v[36:37], v[32:33]
	v_exp_f32_e32 v56, v56
	v_pk_fma_f32 v[54:55], v[52:53], s[42:43], v[142:143] op_sel_hi:[1,0,0]
	v_exp_f32_e32 v57, v57
	v_pk_fma_f32 v[54:55], v[52:53], v[54:55], s[40:41] op_sel_hi:[1,1,0]
	v_cmp_gt_f32_e64 s[0:1], 0, v30
	v_pk_fma_f32 v[54:55], v[52:53], v[54:55], s[92:93] op_sel_hi:[1,1,0]
	s_nop 0
	v_pk_fma_f32 v[54:55], v[52:53], v[54:55], s[20:21] op_sel_hi:[1,1,0]
	s_nop 0
	v_pk_mul_f32 v[52:53], v[52:53], v[54:55]
	v_pk_mul_f32 v[54:55], v[32:33], v[32:33]
	v_pk_mul_f32 v[52:53], v[56:57], v[52:53]
	s_nop 0
	v_pk_mul_f32 v[56:57], v[30:31], v[52:53]
	v_pk_fma_f32 v[52:53], v[30:31], v[52:53], v[30:31] neg_lo:[1,0,0] neg_hi:[1,0,0]
	v_and_b32_e32 v30, 0x7fffffff, v32
	v_cndmask_b32_e64 v56, v52, v56, s[0:1]
	v_cmp_gt_f32_e64 s[0:1], 0, v31
	v_and_b32_e32 v31, 0x7fffffff, v33
	v_pk_fma_f32 v[30:31], v[30:31], s[2:3], 1.0 op_sel_hi:[1,0,0]
	v_cndmask_b32_e64 v57, v53, v57, s[0:1]
	v_rcp_f32_e32 v30, v30
	v_rcp_f32_e32 v31, v31
	v_cmp_gt_f32_e64 s[0:1], 0, v32
	v_mul_f32_e32 v26, v26, v56
	v_mul_f32_e32 v27, v27, v57
	v_pk_fma_f32 v[52:53], v[30:31], s[42:43], v[142:143] op_sel_hi:[1,0,0]
	v_cvt_pk_bf16_f32 v26, v26, v27
	s_nop 0
	v_pk_fma_f32 v[52:53], v[30:31], v[52:53], s[40:41] op_sel_hi:[1,1,0]
	s_nop 0
	v_pk_fma_f32 v[52:53], v[30:31], v[52:53], s[92:93] op_sel_hi:[1,1,0]
	s_nop 0
	v_pk_fma_f32 v[52:53], v[30:31], v[52:53], s[20:21] op_sel_hi:[1,1,0]
	s_nop 0
	v_pk_mul_f32 v[30:31], v[30:31], v[52:53]
	v_pk_mul_f32 v[52:53], v[54:55], s[22:23] op_sel_hi:[1,0]
	s_nop 0
	v_exp_f32_e32 v52, v52
	v_exp_f32_e32 v53, v53
	s_nop 0
	v_pk_mul_f32 v[30:31], v[52:53], v[30:31]
	s_nop 0
	v_pk_mul_f32 v[52:53], v[32:33], v[30:31]
	v_pk_fma_f32 v[30:31], v[32:33], v[30:31], v[32:33] neg_lo:[1,0,0] neg_hi:[1,0,0]
	s_nop 0
	v_cndmask_b32_e64 v30, v30, v52, s[0:1]
	v_cmp_gt_f32_e64 s[0:1], 0, v33
	v_mul_f32_e32 v27, v28, v30
	s_nop 0
	v_cndmask_b32_e64 v31, v31, v53, s[0:1]
	v_mul_f32_e32 v28, v29, v31
	v_cvt_pk_bf16_f32 v27, v27, v28
	v_lshl_add_u64 v[28:29], v[90:91], 0, v[50:51]
	v_lshl_add_u64 v[30:31], v[92:93], 0, v[50:51]
	global_store_dwordx2 v[28:29], v[26:27], off
	v_add_co_u32_e64 v28, s[0:1], s43, v30
	global_load_dword v26, v[138:139], off
	s_nop 0
	v_addc_co_u32_e64 v29, s[0:1], -1, v31, s[0:1]
	v_add_co_u32_e64 v32, s[0:1], s41, v30
	global_load_dwordx2 v[28:29], v[28:29], off offset:-3072
	s_nop 0
	v_addc_co_u32_e64 v33, s[0:1], -1, v31, s[0:1]
	global_load_dwordx2 v[32:33], v[32:33], off offset:-1536
	s_nop 0
	global_load_dwordx2 v[30:31], v[30:31], off
	s_waitcnt vmcnt(3)
	v_pk_mul_f32 v[24:25], v[24:25], v[26:27] op_sel_hi:[1,0]
	v_pk_mul_f32 v[22:23], v[22:23], v[26:27] op_sel_hi:[1,0]
	s_waitcnt vmcnt(2)
	v_lshlrev_b32_e32 v54, 16, v28
	v_and_b32_e32 v55, 0xffff0000, v28
	s_waitcnt vmcnt(1)
	v_lshlrev_b32_e32 v52, 16, v32
	v_and_b32_e32 v53, 0xffff0000, v32
	v_lshlrev_b32_e32 v32, 16, v33
	v_and_b32_e32 v33, 0xffff0000, v33
	v_lshlrev_b32_e32 v28, 16, v29
	v_and_b32_e32 v29, 0xffff0000, v29
	v_pk_mul_f32 v[52:53], v[46:47], v[52:53]
	v_pk_mul_f32 v[32:33], v[48:49], v[32:33]
	s_waitcnt vmcnt(0)
	v_lshlrev_b32_e32 v26, 16, v30
	v_and_b32_e32 v27, 0xffff0000, v30
	v_pk_fma_f32 v[28:29], v[44:45], v[28:29], v[32:33]
	v_pk_fma_f32 v[32:33], v[42:43], v[54:55], v[52:53]
	v_lshlrev_b32_e32 v30, 16, v31
	v_pk_fma_f32 v[26:27], v[38:39], v[26:27], v[32:33]
	v_and_b32_e32 v31, 0xffff0000, v31
	v_pk_add_f32 v[26:27], v[34:35], v[26:27]
	v_pk_fma_f32 v[28:29], v[40:41], v[30:31], v[28:29]
	v_and_b32_e32 v31, 0x7fffffff, v27
	v_and_b32_e32 v30, 0x7fffffff, v26
	v_pk_fma_f32 v[30:31], v[30:31], s[2:3], 1.0 op_sel_hi:[1,0,0]
	v_pk_mul_f32 v[52:53], v[26:27], v[26:27]
	v_rcp_f32_e32 v30, v30
	v_rcp_f32_e32 v31, v31
	v_pk_mul_f32 v[52:53], v[52:53], s[22:23] op_sel_hi:[1,0]
	v_pk_add_f32 v[28:29], v[36:37], v[28:29]
	v_exp_f32_e32 v52, v52
	v_pk_fma_f32 v[32:33], v[30:31], s[42:43], v[142:143] op_sel_hi:[1,0,0]
	v_exp_f32_e32 v53, v53
	v_pk_fma_f32 v[32:33], v[30:31], v[32:33], s[40:41] op_sel_hi:[1,1,0]
	v_cmp_gt_f32_e64 s[0:1], 0, v26
	v_pk_fma_f32 v[32:33], v[30:31], v[32:33], s[92:93] op_sel_hi:[1,1,0]
	s_nop 0
	v_pk_fma_f32 v[32:33], v[30:31], v[32:33], s[20:21] op_sel_hi:[1,1,0]
	s_nop 0
	v_pk_mul_f32 v[30:31], v[30:31], v[32:33]
	v_pk_mul_f32 v[32:33], v[28:29], v[28:29]
	v_pk_mul_f32 v[30:31], v[52:53], v[30:31]
	s_nop 0
	v_pk_mul_f32 v[52:53], v[26:27], v[30:31]
	v_pk_fma_f32 v[30:31], v[26:27], v[30:31], v[26:27] neg_lo:[1,0,0] neg_hi:[1,0,0]
	v_and_b32_e32 v26, 0x7fffffff, v28
	v_cndmask_b32_e64 v52, v30, v52, s[0:1]
	v_cmp_gt_f32_e64 s[0:1], 0, v27
	v_and_b32_e32 v27, 0x7fffffff, v29
	v_pk_fma_f32 v[26:27], v[26:27], s[2:3], 1.0 op_sel_hi:[1,0,0]
	v_cndmask_b32_e64 v53, v31, v53, s[0:1]
	v_rcp_f32_e32 v26, v26
	v_rcp_f32_e32 v27, v27
	v_cmp_gt_f32_e64 s[0:1], 0, v28
	v_mul_f32_e32 v22, v22, v52
	v_mul_f32_e32 v23, v23, v53
	v_pk_fma_f32 v[30:31], v[26:27], s[42:43], v[142:143] op_sel_hi:[1,0,0]
	v_cvt_pk_bf16_f32 v22, v22, v23
	s_nop 0
	v_pk_fma_f32 v[30:31], v[26:27], v[30:31], s[40:41] op_sel_hi:[1,1,0]
	s_nop 0
	v_pk_fma_f32 v[30:31], v[26:27], v[30:31], s[92:93] op_sel_hi:[1,1,0]
	s_nop 0
	v_pk_fma_f32 v[30:31], v[26:27], v[30:31], s[20:21] op_sel_hi:[1,1,0]
	s_nop 0
	v_pk_mul_f32 v[26:27], v[26:27], v[30:31]
	v_pk_mul_f32 v[30:31], v[32:33], s[22:23] op_sel_hi:[1,0]
	s_nop 0
	v_exp_f32_e32 v30, v30
	v_exp_f32_e32 v31, v31
	s_nop 0
	v_pk_mul_f32 v[26:27], v[30:31], v[26:27]
	s_nop 0
	v_pk_mul_f32 v[30:31], v[28:29], v[26:27]
	v_pk_fma_f32 v[26:27], v[28:29], v[26:27], v[28:29] neg_lo:[1,0,0] neg_hi:[1,0,0]
	s_nop 0
	v_cndmask_b32_e64 v26, v26, v30, s[0:1]
	v_cmp_gt_f32_e64 s[0:1], 0, v29
	v_mul_f32_e32 v23, v24, v26
	s_nop 0
	v_cndmask_b32_e64 v27, v27, v31, s[0:1]
	v_mul_f32_e32 v24, v25, v27
	v_cvt_pk_bf16_f32 v23, v23, v24
	v_lshl_add_u64 v[24:25], v[86:87], 0, v[50:51]
	v_lshl_add_u64 v[26:27], v[88:89], 0, v[50:51]
	global_store_dwordx2 v[24:25], v[22:23], off
	v_add_co_u32_e64 v24, s[0:1], s43, v26
	global_load_dword v22, v[134:135], off
	s_nop 0
	v_addc_co_u32_e64 v25, s[0:1], -1, v27, s[0:1]
	v_add_co_u32_e64 v28, s[0:1], s41, v26
	global_load_dwordx2 v[24:25], v[24:25], off offset:-3072
	s_nop 0
	v_addc_co_u32_e64 v29, s[0:1], -1, v27, s[0:1]
	global_load_dwordx2 v[28:29], v[28:29], off offset:-1536
	s_nop 0
	global_load_dwordx2 v[26:27], v[26:27], off
	s_waitcnt vmcnt(3)
	v_pk_mul_f32 v[20:21], v[20:21], v[22:23] op_sel_hi:[1,0]
	v_pk_mul_f32 v[18:19], v[18:19], v[22:23] op_sel_hi:[1,0]
	s_waitcnt vmcnt(2)
	v_lshlrev_b32_e32 v32, 16, v24
	v_and_b32_e32 v33, 0xffff0000, v24
	s_waitcnt vmcnt(1)
	v_lshlrev_b32_e32 v30, 16, v28
	v_and_b32_e32 v31, 0xffff0000, v28
	v_lshlrev_b32_e32 v28, 16, v29
	v_and_b32_e32 v29, 0xffff0000, v29
	v_lshlrev_b32_e32 v24, 16, v25
	v_and_b32_e32 v25, 0xffff0000, v25
	v_pk_mul_f32 v[30:31], v[46:47], v[30:31]
	v_pk_mul_f32 v[28:29], v[48:49], v[28:29]
	s_waitcnt vmcnt(0)
	v_lshlrev_b32_e32 v22, 16, v26
	v_and_b32_e32 v23, 0xffff0000, v26
	v_pk_fma_f32 v[24:25], v[44:45], v[24:25], v[28:29]
	v_pk_fma_f32 v[28:29], v[42:43], v[32:33], v[30:31]
	v_lshlrev_b32_e32 v26, 16, v27
	v_pk_fma_f32 v[22:23], v[38:39], v[22:23], v[28:29]
	v_and_b32_e32 v27, 0xffff0000, v27
	v_pk_add_f32 v[22:23], v[34:35], v[22:23]
	v_pk_fma_f32 v[24:25], v[40:41], v[26:27], v[24:25]
	v_and_b32_e32 v27, 0x7fffffff, v23
	v_and_b32_e32 v26, 0x7fffffff, v22
	v_pk_fma_f32 v[26:27], v[26:27], s[2:3], 1.0 op_sel_hi:[1,0,0]
	v_pk_mul_f32 v[30:31], v[22:23], v[22:23]
	v_rcp_f32_e32 v26, v26
	v_rcp_f32_e32 v27, v27
	v_pk_mul_f32 v[30:31], v[30:31], s[22:23] op_sel_hi:[1,0]
	v_pk_add_f32 v[24:25], v[36:37], v[24:25]
	v_exp_f32_e32 v30, v30
	v_pk_fma_f32 v[28:29], v[26:27], s[42:43], v[142:143] op_sel_hi:[1,0,0]
	v_exp_f32_e32 v31, v31
	v_pk_fma_f32 v[28:29], v[26:27], v[28:29], s[40:41] op_sel_hi:[1,1,0]
	v_cmp_gt_f32_e64 s[0:1], 0, v22
	v_pk_fma_f32 v[28:29], v[26:27], v[28:29], s[92:93] op_sel_hi:[1,1,0]
	s_nop 0
	v_pk_fma_f32 v[28:29], v[26:27], v[28:29], s[20:21] op_sel_hi:[1,1,0]
	s_nop 0
	v_pk_mul_f32 v[26:27], v[26:27], v[28:29]
	v_pk_mul_f32 v[28:29], v[24:25], v[24:25]
	v_pk_mul_f32 v[26:27], v[30:31], v[26:27]
	s_nop 0
	v_pk_mul_f32 v[30:31], v[22:23], v[26:27]
	v_pk_fma_f32 v[26:27], v[22:23], v[26:27], v[22:23] neg_lo:[1,0,0] neg_hi:[1,0,0]
	v_and_b32_e32 v22, 0x7fffffff, v24
	v_cndmask_b32_e64 v30, v26, v30, s[0:1]
	v_cmp_gt_f32_e64 s[0:1], 0, v23
	v_and_b32_e32 v23, 0x7fffffff, v25
	v_pk_fma_f32 v[22:23], v[22:23], s[2:3], 1.0 op_sel_hi:[1,0,0]
	v_cndmask_b32_e64 v31, v27, v31, s[0:1]
	v_rcp_f32_e32 v22, v22
	v_rcp_f32_e32 v23, v23
	v_cmp_gt_f32_e64 s[0:1], 0, v24
	v_mul_f32_e32 v18, v18, v30
	v_mul_f32_e32 v19, v19, v31
	v_pk_fma_f32 v[26:27], v[22:23], s[42:43], v[142:143] op_sel_hi:[1,0,0]
	v_cvt_pk_bf16_f32 v18, v18, v19
	s_nop 0
	v_pk_fma_f32 v[26:27], v[22:23], v[26:27], s[40:41] op_sel_hi:[1,1,0]
	s_nop 0
	v_pk_fma_f32 v[26:27], v[22:23], v[26:27], s[92:93] op_sel_hi:[1,1,0]
	s_nop 0
	v_pk_fma_f32 v[26:27], v[22:23], v[26:27], s[20:21] op_sel_hi:[1,1,0]
	s_nop 0
	v_pk_mul_f32 v[22:23], v[22:23], v[26:27]
	v_pk_mul_f32 v[26:27], v[28:29], s[22:23] op_sel_hi:[1,0]
	s_nop 0
	v_exp_f32_e32 v26, v26
	v_exp_f32_e32 v27, v27
	s_nop 0
	v_pk_mul_f32 v[22:23], v[26:27], v[22:23]
	s_nop 0
	v_pk_mul_f32 v[26:27], v[24:25], v[22:23]
	v_pk_fma_f32 v[22:23], v[24:25], v[22:23], v[24:25] neg_lo:[1,0,0] neg_hi:[1,0,0]
	s_nop 0
	v_cndmask_b32_e64 v22, v22, v26, s[0:1]
	v_cmp_gt_f32_e64 s[0:1], 0, v25
	v_mul_f32_e32 v19, v20, v22
	s_nop 0
	v_cndmask_b32_e64 v23, v23, v27, s[0:1]
	v_mul_f32_e32 v20, v21, v23
	v_cvt_pk_bf16_f32 v19, v19, v20
	v_lshl_add_u64 v[20:21], v[84:85], 0, v[50:51]
	global_store_dwordx2 v[20:21], v[18:19], off
	v_lshl_add_u64 v[18:19], v[176:177], 0, v[50:51]
	v_lshl_add_u64 v[20:21], v[136:137], 0, v[50:51]
	global_load_dwordx2 v[18:19], v[18:19], off
	v_lshl_add_u64 v[22:23], v[170:171], 0, v[50:51]
	global_load_dwordx2 v[20:21], v[20:21], off
	s_nop 0
	global_load_dwordx2 v[22:23], v[22:23], off
	s_nop 0
	global_load_dword v24, v[130:131], off
	s_mov_b64 s[0:1], -1
	s_waitcnt vmcnt(2)
	v_lshlrev_b32_e32 v26, 16, v20
	v_and_b32_e32 v20, 0xffff0000, v20
	v_lshlrev_b32_e32 v27, 16, v21
	s_waitcnt vmcnt(1)
	v_lshlrev_b32_e32 v29, 16, v22
	v_and_b32_e32 v30, 0xffff0000, v22
	v_and_b32_e32 v28, 0xffff0000, v21
	v_cndmask_b32_e64 v21, v20, 0, vcc
	v_cndmask_b32_e64 v20, v26, 0, vcc
	v_cndmask_b32_e64 v22, v27, 0, vcc
	v_cndmask_b32_e64 v27, v30, 0, s[8:9]
	v_cndmask_b32_e64 v26, v29, 0, s[8:9]
	v_lshlrev_b32_e32 v31, 16, v23
	v_and_b32_e32 v32, 0xffff0000, v23
	v_pk_mul_f32 v[26:27], v[42:43], v[26:27]
	s_waitcnt vmcnt(0)
	v_pk_mul_f32 v[16:17], v[16:17], v[24:25] op_sel_hi:[1,0]
	v_pk_mul_f32 v[14:15], v[14:15], v[24:25] op_sel_hi:[1,0]
	v_lshlrev_b32_e32 v24, 16, v18
	v_and_b32_e32 v25, 0xffff0000, v18
	v_cndmask_b32_e64 v23, v28, 0, vcc
	v_cndmask_b32_e64 v29, v32, 0, s[8:9]
	v_cndmask_b32_e64 v28, v31, 0, s[8:9]
	v_pk_fma_f32 v[20:21], v[46:47], v[20:21], v[26:27]
	v_pk_mul_f32 v[28:29], v[44:45], v[28:29]
	v_pk_fma_f32 v[20:21], v[38:39], v[24:25], v[20:21]
	v_lshlrev_b32_e32 v18, 16, v19
	v_and_b32_e32 v19, 0xffff0000, v19
	v_pk_fma_f32 v[22:23], v[48:49], v[22:23], v[28:29]
	v_pk_add_f32 v[20:21], v[34:35], v[20:21]
	v_pk_fma_f32 v[18:19], v[40:41], v[18:19], v[22:23]
	v_and_b32_e32 v23, 0x7fffffff, v21
	v_and_b32_e32 v22, 0x7fffffff, v20
	v_pk_fma_f32 v[22:23], v[22:23], s[2:3], 1.0 op_sel_hi:[1,0,0]
	v_pk_mul_f32 v[26:27], v[20:21], v[20:21]
	v_rcp_f32_e32 v22, v22
	v_rcp_f32_e32 v23, v23
	v_pk_mul_f32 v[26:27], v[26:27], s[22:23] op_sel_hi:[1,0]
	v_pk_add_f32 v[18:19], v[36:37], v[18:19]
	v_exp_f32_e32 v26, v26
	v_pk_fma_f32 v[24:25], v[22:23], s[42:43], v[142:143] op_sel_hi:[1,0,0]
	v_exp_f32_e32 v27, v27
	v_pk_fma_f32 v[24:25], v[22:23], v[24:25], s[40:41] op_sel_hi:[1,1,0]
	v_cmp_gt_f32_e32 vcc, 0, v20
	v_pk_fma_f32 v[24:25], v[22:23], v[24:25], s[92:93] op_sel_hi:[1,1,0]
	s_nop 0
	v_pk_fma_f32 v[24:25], v[22:23], v[24:25], s[20:21] op_sel_hi:[1,1,0]
	s_nop 0
	v_pk_mul_f32 v[22:23], v[22:23], v[24:25]
	v_pk_mul_f32 v[24:25], v[18:19], v[18:19]
	v_pk_mul_f32 v[22:23], v[26:27], v[22:23]
	s_nop 0
	v_pk_mul_f32 v[26:27], v[20:21], v[22:23]
	v_pk_fma_f32 v[22:23], v[20:21], v[22:23], v[20:21] neg_lo:[1,0,0] neg_hi:[1,0,0]
	v_and_b32_e32 v20, 0x7fffffff, v18
	v_cndmask_b32_e32 v26, v22, v26, vcc
	v_cmp_gt_f32_e32 vcc, 0, v21
	v_and_b32_e32 v21, 0x7fffffff, v19
	v_pk_fma_f32 v[20:21], v[20:21], s[2:3], 1.0 op_sel_hi:[1,0,0]
	v_cndmask_b32_e32 v27, v23, v27, vcc
	v_rcp_f32_e32 v20, v20
	v_rcp_f32_e32 v21, v21
	v_cmp_gt_f32_e32 vcc, 0, v18
	v_mul_f32_e32 v14, v14, v26
	v_mul_f32_e32 v15, v15, v27
	v_pk_fma_f32 v[22:23], v[20:21], s[42:43], v[142:143] op_sel_hi:[1,0,0]
	v_cvt_pk_bf16_f32 v14, v14, v15
	s_nop 0
	v_pk_fma_f32 v[22:23], v[20:21], v[22:23], s[40:41] op_sel_hi:[1,1,0]
	s_nop 0
	v_pk_fma_f32 v[22:23], v[20:21], v[22:23], s[92:93] op_sel_hi:[1,1,0]
	s_nop 0
	v_pk_fma_f32 v[22:23], v[20:21], v[22:23], s[20:21] op_sel_hi:[1,1,0]
	s_nop 0
	v_pk_mul_f32 v[20:21], v[20:21], v[22:23]
	v_pk_mul_f32 v[22:23], v[24:25], s[22:23] op_sel_hi:[1,0]
	s_nop 0
	v_exp_f32_e32 v22, v22
	v_exp_f32_e32 v23, v23
	s_nop 0
	v_pk_mul_f32 v[20:21], v[22:23], v[20:21]
	s_nop 0
	v_pk_mul_f32 v[22:23], v[18:19], v[20:21]
	v_pk_fma_f32 v[20:21], v[18:19], v[20:21], v[18:19] neg_lo:[1,0,0] neg_hi:[1,0,0]
	s_nop 0
	v_cndmask_b32_e32 v18, v20, v22, vcc
	v_cmp_gt_f32_e32 vcc, 0, v19
	v_mul_f32_e32 v15, v16, v18
	s_nop 0
	v_cndmask_b32_e32 v19, v21, v23, vcc
	v_mul_f32_e32 v16, v17, v19
	v_cvt_pk_bf16_f32 v15, v15, v16
	v_lshl_add_u64 v[16:17], v[120:121], 0, v[50:51]
	v_lshl_add_u64 v[18:19], v[128:129], 0, v[50:51]
	global_store_dwordx2 v[16:17], v[14:15], off
	v_add_co_u32_e32 v16, vcc, s43, v18
	global_load_dword v14, v[126:127], off
	s_nop 0
	v_addc_co_u32_e32 v17, vcc, -1, v19, vcc
	v_add_co_u32_e32 v20, vcc, s41, v18
	global_load_dwordx2 v[16:17], v[16:17], off offset:-3072
	s_nop 0
	v_addc_co_u32_e32 v21, vcc, -1, v19, vcc
	global_load_dwordx2 v[20:21], v[20:21], off offset:-1536
	s_nop 0
	global_load_dwordx2 v[18:19], v[18:19], off
	s_waitcnt vmcnt(3)
	v_pk_mul_f32 v[12:13], v[12:13], v[14:15] op_sel_hi:[1,0]
	v_pk_mul_f32 v[10:11], v[10:11], v[14:15] op_sel_hi:[1,0]
	s_waitcnt vmcnt(2)
	v_lshlrev_b32_e32 v24, 16, v16
	v_and_b32_e32 v25, 0xffff0000, v16
	s_waitcnt vmcnt(1)
	v_lshlrev_b32_e32 v22, 16, v20
	v_and_b32_e32 v23, 0xffff0000, v20
	v_lshlrev_b32_e32 v20, 16, v21
	v_and_b32_e32 v21, 0xffff0000, v21
	v_lshlrev_b32_e32 v16, 16, v17
	v_and_b32_e32 v17, 0xffff0000, v17
	v_pk_mul_f32 v[22:23], v[46:47], v[22:23]
	v_pk_mul_f32 v[20:21], v[48:49], v[20:21]
	s_waitcnt vmcnt(0)
	v_lshlrev_b32_e32 v14, 16, v18
	v_and_b32_e32 v15, 0xffff0000, v18
	v_pk_fma_f32 v[16:17], v[44:45], v[16:17], v[20:21]
	v_pk_fma_f32 v[20:21], v[42:43], v[24:25], v[22:23]
	v_lshlrev_b32_e32 v18, 16, v19
	v_pk_fma_f32 v[14:15], v[38:39], v[14:15], v[20:21]
	v_and_b32_e32 v19, 0xffff0000, v19
	v_pk_add_f32 v[14:15], v[34:35], v[14:15]
	v_pk_fma_f32 v[16:17], v[40:41], v[18:19], v[16:17]
	v_and_b32_e32 v19, 0x7fffffff, v15
	v_and_b32_e32 v18, 0x7fffffff, v14
	v_pk_fma_f32 v[18:19], v[18:19], s[2:3], 1.0 op_sel_hi:[1,0,0]
	v_pk_mul_f32 v[22:23], v[14:15], v[14:15]
	v_rcp_f32_e32 v18, v18
	v_rcp_f32_e32 v19, v19
	v_pk_mul_f32 v[22:23], v[22:23], s[22:23] op_sel_hi:[1,0]
	v_pk_add_f32 v[16:17], v[36:37], v[16:17]
	v_exp_f32_e32 v22, v22
	v_pk_fma_f32 v[20:21], v[18:19], s[42:43], v[142:143] op_sel_hi:[1,0,0]
	v_exp_f32_e32 v23, v23
	v_pk_fma_f32 v[20:21], v[18:19], v[20:21], s[40:41] op_sel_hi:[1,1,0]
	v_cmp_gt_f32_e32 vcc, 0, v14
	v_pk_fma_f32 v[20:21], v[18:19], v[20:21], s[92:93] op_sel_hi:[1,1,0]
	s_nop 0
	v_pk_fma_f32 v[20:21], v[18:19], v[20:21], s[20:21] op_sel_hi:[1,1,0]
	s_nop 0
	v_pk_mul_f32 v[18:19], v[18:19], v[20:21]
	v_pk_mul_f32 v[20:21], v[16:17], v[16:17]
	v_pk_mul_f32 v[18:19], v[22:23], v[18:19]
	s_nop 0
	v_pk_mul_f32 v[22:23], v[14:15], v[18:19]
	v_pk_fma_f32 v[18:19], v[14:15], v[18:19], v[14:15] neg_lo:[1,0,0] neg_hi:[1,0,0]
	v_and_b32_e32 v14, 0x7fffffff, v16
	v_cndmask_b32_e32 v22, v18, v22, vcc
	v_cmp_gt_f32_e32 vcc, 0, v15
	v_and_b32_e32 v15, 0x7fffffff, v17
	v_pk_fma_f32 v[14:15], v[14:15], s[2:3], 1.0 op_sel_hi:[1,0,0]
	v_cndmask_b32_e32 v23, v19, v23, vcc
	v_rcp_f32_e32 v14, v14
	v_rcp_f32_e32 v15, v15
	v_cmp_gt_f32_e32 vcc, 0, v16
	v_mul_f32_e32 v10, v10, v22
	v_mul_f32_e32 v11, v11, v23
	v_pk_fma_f32 v[18:19], v[14:15], s[42:43], v[142:143] op_sel_hi:[1,0,0]
	v_cvt_pk_bf16_f32 v10, v10, v11
	s_nop 0
	v_pk_fma_f32 v[18:19], v[14:15], v[18:19], s[40:41] op_sel_hi:[1,1,0]
	s_nop 0
	v_pk_fma_f32 v[18:19], v[14:15], v[18:19], s[92:93] op_sel_hi:[1,1,0]
	s_nop 0
	v_pk_fma_f32 v[18:19], v[14:15], v[18:19], s[20:21] op_sel_hi:[1,1,0]
	s_nop 0
	v_pk_mul_f32 v[14:15], v[14:15], v[18:19]
	v_pk_mul_f32 v[18:19], v[20:21], s[22:23] op_sel_hi:[1,0]
	s_nop 0
	v_exp_f32_e32 v18, v18
	v_exp_f32_e32 v19, v19
	s_nop 0
	v_pk_mul_f32 v[14:15], v[18:19], v[14:15]
	s_nop 0
	v_pk_mul_f32 v[18:19], v[16:17], v[14:15]
	v_pk_fma_f32 v[14:15], v[16:17], v[14:15], v[16:17] neg_lo:[1,0,0] neg_hi:[1,0,0]
	s_nop 0
	v_cndmask_b32_e32 v14, v14, v18, vcc
	v_cmp_gt_f32_e32 vcc, 0, v17
	v_mul_f32_e32 v11, v12, v14
	s_nop 0
	v_cndmask_b32_e32 v15, v15, v19, vcc
	v_mul_f32_e32 v12, v13, v15
	v_cvt_pk_bf16_f32 v11, v11, v12
	v_lshl_add_u64 v[12:13], v[132:133], 0, v[50:51]
	v_lshl_add_u64 v[14:15], v[140:141], 0, v[50:51]
	global_store_dwordx2 v[12:13], v[10:11], off
	v_add_co_u32_e32 v12, vcc, s43, v14
	global_load_dword v10, v[124:125], off
	s_nop 0
	v_addc_co_u32_e32 v13, vcc, -1, v15, vcc
	v_add_co_u32_e32 v16, vcc, s41, v14
	global_load_dwordx2 v[12:13], v[12:13], off offset:-3072
	s_nop 0
	v_addc_co_u32_e32 v17, vcc, -1, v15, vcc
	global_load_dwordx2 v[16:17], v[16:17], off offset:-1536
	s_nop 0
	global_load_dwordx2 v[14:15], v[14:15], off
	s_waitcnt vmcnt(3)
	v_pk_mul_f32 v[8:9], v[8:9], v[10:11] op_sel_hi:[1,0]
	v_pk_mul_f32 v[6:7], v[6:7], v[10:11] op_sel_hi:[1,0]
	s_waitcnt vmcnt(2)
	v_lshlrev_b32_e32 v20, 16, v12
	v_and_b32_e32 v21, 0xffff0000, v12
	s_waitcnt vmcnt(1)
	v_lshlrev_b32_e32 v18, 16, v16
	v_and_b32_e32 v19, 0xffff0000, v16
	v_lshlrev_b32_e32 v16, 16, v17
	v_and_b32_e32 v17, 0xffff0000, v17
	v_lshlrev_b32_e32 v12, 16, v13
	v_and_b32_e32 v13, 0xffff0000, v13
	v_pk_mul_f32 v[18:19], v[46:47], v[18:19]
	v_pk_mul_f32 v[16:17], v[48:49], v[16:17]
	s_waitcnt vmcnt(0)
; #define PG8_BAR __builtin_amdgcn_s_barrier()
; template <class Epi, class Sched, bool ALIGN_EPI = false, bool SP2 = false>
; __device__ __forceinline__ void gemm_phase(PG8_LAS unsigned char* lds, const Gemm g, const Sched& S, const Epi& E) {
;     ...
;         if (!has_next) break;
; #pragma unroll
;         for (int a = 0; a < 2; ++a)
; #pragma unroll
;             for (int b = 0; b < 2; ++b)
; #pragma unroll
;                 for (int m = 0; m < 4; ++m)
; #pragma unroll
;                     for (int n = 0; n < 2; ++n) acc[a][b][m][n] = (f32x4){0.f, 0.f, 0.f, 0.f};
;         cur = nxt; cA = nA; cB = nB; ++ui;
;         if constexpr (ALIGN_EPI) { if (wr == 1) PG8_BAR; }
	v_lshlrev_b32_e32 v10, 16, v14
	v_and_b32_e32 v11, 0xffff0000, v14
	v_pk_fma_f32 v[12:13], v[44:45], v[12:13], v[16:17]
	v_pk_fma_f32 v[16:17], v[42:43], v[20:21], v[18:19]
	v_lshlrev_b32_e32 v14, 16, v15
	v_pk_fma_f32 v[10:11], v[38:39], v[10:11], v[16:17]
	v_and_b32_e32 v15, 0xffff0000, v15
	v_pk_add_f32 v[10:11], v[34:35], v[10:11]
	v_pk_fma_f32 v[12:13], v[40:41], v[14:15], v[12:13]
	v_and_b32_e32 v15, 0x7fffffff, v11
	v_and_b32_e32 v14, 0x7fffffff, v10
	v_pk_fma_f32 v[14:15], v[14:15], s[2:3], 1.0 op_sel_hi:[1,0,0]
	v_pk_mul_f32 v[18:19], v[10:11], v[10:11]
	v_rcp_f32_e32 v14, v14
	v_rcp_f32_e32 v15, v15
	v_pk_mul_f32 v[18:19], v[18:19], s[22:23] op_sel_hi:[1,0]
	v_pk_add_f32 v[12:13], v[36:37], v[12:13]
	v_exp_f32_e32 v18, v18
	v_pk_fma_f32 v[16:17], v[14:15], s[42:43], v[142:143] op_sel_hi:[1,0,0]
	v_exp_f32_e32 v19, v19
	v_pk_fma_f32 v[16:17], v[14:15], v[16:17], s[40:41] op_sel_hi:[1,1,0]
	v_cmp_gt_f32_e32 vcc, 0, v10
	v_pk_fma_f32 v[16:17], v[14:15], v[16:17], s[92:93] op_sel_hi:[1,1,0]
	s_nop 0
	v_pk_fma_f32 v[16:17], v[14:15], v[16:17], s[20:21] op_sel_hi:[1,1,0]
	s_nop 0
	v_pk_mul_f32 v[14:15], v[14:15], v[16:17]
	v_pk_mul_f32 v[16:17], v[12:13], v[12:13]
	v_pk_mul_f32 v[14:15], v[18:19], v[14:15]
	s_nop 0
	v_pk_mul_f32 v[18:19], v[10:11], v[14:15]
	v_pk_fma_f32 v[14:15], v[10:11], v[14:15], v[10:11] neg_lo:[1,0,0] neg_hi:[1,0,0]
	v_and_b32_e32 v10, 0x7fffffff, v12
	v_cndmask_b32_e32 v18, v14, v18, vcc
	v_cmp_gt_f32_e32 vcc, 0, v11
	v_and_b32_e32 v11, 0x7fffffff, v13
	v_pk_fma_f32 v[10:11], v[10:11], s[2:3], 1.0 op_sel_hi:[1,0,0]
	v_cndmask_b32_e32 v19, v15, v19, vcc
	v_rcp_f32_e32 v10, v10
	v_rcp_f32_e32 v11, v11
	v_cmp_gt_f32_e32 vcc, 0, v12
	v_mul_f32_e32 v6, v6, v18
	v_mul_f32_e32 v7, v7, v19
	v_pk_fma_f32 v[14:15], v[10:11], s[42:43], v[142:143] op_sel_hi:[1,0,0]
	v_cvt_pk_bf16_f32 v6, v6, v7
	s_nop 0
	v_pk_fma_f32 v[14:15], v[10:11], v[14:15], s[40:41] op_sel_hi:[1,1,0]
	s_nop 0
	v_pk_fma_f32 v[14:15], v[10:11], v[14:15], s[92:93] op_sel_hi:[1,1,0]
	s_nop 0
	v_pk_fma_f32 v[14:15], v[10:11], v[14:15], s[20:21] op_sel_hi:[1,1,0]
	s_nop 0
	v_pk_mul_f32 v[10:11], v[10:11], v[14:15]
	v_pk_mul_f32 v[14:15], v[16:17], s[22:23] op_sel_hi:[1,0]
	s_nop 0
	v_exp_f32_e32 v14, v14
	v_exp_f32_e32 v15, v15
	s_nop 0
	v_pk_mul_f32 v[10:11], v[14:15], v[10:11]
	s_nop 0
	v_pk_mul_f32 v[14:15], v[12:13], v[10:11]
	v_pk_fma_f32 v[10:11], v[12:13], v[10:11], v[12:13] neg_lo:[1,0,0] neg_hi:[1,0,0]
	s_nop 0
	v_cndmask_b32_e32 v10, v10, v14, vcc
	v_cmp_gt_f32_e32 vcc, 0, v13
	v_mul_f32_e32 v7, v8, v10
	s_nop 0
	v_cndmask_b32_e32 v11, v11, v15, vcc
	v_mul_f32_e32 v8, v9, v11
	v_cvt_pk_bf16_f32 v7, v7, v8
	v_lshl_add_u64 v[8:9], v[172:173], 0, v[50:51]
	v_lshl_add_u64 v[10:11], v[174:175], 0, v[50:51]
	global_store_dwordx2 v[8:9], v[6:7], off
	v_add_co_u32_e32 v8, vcc, s43, v10
	global_load_dword v6, v[122:123], off
	s_nop 0
	v_addc_co_u32_e32 v9, vcc, -1, v11, vcc
	v_add_co_u32_e32 v12, vcc, s41, v10
	global_load_dwordx2 v[8:9], v[8:9], off offset:-3072
	s_nop 0
	v_addc_co_u32_e32 v13, vcc, -1, v11, vcc
	global_load_dwordx2 v[12:13], v[12:13], off offset:-1536
	s_nop 0
	global_load_dwordx2 v[10:11], v[10:11], off
	s_waitcnt vmcnt(3)
	v_pk_mul_f32 v[4:5], v[4:5], v[6:7] op_sel_hi:[1,0]
	v_pk_mul_f32 v[2:3], v[2:3], v[6:7] op_sel_hi:[1,0]
	s_waitcnt vmcnt(2)
	v_lshlrev_b32_e32 v16, 16, v8
	v_and_b32_e32 v17, 0xffff0000, v8
	s_waitcnt vmcnt(1)
	v_lshlrev_b32_e32 v14, 16, v12
	v_and_b32_e32 v15, 0xffff0000, v12
	v_lshlrev_b32_e32 v12, 16, v13
	v_and_b32_e32 v13, 0xffff0000, v13
	v_lshlrev_b32_e32 v8, 16, v9
	v_and_b32_e32 v9, 0xffff0000, v9
	v_pk_mul_f32 v[14:15], v[46:47], v[14:15]
	v_pk_mul_f32 v[12:13], v[48:49], v[12:13]
	s_waitcnt vmcnt(0)
	v_lshlrev_b32_e32 v6, 16, v10
	v_and_b32_e32 v7, 0xffff0000, v10
	v_pk_fma_f32 v[8:9], v[44:45], v[8:9], v[12:13]
	v_pk_fma_f32 v[12:13], v[42:43], v[16:17], v[14:15]
	v_lshlrev_b32_e32 v10, 16, v11
	v_pk_fma_f32 v[6:7], v[38:39], v[6:7], v[12:13]
	v_and_b32_e32 v11, 0xffff0000, v11
	v_pk_add_f32 v[6:7], v[34:35], v[6:7]
	v_pk_fma_f32 v[8:9], v[40:41], v[10:11], v[8:9]
	v_and_b32_e32 v11, 0x7fffffff, v7
	v_and_b32_e32 v10, 0x7fffffff, v6
	v_pk_fma_f32 v[10:11], v[10:11], s[2:3], 1.0 op_sel_hi:[1,0,0]
	v_pk_mul_f32 v[14:15], v[6:7], v[6:7]
	v_rcp_f32_e32 v10, v10
	v_rcp_f32_e32 v11, v11
	v_pk_mul_f32 v[14:15], v[14:15], s[22:23] op_sel_hi:[1,0]
	v_pk_add_f32 v[8:9], v[36:37], v[8:9]
	v_exp_f32_e32 v14, v14
	v_pk_fma_f32 v[12:13], v[10:11], s[42:43], v[142:143] op_sel_hi:[1,0,0]
	v_exp_f32_e32 v15, v15
	v_pk_fma_f32 v[12:13], v[10:11], v[12:13], s[40:41] op_sel_hi:[1,1,0]
	v_cmp_gt_f32_e32 vcc, 0, v6
	v_pk_fma_f32 v[12:13], v[10:11], v[12:13], s[92:93] op_sel_hi:[1,1,0]
	s_nop 0
	v_pk_fma_f32 v[12:13], v[10:11], v[12:13], s[20:21] op_sel_hi:[1,1,0]
	s_nop 0
	v_pk_mul_f32 v[10:11], v[10:11], v[12:13]
	v_pk_mul_f32 v[12:13], v[8:9], v[8:9]
	v_pk_mul_f32 v[10:11], v[14:15], v[10:11]
	s_nop 0
	v_pk_mul_f32 v[14:15], v[6:7], v[10:11]
	v_pk_fma_f32 v[10:11], v[6:7], v[10:11], v[6:7] neg_lo:[1,0,0] neg_hi:[1,0,0]
	v_and_b32_e32 v6, 0x7fffffff, v8
	v_cndmask_b32_e32 v14, v10, v14, vcc
	v_cmp_gt_f32_e32 vcc, 0, v7
	v_and_b32_e32 v7, 0x7fffffff, v9
	v_pk_fma_f32 v[6:7], v[6:7], s[2:3], 1.0 op_sel_hi:[1,0,0]
	v_cndmask_b32_e32 v15, v11, v15, vcc
	v_rcp_f32_e32 v6, v6
	v_rcp_f32_e32 v7, v7
	v_cmp_gt_f32_e32 vcc, 0, v8
	v_mul_f32_e32 v2, v2, v14
	v_mul_f32_e32 v3, v3, v15
	v_pk_fma_f32 v[10:11], v[6:7], s[42:43], v[142:143] op_sel_hi:[1,0,0]
	v_cvt_pk_bf16_f32 v2, v2, v3
	s_nop 0
	v_pk_fma_f32 v[10:11], v[6:7], v[10:11], s[40:41] op_sel_hi:[1,1,0]
	s_nop 0
	v_pk_fma_f32 v[10:11], v[6:7], v[10:11], s[92:93] op_sel_hi:[1,1,0]
	s_nop 0
	v_pk_fma_f32 v[10:11], v[6:7], v[10:11], s[20:21] op_sel_hi:[1,1,0]
	s_nop 0
	v_pk_mul_f32 v[6:7], v[6:7], v[10:11]
	v_pk_mul_f32 v[10:11], v[12:13], s[22:23] op_sel_hi:[1,0]
	s_nop 0
	v_exp_f32_e32 v10, v10
	v_exp_f32_e32 v11, v11
	s_nop 0
	v_pk_mul_f32 v[6:7], v[10:11], v[6:7]
	s_nop 0
	v_pk_mul_f32 v[10:11], v[8:9], v[6:7]
	v_pk_fma_f32 v[6:7], v[8:9], v[6:7], v[8:9] neg_lo:[1,0,0] neg_hi:[1,0,0]
	s_nop 0
	v_cndmask_b32_e32 v6, v6, v10, vcc
	v_cmp_gt_f32_e32 vcc, 0, v9
	v_mul_f32_e32 v3, v4, v6
	s_nop 0
	v_cndmask_b32_e32 v7, v7, v11, vcc
	v_mul_f32_e32 v4, v5, v7
	v_cvt_pk_bf16_f32 v3, v3, v4
	v_lshl_add_u64 v[4:5], v[82:83], 0, v[50:51]
	global_store_dwordx2 v[4:5], v[2:3], off
	s_and_b64 vcc, exec, s[4:5]
	s_cbranch_vccnz .LBB0_2616
	s_andn2_b64 vcc, exec, s[26:27]
	s_cbranch_vccnz .LBB0_2615
	s_barrier
	s_branch .LBB0_2615

; #define GAS __attribute__((address_space(1)))
; __device__ __forceinline__ const float* ptr(int i) { const unsigned long long v = *(const volatile unsigned long long*)(g_lds + PTAB_OFF + 8 * i);
;     const unsigned lo = __builtin_amdgcn_readfirstlane((unsigned)v), hi = __builtin_amdgcn_readfirstlane((unsigned)(v >> 32)); return (const float*)(GAS const float*)(((unsigned long long)hi << 32) | lo); }
; __device__ __forceinline__ void xcd_barrier(const XcdBarrier& b) {
;     asm volatile("s_waitcnt vmcnt(0)" ::: "memory");
;     __syncthreads();
;     if (threadIdx.x == 0) {
;         unsigned* bar = b.bar;
;         __builtin_amdgcn_s_waitcnt(0);
;         unsigned nloc = b.st[0], nx = b.st[1];
;         if (nloc == 0u) { xcd_barrier_complete(bar, b.x, nloc, nx); b.st[0] = nloc; b.st[1] = nx; }
.LBB0_2632:
	v_readlane_b32 s0, v254, 4
	v_readlane_b32 s4, v254, 20
	s_cmp_lg_u32 s0, -1
	v_readlane_b32 s5, v254, 21
	s_cselect_b32 s0, s0, 0
	s_cselect_b32 s1, s5, 0
	s_waitcnt vmcnt(0) lgkmcnt(0)
	v_mov_b32_e32 v2, s0
	v_mov_b32_e32 v3, s1
	ds_read_b64 v[2:3], v2
	s_waitcnt lgkmcnt(0)
	s_getreg_b32 s6, hwreg(HW_REG_XCC_ID, 0, 4)
	s_waitcnt vmcnt(0)
	s_waitcnt lgkmcnt(0)
	s_barrier
	v_readfirstlane_b32 s5, v3
	v_readfirstlane_b32 s4, v2
	s_mov_b64 s[0:1], exec
	v_readlane_b32 s8, v254, 1
	v_readlane_b32 s9, v254, 2
	s_and_b64 s[8:9], s[0:1], s[8:9]
	s_mov_b64 exec, s[8:9]
	s_cbranch_execz .LBB0_2608
	v_readlane_b32 s7, v254, 54
	s_waitcnt vmcnt(0) expcnt(0) lgkmcnt(0)
	s_and_b32 s28, s6, 15
	v_mov_b32_e32 v1, s7
	ds_read_b32 v3, v1
	v_readlane_b32 s7, v254, 55
	s_waitcnt lgkmcnt(0)
	v_cmp_ne_u32_e32 vcc, 0, v3
	v_mov_b32_e32 v1, s7
	ds_read_b32 v2, v1
	s_cbranch_vccnz .LBB0_2648
	v_readlane_b32 s6, v254, 5
	v_readlane_b32 s7, v254, 6
	s_load_dwordx2 s[10:11], s[6:7], 0x4
	s_add_u32 s6, s4, 0x1000
	s_addc_u32 s7, s5, 0
	s_add_u32 s8, s4, 0x1100
	s_addc_u32 s9, s5, 0
	v_readlane_b32 s16, v254, 7
	s_waitcnt lgkmcnt(0)
	s_mul_i32 s29, s10, s16
	s_add_u32 s10, s4, 0x1200
	s_mul_i32 s29, s29, s11
	s_addc_u32 s11, s5, 0
	s_add_u32 s16, s4, 0x1300
	s_addc_u32 s17, s5, 0
	s_mov_b32 s30, 1
	s_branch .LBB0_2636

; #define LAS __attribute__((address_space(3)))
; template <int ID, class E> __device__ __forceinline__ void run_gemm(LAS unsigned char* lds, const bf16* A, const bf16* Bt, int M, int N, int K, const E& e) {
;     asm volatile("" : "+s"(K)); asm volatile("" : "+s"(N));
;     pg8::Gemm g{A, Bt, M, N, K}; pg8::StaticOrder S; S.init(M, N, (int)gridDim.x, (int)blockIdx.x);
; __global__ void __launch_bounds__(512, 2) mega_fwd(Args a) {
;     ...
;         if (PH(9)) { { EpiResid e{layer, 1}; run_gemm<10>(ldsl, (const bf16*)(R + R_ACT), (const bf16*)(W + W_FFNOUT), T, 1024, FFN, e); } }
.LBB0_2735:
	s_or_b64 exec, exec, s[0:1]
	v_readlane_b32 s0, v254, 4
	v_readlane_b32 s4, v254, 20
	s_cmp_lg_u32 s0, -1
	v_readlane_b32 s5, v254, 21
	s_cselect_b32 s0, s0, 0
	s_cselect_b32 s1, s5, 0
	s_waitcnt lgkmcnt(0)
	v_mov_b64_e32 v[2:3], s[0:1]
	s_barrier
	ds_read_b64 v[4:5], v2
	s_waitcnt lgkmcnt(0)
	s_movk_i32 s0, 0xb00
	ds_read_b64 v[2:3], v2
	s_waitcnt lgkmcnt(0)
	s_movk_i32 s4, 0x400
	s_ashr_i32 s5, s4, 31
	s_lshr_b32 s5, s5, 24
	s_add_i32 s4, s4, s5
	s_ashr_i32 s26, s4, 8
	s_lshl_b32 s6, s26, 6
	v_readlane_b32 s11, v254, 0
	s_cmp_lt_i32 s11, s6
	v_readfirstlane_b32 s7, v147
	s_cselect_b64 s[4:5], -1, 0
	s_cmp_ge_i32 s11, s6
	s_waitcnt lgkmcnt(0)
	v_readfirstlane_b32 s1, v5
	v_readfirstlane_b32 s8, v4
	v_readfirstlane_b32 s9, v3
	v_readfirstlane_b32 s10, v2
	s_cbranch_scc0 .LBB0_2738
	s_andn2_b64 vcc, exec, s[4:5]
	s_cbranch_vccz .LBB0_2739

.LBB0_2755:
	v_readlane_b32 s28, v254, 4
	v_readlane_b32 s30, v254, 20
	s_cmp_lg_u32 s28, -1
	v_readlane_b32 s31, v254, 21
	s_cselect_b32 s28, s28, 0
	s_cselect_b32 s29, s31, 0
	v_mov_b32_e32 v138, s28
	v_mov_b32_e32 v139, s29
	ds_read_b64 v[154:155], v138
	s_waitcnt lgkmcnt(0)
	v_readlane_b32 s28, v254, 3
	s_cmp_lg_u32 s28, -1
	s_cselect_b32 s28, s28, 0
	s_cselect_b32 s29, s31, 0
	v_mov_b32_e32 v138, s28
	v_mov_b32_e32 v139, s29
	ds_read_b64 v[156:157], v138
	s_waitcnt lgkmcnt(0)
	v_lshl_add_u32 v140, s33, 8, v1
	s_mov_b32 s37, s31
	v_lshl_or_b32 v138, s47, 8, v143
	v_ashrrev_i32_e32 v141, 31, v140
	v_ashrrev_i32_e32 v139, 31, v138
	v_lshlrev_b64 v[158:159], 12, v[140:141]
	v_lshlrev_b64 v[160:161], 2, v[138:139]
	s_waitcnt lgkmcnt(0)
	v_readfirstlane_b32 s34, v154
	v_readfirstlane_b32 s33, v155
	s_add_u32 s28, s34, 0x400000
	s_addc_u32 s29, s33, 0
	s_add_i32 s35, 0, 0x20058
	s_cmp_lg_u32 s35, -1
	s_cselect_b32 s35, s35, 0
	s_cselect_b32 s36, s37, 0
	v_readfirstlane_b32 s31, v157
	v_readfirstlane_b32 s30, v156
	v_mov_b32_e32 v156, s35
	v_mov_b32_e32 v157, s36
	v_lshl_add_u64 v[154:155], s[30:31], 0, v[158:159]
	ds_read_b64 v[158:159], v156
	s_waitcnt lgkmcnt(0)
	v_lshl_add_u64 v[162:163], v[154:155], 0, v[160:161]
	global_load_dwordx4 v[154:157], v[162:163], off
	s_waitcnt lgkmcnt(0)
	v_readfirstlane_b32 s36, v158
	v_readfirstlane_b32 s35, v159
	s_add_u32 s36, s36, s58
	s_waitcnt vmcnt(0)
	v_pk_add_f32 v[156:157], v[128:129], v[156:157]
	v_pk_add_f32 v[154:155], v[126:127], v[154:155]
	s_addc_u32 s37, s35, 0
	global_store_dwordx4 v[162:163], v[154:157], off
	v_lshl_add_u64 v[126:127], s[36:37], 0, v[160:161]
	global_load_dwordx4 v[158:161], v[126:127], off
	v_lshlrev_b64 v[128:129], 11, v[140:141]
	v_lshl_add_u64 v[128:129], s[28:29], 0, v[128:129]
	v_lshl_add_u64 v[128:129], v[138:139], 1, v[128:129]
	v_mul_f32_e32 v145, v157, v157
	v_fmac_f32_e32 v145, v156, v156
	s_add_u32 s34, s34, 0x15a00000
	s_addc_u32 s35, s33, 0
	s_waitcnt vmcnt(0)
	v_pk_mul_f32 v[158:159], v[154:155], v[158:159]
	v_pk_mul_f32 v[160:161], v[156:157], v[160:161]
	v_cvt_pk_bf16_f32 v158, v158, v159
	s_nop 0
	v_cvt_pk_bf16_f32 v159, v160, v161
	global_store_dwordx2 v[128:129], v[158:159], off
	global_load_dwordx4 v[158:161], v[162:163], off offset:64
	s_waitcnt vmcnt(0)
	v_pk_add_f32 v[124:125], v[124:125], v[160:161]
	v_pk_add_f32 v[122:123], v[122:123], v[158:159]
	global_store_dwordx4 v[162:163], v[122:125], off offset:64
	global_load_dwordx4 v[158:161], v[126:127], off offset:64
	s_waitcnt vmcnt(0)
	v_pk_mul_f32 v[158:159], v[122:123], v[158:159]
	v_pk_mul_f32 v[160:161], v[124:125], v[160:161]
	v_cvt_pk_bf16_f32 v158, v158, v159
	v_mul_f32_e32 v123, v123, v123
	v_cvt_pk_bf16_f32 v159, v160, v161
	global_store_dwordx2 v[128:129], v[158:159], off offset:32
	global_load_dwordx4 v[158:161], v[162:163], off offset:512
	v_mul_f32_e32 v125, v125, v125
	v_fmac_f32_e32 v123, v122, v122
	v_fmac_f32_e32 v125, v124, v124
	v_add_f32_e32 v122, v123, v125
	s_waitcnt vmcnt(0)
	v_pk_add_f32 v[120:121], v[120:121], v[160:161]
	v_pk_add_f32 v[118:119], v[118:119], v[158:159]
	global_store_dwordx4 v[162:163], v[118:121], off offset:512
	global_load_dwordx4 v[158:161], v[126:127], off offset:512
	s_waitcnt vmcnt(0)
	v_pk_mul_f32 v[158:159], v[118:119], v[158:159]
	v_pk_mul_f32 v[160:161], v[120:121], v[160:161]
	v_cvt_pk_bf16_f32 v158, v158, v159
	v_mul_f32_e32 v119, v119, v119
	v_cvt_pk_bf16_f32 v159, v160, v161
	global_store_dwordx2 v[128:129], v[158:159], off offset:256
	global_load_dwordx4 v[158:161], v[162:163], off offset:576
	v_mul_f32_e32 v121, v121, v121
	v_fmac_f32_e32 v119, v118, v118
	v_fmac_f32_e32 v121, v120, v120
	v_add_f32_e32 v118, v119, v121
	s_waitcnt vmcnt(0)
	v_pk_add_f32 v[160:161], v[116:117], v[160:161]
	v_pk_add_f32 v[158:159], v[114:115], v[158:159]
	global_store_dwordx4 v[162:163], v[158:161], off offset:576
	global_load_dwordx4 v[162:165], v[126:127], off offset:576
	v_and_b32_e32 v115, 64, v206
	v_xor_b32_e32 v114, 16, v206
	v_add_u32_e32 v115, 64, v115
	v_cmp_lt_i32_e32 vcc, v114, v115
	v_mul_f32_e32 v119, v161, v161
	v_fmac_f32_e32 v119, v160, v160
	v_cndmask_b32_e32 v114, v206, v114, vcc
	v_lshlrev_b32_e32 v116, 2, v114
	v_mul_f32_e32 v114, v155, v155
	v_fmac_f32_e32 v114, v154, v154
	v_add_f32_e32 v114, v114, v145
	v_add_f32_e32 v114, v114, v122
	v_add_f32_e32 v114, v114, v118
	v_mul_f32_e32 v118, v159, v159
	v_fmac_f32_e32 v118, v158, v158
	v_add_f32_e32 v118, v118, v119
	v_add_f32_e32 v114, v114, v118
	ds_bpermute_b32 v118, v116, v114
	v_xor_b32_e32 v117, 32, v206
	v_cmp_lt_i32_e32 vcc, v117, v115
	s_waitcnt lgkmcnt(0)
	v_add_f32_e32 v114, v114, v118
	v_cndmask_b32_e32 v115, v206, v117, vcc
	v_lshlrev_b32_e32 v117, 2, v115
	ds_bpermute_b32 v115, v117, v114
	s_waitcnt vmcnt(0)
	v_pk_mul_f32 v[120:121], v[158:159], v[162:163]
	v_pk_mul_f32 v[118:119], v[160:161], v[164:165]
	v_cvt_pk_bf16_f32 v120, v120, v121
	s_nop 0
	v_cvt_pk_bf16_f32 v121, v118, v119
	global_store_dwordx2 v[128:129], v[120:121], off offset:288
	s_mov_b64 s[36:37], exec
	v_readlane_b32 s66, v254, 25
	v_readlane_b32 s67, v254, 26
	s_and_b64 s[66:67], s[36:37], s[66:67]
	s_mov_b64 exec, s[66:67]
	s_cbranch_execz .LBB0_2757
	s_waitcnt lgkmcnt(0)
	v_add_f32_e32 v118, v114, v115
	s_lshl_b32 s66, s47, 2
	v_lshlrev_b64 v[114:115], 7, v[140:141]
	s_ashr_i32 s67, s66, 31
	v_lshl_add_u64 v[114:115], s[34:35], 0, v[114:115]
	v_lshl_add_u64 v[114:115], s[66:67], 2, v[114:115]
	s_lshl_b32 s96, s52, 2
	v_lshl_add_u64 v[114:115], v[114:115], 0, s[96:97]
	global_store_dword v[114:115], v118, off

; __device__ __forceinline__ v2u pk4(f32x4 v) { v2u o; o.x = pk2(v[0], v[1]); o.y = pk2(v[2], v[3]); return o; }
; __device__ __forceinline__ void conv_p(const Ctx&, const In& in, unsigned char* ws, int layer) { const Ctx c = mk_ctx();
;     const f32x4* src = (const f32x4*)(in[1] + (size_t)layer * T * 256); v2u* dst = (v2u*)(ws + WS_PB);
;     for (int i = c.gw * 64 + c.lane; i < T * 256 / 4; i += c.NGW * 64) dst[i] = pk4(src[i]);
; }
.LBB0_2775:
	v_readlane_b32 s0, v254, 4
	v_readlane_b32 s4, v254, 20
	s_cmp_lg_u32 s0, -1
	v_readlane_b32 s5, v254, 21
	s_cselect_b32 s0, s0, 0
	s_cselect_b32 s1, s5, 0
	v_mov_b32_e32 v2, s0
	s_waitcnt lgkmcnt(0)
	v_mov_b32_e32 v3, s1
	v_mov_b32_e32 v1, v147
	ds_read_b64 v[4:5], v2
	s_waitcnt lgkmcnt(0)
	v_readlane_b32 s4, v254, 19
	v_readfirstlane_b32 s1, v1
	s_andn2_b32 s1, s1, 63
	s_cmp_lg_u32 s4, -1
	s_cselect_b32 s4, s4, 0
	s_cselect_b32 s5, s5, 0
	v_readlane_b32 s0, v254, 0
	v_mov_b32_e32 v2, s4
	v_mov_b32_e32 v3, s5
	ds_read_b64 v[6:7], v2
	s_waitcnt lgkmcnt(0)
	s_lshl_b32 s0, s0, 9
	s_add_i32 s1, s1, s0
	v_and_or_b32 v2, v1, 63, s1
	s_mov_b32 s0, 0x100000
	v_cmp_gt_i32_e32 vcc, s0, v2
	s_waitcnt lgkmcnt(0)
	v_readfirstlane_b32 s5, v5
	v_readfirstlane_b32 s4, v4
	v_readfirstlane_b32 s6, v7
	v_readfirstlane_b32 s7, v6
	s_and_saveexec_b64 s[0:1], vcc
	v_readlane_b32 s10, v254, 50
	v_readlane_b32 s11, v254, 51
	s_cbranch_execz .LBB0_2778
	v_ashrrev_i32_e32 v3, 31, v2
	v_lshl_add_u64 v[4:5], v[2:3], 3, s[4:5]
	s_mov_b64 s[4:5], 0x4400000
	v_lshl_add_u64 v[4:5], v[4:5], 0, s[4:5]
	v_readlane_b32 s4, v254, 52
	v_readlane_b32 s5, v254, 53
	s_add_u32 s4, s7, s4
	s_addc_u32 s5, s6, s5
	v_lshl_add_u64 v[6:7], v[2:3], 4, s[4:5]
	s_mov_b64 s[4:5], 0

; #define GAS __attribute__((address_space(1)))
; __device__ __forceinline__ const float* ptr(int i) { const unsigned long long v = *(const volatile unsigned long long*)(g_lds + PTAB_OFF + 8 * i);
;     const unsigned lo = __builtin_amdgcn_readfirstlane((unsigned)v), hi = __builtin_amdgcn_readfirstlane((unsigned)(v >> 32)); return (const float*)(GAS const float*)(((unsigned long long)hi << 32) | lo); }
; __device__ __forceinline__ void xcd_barrier(const XcdBarrier& b) {
;     asm volatile("s_waitcnt vmcnt(0)" ::: "memory");
;     __syncthreads();
;     if (threadIdx.x == 0) {
;         unsigned* bar = b.bar;
;         __builtin_amdgcn_s_waitcnt(0);
;         unsigned nloc = b.st[0], nx = b.st[1];
;         if (nloc == 0u) { xcd_barrier_complete(bar, b.x, nloc, nx); b.st[0] = nloc; b.st[1] = nx; }
.LBB0_2779:
	v_readlane_b32 s0, v254, 4
	v_readlane_b32 s4, v254, 20
	s_cmp_lg_u32 s0, -1
	v_readlane_b32 s5, v254, 21
	s_cselect_b32 s0, s0, 0
	s_cselect_b32 s1, s5, 0
	s_waitcnt vmcnt(0) lgkmcnt(0)
	v_mov_b32_e32 v2, s0
	s_waitcnt lgkmcnt(0)
	v_mov_b32_e32 v3, s1
	ds_read_b64 v[2:3], v2
	s_waitcnt lgkmcnt(0)
	s_getreg_b32 s6, hwreg(HW_REG_XCC_ID, 0, 4)
	s_waitcnt vmcnt(0)
	s_waitcnt lgkmcnt(0)
	s_barrier
	v_readfirstlane_b32 s5, v3
	v_readfirstlane_b32 s4, v2
	s_mov_b64 s[0:1], exec
	v_readlane_b32 s8, v254, 1
	v_readlane_b32 s9, v254, 2
	s_and_b64 s[8:9], s[0:1], s[8:9]
	s_mov_b64 exec, s[8:9]
	s_cbranch_execz .LBB0_2831
	v_readlane_b32 s7, v254, 54
	s_waitcnt vmcnt(0) expcnt(0) lgkmcnt(0)
	s_and_b32 s28, s6, 15
	v_mov_b32_e32 v1, s7
	ds_read_b32 v3, v1
	v_readlane_b32 s7, v254, 55
	s_waitcnt lgkmcnt(0)
	v_cmp_ne_u32_e32 vcc, 0, v3
	v_mov_b32_e32 v1, s7
	ds_read_b32 v2, v1
	s_cbranch_vccnz .LBB0_2795
	v_readlane_b32 s6, v254, 5
	v_readlane_b32 s7, v254, 6
	s_load_dwordx2 s[10:11], s[6:7], 0x4
	s_add_u32 s6, s4, 0x1000
	s_addc_u32 s7, s5, 0
	s_add_u32 s8, s4, 0x1100
	s_addc_u32 s9, s5, 0
	v_readlane_b32 s16, v254, 7
	s_waitcnt lgkmcnt(0)
	s_mul_i32 s29, s10, s16
	s_add_u32 s10, s4, 0x1200
	s_mul_i32 s29, s29, s11
	s_addc_u32 s11, s5, 0
	s_add_u32 s16, s4, 0x1300
	s_addc_u32 s17, s5, 0
	s_mov_b32 s30, 1
	s_branch .LBB0_2783

; #define LAS __attribute__((address_space(3)))
;     __host__ __device__ bool next(int i, Unit& u) const {
;         const long L = (long)i * G + c; if (L >= nwg) return false;
;         int wgid = (int)L; { const int q = nwg / NXCD, r = nwg % NXCD, xcd = wgid % NXCD, off = wgid / NXCD; wgid = (xcd < r ? xcd * (q + 1) : r * (q + 1) + (xcd - r) * q) + off; }
;         const int nig = WGM * nN, gid = wgid / nig, fm = gid * WGM, gsz = (nM - fm) < WGM ? (nM - fm) : WGM;
;         u.pm = fm + ((wgid % nig) % gsz); u.pn = (wgid % nig) / gsz; return true;
; template <int ID, class E> __device__ __forceinline__ void run_gemm(LAS unsigned char* lds, const bf16* A, const bf16* Bt, int M, int N, int K, const E& e) {
;     asm volatile("" : "+s"(K)); asm volatile("" : "+s"(N));
;     pg8::Gemm g{A, Bt, M, N, K}; pg8::StaticOrder S; S.init(M, N, (int)gridDim.x, (int)blockIdx.x);
.LBB0_2831:
	s_or_b64 exec, exec, s[0:1]
	v_readlane_b32 s0, v254, 4
	v_readlane_b32 s4, v254, 20
	s_cmp_lg_u32 s0, -1
	v_readlane_b32 s5, v254, 21
	s_cselect_b32 s0, s0, 0
	s_cselect_b32 s1, s5, 0
	s_waitcnt lgkmcnt(0)
	v_mov_b64_e32 v[2:3], s[0:1]
	s_barrier
	ds_read_b64 v[4:5], v2
	s_waitcnt lgkmcnt(0)
	s_movk_i32 s0, 0x400
	ds_read_b64 v[2:3], v2
	s_waitcnt lgkmcnt(0)
	s_movk_i32 s4, 0x400
	s_ashr_i32 s5, s4, 31
	s_lshr_b32 s5, s5, 24
	s_add_i32 s4, s4, s5
	s_ashr_i32 s28, s4, 8
	s_lshl_b32 s8, s28, 6
	v_readlane_b32 s11, v254, 0
	s_cmp_lt_i32 s11, s8
	v_readfirstlane_b32 s9, v147
	s_cselect_b64 s[4:5], -1, 0
	s_cmp_ge_i32 s11, s8
	s_waitcnt lgkmcnt(0)
	v_readfirstlane_b32 s1, v5
	v_readfirstlane_b32 s6, v4
	v_readfirstlane_b32 s7, v3
	v_readfirstlane_b32 s10, v2
	s_cbranch_scc1 .LBB0_2833
	s_lshl_b32 s11, s28, 3
	s_abs_i32 s16, s11
	v_cvt_f32_u32_e32 v1, s16
	v_readlane_b32 s17, v254, 24
	s_or_b32 s17, s11, s17
	v_readlane_b32 s18, v254, 37
	v_rcp_iflag_f32_e32 v1, v1
	s_mul_i32 s17, s17, s18
	s_sub_i32 s18, 0, s16
	v_readlane_b32 s19, v254, 23
	v_mul_f32_e32 v1, 0x4f7ffffe, v1
	v_cvt_u32_f32_e32 v1, v1
	s_add_i32 s17, s17, s19
	s_abs_i32 s24, s17
	s_xor_b32 s19, s17, s11
	v_readfirstlane_b32 s25, v1
	s_mul_i32 s18, s18, s25
	s_mul_hi_u32 s18, s25, s18
	s_add_i32 s25, s25, s18
	s_mul_hi_u32 s18, s24, s25
	s_mul_i32 s25, s18, s16
	s_sub_i32 s24, s24, s25
	s_ashr_i32 s19, s19, 31
	s_add_i32 s26, s18, 1
	s_sub_i32 s25, s24, s16
	s_cmp_ge_u32 s24, s16
	s_cselect_b32 s18, s26, s18
	s_cselect_b32 s24, s25, s24
	s_add_i32 s25, s18, 1
	s_cmp_ge_u32 s24, s16
	s_cselect_b32 s16, s25, s18
	s_xor_b32 s16, s16, s19
	s_sub_i32 s16, s16, s19
	s_lshl_b32 s18, s16, 3
	s_sub_i32 s19, 64, s18
	s_min_i32 s19, s19, 8
	s_abs_i32 s24, s19
	v_cvt_f32_u32_e32 v1, s24
	s_sub_i32 s25, 0, s24
	s_mul_i32 s16, s16, s11
	s_sub_i32 s11, s17, s16
	v_rcp_iflag_f32_e32 v1, v1
	s_abs_i32 s16, s11
	s_xor_b32 s17, s11, s19
	s_ashr_i32 s17, s17, 31
	v_mul_f32_e32 v1, 0x4f7ffffe, v1
	v_cvt_u32_f32_e32 v1, v1
	s_nop 0
	v_readfirstlane_b32 s26, v1
	s_mul_i32 s25, s25, s26
	s_mul_hi_u32 s25, s26, s25
	s_add_i32 s26, s26, s25
	s_mul_hi_u32 s25, s16, s26
	s_mul_i32 s26, s25, s24
	s_sub_i32 s16, s16, s26
	s_add_i32 s27, s25, 1
	s_sub_i32 s26, s16, s24
	s_cmp_ge_u32 s16, s24
	s_cselect_b32 s25, s27, s25
	s_cselect_b32 s16, s26, s16
	s_add_i32 s26, s25, 1
	s_cmp_ge_u32 s16, s24
	s_cselect_b32 s16, s26, s25
	s_xor_b32 s16, s16, s17
	s_sub_i32 s57, s16, s17
	s_mul_i32 s16, s57, s19
	s_sub_i32 s11, s11, s16
	s_add_i32 s33, s11, s18

.LBB0_2850:
	v_readlane_b32 s0, v254, 4
	v_readlane_b32 s6, v254, 20
	s_cmp_lg_u32 s0, -1
	v_readlane_b32 s7, v254, 21
	s_cselect_b32 s0, s0, 0
	s_cselect_b32 s1, s7, 0
	v_mov_b32_e32 v130, s0
	v_mov_b32_e32 v131, s1
	ds_read_b64 v[130:131], v130
	s_waitcnt lgkmcnt(0)
	v_readlane_b32 s0, v254, 3
	s_cmp_lg_u32 s0, -1
	s_cselect_b32 s0, s0, 0
	s_cselect_b32 s1, s7, 0
	v_lshl_add_u32 v144, s33, 8, v1
	v_ashrrev_i32_e32 v145, 31, v144
	v_lshlrev_b64 v[154:155], 7, v[144:145]
	v_lshl_or_b32 v140, s57, 8, v169
	s_waitcnt lgkmcnt(0)
	v_readfirstlane_b32 s51, v131
	v_readfirstlane_b32 s50, v130
	v_mov_b32_e32 v130, s0
	v_mov_b32_e32 v131, s1
	ds_read_b64 v[130:131], v130
	s_waitcnt lgkmcnt(0)
	s_add_u32 s36, s50, 0x11c00000
	s_addc_u32 s37, s51, 0
	v_readlane_b32 s0, v254, 8
	s_cmp_lg_u32 s0, -1
	s_cselect_b32 s0, s0, 0
	s_cselect_b32 s1, s7, 0
	s_waitcnt lgkmcnt(0)
	v_readfirstlane_b32 s45, v131
	v_readfirstlane_b32 s44, v130
	v_mov_b32_e32 v130, s0
	v_mov_b32_e32 v131, s1
	ds_read_b64 v[130:131], v130
	s_waitcnt lgkmcnt(0)
	v_readfirstlane_b32 s1, v130
	v_readfirstlane_b32 s0, v131
	s_add_u32 s34, s1, s14
	s_addc_u32 s35, s0, s15
	s_add_u32 s48, s50, 0x15a00000
	s_addc_u32 s49, s51, 0
	s_add_u32 s46, s50, 0x15c00000
	s_addc_u32 s47, s51, 0
	s_add_u32 s38, s50, 0xfc00000
	s_addc_u32 s39, s51, 0
	s_add_i32 s0, 0, 0x20050
	s_cmp_lg_u32 s0, -1
	s_cselect_b32 s0, s0, 0
	s_cselect_b32 s1, s7, 0
	v_mov_b32_e32 v130, s0
	v_mov_b32_e32 v131, s1
	ds_read_b64 v[130:131], v130
	s_waitcnt lgkmcnt(0)
	v_lshl_add_u64 v[142:143], s[48:49], 0, v[154:155]
	s_waitcnt lgkmcnt(0)
	v_readfirstlane_b32 s0, v131
	v_readfirstlane_b32 s1, v130
	global_load_dwordx4 v[130:133], v[142:143], off offset:48
	global_load_dwordx4 v[156:159], v[142:143], off offset:32
	global_load_dwordx4 v[160:163], v[142:143], off offset:16
	global_load_dwordx4 v[164:167], v[142:143], off
	s_add_u32 s6, s1, s69
	s_addc_u32 s7, s0, 0
	s_mov_b32 s0, 0x3a800000
	s_waitcnt vmcnt(2)
	v_add_f32_e32 v156, v156, v157
	v_add_f32_e32 v158, v158, v159
	s_waitcnt vmcnt(0)
	v_mov_b32_e32 v142, v165
	v_mov_b32_e32 v143, v166
	v_mov_b32_e32 v165, v167
	v_pk_add_f32 v[142:143], v[142:143], v[164:165]
	v_mov_b32_e32 v164, v161
	v_mov_b32_e32 v165, v162
	v_mov_b32_e32 v161, v163
	v_pk_add_f32 v[160:161], v[164:165], v[160:161]
	v_add_f32_e32 v141, v142, v143
	v_pk_add_f32 v[160:161], v[160:161], v[160:161] op_sel:[0,1] op_sel_hi:[1,0]
	v_add_f32_e32 v142, 0, v141
	v_mov_b32_e32 v143, v130
	v_mov_b32_e32 v161, v131
	v_mov_b32_e32 v157, v132
	v_mov_b32_e32 v159, v133
	v_pk_add_f32 v[130:131], v[142:143], v[160:161]
	v_pk_add_f32 v[132:133], v[156:157], v[158:159]
	v_lshl_add_u64 v[164:165], s[46:47], 0, v[154:155]
	v_pk_add_f32 v[142:143], v[130:131], v[132:133]
	global_load_dwordx4 v[130:133], v[164:165], off offset:48
	global_load_dwordx4 v[156:159], v[164:165], off offset:32
	global_load_dwordx4 v[160:163], v[164:165], off offset:16
	s_nop 0
	global_load_dwordx4 v[164:167], v[164:165], off
	s_waitcnt vmcnt(2)
	v_add_f32_e32 v156, v156, v157
	v_add_f32_e32 v158, v158, v159
	s_waitcnt vmcnt(0)
	v_mov_b32_e32 v172, v165
	v_mov_b32_e32 v173, v166
	v_mov_b32_e32 v165, v167
	v_mov_b32_e32 v166, v161
	v_mov_b32_e32 v167, v162
	v_mov_b32_e32 v161, v163
	v_pk_add_f32 v[164:165], v[172:173], v[164:165]
	v_pk_add_f32 v[160:161], v[166:167], v[160:161]
	v_add_f32_e32 v141, v164, v165
	v_pk_add_f32 v[160:161], v[160:161], v[160:161] op_sel:[0,1] op_sel_hi:[1,0]
	v_add_f32_e32 v164, 0, v141
	v_mov_b32_e32 v165, v130
	v_mov_b32_e32 v161, v131
	v_mov_b32_e32 v157, v132
	v_mov_b32_e32 v159, v133
	v_pk_add_f32 v[130:131], v[164:165], v[160:161]
	v_pk_add_f32 v[132:133], v[156:157], v[158:159]
	v_ashrrev_i32_e32 v141, 31, v140
	v_pk_add_f32 v[130:131], v[130:131], v[132:133]
	v_mov_b32_e32 v133, v142
	v_mov_b32_e32 v132, v130
	v_mov_b32_e32 v142, v131
	v_pk_add_f32 v[130:131], v[132:133], v[142:143]
	s_nop 0
	v_pk_fma_f32 v[130:131], v[130:131], s[0:1], v[152:153] op_sel_hi:[1,0,0]
	s_nop 0
	v_mul_f32_e32 v132, 0x4b800000, v131
	v_cmp_gt_f32_e64 s[0:1], s93, v131
	v_cmp_gt_f32_e32 vcc, s93, v130
	s_nop 0
	v_cndmask_b32_e64 v131, v131, v132, s[0:1]
	v_rsq_f32_e32 v131, v131
	s_nop 0
	v_mul_f32_e32 v132, 0x45800000, v131
	v_cndmask_b32_e64 v171, v131, v132, s[0:1]
	v_mul_f32_e32 v131, 0x4b800000, v130
	v_cndmask_b32_e32 v130, v130, v131, vcc
	v_rsq_f32_e32 v130, v130
	v_lshlrev_b64 v[132:133], 11, v[144:145]
	v_lshl_add_u64 v[142:143], s[38:39], 0, v[132:133]
	v_lshl_add_u64 v[156:157], s[36:37], 0, v[132:133]
	v_mul_f32_e32 v131, 0x45800000, v130
	v_cndmask_b32_e32 v160, v130, v131, vcc
	v_lshlrev_b64 v[130:131], 12, v[144:145]
	v_lshl_add_u64 v[130:131], s[44:45], 0, v[130:131]
	v_lshlrev_b64 v[132:133], 2, v[140:141]
	v_lshl_add_u64 v[162:163], v[140:141], 1, v[142:143]
	v_lshl_add_u64 v[158:159], v[130:131], 0, v[132:133]
	global_load_dwordx2 v[130:131], v[162:163], off
	v_mul_f32_e32 v126, v126, v171
	v_mul_f32_e32 v127, v127, v171
	v_mul_f32_e32 v126, 0xbfb8aa3b, v126
	v_mul_f32_e32 v127, 0xbfb8aa3b, v127
	v_exp_f32_e32 v126, v126
	v_exp_f32_e32 v127, v127
	v_mul_f32_e32 v128, v128, v171
	v_mul_f32_e32 v129, v129, v171
	v_mul_f32_e32 v128, 0xbfb8aa3b, v128
	v_pk_add_f32 v[126:127], v[126:127], 1.0 op_sel_hi:[1,0]
	v_mul_f32_e32 v129, 0xbfb8aa3b, v129
	v_div_scale_f32 v145, s[0:1], v127, v127, 1.0
	v_exp_f32_e32 v128, v128
	v_exp_f32_e32 v129, v129
	s_waitcnt vmcnt(0)
	v_lshlrev_b32_e32 v142, 16, v130
	v_and_b32_e32 v143, 0xffff0000, v130
	v_lshlrev_b32_e32 v130, 16, v131
	v_and_b32_e32 v131, 0xffff0000, v131
	v_pk_mul_f32 v[172:173], v[160:161], v[142:143] op_sel_hi:[0,1]
	v_lshl_add_u64 v[142:143], s[6:7], 0, v[132:133]
	v_pk_mul_f32 v[174:175], v[160:161], v[130:131] op_sel_hi:[0,1]
	global_load_dwordx4 v[130:133], v[142:143], off
	global_load_dwordx4 v[164:167], v[158:159], off
	v_rcp_f32_e32 v161, v145
	v_pk_add_f32 v[128:129], v[128:129], 1.0 op_sel_hi:[1,0]
	v_fma_f32 v176, -v145, v161, 1.0
	v_fmac_f32_e32 v161, v176, v161
	v_div_scale_f32 v176, vcc, 1.0, v127, 1.0
	v_mul_f32_e32 v177, v176, v161
	v_fma_f32 v178, -v145, v177, v176
	v_fmac_f32_e32 v177, v178, v161
	v_fma_f32 v145, -v145, v177, v176
	v_div_fmas_f32 v145, v145, v161, v177
	v_div_fixup_f32 v127, v145, v127, 1.0
	v_div_scale_f32 v145, s[0:1], v126, v126, 1.0
	v_rcp_f32_e32 v161, v145
	s_waitcnt vmcnt(1)
	v_pk_mul_f32 v[130:131], v[130:131], v[172:173]
	v_fma_f32 v176, -v145, v161, 1.0
	v_fmac_f32_e32 v161, v176, v161
	v_div_scale_f32 v176, vcc, 1.0, v126, 1.0
	v_mul_f32_e32 v177, v176, v161
	v_fma_f32 v178, -v145, v177, v176
	v_fmac_f32_e32 v177, v178, v161
	v_fma_f32 v145, -v145, v177, v176
	v_div_fmas_f32 v145, v145, v161, v177
	v_div_fixup_f32 v126, v145, v126, 1.0
	s_waitcnt vmcnt(0)
	v_pk_fma_f32 v[126:127], v[126:127], v[130:131], v[164:165]
	v_div_scale_f32 v130, s[0:1], v129, v129, 1.0
	v_rcp_f32_e32 v131, v130
	v_pk_mul_f32 v[132:133], v[132:133], v[174:175]
	v_fma_f32 v145, -v130, v131, 1.0
	v_fmac_f32_e32 v131, v145, v131
	v_div_scale_f32 v145, vcc, 1.0, v129, 1.0
	v_mul_f32_e32 v161, v145, v131
	v_fma_f32 v164, -v130, v161, v145
	v_fmac_f32_e32 v161, v164, v131
	v_fma_f32 v130, -v130, v161, v145
	v_div_fmas_f32 v130, v130, v131, v161
	v_div_fixup_f32 v129, v130, v129, 1.0
	v_div_scale_f32 v130, s[0:1], v128, v128, 1.0
	v_rcp_f32_e32 v131, v130
	s_nop 0
	v_fma_f32 v145, -v130, v131, 1.0
	v_fmac_f32_e32 v131, v145, v131
	v_div_scale_f32 v145, vcc, 1.0, v128, 1.0
	v_mul_f32_e32 v161, v145, v131
	v_fma_f32 v164, -v130, v161, v145
	v_fmac_f32_e32 v161, v164, v131
	v_fma_f32 v130, -v130, v161, v145
	v_div_fmas_f32 v130, v130, v131, v161
	v_div_fixup_f32 v128, v130, v128, 1.0
	v_cndmask_b32_e64 v130, 0, 1, s[12:13]
	v_pk_fma_f32 v[128:129], v[128:129], v[132:133], v[166:167]
	v_cmp_ne_u32_e64 s[6:7], 1, v130
	s_andn2_b64 vcc, exec, s[12:13]
	global_store_dwordx4 v[158:159], v[126:129], off
	s_cbranch_vccnz .LBB0_2852
	v_lshl_add_u64 v[130:131], v[140:141], 2, s[34:35]
	global_load_dwordx4 v[130:133], v[130:131], off
	s_waitcnt vmcnt(0)
	v_pk_mul_f32 v[132:133], v[128:129], v[132:133]
	v_pk_mul_f32 v[130:131], v[126:127], v[130:131]
	s_nop 0
	v_cvt_pk_bf16_f32 v130, v130, v131
	v_cvt_pk_bf16_f32 v131, v132, v133
	v_lshl_add_u64 v[132:133], v[140:141], 1, v[156:157]
	global_store_dwordx2 v[132:133], v[130:131], off

; #define GAS __attribute__((address_space(1)))
; __device__ __forceinline__ const float* ptr(int i) { const unsigned long long v = *(const volatile unsigned long long*)(g_lds + PTAB_OFF + 8 * i);
;     const unsigned lo = __builtin_amdgcn_readfirstlane((unsigned)v), hi = __builtin_amdgcn_readfirstlane((unsigned)(v >> 32)); return (const float*)(GAS const float*)(((unsigned long long)hi << 32) | lo); }
; __device__ __forceinline__ void xcd_barrier(const XcdBarrier& b) {
;     asm volatile("s_waitcnt vmcnt(0)" ::: "memory");
;     __syncthreads();
;     if (threadIdx.x == 0) {
;         unsigned* bar = b.bar;
;         __builtin_amdgcn_s_waitcnt(0);
;         unsigned nloc = b.st[0], nx = b.st[1];
;         if (nloc == 0u) { xcd_barrier_complete(bar, b.x, nloc, nx); b.st[0] = nloc; b.st[1] = nx; }
.LBB0_2934:
	v_readlane_b32 s0, v254, 4
	v_readlane_b32 s4, v254, 20
	s_cmp_lg_u32 s0, -1
	v_readlane_b32 s5, v254, 21
	s_cselect_b32 s0, s0, 0
	s_cselect_b32 s1, s5, 0
	s_waitcnt vmcnt(0) lgkmcnt(0)
	v_mov_b32_e32 v2, s0
	s_waitcnt lgkmcnt(0)
	v_mov_b32_e32 v3, s1
	ds_read_b64 v[2:3], v2
	s_waitcnt lgkmcnt(0)
	s_getreg_b32 s6, hwreg(HW_REG_XCC_ID, 0, 4)
	s_waitcnt vmcnt(0)
	s_waitcnt lgkmcnt(0)
	s_barrier
	v_readfirstlane_b32 s5, v3
	v_readfirstlane_b32 s4, v2
	s_mov_b64 s[0:1], exec
	v_readlane_b32 s8, v254, 1
	v_readlane_b32 s9, v254, 2
	s_and_b64 s[8:9], s[0:1], s[8:9]
	s_mov_b64 exec, s[8:9]
	s_cbranch_execnz .LBB0_2935
	s_getpc_b64 s[98:99]

; __device__ __forceinline__ void phase_final(const Ctx&, const In& in, float* h, unsigned char* ws) { const Ctx c = mk_ctx();
;     const float* rss = (const float*)(ws + WS_R + R_RSP + RB_ATTN * RSP_BYTES); const float* g = in[32];
;     for (int row = c.gw; row < T; row += c.NGW) { const float rs = rstd_of(rss, row, 1.f / 1024.f);
; #pragma unroll
;         for (int j = 0; j < 4; ++j) { const int col = 4 * c.lane + 256 * j; float* hp = h + (size_t)row * 1024 + col; *(f32x4*)hp = *(const f32x4*)hp * rs * *(const f32x4*)(g + col); } }
.LBB0_2985:
	s_mov_b64 s[0:1], src_shared_base
	v_readlane_b32 s0, v254, 3
	s_cmp_lg_u32 s0, -1
	s_cselect_b32 s0, s0, 0
	v_mov_b32_e32 v2, s0
	v_readlane_b32 s0, v254, 4
	s_cselect_b32 s2, s1, 0
	s_cmp_lg_u32 s0, -1
	v_mov_b32_e32 v3, s2
	s_cselect_b32 s0, s0, 0
	s_cselect_b32 s2, s1, 0
	v_mov_b32_e32 v4, s0
	v_mov_b32_e32 v5, s2
	v_mov_b32_e32 v1, v147
	v_readlane_b32 s3, v254, 0
	ds_read_b64 v[2:3], v2
	s_waitcnt lgkmcnt(0)
	v_readfirstlane_b32 s4, v3
	ds_read_b64 v[4:5], v4
	s_waitcnt lgkmcnt(0)
	s_lshl_b32 s3, s3, 3
	v_readfirstlane_b32 s0, v1
	s_ashr_i32 s2, s0, 6
	s_add_i32 s6, s2, s3
	s_add_i32 s0, 0, 0x20100
	s_cmp_lg_u32 s0, -1
	s_cselect_b32 s0, s0, 0
	s_cselect_b32 s1, s1, 0
	v_mov_b32_e32 v6, s0
	v_mov_b32_e32 v7, s1
	ds_read_b64 v[6:7], v6
	s_waitcnt lgkmcnt(0)
	s_cmpk_gt_i32 s6, 0x3fff
	v_readfirstlane_b32 s5, v2
	s_waitcnt lgkmcnt(0)
	v_readfirstlane_b32 s7, v5
	v_readfirstlane_b32 s8, v4
	v_readfirstlane_b32 s1, v7
	v_readfirstlane_b32 s0, v6
	s_cbranch_scc1 .LBB0_2988
	v_lshlrev_b32_e32 v2, 4, v1
	v_and_b32_e32 v2, 0x3f0, v2
	v_mov_b32_e32 v3, 0
	v_lshl_add_u64 v[4:5], s[0:1], 0, v[2:3]
	s_ashr_i32 s0, s2, 31
	s_ashr_i32 s1, s3, 31
	s_add_u32 s10, s2, s3
	s_addc_u32 s11, s0, s1
	s_lshl_b64 s[0:1], s[10:11], 7
	s_add_u32 s0, s8, s0
	s_addc_u32 s1, s7, s1
	v_readlane_b32 s12, v254, 48
	s_add_u32 s0, s0, 0x15600000
	v_readlane_b32 s13, v254, 49
	s_addc_u32 s1, s1, 0
	s_lshl_b64 s[2:3], s[12:13], 7
	s_lshl_b64 s[8:9], s[10:11], 12
	v_and_b32_e32 v1, 63, v1
	s_add_u32 s8, s5, s8
	v_lshlrev_b32_e32 v2, 4, v1
	s_addc_u32 s9, s4, s9
	v_lshl_add_u64 v[6:7], s[8:9], 0, v[2:3]
	s_mov_b64 s[4:5], 0xc00
	v_lshl_add_u64 v[6:7], v[6:7], 0, s[4:5]
	s_lshl_b64 s[4:5], s[12:13], 12
	v_mov_b32_e32 v1, 0x358637bd
	s_mov_b32 s7, 0x800000
